# v3_sc1
# baseline (speedup 1.0000x reference)
.LBB0_23:
	s_mul_hi_i32 s4, s64, 0x2aaaaaab
	s_lshr_b32 s5, s4, 31
	s_ashr_i32 s4, s4, 5
	s_add_i32 s4, s4, s5
	s_mul_i32 s5, s4, 0xffffff40
	s_lshl_b32 s65, s4, 6
	s_mul_i32 s6, s4, 0xffffd000
	s_add_i32 s5, s64, s5
	s_add_i32 s6, s16, s6
	v_or_b32_e32 v71, s65, v30
	s_cmp_gt_i32 s5, 63
	s_mov_b64 s[10:11], -1
	v_or_b32_e32 v70, 4, v71
	v_or_b32_e32 v69, 8, v71
	v_or_b32_e32 v68, 12, v71
	v_or_b32_e32 v67, 16, v71
	v_or_b32_e32 v66, 20, v71
	v_or_b32_e32 v65, 24, v71
	v_or_b32_e32 v64, 28, v71
	v_or_b32_e32 v63, 32, v71
	v_or_b32_e32 v62, 36, v71
	v_or_b32_e32 v25, 40, v71
	v_or_b32_e32 v27, 44, v71
	v_or_b32_e32 v29, 48, v71
	v_or_b32_e32 v23, 52, v71
	v_or_b32_e32 v21, 56, v71
	v_or_b32_e32 v19, 60, v71
	v_add_u32_e32 v15, 0x3cf0, v33
	v_add_u32_e32 v17, 0x3cf8, v33
	s_cbranch_scc0 .LBB0_25
	s_mov_b32 s7, s3
	v_lshl_add_u64 v[132:133], s[6:7], 2, v[12:13]
	v_mad_i64_i32 v[72:73], s[10:11], v71, s63, v[132:133]
	v_mad_i64_i32 v[76:77], s[10:11], v70, s63, v[132:133]
	v_mad_i64_i32 v[80:81], s[10:11], v69, s63, v[132:133]
	v_mad_i64_i32 v[84:85], s[10:11], v68, s63, v[132:133]
	v_mad_i64_i32 v[88:89], s[10:11], v67, s63, v[132:133]
	v_mad_i64_i32 v[92:93], s[10:11], v66, s63, v[132:133]
	v_mad_i64_i32 v[96:97], s[10:11], v65, s63, v[132:133]
	v_mad_i64_i32 v[100:101], s[10:11], v64, s63, v[132:133]
	v_mad_i64_i32 v[104:105], s[10:11], v63, s63, v[132:133]
	v_mad_i64_i32 v[108:109], s[10:11], v62, s63, v[132:133]
	v_mad_i64_i32 v[112:113], s[10:11], v25, s63, v[132:133]
	v_mad_i64_i32 v[116:117], s[10:11], v27, s63, v[132:133]
	v_mad_i64_i32 v[120:121], s[10:11], v29, s63, v[132:133]
	v_mad_i64_i32 v[124:125], s[10:11], v23, s63, v[132:133]
	v_mad_i64_i32 v[128:129], s[10:11], v21, s63, v[132:133]
	global_load_dwordx4 v[72:75], v[72:73], off
	s_nop 0
	global_load_dwordx4 v[76:79], v[76:77], off
	s_nop 0
	global_load_dwordx4 v[80:83], v[80:81], off
	s_nop 0
	global_load_dwordx4 v[84:87], v[84:85], off
	s_nop 0
	global_load_dwordx4 v[88:91], v[88:89], off
	s_nop 0
	global_load_dwordx4 v[92:95], v[92:93], off
	s_nop 0
	global_load_dwordx4 v[96:99], v[96:97], off
	s_nop 0
	global_load_dwordx4 v[100:103], v[100:101], off
	v_mad_i64_i32 v[132:133], s[10:11], v19, s63, v[132:133]
	global_load_dwordx4 v[104:107], v[104:105], off
	s_nop 0
	global_load_dwordx4 v[108:111], v[108:109], off
	s_nop 0
	global_load_dwordx4 v[112:115], v[112:113], off
	s_nop 0
	global_load_dwordx4 v[116:119], v[116:117], off
	s_nop 0
	global_load_dwordx4 v[120:123], v[120:121], off
	s_nop 0
	global_load_dwordx4 v[124:127], v[124:125], off
	s_nop 0
	global_load_dwordx4 v[128:131], v[128:129], off
	v_mov_b32_e32 v136, v1
	global_load_dwordx4 v[132:135], v[132:133], off
	v_mov_b32_e32 v137, v1
	v_mov_b32_e32 v138, v1
	v_mov_b32_e32 v139, v1
	s_add_i32 s7, s6, 0xfffff000
	s_ashr_i32 s10, s4, 1
	s_lshr_b32 s7, s7, 3
	s_and_b32 s65, s65, 64
	s_and_b32 s7, s7, 0x3e0
	s_ashr_i32 s11, s10, 31
	s_add_u32 s10, s7, s10
	s_addc_u32 s11, 0, s11
	s_and_b32 s7, s33, 0x6000
	s_lshl_b64 s[10:11], s[10:11], 15
	s_add_u32 s10, s8, s10
	s_addc_u32 s11, s9, s11
	s_add_u32 s7, s10, s7
	s_addc_u32 s11, s11, 0
	s_add_u32 s10, s7, s65
	s_addc_u32 s11, s11, 0
	s_waitcnt vmcnt(15)
	ds_write2_b32 v33, v72, v73 offset1:1
	ds_write2_b32 v33, v74, v75 offset0:2 offset1:3
	s_waitcnt vmcnt(14)
	ds_write2_b32 v34, v76, v77 offset1:1
	ds_write2_b32 v35, v78, v79 offset1:1
	s_waitcnt vmcnt(13)
	ds_write2_b32 v36, v80, v81 offset1:1
	ds_write2_b32 v37, v82, v83 offset1:1
	s_waitcnt vmcnt(12)
	ds_write2_b32 v38, v84, v85 offset1:1
	ds_write2_b32 v39, v86, v87 offset1:1
	s_waitcnt vmcnt(11)
	ds_write2_b32 v40, v88, v89 offset1:1
	ds_write2_b32 v41, v90, v91 offset1:1
	s_waitcnt vmcnt(10)
	ds_write2_b32 v42, v92, v93 offset1:1
	ds_write2_b32 v43, v94, v95 offset1:1
	s_waitcnt vmcnt(9)
	ds_write2_b32 v44, v96, v97 offset1:1
	ds_write2_b32 v45, v98, v99 offset1:1
	s_waitcnt vmcnt(8)
	ds_write2_b32 v46, v100, v101 offset1:1
	ds_write2_b32 v47, v102, v103 offset1:1
	s_waitcnt vmcnt(7)
	ds_write2_b32 v48, v104, v105 offset1:1
	ds_write2_b32 v49, v106, v107 offset1:1
	s_waitcnt vmcnt(6)
	ds_write2_b32 v50, v108, v109 offset1:1
	ds_write2_b32 v51, v110, v111 offset1:1
	s_waitcnt vmcnt(5)
	ds_write2_b32 v52, v112, v113 offset1:1
	ds_write2_b32 v53, v114, v115 offset1:1
	s_waitcnt vmcnt(4)
	ds_write2_b32 v54, v116, v117 offset1:1
	ds_write2_b32 v55, v118, v119 offset1:1
	s_waitcnt vmcnt(3)
	ds_write2_b32 v56, v120, v121 offset1:1
	ds_write2_b32 v57, v122, v123 offset1:1
	s_waitcnt vmcnt(2)
	ds_write2_b32 v58, v124, v125 offset1:1
	ds_write2_b32 v59, v126, v127 offset1:1
	s_waitcnt vmcnt(1)
	ds_write2_b32 v60, v128, v129 offset1:1
	ds_write2_b32 v61, v130, v131 offset1:1
	s_waitcnt vmcnt(0)
	ds_write2_b32 v15, v132, v133 offset1:1
	ds_write2_b32 v17, v134, v135 offset1:1
	s_waitcnt lgkmcnt(0)
	ds_read2_b32 v[72:73], v31 offset1:16
	ds_read2_b32 v[74:75], v31 offset0:65 offset1:81
	v_add_u32_e32 v104, 0x400, v31
	ds_read2_b32 v[76:77], v31 offset0:130 offset1:146
	ds_read2_b32 v[78:79], v31 offset0:195 offset1:211
	ds_read2_b32 v[80:81], v104 offset0:4 offset1:20
	ds_read2_b32 v[82:83], v104 offset0:69 offset1:85
	s_waitcnt lgkmcnt(5)
	v_mul_f32_e32 v72, 0x44800000, v72
	s_waitcnt lgkmcnt(4)
	v_mul_f32_e32 v74, 0x44800000, v74
	v_cvt_pk_fp8_f32 v136, v72, v74
	s_waitcnt lgkmcnt(3)
	v_mul_f32_e32 v72, 0x44800000, v76
	s_waitcnt lgkmcnt(2)
	v_mul_f32_e32 v74, 0x44800000, v78
	ds_read2_b32 v[84:85], v104 offset0:134 offset1:150
	ds_read2_b32 v[86:87], v104 offset0:199 offset1:215
	v_add_u32_e32 v105, 0x800, v31
	v_cvt_pk_fp8_f32 v136, v72, v74 op_sel:[0,0,1]
	s_waitcnt lgkmcnt(3)
	v_mul_f32_e32 v72, 0x44800000, v80
	s_waitcnt lgkmcnt(2)
	v_mul_f32_e32 v74, 0x44800000, v82
	ds_read2_b32 v[88:89], v105 offset0:8 offset1:24
	ds_read2_b32 v[90:91], v105 offset0:73 offset1:89
	v_cvt_pk_fp8_f32 v137, v72, v74
	s_waitcnt lgkmcnt(3)
	v_mul_f32_e32 v72, 0x44800000, v84
	s_waitcnt lgkmcnt(2)
	v_mul_f32_e32 v74, 0x44800000, v86
	ds_read2_b32 v[92:93], v105 offset0:138 offset1:154
	ds_read2_b32 v[94:95], v105 offset0:203 offset1:219
	v_add_u32_e32 v108, 0xc00, v31
	v_cvt_pk_fp8_f32 v137, v72, v74 op_sel:[0,0,1]
	s_waitcnt lgkmcnt(3)
	v_mul_f32_e32 v72, 0x44800000, v88
	s_waitcnt lgkmcnt(2)
	v_mul_f32_e32 v74, 0x44800000, v90
	ds_read2_b32 v[96:97], v108 offset0:12 offset1:28
	ds_read2_b32 v[98:99], v108 offset0:77 offset1:93
	v_cvt_pk_fp8_f32 v138, v72, v74
	s_waitcnt lgkmcnt(3)
	v_mul_f32_e32 v72, 0x44800000, v92
	s_waitcnt lgkmcnt(2)
	v_mul_f32_e32 v74, 0x44800000, v94
	ds_read2_b32 v[100:101], v108 offset0:142 offset1:158
	ds_read2_b32 v[102:103], v108 offset0:207 offset1:223
	v_cvt_pk_fp8_f32 v138, v72, v74 op_sel:[0,0,1]
	s_waitcnt lgkmcnt(3)
	v_mul_f32_e32 v72, 0x44800000, v96
	s_waitcnt lgkmcnt(2)
	v_mul_f32_e32 v74, 0x44800000, v98
	v_cvt_pk_fp8_f32 v139, v72, v74
	v_mul_f32_e32 v73, 0x44800000, v73
	v_mul_f32_e32 v74, 0x44800000, v75
	v_mov_b32_e32 v72, v1
	v_cvt_pk_fp8_f32 v72, v73, v74
	s_waitcnt lgkmcnt(1)
	v_mul_f32_e32 v73, 0x44800000, v100
	s_waitcnt lgkmcnt(0)
	v_mul_f32_e32 v74, 0x44800000, v102
	v_cvt_pk_fp8_f32 v139, v73, v74 op_sel:[0,0,1]
	v_mul_f32_e32 v73, 0x44800000, v77
	v_mul_f32_e32 v74, 0x44800000, v79
	v_cvt_pk_fp8_f32 v72, v73, v74 op_sel:[0,0,1]
	v_mul_f32_e32 v74, 0x44800000, v81
	v_mul_f32_e32 v75, 0x44800000, v83
	v_mov_b32_e32 v73, v1
	v_cvt_pk_fp8_f32 v73, v74, v75
	v_mul_f32_e32 v74, 0x44800000, v85
	v_mul_f32_e32 v75, 0x44800000, v87
	v_mul_f32_e32 v78, 0x44800000, v91
	v_cvt_pk_fp8_f32 v73, v74, v75 op_sel:[0,0,1]
	v_mul_f32_e32 v75, 0x44800000, v89
	v_mov_b32_e32 v74, v1
	v_cvt_pk_fp8_f32 v74, v75, v78
	v_mul_f32_e32 v82, 0x44800000, v97
	v_mul_f32_e32 v83, 0x44800000, v99
	v_mov_b32_e32 v75, v1
	v_cvt_pk_fp8_f32 v75, v82, v83
	v_mul_f32_e32 v78, 0x44800000, v93
	v_mul_f32_e32 v79, 0x44800000, v95
	v_cvt_pk_fp8_f32 v74, v78, v79 op_sel:[0,0,1]
	v_mul_f32_e32 v78, 0x44800000, v101
	v_mul_f32_e32 v79, 0x44800000, v103
	v_cvt_pk_fp8_f32 v75, v78, v79 op_sel:[0,0,1]
	v_lshl_add_u64 v[80:81], s[10:11], 0, v[2:3]
	ds_read2_b32 v[78:79], v31 offset0:32 offset1:48
	ds_read2_b32 v[82:83], v31 offset0:97 offset1:113
	v_lshl_add_u64 v[76:77], v[80:81], 0, v[4:5]
	global_store_dwordx4 v[76:77], v[136:139], off sc1
	v_lshl_add_u64 v[76:77], v[80:81], 0, v[6:7]
	global_store_dwordx4 v[76:77], v[72:75], off sc1
	ds_read2_b32 v[84:85], v31 offset0:162 offset1:178
	ds_read2_b32 v[86:87], v31 offset0:227 offset1:243
	s_waitcnt lgkmcnt(3)
	v_mul_f32_e32 v73, 0x44800000, v78
	s_waitcnt lgkmcnt(2)
	v_mul_f32_e32 v74, 0x44800000, v82
	v_mov_b32_e32 v72, v1
	ds_read2_b32 v[76:77], v104 offset0:36 offset1:52
	ds_read2_b32 v[88:89], v104 offset0:101 offset1:117
	v_cvt_pk_fp8_f32 v72, v73, v74
	s_waitcnt lgkmcnt(3)
	v_mul_f32_e32 v73, 0x44800000, v84
	s_waitcnt lgkmcnt(2)
	v_mul_f32_e32 v74, 0x44800000, v86
	ds_read2_b32 v[90:91], v104 offset0:166 offset1:182
	ds_read2_b32 v[92:93], v104 offset0:231 offset1:247
	v_cvt_pk_fp8_f32 v72, v73, v74 op_sel:[0,0,1]
	s_waitcnt lgkmcnt(3)
	v_mul_f32_e32 v74, 0x44800000, v76
	s_waitcnt lgkmcnt(2)
	v_mul_f32_e32 v75, 0x44800000, v88
	v_mov_b32_e32 v73, v1
	ds_read2_b32 v[94:95], v105 offset0:40 offset1:56
	ds_read2_b32 v[96:97], v105 offset0:105 offset1:121
	v_cvt_pk_fp8_f32 v73, v74, v75
	ds_read2_b32 v[98:99], v105 offset0:170 offset1:186
	ds_read2_b32 v[100:101], v105 offset0:235 offset1:251
	ds_read2_b32 v[102:103], v108 offset0:44 offset1:60
	ds_read2_b32 v[104:105], v108 offset0:109 offset1:125
	s_waitcnt lgkmcnt(7)
	v_mul_f32_e32 v74, 0x44800000, v90
	s_waitcnt lgkmcnt(6)
	v_mul_f32_e32 v75, 0x44800000, v92
	v_cvt_pk_fp8_f32 v73, v74, v75 op_sel:[0,0,1]
	s_waitcnt lgkmcnt(5)
	v_mul_f32_e32 v75, 0x44800000, v94
	s_waitcnt lgkmcnt(4)
	v_mul_f32_e32 v76, 0x44800000, v96
	v_mov_b32_e32 v74, v1
	ds_read2_b32 v[106:107], v108 offset0:174 offset1:190
	ds_read2_b32 v[108:109], v108 offset0:239 offset1:255
	v_cvt_pk_fp8_f32 v74, v75, v76
	v_mov_b32_e32 v75, v1
	s_waitcnt lgkmcnt(3)
	v_mul_f32_e32 v82, 0x44800000, v102
	s_waitcnt lgkmcnt(2)
	v_mul_f32_e32 v84, 0x44800000, v104
	v_cvt_pk_fp8_f32 v75, v82, v84
	v_mul_f32_e32 v76, 0x44800000, v98
	v_mul_f32_e32 v78, 0x44800000, v100
	v_cvt_pk_fp8_f32 v74, v76, v78 op_sel:[0,0,1]
	s_waitcnt lgkmcnt(1)
	v_mul_f32_e32 v76, 0x44800000, v106
	s_waitcnt lgkmcnt(0)
	v_mul_f32_e32 v78, 0x44800000, v108
	v_cvt_pk_fp8_f32 v75, v76, v78 op_sel:[0,0,1]
	v_mul_f32_e32 v78, 0x44800000, v79
	v_mul_f32_e32 v79, 0x44800000, v83
	v_mov_b32_e32 v76, v1
	v_cvt_pk_fp8_f32 v76, v78, v79
	v_mul_f32_e32 v78, 0x44800000, v77
	v_mul_f32_e32 v79, 0x44800000, v89
	v_mov_b32_e32 v77, v1
	v_cvt_pk_fp8_f32 v77, v78, v79
	v_mul_f32_e32 v78, 0x44800000, v85
	v_mul_f32_e32 v79, 0x44800000, v87
	v_cvt_pk_fp8_f32 v76, v78, v79 op_sel:[0,0,1]
	v_mul_f32_e32 v78, 0x44800000, v91
	v_mul_f32_e32 v79, 0x44800000, v93
	v_cvt_pk_fp8_f32 v77, v78, v79 op_sel:[0,0,1]
	v_mul_f32_e32 v79, 0x44800000, v95
	v_mul_f32_e32 v82, 0x44800000, v97
	v_mov_b32_e32 v78, v1
	v_cvt_pk_fp8_f32 v78, v79, v82
	v_mul_f32_e32 v84, 0x44800000, v103
	v_mul_f32_e32 v85, 0x44800000, v105
	v_mov_b32_e32 v79, v1
	v_cvt_pk_fp8_f32 v79, v84, v85
	v_mul_f32_e32 v82, 0x44800000, v99
	v_mul_f32_e32 v83, 0x44800000, v101
	v_cvt_pk_fp8_f32 v78, v82, v83 op_sel:[0,0,1]
	v_mul_f32_e32 v82, 0x44800000, v107
	v_mul_f32_e32 v83, 0x44800000, v109
	v_cvt_pk_fp8_f32 v79, v82, v83 op_sel:[0,0,1]
	v_lshl_add_u64 v[82:83], v[80:81], 0, v[8:9]
	global_store_dwordx4 v[82:83], v[72:75], off sc1
	s_mov_b64 s[10:11], 0
	s_nop 0
	v_lshl_add_u64 v[72:73], v[80:81], 0, v[10:11]
	global_store_dwordx4 v[72:73], v[76:79], off sc1
	s_waitcnt lgkmcnt(0)
.LBB0_25:
	s_andn2_b64 vcc, exec, s[10:11]
	s_cbranch_vccnz .LBB0_22
	s_ashr_i32 s7, s6, 31
	v_lshl_add_u64 v[122:123], s[6:7], 2, v[12:13]
	v_mad_i64_i32 v[72:73], s[6:7], v71, s63, v[122:123]
	v_mad_i64_i32 v[74:75], s[6:7], v70, s63, v[122:123]
	v_mad_i64_i32 v[78:79], s[6:7], v69, s63, v[122:123]
	v_mad_i64_i32 v[68:69], s[6:7], v68, s63, v[122:123]
	global_load_dwordx4 v[70:73], v[72:73], off
	s_nop 0
	global_load_dwordx4 v[74:77], v[74:75], off
	s_nop 0
	global_load_dwordx4 v[78:81], v[78:79], off
	s_nop 0
	global_load_dwordx4 v[82:85], v[68:69], off
	v_mad_i64_i32 v[68:69], s[6:7], v67, s63, v[122:123]
	v_mad_i64_i32 v[86:87], s[6:7], v66, s63, v[122:123]
	v_mad_i64_i32 v[90:91], s[6:7], v65, s63, v[122:123]
	v_mad_i64_i32 v[64:65], s[6:7], v64, s63, v[122:123]
	global_load_dwordx4 v[66:69], v[68:69], off
	s_nop 0
	global_load_dwordx4 v[86:89], v[86:87], off
	s_nop 0
	global_load_dwordx4 v[90:93], v[90:91], off
	s_nop 0
	global_load_dwordx4 v[94:97], v[64:65], off
	v_mad_i64_i32 v[64:65], s[6:7], v63, s63, v[122:123]
	v_mad_i64_i32 v[98:99], s[6:7], v62, s63, v[122:123]
	v_mad_i64_i32 v[102:103], s[6:7], v25, s63, v[122:123]
	v_mad_i64_i32 v[106:107], s[6:7], v27, s63, v[122:123]
	v_mad_i64_i32 v[110:111], s[6:7], v29, s63, v[122:123]
	v_mad_i64_i32 v[114:115], s[6:7], v23, s63, v[122:123]
	v_mad_i64_i32 v[118:119], s[6:7], v21, s63, v[122:123]
	global_load_dwordx4 v[62:65], v[64:65], off
	s_nop 0
	global_load_dwordx4 v[98:101], v[98:99], off
	v_mad_i64_i32 v[122:123], s[6:7], v19, s63, v[122:123]
	global_load_dwordx4 v[102:105], v[102:103], off
	s_nop 0
	global_load_dwordx4 v[106:109], v[106:107], off
	s_nop 0
	global_load_dwordx4 v[110:113], v[110:111], off
	s_nop 0
	global_load_dwordx4 v[114:117], v[114:115], off
	s_nop 0
	global_load_dwordx4 v[118:121], v[118:119], off
	s_ashr_i32 s6, s5, 2
	global_load_dwordx4 v[122:125], v[122:123], off
	s_and_b32 s10, s61, 0x3000
	s_ashr_i32 s5, s4, 31
	s_ashr_i32 s7, s6, 31
	s_lshl_b32 s10, s10, 1
	s_add_u32 s10, s30, s10
	s_addc_u32 s11, s31, 0
	s_lshl_b64 s[6:7], s[6:7], 21
	s_lshl_b64 s[4:5], s[4:5], 15
	s_add_u32 s6, s10, s6
	s_addc_u32 s7, s11, s7
	s_add_u32 s4, s6, s4
	v_add_u32_e32 v29, 0x400, v32
	s_addc_u32 s5, s7, s5
	v_mov_b32_e32 v19, v1
	v_mov_b32_e32 v21, v1
	v_mov_b32_e32 v23, v1
	v_mov_b32_e32 v25, v1
	v_mov_b32_e32 v27, v1
	s_waitcnt vmcnt(15)
	ds_write2_b32 v33, v70, v71 offset1:1
	ds_write2_b32 v33, v72, v73 offset0:2 offset1:3
	s_waitcnt vmcnt(14)
	ds_write2_b32 v34, v74, v75 offset1:1
	ds_write2_b32 v35, v76, v77 offset1:1
	s_waitcnt vmcnt(13)
	ds_write2_b32 v36, v78, v79 offset1:1
	ds_write2_b32 v37, v80, v81 offset1:1
	s_waitcnt vmcnt(12)
	ds_write2_b32 v38, v82, v83 offset1:1
	ds_write2_b32 v39, v84, v85 offset1:1
	s_waitcnt vmcnt(11)
	ds_write2_b32 v40, v66, v67 offset1:1
	ds_write2_b32 v41, v68, v69 offset1:1
	s_waitcnt vmcnt(10)
	ds_write2_b32 v42, v86, v87 offset1:1
	ds_write2_b32 v43, v88, v89 offset1:1
	s_waitcnt vmcnt(9)
	ds_write2_b32 v44, v90, v91 offset1:1
	ds_write2_b32 v45, v92, v93 offset1:1
	s_waitcnt vmcnt(8)
	ds_write2_b32 v46, v94, v95 offset1:1
	ds_write2_b32 v47, v96, v97 offset1:1
	s_waitcnt vmcnt(7)
	ds_write2_b32 v48, v62, v63 offset1:1
	ds_write2_b32 v49, v64, v65 offset1:1
	s_waitcnt vmcnt(6)
	ds_write2_b32 v50, v98, v99 offset1:1
	ds_write2_b32 v51, v100, v101 offset1:1
	s_waitcnt vmcnt(5)
	ds_write2_b32 v52, v102, v103 offset1:1
	ds_write2_b32 v53, v104, v105 offset1:1
	s_waitcnt vmcnt(4)
	ds_write2_b32 v54, v106, v107 offset1:1
	ds_write2_b32 v55, v108, v109 offset1:1
	s_waitcnt vmcnt(3)
	ds_write2_b32 v56, v110, v111 offset1:1
	ds_write2_b32 v57, v112, v113 offset1:1
	s_waitcnt vmcnt(2)
	ds_write2_b32 v58, v114, v115 offset1:1
	ds_write2_b32 v59, v116, v117 offset1:1
	s_waitcnt vmcnt(1)
	ds_write2_b32 v60, v118, v119 offset1:1
	ds_write2_b32 v61, v120, v121 offset1:1
	s_waitcnt vmcnt(0)
	ds_write2_b32 v15, v122, v123 offset1:1
	ds_write2_b32 v17, v124, v125 offset1:1
	s_waitcnt lgkmcnt(0)
	ds_read2_b32 v[62:63], v32 offset1:65
	s_waitcnt lgkmcnt(0)
	v_cvt_pk_bf16_f32 v62, v62, v63
	ds_read2_b32 v[64:65], v32 offset0:130 offset1:195
	v_mov_b32_e32 v15, v1
	s_waitcnt lgkmcnt(0)
	v_cvt_pk_bf16_f32 v63, v64, v65
	ds_read2_b32 v[64:65], v29 offset0:4 offset1:69
	v_lshl_add_u64 v[68:69], s[4:5], 0, v[0:1]
	s_waitcnt lgkmcnt(0)
	v_cvt_pk_bf16_f32 v64, v64, v65
	ds_read2_b32 v[66:67], v29 offset0:134 offset1:199
	s_waitcnt lgkmcnt(0)
	v_cvt_pk_bf16_f32 v65, v66, v67
	v_lshl_add_u64 v[70:71], v[68:69], 0, v[14:15]
	ds_read2_b32 v[66:67], v32 offset0:8 offset1:73
	global_store_dwordx4 v[70:71], v[62:65], off sc1
	v_mov_b32_e32 v17, v1
	v_lshl_add_u64 v[70:71], v[68:69], 0, v[16:17]
	s_waitcnt lgkmcnt(0)
	v_cvt_pk_bf16_f32 v62, v66, v67
	ds_read2_b32 v[64:65], v32 offset0:138 offset1:203
	s_waitcnt lgkmcnt(0)
	v_cvt_pk_bf16_f32 v63, v64, v65
	ds_read2_b32 v[64:65], v29 offset0:12 offset1:77
	s_waitcnt lgkmcnt(0)
	v_cvt_pk_bf16_f32 v64, v64, v65
	ds_read2_b32 v[66:67], v29 offset0:142 offset1:207
	s_waitcnt lgkmcnt(0)
	v_cvt_pk_bf16_f32 v65, v66, v67
	ds_read2_b32 v[66:67], v32 offset0:16 offset1:81
	global_store_dwordx4 v[70:71], v[62:65], off sc1
	v_lshl_add_u64 v[70:71], v[68:69], 0, v[18:19]
	s_waitcnt lgkmcnt(0)
	v_cvt_pk_bf16_f32 v62, v66, v67
	ds_read2_b32 v[64:65], v32 offset0:146 offset1:211
	s_waitcnt lgkmcnt(0)
	v_cvt_pk_bf16_f32 v63, v64, v65
	ds_read2_b32 v[64:65], v29 offset0:20 offset1:85
	s_waitcnt lgkmcnt(0)
	v_cvt_pk_bf16_f32 v64, v64, v65
	ds_read2_b32 v[66:67], v29 offset0:150 offset1:215
	s_waitcnt lgkmcnt(0)
	v_cvt_pk_bf16_f32 v65, v66, v67
	ds_read2_b32 v[66:67], v32 offset0:24 offset1:89
	global_store_dwordx4 v[70:71], v[62:65], off sc1
	v_lshl_add_u64 v[70:71], v[68:69], 0, v[20:21]
	s_waitcnt lgkmcnt(0)
	v_cvt_pk_bf16_f32 v62, v66, v67
	ds_read2_b32 v[64:65], v32 offset0:154 offset1:219
	s_waitcnt lgkmcnt(0)
	v_cvt_pk_bf16_f32 v63, v64, v65
	ds_read2_b32 v[64:65], v29 offset0:28 offset1:93
	s_waitcnt lgkmcnt(0)
	v_cvt_pk_bf16_f32 v64, v64, v65
	ds_read2_b32 v[66:67], v29 offset0:158 offset1:223
	s_waitcnt lgkmcnt(0)
	v_cvt_pk_bf16_f32 v65, v66, v67
	ds_read2_b32 v[66:67], v32 offset0:32 offset1:97
	global_store_dwordx4 v[70:71], v[62:65], off sc1
	v_lshl_add_u64 v[70:71], v[68:69], 0, v[22:23]
	s_waitcnt lgkmcnt(0)
	v_cvt_pk_bf16_f32 v62, v66, v67
	ds_read2_b32 v[64:65], v32 offset0:162 offset1:227
	s_waitcnt lgkmcnt(0)
	v_cvt_pk_bf16_f32 v63, v64, v65
	ds_read2_b32 v[64:65], v29 offset0:36 offset1:101
	s_waitcnt lgkmcnt(0)
	v_cvt_pk_bf16_f32 v64, v64, v65
	ds_read2_b32 v[66:67], v29 offset0:166 offset1:231
	s_waitcnt lgkmcnt(0)
	v_cvt_pk_bf16_f32 v65, v66, v67
	ds_read2_b32 v[66:67], v32 offset0:40 offset1:105
	global_store_dwordx4 v[70:71], v[62:65], off sc1
	v_lshl_add_u64 v[70:71], v[68:69], 0, v[24:25]
	s_waitcnt lgkmcnt(0)
	v_cvt_pk_bf16_f32 v62, v66, v67
	ds_read2_b32 v[64:65], v32 offset0:170 offset1:235
	s_waitcnt lgkmcnt(0)
	v_cvt_pk_bf16_f32 v63, v64, v65
	ds_read2_b32 v[64:65], v29 offset0:44 offset1:109
	s_waitcnt lgkmcnt(0)
	v_cvt_pk_bf16_f32 v64, v64, v65
	ds_read2_b32 v[66:67], v29 offset0:174 offset1:239
	s_waitcnt lgkmcnt(0)
	v_cvt_pk_bf16_f32 v65, v66, v67
	ds_read2_b32 v[66:67], v32 offset0:48 offset1:113
	global_store_dwordx4 v[70:71], v[62:65], off sc1
	v_lshl_add_u64 v[70:71], v[68:69], 0, v[26:27]
	s_waitcnt lgkmcnt(0)
	v_cvt_pk_bf16_f32 v62, v66, v67
	ds_read2_b32 v[64:65], v32 offset0:178 offset1:243
	s_waitcnt lgkmcnt(0)
	v_cvt_pk_bf16_f32 v63, v64, v65
	ds_read2_b32 v[64:65], v29 offset0:52 offset1:117
	s_waitcnt lgkmcnt(0)
	v_cvt_pk_bf16_f32 v64, v64, v65
	ds_read2_b32 v[66:67], v29 offset0:182 offset1:247
	s_waitcnt lgkmcnt(0)
	v_cvt_pk_bf16_f32 v65, v66, v67
	ds_read2_b32 v[66:67], v32 offset0:56 offset1:121
	global_store_dwordx4 v[70:71], v[62:65], off sc1
	s_waitcnt lgkmcnt(0)
	s_nop 0
	v_cvt_pk_bf16_f32 v62, v66, v67
	ds_read2_b32 v[64:65], v32 offset0:186 offset1:251
	s_waitcnt lgkmcnt(0)
	v_cvt_pk_bf16_f32 v63, v64, v65
	ds_read2_b32 v[64:65], v29 offset0:60 offset1:125
	s_waitcnt lgkmcnt(0)
	v_cvt_pk_bf16_f32 v64, v64, v65
	ds_read2_b32 v[66:67], v29 offset0:190 offset1:255
	v_mov_b32_e32 v29, v1
	s_waitcnt lgkmcnt(0)
	v_cvt_pk_bf16_f32 v65, v66, v67
	v_lshl_add_u64 v[66:67], v[68:69], 0, v[28:29]
	global_store_dwordx4 v[66:67], v[62:65], off sc1
	s_waitcnt lgkmcnt(0)
	s_branch .LBB0_22

.LBB0_121:
	s_lshl_b32 s6, s6, 8
	s_add_i32 s6, s6, s85
	v_and_or_b32 v145, v132, 15, s6
	s_lshl_b32 s6, s33, 8
	v_lshrrev_b32_e32 v132, 1, v132
	v_and_or_b32 v132, v132, 24, s6
	v_or_b32_e32 v132, s86, v132
	v_mov_b64_e32 v[134:135], s[14:15]
	v_ashrrev_i32_e32 v133, 31, v132
	v_mad_i64_i32 v[134:135], s[6:7], v145, s84, v[134:135]
	s_nop 1
	v_cvt_pk_bf16_f32 v124, v124, v125
	s_nop 1
	v_cvt_pk_bf16_f32 v125, v126, v127
	s_nop 1
	v_cvt_pk_bf16_f32 v126, v120, v121
	v_cndmask_b32_e64 v120, 0, 1, s[16:17]
	v_lshl_add_u64 v[134:135], v[132:133], 1, v[134:135]
	v_cmp_ne_u32_e64 s[6:7], 1, v120
	s_andn2_b64 vcc, exec, s[16:17]
	s_nop 1
	v_cvt_pk_bf16_f32 v127, v122, v123
	global_store_dwordx4 v[134:135], v[124:127], off sc1
	s_cbranch_vccnz .LBB0_123
	v_mul_f32_e32 v116, 0xbfb8aa3b, v116
	v_mul_f32_e32 v112, 0xbfb8aa3b, v112
	v_mul_f32_e32 v117, 0xbfb8aa3b, v117
	v_mul_f32_e32 v113, 0xbfb8aa3b, v113
	v_mul_f32_e32 v118, 0xbfb8aa3b, v118
	v_mul_f32_e32 v114, 0xbfb8aa3b, v114
	v_mul_f32_e32 v119, 0xbfb8aa3b, v119
	v_mul_f32_e32 v115, 0xbfb8aa3b, v115
	v_exp_f32_e32 v116, v116
	v_exp_f32_e32 v112, v112
	v_exp_f32_e32 v117, v117
	v_exp_f32_e32 v113, v113
	v_exp_f32_e32 v118, v118
	v_exp_f32_e32 v114, v114
	v_exp_f32_e32 v119, v119
	v_exp_f32_e32 v115, v115
	v_add_f32_e32 v116, 1.0, v116
	v_add_f32_e32 v112, 1.0, v112
	v_add_f32_e32 v117, 1.0, v117
	v_add_f32_e32 v113, 1.0, v113
	v_add_f32_e32 v118, 1.0, v118
	v_add_f32_e32 v114, 1.0, v114
	v_add_f32_e32 v119, 1.0, v119
	v_add_f32_e32 v115, 1.0, v115
	v_rcp_f32_e32 v116, v116
	v_rcp_f32_e32 v112, v112
	v_rcp_f32_e32 v117, v117
	v_rcp_f32_e32 v113, v113
	v_rcp_f32_e32 v118, v118
	v_rcp_f32_e32 v114, v114
	v_rcp_f32_e32 v119, v119
	v_rcp_f32_e32 v115, v115
.LBB0_123:
	s_and_b64 vcc, exec, s[6:7]
	s_nop 1
	v_cvt_pk_bf16_f32 v116, v116, v117
	s_nop 1
	v_cvt_pk_bf16_f32 v117, v118, v119
	s_nop 1
	v_cvt_pk_bf16_f32 v118, v112, v113
	s_nop 1
	v_cvt_pk_bf16_f32 v119, v114, v115
	global_store_dwordx4 v[134:135], v[116:119], off offset:256 sc1
	s_cbranch_vccnz .LBB0_125
	v_mul_f32_e32 v108, 0xbfb8aa3b, v108
	v_mul_f32_e32 v104, 0xbfb8aa3b, v104
	v_mul_f32_e32 v109, 0xbfb8aa3b, v109
	v_mul_f32_e32 v105, 0xbfb8aa3b, v105
	v_mul_f32_e32 v110, 0xbfb8aa3b, v110
	v_mul_f32_e32 v106, 0xbfb8aa3b, v106
	v_mul_f32_e32 v111, 0xbfb8aa3b, v111
	v_mul_f32_e32 v107, 0xbfb8aa3b, v107
	v_exp_f32_e32 v108, v108
	v_exp_f32_e32 v104, v104
	v_exp_f32_e32 v109, v109
	v_exp_f32_e32 v105, v105
	v_exp_f32_e32 v110, v110
	v_exp_f32_e32 v106, v106
	v_exp_f32_e32 v111, v111
	v_exp_f32_e32 v107, v107
	v_add_f32_e32 v108, 1.0, v108
	v_add_f32_e32 v104, 1.0, v104
	v_add_f32_e32 v109, 1.0, v109
	v_add_f32_e32 v105, 1.0, v105
	v_add_f32_e32 v110, 1.0, v110
	v_add_f32_e32 v106, 1.0, v106
	v_add_f32_e32 v111, 1.0, v111
	v_add_f32_e32 v107, 1.0, v107
	v_rcp_f32_e32 v108, v108
	v_rcp_f32_e32 v104, v104
	v_rcp_f32_e32 v109, v109
	v_rcp_f32_e32 v105, v105
	v_rcp_f32_e32 v110, v110
	v_rcp_f32_e32 v106, v106
	v_rcp_f32_e32 v111, v111
	v_rcp_f32_e32 v107, v107
.LBB0_125:
	v_or_b32_e32 v114, 16, v145
	v_mov_b64_e32 v[112:113], s[14:15]
	v_mad_i64_i32 v[112:113], s[16:17], v114, s84, v[112:113]
	v_lshl_add_u64 v[112:113], v[132:133], 1, v[112:113]
	s_and_b64 vcc, exec, s[6:7]
	s_nop 1
	v_cvt_pk_bf16_f32 v108, v108, v109
	s_nop 1
	v_cvt_pk_bf16_f32 v109, v110, v111
	s_nop 1
	v_cvt_pk_bf16_f32 v110, v104, v105
	s_nop 1
	v_cvt_pk_bf16_f32 v111, v106, v107
	global_store_dwordx4 v[112:113], v[108:111], off sc1
	s_cbranch_vccnz .LBB0_127
	v_mul_f32_e32 v100, 0xbfb8aa3b, v100
	v_mul_f32_e32 v96, 0xbfb8aa3b, v96
	v_mul_f32_e32 v101, 0xbfb8aa3b, v101
	v_mul_f32_e32 v97, 0xbfb8aa3b, v97
	v_mul_f32_e32 v102, 0xbfb8aa3b, v102
	v_mul_f32_e32 v98, 0xbfb8aa3b, v98
	v_mul_f32_e32 v103, 0xbfb8aa3b, v103
	v_mul_f32_e32 v99, 0xbfb8aa3b, v99
	v_exp_f32_e32 v100, v100
	v_exp_f32_e32 v96, v96
	v_exp_f32_e32 v101, v101
	v_exp_f32_e32 v97, v97
	v_exp_f32_e32 v102, v102
	v_exp_f32_e32 v98, v98
	v_exp_f32_e32 v103, v103
	v_exp_f32_e32 v99, v99
	v_add_f32_e32 v100, 1.0, v100
	v_add_f32_e32 v96, 1.0, v96
	v_add_f32_e32 v101, 1.0, v101
	v_add_f32_e32 v97, 1.0, v97
	v_add_f32_e32 v102, 1.0, v102
	v_add_f32_e32 v98, 1.0, v98
	v_add_f32_e32 v103, 1.0, v103
	v_add_f32_e32 v99, 1.0, v99
	v_rcp_f32_e32 v100, v100
	v_rcp_f32_e32 v96, v96
	v_rcp_f32_e32 v101, v101
	v_rcp_f32_e32 v97, v97
	v_rcp_f32_e32 v102, v102
	v_rcp_f32_e32 v98, v98
	v_rcp_f32_e32 v103, v103
	v_rcp_f32_e32 v99, v99
.LBB0_127:
	s_and_b64 vcc, exec, s[6:7]
	s_nop 1
	v_cvt_pk_bf16_f32 v100, v100, v101
	s_nop 1
	v_cvt_pk_bf16_f32 v101, v102, v103
	s_nop 1
	v_cvt_pk_bf16_f32 v102, v96, v97
	s_nop 1
	v_cvt_pk_bf16_f32 v103, v98, v99
	global_store_dwordx4 v[112:113], v[100:103], off offset:256 sc1
	s_cbranch_vccnz .LBB0_129
	v_mul_f32_e32 v92, 0xbfb8aa3b, v92
	v_mul_f32_e32 v88, 0xbfb8aa3b, v88
	v_mul_f32_e32 v93, 0xbfb8aa3b, v93
	v_mul_f32_e32 v89, 0xbfb8aa3b, v89
	v_mul_f32_e32 v94, 0xbfb8aa3b, v94
	v_mul_f32_e32 v90, 0xbfb8aa3b, v90
	v_mul_f32_e32 v95, 0xbfb8aa3b, v95
	v_mul_f32_e32 v91, 0xbfb8aa3b, v91
	v_exp_f32_e32 v92, v92
	v_exp_f32_e32 v88, v88
	v_exp_f32_e32 v93, v93
	v_exp_f32_e32 v89, v89
	v_exp_f32_e32 v94, v94
	v_exp_f32_e32 v90, v90
	v_exp_f32_e32 v95, v95
	v_exp_f32_e32 v91, v91
	v_add_f32_e32 v92, 1.0, v92
	v_add_f32_e32 v88, 1.0, v88
	v_add_f32_e32 v93, 1.0, v93
	v_add_f32_e32 v89, 1.0, v89
	v_add_f32_e32 v94, 1.0, v94
	v_add_f32_e32 v90, 1.0, v90
	v_add_f32_e32 v95, 1.0, v95
	v_add_f32_e32 v91, 1.0, v91
	v_rcp_f32_e32 v92, v92
	v_rcp_f32_e32 v88, v88
	v_rcp_f32_e32 v93, v93
	v_rcp_f32_e32 v89, v89
	v_rcp_f32_e32 v94, v94
	v_rcp_f32_e32 v90, v90
	v_rcp_f32_e32 v95, v95
	v_rcp_f32_e32 v91, v91
.LBB0_129:
	v_or_b32_e32 v98, 32, v145
	v_mov_b64_e32 v[96:97], s[14:15]
	v_mad_i64_i32 v[96:97], s[16:17], v98, s84, v[96:97]
	v_lshl_add_u64 v[96:97], v[132:133], 1, v[96:97]
	s_and_b64 vcc, exec, s[6:7]
	s_nop 1
	v_cvt_pk_bf16_f32 v92, v92, v93
	s_nop 1
	v_cvt_pk_bf16_f32 v93, v94, v95
	s_nop 1
	v_cvt_pk_bf16_f32 v94, v88, v89
	s_nop 1
	v_cvt_pk_bf16_f32 v95, v90, v91
	global_store_dwordx4 v[96:97], v[92:95], off sc1
	s_cbranch_vccnz .LBB0_131
	v_mul_f32_e32 v84, 0xbfb8aa3b, v84
	v_mul_f32_e32 v80, 0xbfb8aa3b, v80
	v_mul_f32_e32 v85, 0xbfb8aa3b, v85
	v_mul_f32_e32 v81, 0xbfb8aa3b, v81
	v_mul_f32_e32 v86, 0xbfb8aa3b, v86
	v_mul_f32_e32 v82, 0xbfb8aa3b, v82
	v_mul_f32_e32 v87, 0xbfb8aa3b, v87
	v_mul_f32_e32 v83, 0xbfb8aa3b, v83
	v_exp_f32_e32 v84, v84
	v_exp_f32_e32 v80, v80
	v_exp_f32_e32 v85, v85
	v_exp_f32_e32 v81, v81
	v_exp_f32_e32 v86, v86
	v_exp_f32_e32 v82, v82
	v_exp_f32_e32 v87, v87
	v_exp_f32_e32 v83, v83
	v_add_f32_e32 v84, 1.0, v84
	v_add_f32_e32 v80, 1.0, v80
	v_add_f32_e32 v85, 1.0, v85
	v_add_f32_e32 v81, 1.0, v81
	v_add_f32_e32 v86, 1.0, v86
	v_add_f32_e32 v82, 1.0, v82
	v_add_f32_e32 v87, 1.0, v87
	v_add_f32_e32 v83, 1.0, v83
	v_rcp_f32_e32 v84, v84
	v_rcp_f32_e32 v80, v80
	v_rcp_f32_e32 v85, v85
	v_rcp_f32_e32 v81, v81
	v_rcp_f32_e32 v86, v86
	v_rcp_f32_e32 v82, v82
	v_rcp_f32_e32 v87, v87
	v_rcp_f32_e32 v83, v83
.LBB0_131:
	s_and_b64 vcc, exec, s[6:7]
	s_nop 1
	v_cvt_pk_bf16_f32 v84, v84, v85
	s_nop 1
	v_cvt_pk_bf16_f32 v85, v86, v87
	s_nop 1
	v_cvt_pk_bf16_f32 v86, v80, v81
	s_nop 1
	v_cvt_pk_bf16_f32 v87, v82, v83
	global_store_dwordx4 v[96:97], v[84:87], off offset:256 sc1
	s_cbranch_vccnz .LBB0_133
	v_mul_f32_e32 v76, 0xbfb8aa3b, v76
	v_mul_f32_e32 v72, 0xbfb8aa3b, v72
	v_mul_f32_e32 v77, 0xbfb8aa3b, v77
	v_mul_f32_e32 v73, 0xbfb8aa3b, v73
	v_mul_f32_e32 v78, 0xbfb8aa3b, v78
	v_mul_f32_e32 v74, 0xbfb8aa3b, v74
	v_mul_f32_e32 v79, 0xbfb8aa3b, v79
	v_mul_f32_e32 v75, 0xbfb8aa3b, v75
	v_exp_f32_e32 v76, v76
	v_exp_f32_e32 v72, v72
	v_exp_f32_e32 v77, v77
	v_exp_f32_e32 v73, v73
	v_exp_f32_e32 v78, v78
	v_exp_f32_e32 v74, v74
	v_exp_f32_e32 v79, v79
	v_exp_f32_e32 v75, v75
	v_add_f32_e32 v76, 1.0, v76
	v_add_f32_e32 v72, 1.0, v72
	v_add_f32_e32 v77, 1.0, v77
	v_add_f32_e32 v73, 1.0, v73
	v_add_f32_e32 v78, 1.0, v78
	v_add_f32_e32 v74, 1.0, v74
	v_add_f32_e32 v79, 1.0, v79
	v_add_f32_e32 v75, 1.0, v75
	v_rcp_f32_e32 v76, v76
	v_rcp_f32_e32 v72, v72
	v_rcp_f32_e32 v77, v77
	v_rcp_f32_e32 v73, v73
	v_rcp_f32_e32 v78, v78
	v_rcp_f32_e32 v74, v74
	v_rcp_f32_e32 v79, v79
	v_rcp_f32_e32 v75, v75
.LBB0_133:
	v_or_b32_e32 v82, 48, v145
	v_mov_b64_e32 v[80:81], s[14:15]
	v_mad_i64_i32 v[80:81], s[16:17], v82, s84, v[80:81]
	v_lshl_add_u64 v[80:81], v[132:133], 1, v[80:81]
	s_and_b64 vcc, exec, s[6:7]
	s_nop 1
	v_cvt_pk_bf16_f32 v76, v76, v77
	s_nop 1
	v_cvt_pk_bf16_f32 v77, v78, v79
	s_nop 1
	v_cvt_pk_bf16_f32 v78, v72, v73
	s_nop 1
	v_cvt_pk_bf16_f32 v79, v74, v75
	global_store_dwordx4 v[80:81], v[76:79], off sc1
	s_cbranch_vccnz .LBB0_135
	v_mul_f32_e32 v68, 0xbfb8aa3b, v68
	v_mul_f32_e32 v64, 0xbfb8aa3b, v64
	v_mul_f32_e32 v69, 0xbfb8aa3b, v69
	v_mul_f32_e32 v65, 0xbfb8aa3b, v65
	v_mul_f32_e32 v70, 0xbfb8aa3b, v70
	v_mul_f32_e32 v66, 0xbfb8aa3b, v66
	v_mul_f32_e32 v71, 0xbfb8aa3b, v71
	v_mul_f32_e32 v67, 0xbfb8aa3b, v67
	v_exp_f32_e32 v68, v68
	v_exp_f32_e32 v64, v64
	v_exp_f32_e32 v69, v69
	v_exp_f32_e32 v65, v65
	v_exp_f32_e32 v70, v70
	v_exp_f32_e32 v66, v66
	v_exp_f32_e32 v71, v71
	v_exp_f32_e32 v67, v67
	v_add_f32_e32 v68, 1.0, v68
	v_add_f32_e32 v64, 1.0, v64
	v_add_f32_e32 v69, 1.0, v69
	v_add_f32_e32 v65, 1.0, v65
	v_add_f32_e32 v70, 1.0, v70
	v_add_f32_e32 v66, 1.0, v66
	v_add_f32_e32 v71, 1.0, v71
	v_add_f32_e32 v67, 1.0, v67
	v_rcp_f32_e32 v68, v68
	v_rcp_f32_e32 v64, v64
	v_rcp_f32_e32 v69, v69
	v_rcp_f32_e32 v65, v65
	v_rcp_f32_e32 v70, v70
	v_rcp_f32_e32 v66, v66
	v_rcp_f32_e32 v71, v71
	v_rcp_f32_e32 v67, v67
.LBB0_135:
	s_and_b64 vcc, exec, s[6:7]
	s_nop 1
	v_cvt_pk_bf16_f32 v68, v68, v69
	s_nop 1
	v_cvt_pk_bf16_f32 v69, v70, v71
	s_nop 1
	v_cvt_pk_bf16_f32 v70, v64, v65
	s_nop 1
	v_cvt_pk_bf16_f32 v71, v66, v67
	global_store_dwordx4 v[80:81], v[68:71], off offset:256 sc1
	s_cbranch_vccnz .LBB0_137
	v_mul_f32_e32 v60, 0xbfb8aa3b, v60
	v_mul_f32_e32 v56, 0xbfb8aa3b, v56
	v_mul_f32_e32 v61, 0xbfb8aa3b, v61
	v_mul_f32_e32 v57, 0xbfb8aa3b, v57
	v_mul_f32_e32 v62, 0xbfb8aa3b, v62
	v_mul_f32_e32 v58, 0xbfb8aa3b, v58
	v_mul_f32_e32 v63, 0xbfb8aa3b, v63
	v_mul_f32_e32 v59, 0xbfb8aa3b, v59
	v_exp_f32_e32 v60, v60
	v_exp_f32_e32 v56, v56
	v_exp_f32_e32 v61, v61
	v_exp_f32_e32 v57, v57
	v_exp_f32_e32 v62, v62
	v_exp_f32_e32 v58, v58
	v_exp_f32_e32 v63, v63
	v_exp_f32_e32 v59, v59
	v_add_f32_e32 v60, 1.0, v60
	v_add_f32_e32 v56, 1.0, v56
	v_add_f32_e32 v61, 1.0, v61
	v_add_f32_e32 v57, 1.0, v57
	v_add_f32_e32 v62, 1.0, v62
	v_add_f32_e32 v58, 1.0, v58
	v_add_f32_e32 v63, 1.0, v63
	v_add_f32_e32 v59, 1.0, v59
	v_rcp_f32_e32 v60, v60
	v_rcp_f32_e32 v56, v56
	v_rcp_f32_e32 v61, v61
	v_rcp_f32_e32 v57, v57
	v_rcp_f32_e32 v62, v62
	v_rcp_f32_e32 v58, v58
	v_rcp_f32_e32 v63, v63
	v_rcp_f32_e32 v59, v59
.LBB0_137:
	v_add_u32_e32 v66, 0x80, v145
	v_mov_b64_e32 v[64:65], s[14:15]
	v_mad_i64_i32 v[64:65], s[16:17], v66, s84, v[64:65]
	v_lshl_add_u64 v[64:65], v[132:133], 1, v[64:65]
	s_and_b64 vcc, exec, s[6:7]
	s_nop 1
	v_cvt_pk_bf16_f32 v60, v60, v61
	s_nop 1
	v_cvt_pk_bf16_f32 v61, v62, v63
	s_nop 1
	v_cvt_pk_bf16_f32 v62, v56, v57
	s_nop 1
	v_cvt_pk_bf16_f32 v63, v58, v59
	global_store_dwordx4 v[64:65], v[60:63], off sc1
	s_cbranch_vccnz .LBB0_139
	v_mul_f32_e32 v52, 0xbfb8aa3b, v52
	v_mul_f32_e32 v48, 0xbfb8aa3b, v48
	v_mul_f32_e32 v53, 0xbfb8aa3b, v53
	v_mul_f32_e32 v49, 0xbfb8aa3b, v49
	v_mul_f32_e32 v54, 0xbfb8aa3b, v54
	v_mul_f32_e32 v50, 0xbfb8aa3b, v50
	v_mul_f32_e32 v55, 0xbfb8aa3b, v55
	v_mul_f32_e32 v51, 0xbfb8aa3b, v51
	v_exp_f32_e32 v52, v52
	v_exp_f32_e32 v48, v48
	v_exp_f32_e32 v53, v53
	v_exp_f32_e32 v49, v49
	v_exp_f32_e32 v54, v54
	v_exp_f32_e32 v50, v50
	v_exp_f32_e32 v55, v55
	v_exp_f32_e32 v51, v51
	v_add_f32_e32 v52, 1.0, v52
	v_add_f32_e32 v48, 1.0, v48
	v_add_f32_e32 v53, 1.0, v53
	v_add_f32_e32 v49, 1.0, v49
	v_add_f32_e32 v54, 1.0, v54
	v_add_f32_e32 v50, 1.0, v50
	v_add_f32_e32 v55, 1.0, v55
	v_add_f32_e32 v51, 1.0, v51
	v_rcp_f32_e32 v52, v52
	v_rcp_f32_e32 v48, v48
	v_rcp_f32_e32 v53, v53
	v_rcp_f32_e32 v49, v49
	v_rcp_f32_e32 v54, v54
	v_rcp_f32_e32 v50, v50
	v_rcp_f32_e32 v55, v55
	v_rcp_f32_e32 v51, v51
.LBB0_139:
	s_and_b64 vcc, exec, s[6:7]
	s_nop 1
	v_cvt_pk_bf16_f32 v52, v52, v53
	s_nop 1
	v_cvt_pk_bf16_f32 v53, v54, v55
	s_nop 1
	v_cvt_pk_bf16_f32 v54, v48, v49
	s_nop 1
	v_cvt_pk_bf16_f32 v55, v50, v51
	global_store_dwordx4 v[64:65], v[52:55], off offset:256 sc1
	s_cbranch_vccnz .LBB0_141
	v_mul_f32_e32 v44, 0xbfb8aa3b, v44
	v_mul_f32_e32 v40, 0xbfb8aa3b, v40
	v_mul_f32_e32 v45, 0xbfb8aa3b, v45
	v_mul_f32_e32 v41, 0xbfb8aa3b, v41
	v_mul_f32_e32 v46, 0xbfb8aa3b, v46
	v_mul_f32_e32 v42, 0xbfb8aa3b, v42
	v_mul_f32_e32 v47, 0xbfb8aa3b, v47
	v_mul_f32_e32 v43, 0xbfb8aa3b, v43
	v_exp_f32_e32 v44, v44
	v_exp_f32_e32 v40, v40
	v_exp_f32_e32 v45, v45
	v_exp_f32_e32 v41, v41
	v_exp_f32_e32 v46, v46
	v_exp_f32_e32 v42, v42
	v_exp_f32_e32 v47, v47
	v_exp_f32_e32 v43, v43
	v_add_f32_e32 v44, 1.0, v44
	v_add_f32_e32 v40, 1.0, v40
	v_add_f32_e32 v45, 1.0, v45
	v_add_f32_e32 v41, 1.0, v41
	v_add_f32_e32 v46, 1.0, v46
	v_add_f32_e32 v42, 1.0, v42
	v_add_f32_e32 v47, 1.0, v47
	v_add_f32_e32 v43, 1.0, v43
	v_rcp_f32_e32 v44, v44
	v_rcp_f32_e32 v40, v40
	v_rcp_f32_e32 v45, v45
	v_rcp_f32_e32 v41, v41
	v_rcp_f32_e32 v46, v46
	v_rcp_f32_e32 v42, v42
	v_rcp_f32_e32 v47, v47
	v_rcp_f32_e32 v43, v43
.LBB0_141:
	v_add_u32_e32 v50, 0x90, v145
	v_mov_b64_e32 v[48:49], s[14:15]
	v_mad_i64_i32 v[48:49], s[16:17], v50, s84, v[48:49]
	v_lshl_add_u64 v[48:49], v[132:133], 1, v[48:49]
	s_and_b64 vcc, exec, s[6:7]
	s_nop 1
	v_cvt_pk_bf16_f32 v44, v44, v45
	s_nop 1
	v_cvt_pk_bf16_f32 v45, v46, v47
	s_nop 1
	v_cvt_pk_bf16_f32 v46, v40, v41
	s_nop 1
	v_cvt_pk_bf16_f32 v47, v42, v43
	global_store_dwordx4 v[48:49], v[44:47], off sc1
	s_cbranch_vccnz .LBB0_143
	v_mul_f32_e32 v36, 0xbfb8aa3b, v36
	v_mul_f32_e32 v32, 0xbfb8aa3b, v32
	v_mul_f32_e32 v37, 0xbfb8aa3b, v37
	v_mul_f32_e32 v33, 0xbfb8aa3b, v33
	v_mul_f32_e32 v38, 0xbfb8aa3b, v38
	v_mul_f32_e32 v34, 0xbfb8aa3b, v34
	v_mul_f32_e32 v39, 0xbfb8aa3b, v39
	v_mul_f32_e32 v35, 0xbfb8aa3b, v35
	v_exp_f32_e32 v36, v36
	v_exp_f32_e32 v32, v32
	v_exp_f32_e32 v37, v37
	v_exp_f32_e32 v33, v33
	v_exp_f32_e32 v38, v38
	v_exp_f32_e32 v34, v34
	v_exp_f32_e32 v39, v39
	v_exp_f32_e32 v35, v35
	v_add_f32_e32 v36, 1.0, v36
	v_add_f32_e32 v32, 1.0, v32
	v_add_f32_e32 v37, 1.0, v37
	v_add_f32_e32 v33, 1.0, v33
	v_add_f32_e32 v38, 1.0, v38
	v_add_f32_e32 v34, 1.0, v34
	v_add_f32_e32 v39, 1.0, v39
	v_add_f32_e32 v35, 1.0, v35
	v_rcp_f32_e32 v36, v36
	v_rcp_f32_e32 v32, v32
	v_rcp_f32_e32 v37, v37
	v_rcp_f32_e32 v33, v33
	v_rcp_f32_e32 v38, v38
	v_rcp_f32_e32 v34, v34
	v_rcp_f32_e32 v39, v39
	v_rcp_f32_e32 v35, v35
.LBB0_143:
	s_and_b64 vcc, exec, s[6:7]
	s_nop 1
	v_cvt_pk_bf16_f32 v36, v36, v37
	s_nop 1
	v_cvt_pk_bf16_f32 v37, v38, v39
	s_nop 1
	v_cvt_pk_bf16_f32 v38, v32, v33
	s_nop 1
	v_cvt_pk_bf16_f32 v39, v34, v35
	global_store_dwordx4 v[48:49], v[36:39], off offset:256 sc1
	s_cbranch_vccnz .LBB0_145
	v_mul_f32_e32 v28, 0xbfb8aa3b, v28
	v_mul_f32_e32 v24, 0xbfb8aa3b, v24
	v_mul_f32_e32 v29, 0xbfb8aa3b, v29
	v_mul_f32_e32 v25, 0xbfb8aa3b, v25
	v_mul_f32_e32 v30, 0xbfb8aa3b, v30
	v_mul_f32_e32 v26, 0xbfb8aa3b, v26
	v_mul_f32_e32 v31, 0xbfb8aa3b, v31
	v_mul_f32_e32 v27, 0xbfb8aa3b, v27
	v_exp_f32_e32 v28, v28
	v_exp_f32_e32 v24, v24
	v_exp_f32_e32 v29, v29
	v_exp_f32_e32 v25, v25
	v_exp_f32_e32 v30, v30
	v_exp_f32_e32 v26, v26
	v_exp_f32_e32 v31, v31
	v_exp_f32_e32 v27, v27
	v_add_f32_e32 v28, 1.0, v28
	v_add_f32_e32 v24, 1.0, v24
	v_add_f32_e32 v29, 1.0, v29
	v_add_f32_e32 v25, 1.0, v25
	v_add_f32_e32 v30, 1.0, v30
	v_add_f32_e32 v26, 1.0, v26
	v_add_f32_e32 v31, 1.0, v31
	v_add_f32_e32 v27, 1.0, v27
	v_rcp_f32_e32 v28, v28
	v_rcp_f32_e32 v24, v24
	v_rcp_f32_e32 v29, v29
	v_rcp_f32_e32 v25, v25
	v_rcp_f32_e32 v30, v30
	v_rcp_f32_e32 v26, v26
	v_rcp_f32_e32 v31, v31
	v_rcp_f32_e32 v27, v27
.LBB0_145:
	v_add_u32_e32 v34, 0xa0, v145
	v_mov_b64_e32 v[32:33], s[14:15]
	v_mad_i64_i32 v[32:33], s[16:17], v34, s84, v[32:33]
	v_lshl_add_u64 v[32:33], v[132:133], 1, v[32:33]
	s_and_b64 vcc, exec, s[6:7]
	s_nop 1
	v_cvt_pk_bf16_f32 v28, v28, v29
	s_nop 1
	v_cvt_pk_bf16_f32 v29, v30, v31
	s_nop 1
	v_cvt_pk_bf16_f32 v30, v24, v25
	s_nop 1
	v_cvt_pk_bf16_f32 v31, v26, v27
	global_store_dwordx4 v[32:33], v[28:31], off sc1
	s_cbranch_vccnz .LBB0_147
	v_mul_f32_e32 v20, 0xbfb8aa3b, v20
	v_mul_f32_e32 v16, 0xbfb8aa3b, v16
	v_mul_f32_e32 v21, 0xbfb8aa3b, v21
	v_mul_f32_e32 v17, 0xbfb8aa3b, v17
	v_mul_f32_e32 v22, 0xbfb8aa3b, v22
	v_mul_f32_e32 v18, 0xbfb8aa3b, v18
	v_mul_f32_e32 v23, 0xbfb8aa3b, v23
	v_mul_f32_e32 v19, 0xbfb8aa3b, v19
	v_exp_f32_e32 v20, v20
	v_exp_f32_e32 v16, v16
	v_exp_f32_e32 v21, v21
	v_exp_f32_e32 v17, v17
	v_exp_f32_e32 v22, v22
	v_exp_f32_e32 v18, v18
	v_exp_f32_e32 v23, v23
	v_exp_f32_e32 v19, v19
	v_add_f32_e32 v20, 1.0, v20
	v_add_f32_e32 v16, 1.0, v16
	v_add_f32_e32 v21, 1.0, v21
	v_add_f32_e32 v17, 1.0, v17
	v_add_f32_e32 v22, 1.0, v22
	v_add_f32_e32 v18, 1.0, v18
	v_add_f32_e32 v23, 1.0, v23
	v_add_f32_e32 v19, 1.0, v19
	v_rcp_f32_e32 v20, v20
	v_rcp_f32_e32 v16, v16
	v_rcp_f32_e32 v21, v21
	v_rcp_f32_e32 v17, v17
	v_rcp_f32_e32 v22, v22
	v_rcp_f32_e32 v18, v18
	v_rcp_f32_e32 v23, v23
	v_rcp_f32_e32 v19, v19
.LBB0_147:
	s_and_b64 vcc, exec, s[6:7]
	s_nop 1
	v_cvt_pk_bf16_f32 v20, v20, v21
	s_nop 1
	v_cvt_pk_bf16_f32 v21, v22, v23
	s_nop 1
	v_cvt_pk_bf16_f32 v22, v16, v17
	s_nop 1
	v_cvt_pk_bf16_f32 v23, v18, v19
	global_store_dwordx4 v[32:33], v[20:23], off offset:256 sc1
	s_cbranch_vccnz .LBB0_149
	v_mul_f32_e32 v12, 0xbfb8aa3b, v12
	v_mul_f32_e32 v8, 0xbfb8aa3b, v8
	v_mul_f32_e32 v13, 0xbfb8aa3b, v13
	v_mul_f32_e32 v9, 0xbfb8aa3b, v9
	v_mul_f32_e32 v14, 0xbfb8aa3b, v14
	v_mul_f32_e32 v10, 0xbfb8aa3b, v10
	v_mul_f32_e32 v15, 0xbfb8aa3b, v15
	v_mul_f32_e32 v11, 0xbfb8aa3b, v11
	v_exp_f32_e32 v12, v12
	v_exp_f32_e32 v8, v8
	v_exp_f32_e32 v13, v13
	v_exp_f32_e32 v9, v9
	v_exp_f32_e32 v14, v14
	v_exp_f32_e32 v10, v10
	v_exp_f32_e32 v15, v15
	v_exp_f32_e32 v11, v11
	v_add_f32_e32 v12, 1.0, v12
	v_add_f32_e32 v8, 1.0, v8
	v_add_f32_e32 v13, 1.0, v13
	v_add_f32_e32 v9, 1.0, v9
	v_add_f32_e32 v14, 1.0, v14
	v_add_f32_e32 v10, 1.0, v10
	v_add_f32_e32 v15, 1.0, v15
	v_add_f32_e32 v11, 1.0, v11
	v_rcp_f32_e32 v12, v12
	v_rcp_f32_e32 v8, v8
	v_rcp_f32_e32 v13, v13
	v_rcp_f32_e32 v9, v9
	v_rcp_f32_e32 v14, v14
	v_rcp_f32_e32 v10, v10
	v_rcp_f32_e32 v15, v15
	v_rcp_f32_e32 v11, v11
.LBB0_149:
	v_add_u32_e32 v18, 0xb0, v145
	v_mov_b64_e32 v[16:17], s[14:15]
	v_mad_i64_i32 v[16:17], s[16:17], v18, s84, v[16:17]
	v_lshl_add_u64 v[16:17], v[132:133], 1, v[16:17]
	s_and_b64 vcc, exec, s[6:7]
	s_nop 1
	v_cvt_pk_bf16_f32 v12, v12, v13
	s_nop 1
	v_cvt_pk_bf16_f32 v13, v14, v15
	s_nop 1
	v_cvt_pk_bf16_f32 v14, v8, v9
	s_nop 1
	v_cvt_pk_bf16_f32 v15, v10, v11
	global_store_dwordx4 v[16:17], v[12:15], off sc1
	s_cbranch_vccnz .LBB0_151
	v_mul_f32_e32 v4, 0xbfb8aa3b, v4
	v_mul_f32_e32 v0, 0xbfb8aa3b, v0
	v_mul_f32_e32 v5, 0xbfb8aa3b, v5
	v_mul_f32_e32 v1, 0xbfb8aa3b, v1
	v_mul_f32_e32 v6, 0xbfb8aa3b, v6
	v_mul_f32_e32 v2, 0xbfb8aa3b, v2
	v_mul_f32_e32 v7, 0xbfb8aa3b, v7
	v_mul_f32_e32 v3, 0xbfb8aa3b, v3
	v_exp_f32_e32 v4, v4
	v_exp_f32_e32 v0, v0
	v_exp_f32_e32 v5, v5
	v_exp_f32_e32 v1, v1
	v_exp_f32_e32 v6, v6
	v_exp_f32_e32 v2, v2
	v_exp_f32_e32 v7, v7
	v_exp_f32_e32 v3, v3
	v_add_f32_e32 v4, 1.0, v4
	v_add_f32_e32 v0, 1.0, v0
	v_add_f32_e32 v5, 1.0, v5
	v_add_f32_e32 v1, 1.0, v1
	v_add_f32_e32 v6, 1.0, v6
	v_add_f32_e32 v2, 1.0, v2
	v_add_f32_e32 v7, 1.0, v7
	v_add_f32_e32 v3, 1.0, v3
	v_rcp_f32_e32 v4, v4
	v_rcp_f32_e32 v0, v0
	v_rcp_f32_e32 v5, v5
	v_rcp_f32_e32 v1, v1
	v_rcp_f32_e32 v6, v6
	v_rcp_f32_e32 v2, v2
	v_rcp_f32_e32 v7, v7
	v_rcp_f32_e32 v3, v3
.LBB0_151:
	s_andn2_b64 vcc, exec, s[4:5]
	s_mov_b64 s[4:5], -1
	s_nop 1
	v_cvt_pk_bf16_f32 v4, v4, v5
	s_nop 1
	v_cvt_pk_bf16_f32 v5, v6, v7
	s_nop 1
	v_cvt_pk_bf16_f32 v6, v0, v1
	s_nop 1
	v_cvt_pk_bf16_f32 v7, v2, v3
	global_store_dwordx4 v[16:17], v[4:7], off offset:256 sc1
	s_cbranch_vccnz .LBB0_108
	s_andn2_b64 vcc, exec, s[36:37]
	s_cbranch_vccnz .LBB0_107
	s_barrier
	s_branch .LBB0_107

.LBB0_179:
	s_lshl_b32 s6, s6, 8
	s_add_i32 s6, s6, s88
	v_and_or_b32 v146, v132, 15, s6
	s_lshl_b32 s6, s33, 8
	s_addk_i32 s6, 0x1000
	v_lshrrev_b32_e32 v132, 1, v132
	v_and_or_b32 v132, v132, 24, s6
	v_or_b32_e32 v132, s89, v132
	v_mov_b64_e32 v[134:135], s[14:15]
	v_ashrrev_i32_e32 v133, 31, v132
	v_mad_i64_i32 v[134:135], s[6:7], v146, s87, v[134:135]
	s_nop 1
	v_cvt_pk_bf16_f32 v124, v124, v125
	s_nop 1
	v_cvt_pk_bf16_f32 v125, v126, v127
	s_nop 1
	v_cvt_pk_bf16_f32 v126, v120, v121
	v_cndmask_b32_e64 v120, 0, 1, s[16:17]
	v_lshl_add_u64 v[134:135], v[132:133], 1, v[134:135]
	v_cmp_ne_u32_e64 s[6:7], 1, v120
	s_andn2_b64 vcc, exec, s[16:17]
	s_nop 1
	v_cvt_pk_bf16_f32 v127, v122, v123
	global_store_dwordx4 v[134:135], v[124:127], off sc1
	s_cbranch_vccnz .LBB0_181
	v_mul_f32_e32 v116, 0x38800000, v116
	v_mul_f32_e32 v112, 0x38800000, v112
	v_mul_f32_e32 v117, 0x38800000, v117
	v_mul_f32_e32 v113, 0x38800000, v113
	v_mul_f32_e32 v118, 0x38800000, v118
	v_mul_f32_e32 v114, 0x38800000, v114
	v_mul_f32_e32 v119, 0x38800000, v119
	v_mul_f32_e32 v115, 0x38800000, v115
	v_mul_f32_e32 v116, 0xbfb8aa3b, v116
	v_mul_f32_e32 v112, 0xbfb8aa3b, v112
	v_mul_f32_e32 v117, 0xbfb8aa3b, v117
	v_mul_f32_e32 v113, 0xbfb8aa3b, v113
	v_mul_f32_e32 v118, 0xbfb8aa3b, v118
	v_mul_f32_e32 v114, 0xbfb8aa3b, v114
	v_mul_f32_e32 v119, 0xbfb8aa3b, v119
	v_mul_f32_e32 v115, 0xbfb8aa3b, v115
	v_exp_f32_e32 v116, v116
	v_exp_f32_e32 v112, v112
	v_exp_f32_e32 v117, v117
	v_exp_f32_e32 v113, v113
	v_exp_f32_e32 v118, v118
	v_exp_f32_e32 v114, v114
	v_exp_f32_e32 v119, v119
	v_exp_f32_e32 v115, v115
	v_add_f32_e32 v116, 1.0, v116
	v_add_f32_e32 v112, 1.0, v112
	v_add_f32_e32 v117, 1.0, v117
	v_add_f32_e32 v113, 1.0, v113
	v_add_f32_e32 v118, 1.0, v118
	v_add_f32_e32 v114, 1.0, v114
	v_add_f32_e32 v119, 1.0, v119
	v_add_f32_e32 v115, 1.0, v115
	v_rcp_f32_e32 v116, v116
	v_rcp_f32_e32 v112, v112
	v_rcp_f32_e32 v117, v117
	v_rcp_f32_e32 v113, v113
	v_rcp_f32_e32 v118, v118
	v_rcp_f32_e32 v114, v114
	v_rcp_f32_e32 v119, v119
	v_rcp_f32_e32 v115, v115
.LBB0_181:
	s_and_b64 vcc, exec, s[6:7]
	s_nop 1
	v_cvt_pk_bf16_f32 v116, v116, v117
	s_nop 1
	v_cvt_pk_bf16_f32 v117, v118, v119
	s_nop 1
	v_cvt_pk_bf16_f32 v118, v112, v113
	s_nop 1
	v_cvt_pk_bf16_f32 v119, v114, v115
	global_store_dwordx4 v[134:135], v[116:119], off offset:256 sc1
	s_cbranch_vccnz .LBB0_183
	v_mul_f32_e32 v108, 0x38800000, v108
	v_mul_f32_e32 v104, 0x38800000, v104
	v_mul_f32_e32 v109, 0x38800000, v109
	v_mul_f32_e32 v105, 0x38800000, v105
	v_mul_f32_e32 v110, 0x38800000, v110
	v_mul_f32_e32 v106, 0x38800000, v106
	v_mul_f32_e32 v111, 0x38800000, v111
	v_mul_f32_e32 v107, 0x38800000, v107
	v_mul_f32_e32 v108, 0xbfb8aa3b, v108
	v_mul_f32_e32 v104, 0xbfb8aa3b, v104
	v_mul_f32_e32 v109, 0xbfb8aa3b, v109
	v_mul_f32_e32 v105, 0xbfb8aa3b, v105
	v_mul_f32_e32 v110, 0xbfb8aa3b, v110
	v_mul_f32_e32 v106, 0xbfb8aa3b, v106
	v_mul_f32_e32 v111, 0xbfb8aa3b, v111
	v_mul_f32_e32 v107, 0xbfb8aa3b, v107
	v_exp_f32_e32 v108, v108
	v_exp_f32_e32 v104, v104
	v_exp_f32_e32 v109, v109
	v_exp_f32_e32 v105, v105
	v_exp_f32_e32 v110, v110
	v_exp_f32_e32 v106, v106
	v_exp_f32_e32 v111, v111
	v_exp_f32_e32 v107, v107
	v_add_f32_e32 v108, 1.0, v108
	v_add_f32_e32 v104, 1.0, v104
	v_add_f32_e32 v109, 1.0, v109
	v_add_f32_e32 v105, 1.0, v105
	v_add_f32_e32 v110, 1.0, v110
	v_add_f32_e32 v106, 1.0, v106
	v_add_f32_e32 v111, 1.0, v111
	v_add_f32_e32 v107, 1.0, v107
	v_rcp_f32_e32 v108, v108
	v_rcp_f32_e32 v104, v104
	v_rcp_f32_e32 v109, v109
	v_rcp_f32_e32 v105, v105
	v_rcp_f32_e32 v110, v110
	v_rcp_f32_e32 v106, v106
	v_rcp_f32_e32 v111, v111
	v_rcp_f32_e32 v107, v107
.LBB0_183:
	v_or_b32_e32 v114, 16, v146
	v_mov_b64_e32 v[112:113], s[14:15]
	v_mad_i64_i32 v[112:113], s[16:17], v114, s87, v[112:113]
	v_lshl_add_u64 v[112:113], v[132:133], 1, v[112:113]
	s_and_b64 vcc, exec, s[6:7]
	s_nop 1
	v_cvt_pk_bf16_f32 v108, v108, v109
	s_nop 1
	v_cvt_pk_bf16_f32 v109, v110, v111
	s_nop 1
	v_cvt_pk_bf16_f32 v110, v104, v105
	s_nop 1
	v_cvt_pk_bf16_f32 v111, v106, v107
	global_store_dwordx4 v[112:113], v[108:111], off sc1
	s_cbranch_vccnz .LBB0_185
	v_mul_f32_e32 v100, 0x38800000, v100
	v_mul_f32_e32 v96, 0x38800000, v96
	v_mul_f32_e32 v101, 0x38800000, v101
	v_mul_f32_e32 v97, 0x38800000, v97
	v_mul_f32_e32 v102, 0x38800000, v102
	v_mul_f32_e32 v98, 0x38800000, v98
	v_mul_f32_e32 v103, 0x38800000, v103
	v_mul_f32_e32 v99, 0x38800000, v99
	v_mul_f32_e32 v100, 0xbfb8aa3b, v100
	v_mul_f32_e32 v96, 0xbfb8aa3b, v96
	v_mul_f32_e32 v101, 0xbfb8aa3b, v101
	v_mul_f32_e32 v97, 0xbfb8aa3b, v97
	v_mul_f32_e32 v102, 0xbfb8aa3b, v102
	v_mul_f32_e32 v98, 0xbfb8aa3b, v98
	v_mul_f32_e32 v103, 0xbfb8aa3b, v103
	v_mul_f32_e32 v99, 0xbfb8aa3b, v99
	v_exp_f32_e32 v100, v100
	v_exp_f32_e32 v96, v96
	v_exp_f32_e32 v101, v101
	v_exp_f32_e32 v97, v97
	v_exp_f32_e32 v102, v102
	v_exp_f32_e32 v98, v98
	v_exp_f32_e32 v103, v103
	v_exp_f32_e32 v99, v99
	v_add_f32_e32 v100, 1.0, v100
	v_add_f32_e32 v96, 1.0, v96
	v_add_f32_e32 v101, 1.0, v101
	v_add_f32_e32 v97, 1.0, v97
	v_add_f32_e32 v102, 1.0, v102
	v_add_f32_e32 v98, 1.0, v98
	v_add_f32_e32 v103, 1.0, v103
	v_add_f32_e32 v99, 1.0, v99
	v_rcp_f32_e32 v100, v100
	v_rcp_f32_e32 v96, v96
	v_rcp_f32_e32 v101, v101
	v_rcp_f32_e32 v97, v97
	v_rcp_f32_e32 v102, v102
	v_rcp_f32_e32 v98, v98
	v_rcp_f32_e32 v103, v103
	v_rcp_f32_e32 v99, v99
.LBB0_185:
	s_and_b64 vcc, exec, s[6:7]
	s_nop 1
	v_cvt_pk_bf16_f32 v100, v100, v101
	s_nop 1
	v_cvt_pk_bf16_f32 v101, v102, v103
	s_nop 1
	v_cvt_pk_bf16_f32 v102, v96, v97
	s_nop 1
	v_cvt_pk_bf16_f32 v103, v98, v99
	global_store_dwordx4 v[112:113], v[100:103], off offset:256 sc1
	s_cbranch_vccnz .LBB0_187
	v_mul_f32_e32 v92, 0x38800000, v92
	v_mul_f32_e32 v88, 0x38800000, v88
	v_mul_f32_e32 v93, 0x38800000, v93
	v_mul_f32_e32 v89, 0x38800000, v89
	v_mul_f32_e32 v94, 0x38800000, v94
	v_mul_f32_e32 v90, 0x38800000, v90
	v_mul_f32_e32 v95, 0x38800000, v95
	v_mul_f32_e32 v91, 0x38800000, v91
	v_mul_f32_e32 v92, 0xbfb8aa3b, v92
	v_mul_f32_e32 v88, 0xbfb8aa3b, v88
	v_mul_f32_e32 v93, 0xbfb8aa3b, v93
	v_mul_f32_e32 v89, 0xbfb8aa3b, v89
	v_mul_f32_e32 v94, 0xbfb8aa3b, v94
	v_mul_f32_e32 v90, 0xbfb8aa3b, v90
	v_mul_f32_e32 v95, 0xbfb8aa3b, v95
	v_mul_f32_e32 v91, 0xbfb8aa3b, v91
	v_exp_f32_e32 v92, v92
	v_exp_f32_e32 v88, v88
	v_exp_f32_e32 v93, v93
	v_exp_f32_e32 v89, v89
	v_exp_f32_e32 v94, v94
	v_exp_f32_e32 v90, v90
	v_exp_f32_e32 v95, v95
	v_exp_f32_e32 v91, v91
	v_add_f32_e32 v92, 1.0, v92
	v_add_f32_e32 v88, 1.0, v88
	v_add_f32_e32 v93, 1.0, v93
	v_add_f32_e32 v89, 1.0, v89
	v_add_f32_e32 v94, 1.0, v94
	v_add_f32_e32 v90, 1.0, v90
	v_add_f32_e32 v95, 1.0, v95
	v_add_f32_e32 v91, 1.0, v91
	v_rcp_f32_e32 v92, v92
	v_rcp_f32_e32 v88, v88
	v_rcp_f32_e32 v93, v93
	v_rcp_f32_e32 v89, v89
	v_rcp_f32_e32 v94, v94
	v_rcp_f32_e32 v90, v90
	v_rcp_f32_e32 v95, v95
	v_rcp_f32_e32 v91, v91
.LBB0_187:
	v_or_b32_e32 v98, 32, v146
	v_mov_b64_e32 v[96:97], s[14:15]
	v_mad_i64_i32 v[96:97], s[16:17], v98, s87, v[96:97]
	v_lshl_add_u64 v[96:97], v[132:133], 1, v[96:97]
	s_and_b64 vcc, exec, s[6:7]
	s_nop 1
	v_cvt_pk_bf16_f32 v92, v92, v93
	s_nop 1
	v_cvt_pk_bf16_f32 v93, v94, v95
	s_nop 1
	v_cvt_pk_bf16_f32 v94, v88, v89
	s_nop 1
	v_cvt_pk_bf16_f32 v95, v90, v91
	global_store_dwordx4 v[96:97], v[92:95], off sc1
	s_cbranch_vccnz .LBB0_189
	v_mul_f32_e32 v84, 0x38800000, v84
	v_mul_f32_e32 v80, 0x38800000, v80
	v_mul_f32_e32 v85, 0x38800000, v85
	v_mul_f32_e32 v81, 0x38800000, v81
	v_mul_f32_e32 v86, 0x38800000, v86
	v_mul_f32_e32 v82, 0x38800000, v82
	v_mul_f32_e32 v87, 0x38800000, v87
	v_mul_f32_e32 v83, 0x38800000, v83
	v_mul_f32_e32 v84, 0xbfb8aa3b, v84
	v_mul_f32_e32 v80, 0xbfb8aa3b, v80
	v_mul_f32_e32 v85, 0xbfb8aa3b, v85
	v_mul_f32_e32 v81, 0xbfb8aa3b, v81
	v_mul_f32_e32 v86, 0xbfb8aa3b, v86
	v_mul_f32_e32 v82, 0xbfb8aa3b, v82
	v_mul_f32_e32 v87, 0xbfb8aa3b, v87
	v_mul_f32_e32 v83, 0xbfb8aa3b, v83
	v_exp_f32_e32 v84, v84
	v_exp_f32_e32 v80, v80
	v_exp_f32_e32 v85, v85
	v_exp_f32_e32 v81, v81
	v_exp_f32_e32 v86, v86
	v_exp_f32_e32 v82, v82
	v_exp_f32_e32 v87, v87
	v_exp_f32_e32 v83, v83
	v_add_f32_e32 v84, 1.0, v84
	v_add_f32_e32 v80, 1.0, v80
	v_add_f32_e32 v85, 1.0, v85
	v_add_f32_e32 v81, 1.0, v81
	v_add_f32_e32 v86, 1.0, v86
	v_add_f32_e32 v82, 1.0, v82
	v_add_f32_e32 v87, 1.0, v87
	v_add_f32_e32 v83, 1.0, v83
	v_rcp_f32_e32 v84, v84
	v_rcp_f32_e32 v80, v80
	v_rcp_f32_e32 v85, v85
	v_rcp_f32_e32 v81, v81
	v_rcp_f32_e32 v86, v86
	v_rcp_f32_e32 v82, v82
	v_rcp_f32_e32 v87, v87
	v_rcp_f32_e32 v83, v83
.LBB0_189:
	s_and_b64 vcc, exec, s[6:7]
	s_nop 1
	v_cvt_pk_bf16_f32 v84, v84, v85
	s_nop 1
	v_cvt_pk_bf16_f32 v85, v86, v87
	s_nop 1
	v_cvt_pk_bf16_f32 v86, v80, v81
	s_nop 1
	v_cvt_pk_bf16_f32 v87, v82, v83
	global_store_dwordx4 v[96:97], v[84:87], off offset:256 sc1
	s_cbranch_vccnz .LBB0_191
	v_mul_f32_e32 v76, 0x38800000, v76
	v_mul_f32_e32 v72, 0x38800000, v72
	v_mul_f32_e32 v77, 0x38800000, v77
	v_mul_f32_e32 v73, 0x38800000, v73
	v_mul_f32_e32 v78, 0x38800000, v78
	v_mul_f32_e32 v74, 0x38800000, v74
	v_mul_f32_e32 v79, 0x38800000, v79
	v_mul_f32_e32 v75, 0x38800000, v75
	v_mul_f32_e32 v76, 0xbfb8aa3b, v76
	v_mul_f32_e32 v72, 0xbfb8aa3b, v72
	v_mul_f32_e32 v77, 0xbfb8aa3b, v77
	v_mul_f32_e32 v73, 0xbfb8aa3b, v73
	v_mul_f32_e32 v78, 0xbfb8aa3b, v78
	v_mul_f32_e32 v74, 0xbfb8aa3b, v74
	v_mul_f32_e32 v79, 0xbfb8aa3b, v79
	v_mul_f32_e32 v75, 0xbfb8aa3b, v75
	v_exp_f32_e32 v76, v76
	v_exp_f32_e32 v72, v72
	v_exp_f32_e32 v77, v77
	v_exp_f32_e32 v73, v73
	v_exp_f32_e32 v78, v78
	v_exp_f32_e32 v74, v74
	v_exp_f32_e32 v79, v79
	v_exp_f32_e32 v75, v75
	v_add_f32_e32 v76, 1.0, v76
	v_add_f32_e32 v72, 1.0, v72
	v_add_f32_e32 v77, 1.0, v77
	v_add_f32_e32 v73, 1.0, v73
	v_add_f32_e32 v78, 1.0, v78
	v_add_f32_e32 v74, 1.0, v74
	v_add_f32_e32 v79, 1.0, v79
	v_add_f32_e32 v75, 1.0, v75
	v_rcp_f32_e32 v76, v76
	v_rcp_f32_e32 v72, v72
	v_rcp_f32_e32 v77, v77
	v_rcp_f32_e32 v73, v73
	v_rcp_f32_e32 v78, v78
	v_rcp_f32_e32 v74, v74
	v_rcp_f32_e32 v79, v79
	v_rcp_f32_e32 v75, v75
.LBB0_191:
	v_or_b32_e32 v82, 48, v146
	v_mov_b64_e32 v[80:81], s[14:15]
	v_mad_i64_i32 v[80:81], s[16:17], v82, s87, v[80:81]
	v_lshl_add_u64 v[80:81], v[132:133], 1, v[80:81]
	s_and_b64 vcc, exec, s[6:7]
	s_nop 1
	v_cvt_pk_bf16_f32 v76, v76, v77
	s_nop 1
	v_cvt_pk_bf16_f32 v77, v78, v79
	s_nop 1
	v_cvt_pk_bf16_f32 v78, v72, v73
	s_nop 1
	v_cvt_pk_bf16_f32 v79, v74, v75
	global_store_dwordx4 v[80:81], v[76:79], off sc1
	s_cbranch_vccnz .LBB0_193
	v_mul_f32_e32 v68, 0x38800000, v68
	v_mul_f32_e32 v64, 0x38800000, v64
	v_mul_f32_e32 v69, 0x38800000, v69
	v_mul_f32_e32 v65, 0x38800000, v65
	v_mul_f32_e32 v70, 0x38800000, v70
	v_mul_f32_e32 v66, 0x38800000, v66
	v_mul_f32_e32 v71, 0x38800000, v71
	v_mul_f32_e32 v67, 0x38800000, v67
	v_mul_f32_e32 v68, 0xbfb8aa3b, v68
	v_mul_f32_e32 v64, 0xbfb8aa3b, v64
	v_mul_f32_e32 v69, 0xbfb8aa3b, v69
	v_mul_f32_e32 v65, 0xbfb8aa3b, v65
	v_mul_f32_e32 v70, 0xbfb8aa3b, v70
	v_mul_f32_e32 v66, 0xbfb8aa3b, v66
	v_mul_f32_e32 v71, 0xbfb8aa3b, v71
	v_mul_f32_e32 v67, 0xbfb8aa3b, v67
	v_exp_f32_e32 v68, v68
	v_exp_f32_e32 v64, v64
	v_exp_f32_e32 v69, v69
	v_exp_f32_e32 v65, v65
	v_exp_f32_e32 v70, v70
	v_exp_f32_e32 v66, v66
	v_exp_f32_e32 v71, v71
	v_exp_f32_e32 v67, v67
	v_add_f32_e32 v68, 1.0, v68
	v_add_f32_e32 v64, 1.0, v64
	v_add_f32_e32 v69, 1.0, v69
	v_add_f32_e32 v65, 1.0, v65
	v_add_f32_e32 v70, 1.0, v70
	v_add_f32_e32 v66, 1.0, v66
	v_add_f32_e32 v71, 1.0, v71
	v_add_f32_e32 v67, 1.0, v67
	v_rcp_f32_e32 v68, v68
	v_rcp_f32_e32 v64, v64
	v_rcp_f32_e32 v69, v69
	v_rcp_f32_e32 v65, v65
	v_rcp_f32_e32 v70, v70
	v_rcp_f32_e32 v66, v66
	v_rcp_f32_e32 v71, v71
	v_rcp_f32_e32 v67, v67
.LBB0_193:
	s_and_b64 vcc, exec, s[6:7]
	s_nop 1
	v_cvt_pk_bf16_f32 v68, v68, v69
	s_nop 1
	v_cvt_pk_bf16_f32 v69, v70, v71
	s_nop 1
	v_cvt_pk_bf16_f32 v70, v64, v65
	s_nop 1
	v_cvt_pk_bf16_f32 v71, v66, v67
	global_store_dwordx4 v[80:81], v[68:71], off offset:256 sc1
	s_cbranch_vccnz .LBB0_195
	v_mul_f32_e32 v60, 0x38800000, v60
	v_mul_f32_e32 v56, 0x38800000, v56
	v_mul_f32_e32 v61, 0x38800000, v61
	v_mul_f32_e32 v57, 0x38800000, v57
	v_mul_f32_e32 v62, 0x38800000, v62
	v_mul_f32_e32 v58, 0x38800000, v58
	v_mul_f32_e32 v63, 0x38800000, v63
	v_mul_f32_e32 v59, 0x38800000, v59
	v_mul_f32_e32 v60, 0xbfb8aa3b, v60
	v_mul_f32_e32 v56, 0xbfb8aa3b, v56
	v_mul_f32_e32 v61, 0xbfb8aa3b, v61
	v_mul_f32_e32 v57, 0xbfb8aa3b, v57
	v_mul_f32_e32 v62, 0xbfb8aa3b, v62
	v_mul_f32_e32 v58, 0xbfb8aa3b, v58
	v_mul_f32_e32 v63, 0xbfb8aa3b, v63
	v_mul_f32_e32 v59, 0xbfb8aa3b, v59
	v_exp_f32_e32 v60, v60
	v_exp_f32_e32 v56, v56
	v_exp_f32_e32 v61, v61
	v_exp_f32_e32 v57, v57
	v_exp_f32_e32 v62, v62
	v_exp_f32_e32 v58, v58
	v_exp_f32_e32 v63, v63
	v_exp_f32_e32 v59, v59
	v_add_f32_e32 v60, 1.0, v60
	v_add_f32_e32 v56, 1.0, v56
	v_add_f32_e32 v61, 1.0, v61
	v_add_f32_e32 v57, 1.0, v57
	v_add_f32_e32 v62, 1.0, v62
	v_add_f32_e32 v58, 1.0, v58
	v_add_f32_e32 v63, 1.0, v63
	v_add_f32_e32 v59, 1.0, v59
	v_rcp_f32_e32 v60, v60
	v_rcp_f32_e32 v56, v56
	v_rcp_f32_e32 v61, v61
	v_rcp_f32_e32 v57, v57
	v_rcp_f32_e32 v62, v62
	v_rcp_f32_e32 v58, v58
	v_rcp_f32_e32 v63, v63
	v_rcp_f32_e32 v59, v59
.LBB0_195:
	v_add_u32_e32 v66, 0x80, v146
	v_mov_b64_e32 v[64:65], s[14:15]
	v_mad_i64_i32 v[64:65], s[16:17], v66, s87, v[64:65]
	v_lshl_add_u64 v[64:65], v[132:133], 1, v[64:65]
	s_and_b64 vcc, exec, s[6:7]
	s_nop 1
	v_cvt_pk_bf16_f32 v60, v60, v61
	s_nop 1
	v_cvt_pk_bf16_f32 v61, v62, v63
	s_nop 1
	v_cvt_pk_bf16_f32 v62, v56, v57
	s_nop 1
	v_cvt_pk_bf16_f32 v63, v58, v59
	global_store_dwordx4 v[64:65], v[60:63], off sc1
	s_cbranch_vccnz .LBB0_197
	v_mul_f32_e32 v52, 0x38800000, v52
	v_mul_f32_e32 v48, 0x38800000, v48
	v_mul_f32_e32 v53, 0x38800000, v53
	v_mul_f32_e32 v49, 0x38800000, v49
	v_mul_f32_e32 v54, 0x38800000, v54
	v_mul_f32_e32 v50, 0x38800000, v50
	v_mul_f32_e32 v55, 0x38800000, v55
	v_mul_f32_e32 v51, 0x38800000, v51
	v_mul_f32_e32 v52, 0xbfb8aa3b, v52
	v_mul_f32_e32 v48, 0xbfb8aa3b, v48
	v_mul_f32_e32 v53, 0xbfb8aa3b, v53
	v_mul_f32_e32 v49, 0xbfb8aa3b, v49
	v_mul_f32_e32 v54, 0xbfb8aa3b, v54
	v_mul_f32_e32 v50, 0xbfb8aa3b, v50
	v_mul_f32_e32 v55, 0xbfb8aa3b, v55
	v_mul_f32_e32 v51, 0xbfb8aa3b, v51
	v_exp_f32_e32 v52, v52
	v_exp_f32_e32 v48, v48
	v_exp_f32_e32 v53, v53
	v_exp_f32_e32 v49, v49
	v_exp_f32_e32 v54, v54
	v_exp_f32_e32 v50, v50
	v_exp_f32_e32 v55, v55
	v_exp_f32_e32 v51, v51
	v_add_f32_e32 v52, 1.0, v52
	v_add_f32_e32 v48, 1.0, v48
	v_add_f32_e32 v53, 1.0, v53
	v_add_f32_e32 v49, 1.0, v49
	v_add_f32_e32 v54, 1.0, v54
	v_add_f32_e32 v50, 1.0, v50
	v_add_f32_e32 v55, 1.0, v55
	v_add_f32_e32 v51, 1.0, v51
	v_rcp_f32_e32 v52, v52
	v_rcp_f32_e32 v48, v48
	v_rcp_f32_e32 v53, v53
	v_rcp_f32_e32 v49, v49
	v_rcp_f32_e32 v54, v54
	v_rcp_f32_e32 v50, v50
	v_rcp_f32_e32 v55, v55
	v_rcp_f32_e32 v51, v51
.LBB0_197:
	s_and_b64 vcc, exec, s[6:7]
	s_nop 1
	v_cvt_pk_bf16_f32 v52, v52, v53
	s_nop 1
	v_cvt_pk_bf16_f32 v53, v54, v55
	s_nop 1
	v_cvt_pk_bf16_f32 v54, v48, v49
	s_nop 1
	v_cvt_pk_bf16_f32 v55, v50, v51
	global_store_dwordx4 v[64:65], v[52:55], off offset:256 sc1
	s_cbranch_vccnz .LBB0_199
	v_mul_f32_e32 v44, 0x38800000, v44
	v_mul_f32_e32 v40, 0x38800000, v40
	v_mul_f32_e32 v45, 0x38800000, v45
	v_mul_f32_e32 v41, 0x38800000, v41
	v_mul_f32_e32 v46, 0x38800000, v46
	v_mul_f32_e32 v42, 0x38800000, v42
	v_mul_f32_e32 v47, 0x38800000, v47
	v_mul_f32_e32 v43, 0x38800000, v43
	v_mul_f32_e32 v44, 0xbfb8aa3b, v44
	v_mul_f32_e32 v40, 0xbfb8aa3b, v40
	v_mul_f32_e32 v45, 0xbfb8aa3b, v45
	v_mul_f32_e32 v41, 0xbfb8aa3b, v41
	v_mul_f32_e32 v46, 0xbfb8aa3b, v46
	v_mul_f32_e32 v42, 0xbfb8aa3b, v42
	v_mul_f32_e32 v47, 0xbfb8aa3b, v47
	v_mul_f32_e32 v43, 0xbfb8aa3b, v43
	v_exp_f32_e32 v44, v44
	v_exp_f32_e32 v40, v40
	v_exp_f32_e32 v45, v45
	v_exp_f32_e32 v41, v41
	v_exp_f32_e32 v46, v46
	v_exp_f32_e32 v42, v42
	v_exp_f32_e32 v47, v47
	v_exp_f32_e32 v43, v43
	v_add_f32_e32 v44, 1.0, v44
	v_add_f32_e32 v40, 1.0, v40
	v_add_f32_e32 v45, 1.0, v45
	v_add_f32_e32 v41, 1.0, v41
	v_add_f32_e32 v46, 1.0, v46
	v_add_f32_e32 v42, 1.0, v42
	v_add_f32_e32 v47, 1.0, v47
	v_add_f32_e32 v43, 1.0, v43
	v_rcp_f32_e32 v44, v44
	v_rcp_f32_e32 v40, v40
	v_rcp_f32_e32 v45, v45
	v_rcp_f32_e32 v41, v41
	v_rcp_f32_e32 v46, v46
	v_rcp_f32_e32 v42, v42
	v_rcp_f32_e32 v47, v47
	v_rcp_f32_e32 v43, v43
.LBB0_199:
	v_add_u32_e32 v50, 0x90, v146
	v_mov_b64_e32 v[48:49], s[14:15]
	v_mad_i64_i32 v[48:49], s[16:17], v50, s87, v[48:49]
	v_lshl_add_u64 v[48:49], v[132:133], 1, v[48:49]
	s_and_b64 vcc, exec, s[6:7]
	s_nop 1
	v_cvt_pk_bf16_f32 v44, v44, v45
	s_nop 1
	v_cvt_pk_bf16_f32 v45, v46, v47
	s_nop 1
	v_cvt_pk_bf16_f32 v46, v40, v41
	s_nop 1
	v_cvt_pk_bf16_f32 v47, v42, v43
	global_store_dwordx4 v[48:49], v[44:47], off sc1
	s_cbranch_vccnz .LBB0_201
	v_mul_f32_e32 v36, 0x38800000, v36
	v_mul_f32_e32 v32, 0x38800000, v32
	v_mul_f32_e32 v37, 0x38800000, v37
	v_mul_f32_e32 v33, 0x38800000, v33
	v_mul_f32_e32 v38, 0x38800000, v38
	v_mul_f32_e32 v34, 0x38800000, v34
	v_mul_f32_e32 v39, 0x38800000, v39
	v_mul_f32_e32 v35, 0x38800000, v35
	v_mul_f32_e32 v36, 0xbfb8aa3b, v36
	v_mul_f32_e32 v32, 0xbfb8aa3b, v32
	v_mul_f32_e32 v37, 0xbfb8aa3b, v37
	v_mul_f32_e32 v33, 0xbfb8aa3b, v33
	v_mul_f32_e32 v38, 0xbfb8aa3b, v38
	v_mul_f32_e32 v34, 0xbfb8aa3b, v34
	v_mul_f32_e32 v39, 0xbfb8aa3b, v39
	v_mul_f32_e32 v35, 0xbfb8aa3b, v35
	v_exp_f32_e32 v36, v36
	v_exp_f32_e32 v32, v32
	v_exp_f32_e32 v37, v37
	v_exp_f32_e32 v33, v33
	v_exp_f32_e32 v38, v38
	v_exp_f32_e32 v34, v34
	v_exp_f32_e32 v39, v39
	v_exp_f32_e32 v35, v35
	v_add_f32_e32 v36, 1.0, v36
	v_add_f32_e32 v32, 1.0, v32
	v_add_f32_e32 v37, 1.0, v37
	v_add_f32_e32 v33, 1.0, v33
	v_add_f32_e32 v38, 1.0, v38
	v_add_f32_e32 v34, 1.0, v34
	v_add_f32_e32 v39, 1.0, v39
	v_add_f32_e32 v35, 1.0, v35
	v_rcp_f32_e32 v36, v36
	v_rcp_f32_e32 v32, v32
	v_rcp_f32_e32 v37, v37
	v_rcp_f32_e32 v33, v33
	v_rcp_f32_e32 v38, v38
	v_rcp_f32_e32 v34, v34
	v_rcp_f32_e32 v39, v39
	v_rcp_f32_e32 v35, v35
.LBB0_201:
	s_and_b64 vcc, exec, s[6:7]
	s_nop 1
	v_cvt_pk_bf16_f32 v36, v36, v37
	s_nop 1
	v_cvt_pk_bf16_f32 v37, v38, v39
	s_nop 1
	v_cvt_pk_bf16_f32 v38, v32, v33
	s_nop 1
	v_cvt_pk_bf16_f32 v39, v34, v35
	global_store_dwordx4 v[48:49], v[36:39], off offset:256 sc1
	s_cbranch_vccnz .LBB0_203
	v_mul_f32_e32 v28, 0x38800000, v28
	v_mul_f32_e32 v24, 0x38800000, v24
	v_mul_f32_e32 v29, 0x38800000, v29
	v_mul_f32_e32 v25, 0x38800000, v25
	v_mul_f32_e32 v30, 0x38800000, v30
	v_mul_f32_e32 v26, 0x38800000, v26
	v_mul_f32_e32 v31, 0x38800000, v31
	v_mul_f32_e32 v27, 0x38800000, v27
	v_mul_f32_e32 v28, 0xbfb8aa3b, v28
	v_mul_f32_e32 v24, 0xbfb8aa3b, v24
	v_mul_f32_e32 v29, 0xbfb8aa3b, v29
	v_mul_f32_e32 v25, 0xbfb8aa3b, v25
	v_mul_f32_e32 v30, 0xbfb8aa3b, v30
	v_mul_f32_e32 v26, 0xbfb8aa3b, v26
	v_mul_f32_e32 v31, 0xbfb8aa3b, v31
	v_mul_f32_e32 v27, 0xbfb8aa3b, v27
	v_exp_f32_e32 v28, v28
	v_exp_f32_e32 v24, v24
	v_exp_f32_e32 v29, v29
	v_exp_f32_e32 v25, v25
	v_exp_f32_e32 v30, v30
	v_exp_f32_e32 v26, v26
	v_exp_f32_e32 v31, v31
	v_exp_f32_e32 v27, v27
	v_add_f32_e32 v28, 1.0, v28
	v_add_f32_e32 v24, 1.0, v24
	v_add_f32_e32 v29, 1.0, v29
	v_add_f32_e32 v25, 1.0, v25
	v_add_f32_e32 v30, 1.0, v30
	v_add_f32_e32 v26, 1.0, v26
	v_add_f32_e32 v31, 1.0, v31
	v_add_f32_e32 v27, 1.0, v27
	v_rcp_f32_e32 v28, v28
	v_rcp_f32_e32 v24, v24
	v_rcp_f32_e32 v29, v29
	v_rcp_f32_e32 v25, v25
	v_rcp_f32_e32 v30, v30
	v_rcp_f32_e32 v26, v26
	v_rcp_f32_e32 v31, v31
	v_rcp_f32_e32 v27, v27
.LBB0_203:
	v_add_u32_e32 v34, 0xa0, v146
	v_mov_b64_e32 v[32:33], s[14:15]
	v_mad_i64_i32 v[32:33], s[16:17], v34, s87, v[32:33]
	v_lshl_add_u64 v[32:33], v[132:133], 1, v[32:33]
	s_and_b64 vcc, exec, s[6:7]
	s_nop 1
	v_cvt_pk_bf16_f32 v28, v28, v29
	s_nop 1
	v_cvt_pk_bf16_f32 v29, v30, v31
	s_nop 1
	v_cvt_pk_bf16_f32 v30, v24, v25
	s_nop 1
	v_cvt_pk_bf16_f32 v31, v26, v27
	global_store_dwordx4 v[32:33], v[28:31], off sc1
	s_cbranch_vccnz .LBB0_205
	v_mul_f32_e32 v20, 0x38800000, v20
	v_mul_f32_e32 v16, 0x38800000, v16
	v_mul_f32_e32 v21, 0x38800000, v21
	v_mul_f32_e32 v17, 0x38800000, v17
	v_mul_f32_e32 v22, 0x38800000, v22
	v_mul_f32_e32 v18, 0x38800000, v18
	v_mul_f32_e32 v23, 0x38800000, v23
	v_mul_f32_e32 v19, 0x38800000, v19
	v_mul_f32_e32 v20, 0xbfb8aa3b, v20
	v_mul_f32_e32 v16, 0xbfb8aa3b, v16
	v_mul_f32_e32 v21, 0xbfb8aa3b, v21
	v_mul_f32_e32 v17, 0xbfb8aa3b, v17
	v_mul_f32_e32 v22, 0xbfb8aa3b, v22
	v_mul_f32_e32 v18, 0xbfb8aa3b, v18
	v_mul_f32_e32 v23, 0xbfb8aa3b, v23
	v_mul_f32_e32 v19, 0xbfb8aa3b, v19
	v_exp_f32_e32 v20, v20
	v_exp_f32_e32 v16, v16
	v_exp_f32_e32 v21, v21
	v_exp_f32_e32 v17, v17
	v_exp_f32_e32 v22, v22
	v_exp_f32_e32 v18, v18
	v_exp_f32_e32 v23, v23
	v_exp_f32_e32 v19, v19
	v_add_f32_e32 v20, 1.0, v20
	v_add_f32_e32 v16, 1.0, v16
	v_add_f32_e32 v21, 1.0, v21
	v_add_f32_e32 v17, 1.0, v17
	v_add_f32_e32 v22, 1.0, v22
	v_add_f32_e32 v18, 1.0, v18
	v_add_f32_e32 v23, 1.0, v23
	v_add_f32_e32 v19, 1.0, v19
	v_rcp_f32_e32 v20, v20
	v_rcp_f32_e32 v16, v16
	v_rcp_f32_e32 v21, v21
	v_rcp_f32_e32 v17, v17
	v_rcp_f32_e32 v22, v22
	v_rcp_f32_e32 v18, v18
	v_rcp_f32_e32 v23, v23
	v_rcp_f32_e32 v19, v19
.LBB0_205:
	s_and_b64 vcc, exec, s[6:7]
	s_nop 1
	v_cvt_pk_bf16_f32 v20, v20, v21
	s_nop 1
	v_cvt_pk_bf16_f32 v21, v22, v23
	s_nop 1
	v_cvt_pk_bf16_f32 v22, v16, v17
	s_nop 1
	v_cvt_pk_bf16_f32 v23, v18, v19
	global_store_dwordx4 v[32:33], v[20:23], off offset:256 sc1
	s_cbranch_vccnz .LBB0_207
	v_mul_f32_e32 v12, 0x38800000, v12
	v_mul_f32_e32 v8, 0x38800000, v8
	v_mul_f32_e32 v13, 0x38800000, v13
	v_mul_f32_e32 v9, 0x38800000, v9
	v_mul_f32_e32 v14, 0x38800000, v14
	v_mul_f32_e32 v10, 0x38800000, v10
	v_mul_f32_e32 v15, 0x38800000, v15
	v_mul_f32_e32 v11, 0x38800000, v11
	v_mul_f32_e32 v12, 0xbfb8aa3b, v12
	v_mul_f32_e32 v8, 0xbfb8aa3b, v8
	v_mul_f32_e32 v13, 0xbfb8aa3b, v13
	v_mul_f32_e32 v9, 0xbfb8aa3b, v9
	v_mul_f32_e32 v14, 0xbfb8aa3b, v14
	v_mul_f32_e32 v10, 0xbfb8aa3b, v10
	v_mul_f32_e32 v15, 0xbfb8aa3b, v15
	v_mul_f32_e32 v11, 0xbfb8aa3b, v11
	v_exp_f32_e32 v12, v12
	v_exp_f32_e32 v8, v8
	v_exp_f32_e32 v13, v13
	v_exp_f32_e32 v9, v9
	v_exp_f32_e32 v14, v14
	v_exp_f32_e32 v10, v10
	v_exp_f32_e32 v15, v15
	v_exp_f32_e32 v11, v11
	v_add_f32_e32 v12, 1.0, v12
	v_add_f32_e32 v8, 1.0, v8
	v_add_f32_e32 v13, 1.0, v13
	v_add_f32_e32 v9, 1.0, v9
	v_add_f32_e32 v14, 1.0, v14
	v_add_f32_e32 v10, 1.0, v10
	v_add_f32_e32 v15, 1.0, v15
	v_add_f32_e32 v11, 1.0, v11
	v_rcp_f32_e32 v12, v12
	v_rcp_f32_e32 v8, v8
	v_rcp_f32_e32 v13, v13
	v_rcp_f32_e32 v9, v9
	v_rcp_f32_e32 v14, v14
	v_rcp_f32_e32 v10, v10
	v_rcp_f32_e32 v15, v15
	v_rcp_f32_e32 v11, v11
.LBB0_207:
	v_add_u32_e32 v18, 0xb0, v146
	v_mov_b64_e32 v[16:17], s[14:15]
	v_mad_i64_i32 v[16:17], s[16:17], v18, s87, v[16:17]
	v_lshl_add_u64 v[16:17], v[132:133], 1, v[16:17]
	s_and_b64 vcc, exec, s[6:7]
	s_nop 1
	v_cvt_pk_bf16_f32 v12, v12, v13
	s_nop 1
	v_cvt_pk_bf16_f32 v13, v14, v15
	s_nop 1
	v_cvt_pk_bf16_f32 v14, v8, v9
	s_nop 1
	v_cvt_pk_bf16_f32 v15, v10, v11
	global_store_dwordx4 v[16:17], v[12:15], off sc1
	s_cbranch_vccnz .LBB0_209
	v_mul_f32_e32 v4, 0x38800000, v4
	v_mul_f32_e32 v0, 0x38800000, v0
	v_mul_f32_e32 v5, 0x38800000, v5
	v_mul_f32_e32 v1, 0x38800000, v1
	v_mul_f32_e32 v6, 0x38800000, v6
	v_mul_f32_e32 v2, 0x38800000, v2
	v_mul_f32_e32 v7, 0x38800000, v7
	v_mul_f32_e32 v3, 0x38800000, v3
	v_mul_f32_e32 v4, 0xbfb8aa3b, v4
	v_mul_f32_e32 v0, 0xbfb8aa3b, v0
	v_mul_f32_e32 v5, 0xbfb8aa3b, v5
	v_mul_f32_e32 v1, 0xbfb8aa3b, v1
	v_mul_f32_e32 v6, 0xbfb8aa3b, v6
	v_mul_f32_e32 v2, 0xbfb8aa3b, v2
	v_mul_f32_e32 v7, 0xbfb8aa3b, v7
	v_mul_f32_e32 v3, 0xbfb8aa3b, v3
	v_exp_f32_e32 v4, v4
	v_exp_f32_e32 v0, v0
	v_exp_f32_e32 v5, v5
	v_exp_f32_e32 v1, v1
	v_exp_f32_e32 v6, v6
	v_exp_f32_e32 v2, v2
	v_exp_f32_e32 v7, v7
	v_exp_f32_e32 v3, v3
	v_add_f32_e32 v4, 1.0, v4
	v_add_f32_e32 v0, 1.0, v0
	v_add_f32_e32 v5, 1.0, v5
	v_add_f32_e32 v1, 1.0, v1
	v_add_f32_e32 v6, 1.0, v6
	v_add_f32_e32 v2, 1.0, v2
	v_add_f32_e32 v7, 1.0, v7
	v_add_f32_e32 v3, 1.0, v3
	v_rcp_f32_e32 v4, v4
	v_rcp_f32_e32 v0, v0
	v_rcp_f32_e32 v5, v5
	v_rcp_f32_e32 v1, v1
	v_rcp_f32_e32 v6, v6
	v_rcp_f32_e32 v2, v2
	v_rcp_f32_e32 v7, v7
	v_rcp_f32_e32 v3, v3

.LBB0_306:
	s_lshr_b32 s38, s33, 4
	s_ashr_i32 s37, s36, 31
	s_and_b32 s38, s38, 0x7f
	s_lshl_b32 s39, s38, 16
	s_lshl_b64 s[36:37], s[36:37], 12
	s_add_u32 s36, s39, s36
	s_addc_u32 s37, 0, s37
	s_or_b64 s[36:37], s[36:37], s[4:5]
	s_mul_i32 s38, s38, 0x60000
	s_add_u32 s38, s38, s71
	s_addc_u32 s39, 0, s70
	s_add_u32 s38, s38, s4
	s_addc_u32 s39, s39, 0
	s_and_b32 s70, s69, 0xfffff800
	s_ashr_i32 s71, s70, 31
	s_mul_i32 s69, s70, 0x6000
	s_mul_hi_i32 s4, s70, 0x6000
	s_add_u32 s69, s58, s69
	s_addc_u32 s4, s59, s4
	s_lshl_b32 s72, s68, 10
	s_add_u32 s68, s69, s72
	s_addc_u32 s69, s4, 0
	v_lshl_add_u64 v[8:9], s[68:69], 0, v[0:1]
	v_lshl_add_u64 v[8:9], v[8:9], 0, s[0:1]
	s_mul_i32 s4, s66, 0x6000
	v_lshl_add_u64 v[10:11], v[8:9], 0, s[4:5]
	global_load_dwordx4 v[22:25], v[10:11], off
	v_lshl_add_u64 v[10:11], v[4:5], 0, s[36:37]
	s_lshl_b64 s[36:37], s[70:71], 12
	s_add_u32 s4, s8, s36
	s_addc_u32 s37, s9, s37
	s_add_u32 s36, s4, s72
	v_lshl_add_u64 v[12:13], v[6:7], 0, s[38:39]
	s_addc_u32 s37, s37, 0
	s_or_b32 s38, s66, 1
	v_lshl_add_u64 v[26:27], s[36:37], 0, v[0:1]
	s_min_u32 s36, s38, s65
	v_cvt_f32_ubyte0_e32 v28, s36
	v_div_scale_f32 v29, s[36:37], v28, v28, 1.0
	v_rcp_f32_e32 v31, v29
	v_div_scale_f32 v32, vcc, 1.0, v28, 1.0
	s_lshl_b32 s4, s66, 12
	v_fma_f32 v33, -v29, v31, 1.0
	v_fmac_f32_e32 v31, v33, v31
	v_mul_f32_e32 v33, v32, v31
	v_fma_f32 v34, -v29, v33, v32
	v_fmac_f32_e32 v33, v34, v31
	v_fma_f32 v29, -v29, v33, v32
	v_div_fmas_f32 v29, v29, v31, v33
	v_div_fixup_f32 v28, v29, v28, 1.0
	v_lshl_add_u64 v[26:27], v[26:27], 0, s[4:5]
	s_mov_b32 s4, 0
	s_waitcnt vmcnt(0)
	v_lshlrev_b32_e32 v32, 16, v22
	v_and_b32_e32 v33, 0xffff0000, v22
	v_lshlrev_b32_e32 v22, 16, v23
	v_and_b32_e32 v23, 0xffff0000, v23
	v_lshlrev_b32_e32 v34, 16, v24
	v_and_b32_e32 v35, 0xffff0000, v24
	v_lshlrev_b32_e32 v24, 16, v25
	v_and_b32_e32 v25, 0xffff0000, v25
	v_pk_add_f32 v[20:21], v[20:21], v[22:23]
	v_pk_add_f32 v[18:19], v[18:19], v[32:33]
	v_pk_add_f32 v[14:15], v[14:15], v[24:25]
	v_pk_add_f32 v[16:17], v[16:17], v[34:35]
	v_xor_b32_e32 v23, 0x80000000, v23
	v_xor_b32_e32 v22, 0x80000000, v22
	v_xor_b32_e32 v33, 0x80000000, v33
	v_xor_b32_e32 v32, 0x80000000, v32
	v_xor_b32_e32 v25, 0x80000000, v25
	v_xor_b32_e32 v24, 0x80000000, v24
	v_xor_b32_e32 v35, 0x80000000, v35
	v_xor_b32_e32 v34, 0x80000000, v34
	v_pk_fma_f32 v[36:37], v[28:29], v[20:21], v[22:23] op_sel_hi:[0,1,1]
	v_pk_fma_f32 v[22:23], v[28:29], v[18:19], v[32:33] op_sel_hi:[0,1,1]
	v_pk_fma_f32 v[32:33], v[28:29], v[14:15], v[24:25] op_sel_hi:[0,1,1]
	v_pk_fma_f32 v[24:25], v[28:29], v[16:17], v[34:35] op_sel_hi:[0,1,1]
	v_cvt_pk_bf16_f32 v22, v22, v23
	v_cvt_pk_bf16_f32 v23, v36, v37
	v_cvt_pk_bf16_f32 v24, v24, v25
	v_cvt_pk_bf16_f32 v25, v32, v33
	global_store_dwordx4 v[26:27], v[22:25], off sc1
	s_branch .LBB0_308
.LBB0_307:
	s_add_i32 s36, s36, 2
	s_min_u32 s36, s36, s65
	v_cvt_f32_ubyte0_e32 v31, s36
	v_div_scale_f32 v32, s[36:37], v31, v31, 1.0
	v_rcp_f32_e32 v33, v32
	v_div_scale_f32 v34, vcc, 1.0, v31, 1.0
	v_xor_b32_e32 v29, 0x80000000, v29
	v_fma_f32 v35, -v32, v33, 1.0
	v_fmac_f32_e32 v33, v35, v33
	v_mul_f32_e32 v35, v34, v33
	v_fma_f32 v36, -v32, v35, v34
	v_fmac_f32_e32 v35, v36, v33
	v_fma_f32 v32, -v32, v35, v34
	v_div_fmas_f32 v32, v32, v33, v35
	v_div_fixup_f32 v32, v32, v31, 1.0
	v_xor_b32_e32 v28, 0x80000000, v28
	v_pk_fma_f32 v[24:25], v[32:33], v[18:19], v[24:25] op_sel_hi:[0,1,1] neg_lo:[0,0,1] neg_hi:[0,0,1]
	v_xor_b32_e32 v27, 0x80000000, v27
	v_xor_b32_e32 v26, 0x80000000, v26
	s_add_i32 s4, s4, 1
	v_pk_fma_f32 v[28:29], v[32:33], v[20:21], v[28:29] op_sel_hi:[0,1,1]
	v_pk_fma_f32 v[26:27], v[32:33], v[14:15], v[26:27] op_sel_hi:[0,1,1]
	v_pk_fma_f32 v[32:33], v[32:33], v[16:17], v[22:23] op_sel_hi:[0,1,1] neg_lo:[0,0,1] neg_hi:[0,0,1]
	v_cvt_pk_bf16_f32 v22, v24, v25
	v_cvt_pk_bf16_f32 v23, v28, v29
	v_cvt_pk_bf16_f32 v24, v32, v33
	v_cvt_pk_bf16_f32 v25, v26, v27
	global_store_dwordx4 v[10:11], v[22:25], off sc1
	v_lshl_add_u64 v[10:11], v[10:11], 0, s[14:15]
	s_cmp_eq_u32 s4, 15
	v_lshl_add_u64 v[12:13], v[12:13], 0, s[10:11]
	s_cbranch_scc1 .LBB0_300

.LBB0_314:
	s_cmpk_gt_i32 s35, 0x55ff
	s_mov_b64 s[4:5], -1
	s_cbranch_scc0 .LBB0_332
	s_cmpk_gt_u32 s35, 0x59ff
	s_cbranch_scc0 .LBB0_329
	s_cmpk_gt_u32 s35, 0x5aff
	s_cbranch_scc0 .LBB0_326
	s_cmpk_gt_u32 s35, 0x62ff
	s_cbranch_scc0 .LBB0_323
	s_and_b32 s33, s16, 0xfc0
	s_cmpk_gt_u32 s35, 0x6aff
	s_cbranch_scc0 .LBB0_320
	s_add_i32 s4, s35, 0xffff9500
	s_and_b32 s0, s4, 0xffffffc0
	v_or_b32_e32 v0, s0, v3
	s_lshl_b32 s0, s33, 2
	v_or_b32_e32 v50, 4, v0
	v_mov_b32_e32 v51, v1
	v_or_b32_e32 v56, 8, v0
	v_mov_b32_e32 v57, v1
	v_or_b32_e32 v58, 12, v0
	v_mov_b32_e32 v59, v1
	v_or_b32_e32 v64, 16, v0
	v_mov_b32_e32 v65, v1
	v_or_b32_e32 v66, 20, v0
	v_mov_b32_e32 v67, v1
	v_or_b32_e32 v72, 24, v0
	v_mov_b32_e32 v73, v1
	v_or_b32_e32 v74, 28, v0
	v_mov_b32_e32 v75, v1
	v_or_b32_e32 v80, 32, v0
	v_mov_b32_e32 v81, v1
	v_or_b32_e32 v82, 36, v0
	v_mov_b32_e32 v83, v1
	v_lshl_add_u64 v[108:109], v[20:21], 0, s[0:1]
	v_lshlrev_b64 v[48:49], 14, v[0:1]
	v_lshlrev_b64 v[50:51], 14, v[50:51]
	v_lshlrev_b64 v[56:57], 14, v[56:57]
	v_lshlrev_b64 v[58:59], 14, v[58:59]
	v_lshlrev_b64 v[64:65], 14, v[64:65]
	v_lshlrev_b64 v[66:67], 14, v[66:67]
	v_lshlrev_b64 v[72:73], 14, v[72:73]
	v_lshlrev_b64 v[74:75], 14, v[74:75]
	v_lshlrev_b64 v[80:81], 14, v[80:81]
	v_lshlrev_b64 v[82:83], 14, v[82:83]
	v_or_b32_e32 v88, 40, v0
	v_mov_b32_e32 v89, v1
	v_or_b32_e32 v90, 44, v0
	v_mov_b32_e32 v91, v1
	v_lshl_add_u64 v[48:49], v[108:109], 0, v[48:49]
	v_lshl_add_u64 v[52:53], v[108:109], 0, v[50:51]
	v_lshl_add_u64 v[56:57], v[108:109], 0, v[56:57]
	v_lshl_add_u64 v[60:61], v[108:109], 0, v[58:59]
	v_lshl_add_u64 v[64:65], v[108:109], 0, v[64:65]
	v_lshl_add_u64 v[68:69], v[108:109], 0, v[66:67]
	v_lshl_add_u64 v[72:73], v[108:109], 0, v[72:73]
	v_lshl_add_u64 v[76:77], v[108:109], 0, v[74:75]
	v_lshl_add_u64 v[80:81], v[108:109], 0, v[80:81]
	v_lshl_add_u64 v[84:85], v[108:109], 0, v[82:83]
	v_lshlrev_b64 v[88:89], 14, v[88:89]
	v_lshlrev_b64 v[90:91], 14, v[90:91]
	global_load_dwordx4 v[48:51], v[48:49], off
	s_nop 0
	global_load_dwordx4 v[52:55], v[52:53], off
	s_nop 0
	global_load_dwordx4 v[56:59], v[56:57], off
	s_nop 0
	global_load_dwordx4 v[60:63], v[60:61], off
	s_nop 0
	global_load_dwordx4 v[64:67], v[64:65], off
	s_nop 0
	global_load_dwordx4 v[68:71], v[68:69], off
	s_nop 0
	global_load_dwordx4 v[72:75], v[72:73], off
	s_nop 0
	global_load_dwordx4 v[76:79], v[76:77], off
	s_nop 0
	global_load_dwordx4 v[80:83], v[80:81], off
	s_nop 0
	global_load_dwordx4 v[84:87], v[84:85], off
	v_lshl_add_u64 v[88:89], v[108:109], 0, v[88:89]
	v_lshl_add_u64 v[92:93], v[108:109], 0, v[90:91]
	global_load_dwordx4 v[88:91], v[88:89], off
	s_nop 0
	global_load_dwordx4 v[92:95], v[92:93], off
	v_or_b32_e32 v96, 48, v0
	v_mov_b32_e32 v97, v1
	v_lshlrev_b64 v[96:97], 14, v[96:97]
	v_lshl_add_u64 v[96:97], v[108:109], 0, v[96:97]
	v_or_b32_e32 v100, 52, v0
	v_mov_b32_e32 v101, v1
	global_load_dwordx4 v[96:99], v[96:97], off
	v_lshlrev_b64 v[100:101], 14, v[100:101]
	v_lshl_add_u64 v[100:101], v[108:109], 0, v[100:101]
	v_or_b32_e32 v104, 56, v0
	v_mov_b32_e32 v105, v1
	global_load_dwordx4 v[100:103], v[100:101], off
	v_lshlrev_b64 v[104:105], 14, v[104:105]
	v_lshl_add_u64 v[104:105], v[108:109], 0, v[104:105]
	v_or_b32_e32 v0, 60, v0
	global_load_dwordx4 v[104:107], v[104:105], off
	v_lshlrev_b64 v[110:111], 14, v[0:1]
	v_lshl_add_u64 v[108:109], v[108:109], 0, v[110:111]
	global_load_dwordx4 v[108:111], v[108:109], off
	v_add_u32_e32 v0, 0xf0a0, v5
	s_lshr_b32 s0, s4, 6
	s_and_b32 s4, s18, 0x3c0
	s_add_i32 s0, s4, s0
	s_lshl_b32 s4, s33, 7
	s_and_b32 s4, s4, 0x6000
	s_add_u32 s62, s3, s4
	v_add_u32_e32 v31, 0xc800, v9
	s_addc_u32 s63, s8, 0
	s_lshl_b64 s[4:5], s[0:1], 15
	s_waitcnt vmcnt(15)
	ds_write2_b32 v7, v48, v49 offset1:1
	ds_write2_b32 v11, v50, v51 offset1:1
	s_waitcnt vmcnt(14)
	ds_write2_b32 v13, v52, v53 offset1:1
	ds_write2_b32 v15, v54, v55 offset1:1
	s_waitcnt vmcnt(13)
	ds_write2_b32 v17, v56, v57 offset1:1
	ds_write2_b32 v19, v58, v59 offset1:1
	s_waitcnt vmcnt(12)
	ds_write2_b32 v32, v60, v61 offset1:1
	ds_write2_b32 v33, v62, v63 offset1:1
	s_waitcnt vmcnt(11)
	ds_write2_b32 v34, v64, v65 offset1:1
	ds_write2_b32 v36, v66, v67 offset1:1
	s_waitcnt vmcnt(10)
	ds_write2_b32 v37, v68, v69 offset1:1
	ds_write2_b32 v38, v70, v71 offset1:1
	s_waitcnt vmcnt(9)
	ds_write2_b32 v39, v72, v73 offset1:1
	ds_write2_b32 v40, v74, v75 offset1:1
	s_waitcnt vmcnt(8)
	ds_write2_b32 v41, v76, v77 offset1:1
	ds_write2_b32 v42, v78, v79 offset1:1
	s_waitcnt vmcnt(7)
	ds_write2_b32 v43, v80, v81 offset1:1
	ds_write2_b32 v44, v82, v83 offset1:1
	s_waitcnt vmcnt(6)
	ds_write2_b32 v45, v84, v85 offset1:1
	ds_write2_b32 v46, v86, v87 offset1:1
	s_add_u32 s4, s62, s4
	s_waitcnt vmcnt(5)
	ds_write2_b32 v0, v88, v89 offset1:1
	v_add_u32_e32 v0, 0xf0a8, v5
	ds_write2_b32 v0, v90, v91 offset1:1
	v_add_u32_e32 v0, 0xf4b0, v5
	s_waitcnt vmcnt(4)
	ds_write2_b32 v0, v92, v93 offset1:1
	v_add_u32_e32 v0, 0xf4b8, v5
	ds_write2_b32 v0, v94, v95 offset1:1
	v_add_u32_e32 v0, 0xf8c0, v5
	s_waitcnt vmcnt(3)
	ds_write2_b32 v0, v96, v97 offset1:1
	v_add_u32_e32 v0, 0xf8c8, v5
	ds_write2_b32 v0, v98, v99 offset1:1
	v_add_u32_e32 v0, 0xfcd0, v5
	v_add_u32_e32 v47, 0xcc00, v9
	s_waitcnt vmcnt(2)
	ds_write2_b32 v0, v100, v101 offset1:1
	v_add_u32_e32 v0, 0xfcd8, v5
	ds_write2_b32 v0, v102, v103 offset1:1
	v_add_u32_e32 v0, 0x38e0, v7
	s_waitcnt vmcnt(1)
	ds_write2_b32 v0, v104, v105 offset1:1
	v_add_u32_e32 v0, 0x38e8, v7
	ds_write2_b32 v0, v106, v107 offset1:1
	v_add_u32_e32 v0, 0x3cf0, v7
	s_waitcnt vmcnt(0)
	ds_write2_b32 v0, v108, v109 offset1:1
	v_add_u32_e32 v0, 0x3cf8, v7
	ds_write2_b32 v0, v110, v111 offset1:1
	s_waitcnt lgkmcnt(0)
	ds_read2_b32 v[48:49], v31 offset1:65
	s_waitcnt lgkmcnt(0)
	v_cvt_pk_bf16_f32 v48, v48, v49
	ds_read2_b32 v[50:51], v31 offset0:130 offset1:195
	s_addc_u32 s5, s63, s5
	v_lshlrev_b32_e32 v0, 1, v2
	s_waitcnt lgkmcnt(0)
	v_cvt_pk_bf16_f32 v49, v50, v51
	ds_read2_b32 v[50:51], v47 offset0:4 offset1:69
	v_lshl_add_u64 v[54:55], s[4:5], 0, v[0:1]
	v_lshlrev_b32_e32 v0, 1, v4
	s_waitcnt lgkmcnt(0)
	v_cvt_pk_bf16_f32 v50, v50, v51
	ds_read2_b32 v[52:53], v47 offset0:134 offset1:199
	s_waitcnt lgkmcnt(0)
	v_cvt_pk_bf16_f32 v51, v52, v53
	v_lshl_add_u64 v[56:57], v[54:55], 0, v[0:1]
	ds_read2_b32 v[52:53], v31 offset0:8 offset1:73
	global_store_dwordx4 v[56:57], v[48:51], off sc1
	v_lshlrev_b32_e32 v0, 1, v6
	v_lshl_add_u64 v[56:57], v[54:55], 0, v[0:1]
	s_waitcnt lgkmcnt(0)
	v_cvt_pk_bf16_f32 v48, v52, v53
	ds_read2_b32 v[50:51], v31 offset0:138 offset1:203
	s_waitcnt lgkmcnt(0)
	v_cvt_pk_bf16_f32 v49, v50, v51
	ds_read2_b32 v[50:51], v47 offset0:12 offset1:77
	s_waitcnt lgkmcnt(0)
	v_cvt_pk_bf16_f32 v50, v50, v51
	ds_read2_b32 v[52:53], v47 offset0:142 offset1:207
	s_waitcnt lgkmcnt(0)
	v_cvt_pk_bf16_f32 v51, v52, v53
	ds_read2_b32 v[52:53], v31 offset0:16 offset1:81
	global_store_dwordx4 v[56:57], v[48:51], off sc1
	v_lshlrev_b32_e32 v0, 1, v8
	v_lshl_add_u64 v[56:57], v[54:55], 0, v[0:1]
	s_waitcnt lgkmcnt(0)
	v_cvt_pk_bf16_f32 v48, v52, v53
	ds_read2_b32 v[50:51], v31 offset0:146 offset1:211
	s_waitcnt lgkmcnt(0)
	v_cvt_pk_bf16_f32 v49, v50, v51
	ds_read2_b32 v[50:51], v47 offset0:20 offset1:85
	s_waitcnt lgkmcnt(0)
	v_cvt_pk_bf16_f32 v50, v50, v51
	ds_read2_b32 v[52:53], v47 offset0:150 offset1:215
	s_waitcnt lgkmcnt(0)
	v_cvt_pk_bf16_f32 v51, v52, v53
	ds_read2_b32 v[52:53], v31 offset0:24 offset1:89
	global_store_dwordx4 v[56:57], v[48:51], off sc1
	v_lshlrev_b32_e32 v0, 1, v10
	v_lshl_add_u64 v[56:57], v[54:55], 0, v[0:1]
	s_waitcnt lgkmcnt(0)
	v_cvt_pk_bf16_f32 v48, v52, v53
	ds_read2_b32 v[50:51], v31 offset0:154 offset1:219
	s_waitcnt lgkmcnt(0)
	v_cvt_pk_bf16_f32 v49, v50, v51
	ds_read2_b32 v[50:51], v47 offset0:28 offset1:93
	s_waitcnt lgkmcnt(0)
	v_cvt_pk_bf16_f32 v50, v50, v51
	ds_read2_b32 v[52:53], v47 offset0:158 offset1:223
	s_waitcnt lgkmcnt(0)
	v_cvt_pk_bf16_f32 v51, v52, v53
	ds_read2_b32 v[52:53], v31 offset0:32 offset1:97
	global_store_dwordx4 v[56:57], v[48:51], off sc1
	v_lshlrev_b32_e32 v0, 1, v12
	v_lshl_add_u64 v[56:57], v[54:55], 0, v[0:1]
	s_waitcnt lgkmcnt(0)
	v_cvt_pk_bf16_f32 v48, v52, v53
	ds_read2_b32 v[50:51], v31 offset0:162 offset1:227
	s_waitcnt lgkmcnt(0)
	v_cvt_pk_bf16_f32 v49, v50, v51
	ds_read2_b32 v[50:51], v47 offset0:36 offset1:101
	s_waitcnt lgkmcnt(0)
	v_cvt_pk_bf16_f32 v50, v50, v51
	ds_read2_b32 v[52:53], v47 offset0:166 offset1:231
	s_waitcnt lgkmcnt(0)
	v_cvt_pk_bf16_f32 v51, v52, v53
	ds_read2_b32 v[52:53], v31 offset0:40 offset1:105
	global_store_dwordx4 v[56:57], v[48:51], off sc1
	v_lshlrev_b32_e32 v0, 1, v14
	v_lshl_add_u64 v[56:57], v[54:55], 0, v[0:1]
	s_waitcnt lgkmcnt(0)
	v_cvt_pk_bf16_f32 v48, v52, v53
	ds_read2_b32 v[50:51], v31 offset0:170 offset1:235
	s_waitcnt lgkmcnt(0)
	v_cvt_pk_bf16_f32 v49, v50, v51
	ds_read2_b32 v[50:51], v47 offset0:44 offset1:109
	s_waitcnt lgkmcnt(0)
	v_cvt_pk_bf16_f32 v50, v50, v51
	ds_read2_b32 v[52:53], v47 offset0:174 offset1:239
	s_waitcnt lgkmcnt(0)
	v_cvt_pk_bf16_f32 v51, v52, v53
	ds_read2_b32 v[52:53], v31 offset0:48 offset1:113
	global_store_dwordx4 v[56:57], v[48:51], off sc1
	v_lshlrev_b32_e32 v0, 1, v16
	v_lshl_add_u64 v[56:57], v[54:55], 0, v[0:1]
	s_waitcnt lgkmcnt(0)
	v_cvt_pk_bf16_f32 v48, v52, v53
	ds_read2_b32 v[50:51], v31 offset0:178 offset1:243
	s_waitcnt lgkmcnt(0)
	v_cvt_pk_bf16_f32 v49, v50, v51
	ds_read2_b32 v[50:51], v47 offset0:52 offset1:117
	s_waitcnt lgkmcnt(0)
	v_cvt_pk_bf16_f32 v50, v50, v51
	ds_read2_b32 v[52:53], v47 offset0:182 offset1:247
	s_waitcnt lgkmcnt(0)
	v_cvt_pk_bf16_f32 v51, v52, v53
	ds_read2_b32 v[52:53], v31 offset0:56 offset1:121
	global_store_dwordx4 v[56:57], v[48:51], off sc1
	v_lshlrev_b32_e32 v0, 1, v18
	s_mov_b64 s[4:5], 0
	s_waitcnt lgkmcnt(0)
	v_cvt_pk_bf16_f32 v48, v52, v53
	ds_read2_b32 v[50:51], v31 offset0:186 offset1:251
	s_waitcnt lgkmcnt(0)
	v_cvt_pk_bf16_f32 v49, v50, v51
	ds_read2_b32 v[50:51], v47 offset0:60 offset1:125
	s_waitcnt lgkmcnt(0)
	v_cvt_pk_bf16_f32 v50, v50, v51
	ds_read2_b32 v[52:53], v47 offset0:190 offset1:255
	s_waitcnt lgkmcnt(0)
	v_cvt_pk_bf16_f32 v51, v52, v53
	v_lshl_add_u64 v[52:53], v[54:55], 0, v[0:1]
	global_store_dwordx4 v[52:53], v[48:51], off sc1
	s_waitcnt lgkmcnt(0)
.LBB0_320:
	s_andn2_b64 vcc, exec, s[4:5]
	s_cbranch_vccnz .LBB0_322
	s_add_i32 s4, s35, 0xffff9d00
	s_and_b32 s0, s4, 0xffffffc0
	v_or_b32_e32 v0, s0, v3
	s_lshl_b32 s0, s33, 2
	v_or_b32_e32 v50, 4, v0
	v_mov_b32_e32 v51, v1
	v_or_b32_e32 v56, 8, v0
	v_mov_b32_e32 v57, v1
	v_or_b32_e32 v58, 12, v0
	v_mov_b32_e32 v59, v1
	v_or_b32_e32 v64, 16, v0
	v_mov_b32_e32 v65, v1
	v_or_b32_e32 v66, 20, v0
	v_mov_b32_e32 v67, v1
	v_or_b32_e32 v72, 24, v0
	v_mov_b32_e32 v73, v1
	v_or_b32_e32 v74, 28, v0
	v_mov_b32_e32 v75, v1
	v_or_b32_e32 v80, 32, v0
	v_mov_b32_e32 v81, v1
	v_or_b32_e32 v82, 36, v0
	v_mov_b32_e32 v83, v1
	v_lshl_add_u64 v[108:109], v[22:23], 0, s[0:1]
	v_lshlrev_b64 v[48:49], 14, v[0:1]
	v_lshlrev_b64 v[50:51], 14, v[50:51]
	v_lshlrev_b64 v[56:57], 14, v[56:57]
	v_lshlrev_b64 v[58:59], 14, v[58:59]
	v_lshlrev_b64 v[64:65], 14, v[64:65]
	v_lshlrev_b64 v[66:67], 14, v[66:67]
	v_lshlrev_b64 v[72:73], 14, v[72:73]
	v_lshlrev_b64 v[74:75], 14, v[74:75]
	v_lshlrev_b64 v[80:81], 14, v[80:81]
	v_lshlrev_b64 v[82:83], 14, v[82:83]
	v_or_b32_e32 v88, 40, v0
	v_mov_b32_e32 v89, v1
	v_or_b32_e32 v90, 44, v0
	v_mov_b32_e32 v91, v1
	v_lshl_add_u64 v[48:49], v[108:109], 0, v[48:49]
	v_lshl_add_u64 v[52:53], v[108:109], 0, v[50:51]
	v_lshl_add_u64 v[56:57], v[108:109], 0, v[56:57]
	v_lshl_add_u64 v[60:61], v[108:109], 0, v[58:59]
	v_lshl_add_u64 v[64:65], v[108:109], 0, v[64:65]
	v_lshl_add_u64 v[68:69], v[108:109], 0, v[66:67]
	v_lshl_add_u64 v[72:73], v[108:109], 0, v[72:73]
	v_lshl_add_u64 v[76:77], v[108:109], 0, v[74:75]
	v_lshl_add_u64 v[80:81], v[108:109], 0, v[80:81]
	v_lshl_add_u64 v[84:85], v[108:109], 0, v[82:83]
	v_lshlrev_b64 v[88:89], 14, v[88:89]
	v_lshlrev_b64 v[90:91], 14, v[90:91]
	global_load_dwordx4 v[48:51], v[48:49], off
	s_nop 0
	global_load_dwordx4 v[52:55], v[52:53], off
	s_nop 0
	global_load_dwordx4 v[56:59], v[56:57], off
	s_nop 0
	global_load_dwordx4 v[60:63], v[60:61], off
	s_nop 0
	global_load_dwordx4 v[64:67], v[64:65], off
	s_nop 0
	global_load_dwordx4 v[68:71], v[68:69], off
	s_nop 0
	global_load_dwordx4 v[72:75], v[72:73], off
	s_nop 0
	global_load_dwordx4 v[76:79], v[76:77], off
	s_nop 0
	global_load_dwordx4 v[80:83], v[80:81], off
	s_nop 0
	global_load_dwordx4 v[84:87], v[84:85], off
	v_lshl_add_u64 v[88:89], v[108:109], 0, v[88:89]
	v_lshl_add_u64 v[92:93], v[108:109], 0, v[90:91]
	global_load_dwordx4 v[88:91], v[88:89], off
	s_nop 0
	global_load_dwordx4 v[92:95], v[92:93], off
	v_or_b32_e32 v96, 48, v0
	v_mov_b32_e32 v97, v1
	v_lshlrev_b64 v[96:97], 14, v[96:97]
	v_lshl_add_u64 v[96:97], v[108:109], 0, v[96:97]
	v_or_b32_e32 v100, 52, v0
	v_mov_b32_e32 v101, v1
	global_load_dwordx4 v[96:99], v[96:97], off
	v_lshlrev_b64 v[100:101], 14, v[100:101]
	v_lshl_add_u64 v[100:101], v[108:109], 0, v[100:101]
	v_or_b32_e32 v104, 56, v0
	v_mov_b32_e32 v105, v1
	global_load_dwordx4 v[100:103], v[100:101], off
	v_lshlrev_b64 v[104:105], 14, v[104:105]
	v_lshl_add_u64 v[104:105], v[108:109], 0, v[104:105]
	v_or_b32_e32 v0, 60, v0
	global_load_dwordx4 v[104:107], v[104:105], off
	v_lshlrev_b64 v[110:111], 14, v[0:1]
	v_lshl_add_u64 v[108:109], v[108:109], 0, v[110:111]
	global_load_dwordx4 v[108:111], v[108:109], off
	v_add_u32_e32 v0, 0xf0a0, v5
	s_lshr_b32 s0, s4, 6
	s_and_b32 s4, s20, 0x3000
	s_and_b32 s5, s26, 0x1e0
	s_add_i32 s0, s5, s0
	s_lshl_b32 s4, s4, 1
	s_add_u32 s33, s9, s4
	v_add_u32_e32 v31, 0xc800, v9
	s_addc_u32 s62, s10, 0
	s_lshl_b64 s[4:5], s[0:1], 15
	s_waitcnt vmcnt(15)
	ds_write2_b32 v7, v48, v49 offset1:1
	ds_write2_b32 v11, v50, v51 offset1:1
	s_waitcnt vmcnt(14)
	ds_write2_b32 v13, v52, v53 offset1:1
	ds_write2_b32 v15, v54, v55 offset1:1
	s_waitcnt vmcnt(13)
	ds_write2_b32 v17, v56, v57 offset1:1
	ds_write2_b32 v19, v58, v59 offset1:1
	s_waitcnt vmcnt(12)
	ds_write2_b32 v32, v60, v61 offset1:1
	ds_write2_b32 v33, v62, v63 offset1:1
	s_waitcnt vmcnt(11)
	ds_write2_b32 v34, v64, v65 offset1:1
	ds_write2_b32 v36, v66, v67 offset1:1
	s_waitcnt vmcnt(10)
	ds_write2_b32 v37, v68, v69 offset1:1
	ds_write2_b32 v38, v70, v71 offset1:1
	s_waitcnt vmcnt(9)
	ds_write2_b32 v39, v72, v73 offset1:1
	ds_write2_b32 v40, v74, v75 offset1:1
	s_waitcnt vmcnt(8)
	ds_write2_b32 v41, v76, v77 offset1:1
	ds_write2_b32 v42, v78, v79 offset1:1
	s_waitcnt vmcnt(7)
	ds_write2_b32 v43, v80, v81 offset1:1
	ds_write2_b32 v44, v82, v83 offset1:1
	s_waitcnt vmcnt(6)
	ds_write2_b32 v45, v84, v85 offset1:1
	ds_write2_b32 v46, v86, v87 offset1:1
	s_add_u32 s4, s33, s4
	s_waitcnt vmcnt(5)
	ds_write2_b32 v0, v88, v89 offset1:1
	v_add_u32_e32 v0, 0xf0a8, v5
	ds_write2_b32 v0, v90, v91 offset1:1
	v_add_u32_e32 v0, 0xf4b0, v5
	s_waitcnt vmcnt(4)
	ds_write2_b32 v0, v92, v93 offset1:1
	v_add_u32_e32 v0, 0xf4b8, v5
	ds_write2_b32 v0, v94, v95 offset1:1
	v_add_u32_e32 v0, 0xf8c0, v5
	s_waitcnt vmcnt(3)
	ds_write2_b32 v0, v96, v97 offset1:1
	v_add_u32_e32 v0, 0xf8c8, v5
	ds_write2_b32 v0, v98, v99 offset1:1
	v_add_u32_e32 v0, 0xfcd0, v5
	v_add_u32_e32 v47, 0xcc00, v9
	s_waitcnt vmcnt(2)
	ds_write2_b32 v0, v100, v101 offset1:1
	v_add_u32_e32 v0, 0xfcd8, v5
	ds_write2_b32 v0, v102, v103 offset1:1
	v_add_u32_e32 v0, 0x38e0, v7
	s_waitcnt vmcnt(1)
	ds_write2_b32 v0, v104, v105 offset1:1
	v_add_u32_e32 v0, 0x38e8, v7
	ds_write2_b32 v0, v106, v107 offset1:1
	v_add_u32_e32 v0, 0x3cf0, v7
	s_waitcnt vmcnt(0)
	ds_write2_b32 v0, v108, v109 offset1:1
	v_add_u32_e32 v0, 0x3cf8, v7
	ds_write2_b32 v0, v110, v111 offset1:1
	s_waitcnt lgkmcnt(0)
	ds_read2_b32 v[48:49], v31 offset1:65
	s_waitcnt lgkmcnt(0)
	v_cvt_pk_bf16_f32 v48, v48, v49
	ds_read2_b32 v[50:51], v31 offset0:130 offset1:195
	s_addc_u32 s5, s62, s5
	v_lshlrev_b32_e32 v0, 1, v2
	s_waitcnt lgkmcnt(0)
	v_cvt_pk_bf16_f32 v49, v50, v51
	ds_read2_b32 v[50:51], v47 offset0:4 offset1:69
	v_lshl_add_u64 v[54:55], s[4:5], 0, v[0:1]
	v_lshlrev_b32_e32 v0, 1, v4
	s_waitcnt lgkmcnt(0)
	v_cvt_pk_bf16_f32 v50, v50, v51
	ds_read2_b32 v[52:53], v47 offset0:134 offset1:199
	s_waitcnt lgkmcnt(0)
	v_cvt_pk_bf16_f32 v51, v52, v53
	v_lshl_add_u64 v[56:57], v[54:55], 0, v[0:1]
	ds_read2_b32 v[52:53], v31 offset0:8 offset1:73
	global_store_dwordx4 v[56:57], v[48:51], off sc1
	v_lshlrev_b32_e32 v0, 1, v6
	v_lshl_add_u64 v[56:57], v[54:55], 0, v[0:1]
	s_waitcnt lgkmcnt(0)
	v_cvt_pk_bf16_f32 v48, v52, v53
	ds_read2_b32 v[50:51], v31 offset0:138 offset1:203
	s_waitcnt lgkmcnt(0)
	v_cvt_pk_bf16_f32 v49, v50, v51
	ds_read2_b32 v[50:51], v47 offset0:12 offset1:77
	s_waitcnt lgkmcnt(0)
	v_cvt_pk_bf16_f32 v50, v50, v51
	ds_read2_b32 v[52:53], v47 offset0:142 offset1:207
	s_waitcnt lgkmcnt(0)
	v_cvt_pk_bf16_f32 v51, v52, v53
	ds_read2_b32 v[52:53], v31 offset0:16 offset1:81
	global_store_dwordx4 v[56:57], v[48:51], off sc1
	v_lshlrev_b32_e32 v0, 1, v8
	v_lshl_add_u64 v[56:57], v[54:55], 0, v[0:1]
	s_waitcnt lgkmcnt(0)
	v_cvt_pk_bf16_f32 v48, v52, v53
	ds_read2_b32 v[50:51], v31 offset0:146 offset1:211
	s_waitcnt lgkmcnt(0)
	v_cvt_pk_bf16_f32 v49, v50, v51
	ds_read2_b32 v[50:51], v47 offset0:20 offset1:85
	s_waitcnt lgkmcnt(0)
	v_cvt_pk_bf16_f32 v50, v50, v51
	ds_read2_b32 v[52:53], v47 offset0:150 offset1:215
	s_waitcnt lgkmcnt(0)
	v_cvt_pk_bf16_f32 v51, v52, v53
	ds_read2_b32 v[52:53], v31 offset0:24 offset1:89
	global_store_dwordx4 v[56:57], v[48:51], off sc1
	v_lshlrev_b32_e32 v0, 1, v10
	v_lshl_add_u64 v[56:57], v[54:55], 0, v[0:1]
	s_waitcnt lgkmcnt(0)
	v_cvt_pk_bf16_f32 v48, v52, v53
	ds_read2_b32 v[50:51], v31 offset0:154 offset1:219
	s_waitcnt lgkmcnt(0)
	v_cvt_pk_bf16_f32 v49, v50, v51
	ds_read2_b32 v[50:51], v47 offset0:28 offset1:93
	s_waitcnt lgkmcnt(0)
	v_cvt_pk_bf16_f32 v50, v50, v51
	ds_read2_b32 v[52:53], v47 offset0:158 offset1:223
	s_waitcnt lgkmcnt(0)
	v_cvt_pk_bf16_f32 v51, v52, v53
	ds_read2_b32 v[52:53], v31 offset0:32 offset1:97
	global_store_dwordx4 v[56:57], v[48:51], off sc1
	v_lshlrev_b32_e32 v0, 1, v12
	v_lshl_add_u64 v[56:57], v[54:55], 0, v[0:1]
	s_waitcnt lgkmcnt(0)
	v_cvt_pk_bf16_f32 v48, v52, v53
	ds_read2_b32 v[50:51], v31 offset0:162 offset1:227
	s_waitcnt lgkmcnt(0)
	v_cvt_pk_bf16_f32 v49, v50, v51
	ds_read2_b32 v[50:51], v47 offset0:36 offset1:101
	s_waitcnt lgkmcnt(0)
	v_cvt_pk_bf16_f32 v50, v50, v51
	ds_read2_b32 v[52:53], v47 offset0:166 offset1:231
	s_waitcnt lgkmcnt(0)
	v_cvt_pk_bf16_f32 v51, v52, v53
	ds_read2_b32 v[52:53], v31 offset0:40 offset1:105
	global_store_dwordx4 v[56:57], v[48:51], off sc1
	v_lshlrev_b32_e32 v0, 1, v14
	v_lshl_add_u64 v[56:57], v[54:55], 0, v[0:1]
	s_waitcnt lgkmcnt(0)
	v_cvt_pk_bf16_f32 v48, v52, v53
	ds_read2_b32 v[50:51], v31 offset0:170 offset1:235
	s_waitcnt lgkmcnt(0)
	v_cvt_pk_bf16_f32 v49, v50, v51
	ds_read2_b32 v[50:51], v47 offset0:44 offset1:109
	s_waitcnt lgkmcnt(0)
	v_cvt_pk_bf16_f32 v50, v50, v51
	ds_read2_b32 v[52:53], v47 offset0:174 offset1:239
	s_waitcnt lgkmcnt(0)
	v_cvt_pk_bf16_f32 v51, v52, v53
	ds_read2_b32 v[52:53], v31 offset0:48 offset1:113
	global_store_dwordx4 v[56:57], v[48:51], off sc1
	v_lshlrev_b32_e32 v0, 1, v16
	v_lshl_add_u64 v[56:57], v[54:55], 0, v[0:1]
	s_waitcnt lgkmcnt(0)
	v_cvt_pk_bf16_f32 v48, v52, v53
	ds_read2_b32 v[50:51], v31 offset0:178 offset1:243
	s_waitcnt lgkmcnt(0)
	v_cvt_pk_bf16_f32 v49, v50, v51
	ds_read2_b32 v[50:51], v47 offset0:52 offset1:117
	s_waitcnt lgkmcnt(0)
	v_cvt_pk_bf16_f32 v50, v50, v51
	ds_read2_b32 v[52:53], v47 offset0:182 offset1:247
	s_waitcnt lgkmcnt(0)
	v_cvt_pk_bf16_f32 v51, v52, v53
	ds_read2_b32 v[52:53], v31 offset0:56 offset1:121
	global_store_dwordx4 v[56:57], v[48:51], off sc1
	v_lshlrev_b32_e32 v0, 1, v18
	s_waitcnt lgkmcnt(0)
	v_cvt_pk_bf16_f32 v48, v52, v53
	ds_read2_b32 v[50:51], v31 offset0:186 offset1:251
	s_waitcnt lgkmcnt(0)
	v_cvt_pk_bf16_f32 v49, v50, v51
	ds_read2_b32 v[50:51], v47 offset0:60 offset1:125
	s_waitcnt lgkmcnt(0)
	v_cvt_pk_bf16_f32 v50, v50, v51
	ds_read2_b32 v[52:53], v47 offset0:190 offset1:255
	s_waitcnt lgkmcnt(0)
	v_cvt_pk_bf16_f32 v51, v52, v53
	v_lshl_add_u64 v[52:53], v[54:55], 0, v[0:1]
	global_store_dwordx4 v[52:53], v[48:51], off sc1
	s_waitcnt lgkmcnt(0)

.LBB0_323:
	s_andn2_b64 vcc, exec, s[4:5]
	s_cbranch_vccnz .LBB0_325
	s_add_i32 s4, s35, 0xffffa500
	s_and_b32 s0, s4, 0xffffffc0
	s_and_b32 s5, s16, 0xfc0
	v_or_b32_e32 v0, s0, v3
	s_lshl_b32 s0, s5, 2
	v_or_b32_e32 v50, 4, v0
	v_mov_b32_e32 v51, v1
	v_or_b32_e32 v56, 8, v0
	v_mov_b32_e32 v57, v1
	v_or_b32_e32 v58, 12, v0
	v_mov_b32_e32 v59, v1
	v_or_b32_e32 v64, 16, v0
	v_mov_b32_e32 v65, v1
	v_or_b32_e32 v66, 20, v0
	v_mov_b32_e32 v67, v1
	v_or_b32_e32 v72, 24, v0
	v_mov_b32_e32 v73, v1
	v_or_b32_e32 v74, 28, v0
	v_mov_b32_e32 v75, v1
	v_or_b32_e32 v80, 32, v0
	v_mov_b32_e32 v81, v1
	v_or_b32_e32 v82, 36, v0
	v_mov_b32_e32 v83, v1
	v_lshl_add_u64 v[108:109], v[24:25], 0, s[0:1]
	v_lshlrev_b64 v[48:49], 14, v[0:1]
	v_lshlrev_b64 v[50:51], 14, v[50:51]
	v_lshlrev_b64 v[56:57], 14, v[56:57]
	v_lshlrev_b64 v[58:59], 14, v[58:59]
	v_lshlrev_b64 v[64:65], 14, v[64:65]
	v_lshlrev_b64 v[66:67], 14, v[66:67]
	v_lshlrev_b64 v[72:73], 14, v[72:73]
	v_lshlrev_b64 v[74:75], 14, v[74:75]
	v_lshlrev_b64 v[80:81], 14, v[80:81]
	v_lshlrev_b64 v[82:83], 14, v[82:83]
	v_or_b32_e32 v88, 40, v0
	v_mov_b32_e32 v89, v1
	v_or_b32_e32 v90, 44, v0
	v_mov_b32_e32 v91, v1
	v_lshl_add_u64 v[48:49], v[108:109], 0, v[48:49]
	v_lshl_add_u64 v[52:53], v[108:109], 0, v[50:51]
	v_lshl_add_u64 v[56:57], v[108:109], 0, v[56:57]
	v_lshl_add_u64 v[60:61], v[108:109], 0, v[58:59]
	v_lshl_add_u64 v[64:65], v[108:109], 0, v[64:65]
	v_lshl_add_u64 v[68:69], v[108:109], 0, v[66:67]
	v_lshl_add_u64 v[72:73], v[108:109], 0, v[72:73]
	v_lshl_add_u64 v[76:77], v[108:109], 0, v[74:75]
	v_lshl_add_u64 v[80:81], v[108:109], 0, v[80:81]
	v_lshl_add_u64 v[84:85], v[108:109], 0, v[82:83]
	v_lshlrev_b64 v[88:89], 14, v[88:89]
	v_lshlrev_b64 v[90:91], 14, v[90:91]
	global_load_dwordx4 v[48:51], v[48:49], off
	s_nop 0
	global_load_dwordx4 v[52:55], v[52:53], off
	s_nop 0
	global_load_dwordx4 v[56:59], v[56:57], off
	s_nop 0
	global_load_dwordx4 v[60:63], v[60:61], off
	s_nop 0
	global_load_dwordx4 v[64:67], v[64:65], off
	s_nop 0
	global_load_dwordx4 v[68:71], v[68:69], off
	s_nop 0
	global_load_dwordx4 v[72:75], v[72:73], off
	s_nop 0
	global_load_dwordx4 v[76:79], v[76:77], off
	s_nop 0
	global_load_dwordx4 v[80:83], v[80:81], off
	s_nop 0
	global_load_dwordx4 v[84:87], v[84:85], off
	v_lshl_add_u64 v[88:89], v[108:109], 0, v[88:89]
	v_lshl_add_u64 v[92:93], v[108:109], 0, v[90:91]
	global_load_dwordx4 v[88:91], v[88:89], off
	s_nop 0
	global_load_dwordx4 v[92:95], v[92:93], off
	v_or_b32_e32 v96, 48, v0
	v_mov_b32_e32 v97, v1
	v_lshlrev_b64 v[96:97], 14, v[96:97]
	v_lshl_add_u64 v[96:97], v[108:109], 0, v[96:97]
	v_or_b32_e32 v100, 52, v0
	v_mov_b32_e32 v101, v1
	global_load_dwordx4 v[96:99], v[96:97], off
	v_lshlrev_b64 v[100:101], 14, v[100:101]
	v_lshl_add_u64 v[100:101], v[108:109], 0, v[100:101]
	v_or_b32_e32 v104, 56, v0
	v_mov_b32_e32 v105, v1
	global_load_dwordx4 v[100:103], v[100:101], off
	v_lshlrev_b64 v[104:105], 14, v[104:105]
	v_lshl_add_u64 v[104:105], v[108:109], 0, v[104:105]
	v_or_b32_e32 v0, 60, v0
	global_load_dwordx4 v[104:107], v[104:105], off
	v_lshlrev_b64 v[110:111], 14, v[0:1]
	v_lshl_add_u64 v[108:109], v[108:109], 0, v[110:111]
	global_load_dwordx4 v[108:111], v[108:109], off
	v_add_u32_e32 v0, 0xf0a0, v5
	s_lshr_b32 s0, s4, 6
	s_and_b32 s4, s20, 0x3000
	s_and_b32 s5, s26, 0x1e0
	s_add_i32 s0, s5, s0
	s_lshl_b32 s4, s4, 1
	s_add_u32 s33, s11, s4
	v_add_u32_e32 v31, 0xc800, v9
	s_addc_u32 s62, s14, 0
	s_waitcnt vmcnt(15)
	ds_write2_b32 v7, v48, v49 offset1:1
	ds_write2_b32 v11, v50, v51 offset1:1
	s_waitcnt vmcnt(14)
	ds_write2_b32 v13, v52, v53 offset1:1
	ds_write2_b32 v15, v54, v55 offset1:1
	s_waitcnt vmcnt(13)
	ds_write2_b32 v17, v56, v57 offset1:1
	ds_write2_b32 v19, v58, v59 offset1:1
	s_waitcnt vmcnt(12)
	ds_write2_b32 v32, v60, v61 offset1:1
	ds_write2_b32 v33, v62, v63 offset1:1
	s_waitcnt vmcnt(11)
	ds_write2_b32 v34, v64, v65 offset1:1
	ds_write2_b32 v36, v66, v67 offset1:1
	s_waitcnt vmcnt(10)
	ds_write2_b32 v37, v68, v69 offset1:1
	ds_write2_b32 v38, v70, v71 offset1:1
	s_waitcnt vmcnt(9)
	ds_write2_b32 v39, v72, v73 offset1:1
	ds_write2_b32 v40, v74, v75 offset1:1
	s_waitcnt vmcnt(8)
	ds_write2_b32 v41, v76, v77 offset1:1
	ds_write2_b32 v42, v78, v79 offset1:1
	s_waitcnt vmcnt(7)
	ds_write2_b32 v43, v80, v81 offset1:1
	ds_write2_b32 v44, v82, v83 offset1:1
	s_waitcnt vmcnt(6)
	ds_write2_b32 v45, v84, v85 offset1:1
	ds_write2_b32 v46, v86, v87 offset1:1
	s_lshl_b64 s[4:5], s[0:1], 15
	s_waitcnt vmcnt(5)
	ds_write2_b32 v0, v88, v89 offset1:1
	v_add_u32_e32 v0, 0xf0a8, v5
	ds_write2_b32 v0, v90, v91 offset1:1
	v_add_u32_e32 v0, 0xf4b0, v5
	s_waitcnt vmcnt(4)
	ds_write2_b32 v0, v92, v93 offset1:1
	v_add_u32_e32 v0, 0xf4b8, v5
	ds_write2_b32 v0, v94, v95 offset1:1
	v_add_u32_e32 v0, 0xf8c0, v5
	s_waitcnt vmcnt(3)
	ds_write2_b32 v0, v96, v97 offset1:1
	v_add_u32_e32 v0, 0xf8c8, v5
	ds_write2_b32 v0, v98, v99 offset1:1
	v_add_u32_e32 v0, 0xfcd0, v5
	s_add_u32 s4, s33, s4
	s_waitcnt vmcnt(2)
	ds_write2_b32 v0, v100, v101 offset1:1
	v_add_u32_e32 v0, 0xfcd8, v5
	ds_write2_b32 v0, v102, v103 offset1:1
	v_add_u32_e32 v0, 0x38e0, v7
	s_waitcnt vmcnt(1)
	ds_write2_b32 v0, v104, v105 offset1:1
	v_add_u32_e32 v0, 0x38e8, v7
	ds_write2_b32 v0, v106, v107 offset1:1
	v_add_u32_e32 v0, 0x3cf0, v7
	s_waitcnt vmcnt(0)
	ds_write2_b32 v0, v108, v109 offset1:1
	v_add_u32_e32 v0, 0x3cf8, v7
	ds_write2_b32 v0, v110, v111 offset1:1
	s_waitcnt lgkmcnt(0)
	ds_read2_b32 v[48:49], v31 offset1:65
	s_waitcnt lgkmcnt(0)
	v_cvt_pk_bf16_f32 v48, v48, v49
	ds_read2_b32 v[50:51], v31 offset0:130 offset1:195
	v_add_u32_e32 v47, 0xcc00, v9
	s_addc_u32 s5, s62, s5
	v_lshlrev_b32_e32 v0, 1, v2
	s_waitcnt lgkmcnt(0)
	v_cvt_pk_bf16_f32 v49, v50, v51
	ds_read2_b32 v[50:51], v47 offset0:4 offset1:69
	v_lshl_add_u64 v[54:55], s[4:5], 0, v[0:1]
	v_lshlrev_b32_e32 v0, 1, v4
	s_waitcnt lgkmcnt(0)
	v_cvt_pk_bf16_f32 v50, v50, v51
	ds_read2_b32 v[52:53], v47 offset0:134 offset1:199
	s_waitcnt lgkmcnt(0)
	v_cvt_pk_bf16_f32 v51, v52, v53
	v_lshl_add_u64 v[56:57], v[54:55], 0, v[0:1]
	ds_read2_b32 v[52:53], v31 offset0:8 offset1:73
	global_store_dwordx4 v[56:57], v[48:51], off sc1
	v_lshlrev_b32_e32 v0, 1, v6
	v_lshl_add_u64 v[56:57], v[54:55], 0, v[0:1]
	s_waitcnt lgkmcnt(0)
	v_cvt_pk_bf16_f32 v48, v52, v53
	ds_read2_b32 v[50:51], v31 offset0:138 offset1:203
	s_waitcnt lgkmcnt(0)
	v_cvt_pk_bf16_f32 v49, v50, v51
	ds_read2_b32 v[50:51], v47 offset0:12 offset1:77
	s_waitcnt lgkmcnt(0)
	v_cvt_pk_bf16_f32 v50, v50, v51
	ds_read2_b32 v[52:53], v47 offset0:142 offset1:207
	s_waitcnt lgkmcnt(0)
	v_cvt_pk_bf16_f32 v51, v52, v53
	ds_read2_b32 v[52:53], v31 offset0:16 offset1:81
	global_store_dwordx4 v[56:57], v[48:51], off sc1
	v_lshlrev_b32_e32 v0, 1, v8
	v_lshl_add_u64 v[56:57], v[54:55], 0, v[0:1]
	s_waitcnt lgkmcnt(0)
	v_cvt_pk_bf16_f32 v48, v52, v53
	ds_read2_b32 v[50:51], v31 offset0:146 offset1:211
	s_waitcnt lgkmcnt(0)
	v_cvt_pk_bf16_f32 v49, v50, v51
	ds_read2_b32 v[50:51], v47 offset0:20 offset1:85
	s_waitcnt lgkmcnt(0)
	v_cvt_pk_bf16_f32 v50, v50, v51
	ds_read2_b32 v[52:53], v47 offset0:150 offset1:215
	s_waitcnt lgkmcnt(0)
	v_cvt_pk_bf16_f32 v51, v52, v53
	ds_read2_b32 v[52:53], v31 offset0:24 offset1:89
	global_store_dwordx4 v[56:57], v[48:51], off sc1
	v_lshlrev_b32_e32 v0, 1, v10
	v_lshl_add_u64 v[56:57], v[54:55], 0, v[0:1]
	s_waitcnt lgkmcnt(0)
	v_cvt_pk_bf16_f32 v48, v52, v53
	ds_read2_b32 v[50:51], v31 offset0:154 offset1:219
	s_waitcnt lgkmcnt(0)
	v_cvt_pk_bf16_f32 v49, v50, v51
	ds_read2_b32 v[50:51], v47 offset0:28 offset1:93
	s_waitcnt lgkmcnt(0)
	v_cvt_pk_bf16_f32 v50, v50, v51
	ds_read2_b32 v[52:53], v47 offset0:158 offset1:223
	s_waitcnt lgkmcnt(0)
	v_cvt_pk_bf16_f32 v51, v52, v53
	ds_read2_b32 v[52:53], v31 offset0:32 offset1:97
	global_store_dwordx4 v[56:57], v[48:51], off sc1
	v_lshlrev_b32_e32 v0, 1, v12
	v_lshl_add_u64 v[56:57], v[54:55], 0, v[0:1]
	s_waitcnt lgkmcnt(0)
	v_cvt_pk_bf16_f32 v48, v52, v53
	ds_read2_b32 v[50:51], v31 offset0:162 offset1:227
	s_waitcnt lgkmcnt(0)
	v_cvt_pk_bf16_f32 v49, v50, v51
	ds_read2_b32 v[50:51], v47 offset0:36 offset1:101
	s_waitcnt lgkmcnt(0)
	v_cvt_pk_bf16_f32 v50, v50, v51
	ds_read2_b32 v[52:53], v47 offset0:166 offset1:231
	s_waitcnt lgkmcnt(0)
	v_cvt_pk_bf16_f32 v51, v52, v53
	ds_read2_b32 v[52:53], v31 offset0:40 offset1:105
	global_store_dwordx4 v[56:57], v[48:51], off sc1
	v_lshlrev_b32_e32 v0, 1, v14
	v_lshl_add_u64 v[56:57], v[54:55], 0, v[0:1]
	s_waitcnt lgkmcnt(0)
	v_cvt_pk_bf16_f32 v48, v52, v53
	ds_read2_b32 v[50:51], v31 offset0:170 offset1:235
	s_waitcnt lgkmcnt(0)
	v_cvt_pk_bf16_f32 v49, v50, v51
	ds_read2_b32 v[50:51], v47 offset0:44 offset1:109
	s_waitcnt lgkmcnt(0)
	v_cvt_pk_bf16_f32 v50, v50, v51
	ds_read2_b32 v[52:53], v47 offset0:174 offset1:239
	s_waitcnt lgkmcnt(0)
	v_cvt_pk_bf16_f32 v51, v52, v53
	ds_read2_b32 v[52:53], v31 offset0:48 offset1:113
	global_store_dwordx4 v[56:57], v[48:51], off sc1
	v_lshlrev_b32_e32 v0, 1, v16
	v_lshl_add_u64 v[56:57], v[54:55], 0, v[0:1]
	s_waitcnt lgkmcnt(0)
	v_cvt_pk_bf16_f32 v48, v52, v53
	ds_read2_b32 v[50:51], v31 offset0:178 offset1:243
	s_waitcnt lgkmcnt(0)
	v_cvt_pk_bf16_f32 v49, v50, v51
	ds_read2_b32 v[50:51], v47 offset0:52 offset1:117
	s_waitcnt lgkmcnt(0)
	v_cvt_pk_bf16_f32 v50, v50, v51
	ds_read2_b32 v[52:53], v47 offset0:182 offset1:247
	s_waitcnt lgkmcnt(0)
	v_cvt_pk_bf16_f32 v51, v52, v53
	ds_read2_b32 v[52:53], v31 offset0:56 offset1:121
	global_store_dwordx4 v[56:57], v[48:51], off sc1
	v_lshlrev_b32_e32 v0, 1, v18
	s_waitcnt lgkmcnt(0)
	v_cvt_pk_bf16_f32 v48, v52, v53
	ds_read2_b32 v[50:51], v31 offset0:186 offset1:251
	s_waitcnt lgkmcnt(0)
	v_cvt_pk_bf16_f32 v49, v50, v51
	ds_read2_b32 v[50:51], v47 offset0:60 offset1:125
	s_waitcnt lgkmcnt(0)
	v_cvt_pk_bf16_f32 v50, v50, v51
	ds_read2_b32 v[52:53], v47 offset0:190 offset1:255
	s_waitcnt lgkmcnt(0)
	v_cvt_pk_bf16_f32 v51, v52, v53
	v_lshl_add_u64 v[52:53], v[54:55], 0, v[0:1]
	global_store_dwordx4 v[52:53], v[48:51], off sc1
	s_waitcnt lgkmcnt(0)

; #define LAS __attribute__((address_space(3)))
; #define LDS_WAIT() asm volatile("s_waitcnt lgkmcnt(0)" ::: "memory")
; __device__ __forceinline__ void transpose_item(const float* W, int N, bf16_t* WT, int nkt, int k0, int n0, int r0, int kbd, LAS float* scr, int lane) {
;     const size_t dst_off = ((size_t)(r0 >> 8) * nkt + kbd) * 16384 + (size_t)(r0 & 255) * 64;
;     const int l15 = lane & 15, lq = lane >> 4;
;     f32x4 v[16];
; #pragma unroll
;     for (int i = 0; i < 16; ++i) v[i] = *(const f32x4*)(W + (size_t)(k0 + 4 * i + lq) * N + n0 + 4 * l15);
; #pragma unroll
;     for (int i = 0; i < 16; ++i) { LAS float* d = scr + (4 * i + lq) * 65 + 4 * l15; d[0] = v[i][0]; d[1] = v[i][1]; d[2] = v[i][2]; d[3] = v[i][3]; }
;     LDS_WAIT();
; __device__ __forceinline__ void phase_convert_late(const Params& p, LAS float* scr, int cw, int NCW, int lane) {
;     ...
;         if (r < I2) { const int g = r >> 6, q = r & 63, nb = q & 7, kb = q >> 3; transpose_item(p.in[13] + (size_t)g * 512 * 512, 512, (bf16_t*)(ws + WS_W_POOL), 32, kb * 64, nb * 64, nb * 64, g * 8 + kb, scr, lane); continue; } r -= I2;
.LBB0_326:
	s_andn2_b64 vcc, exec, s[4:5]
	s_cbranch_vccnz .LBB0_328
	s_add_i32 s0, s35, 0xffffa600
	s_lshr_b32 s0, s0, 6
	s_bfe_u32 s33, s35, 0x30003
	s_lshl_b64 s[4:5], s[0:1], 20
	s_add_u32 s4, s46, s4
	s_addc_u32 s5, s47, s5
	s_and_b32 s62, s16, 0x1c0
	s_lshl_b32 s0, s0, 3
	s_and_b32 s63, s20, 0x3000
	s_lshl_b32 s62, s62, 2
	s_add_u32 s4, s4, s62
	s_addc_u32 s5, s5, 0
	v_mov_b32_e32 v31, v1
	v_lshl_add_u64 v[48:49], s[4:5], 0, v[30:31]
	v_lshl_or_b32 v0, s33, 17, v35
	v_lshl_add_u64 v[108:109], v[48:49], 0, v[0:1]
	v_add_co_u32_e32 v52, vcc, s43, v108
	v_add_u32_e32 v0, 0xf0a0, v5
	s_nop 0
	v_addc_co_u32_e32 v53, vcc, 0, v109, vcc
	v_add_co_u32_e32 v56, vcc, s61, v108
	global_load_dwordx4 v[48:51], v[108:109], off
	s_nop 0
	global_load_dwordx4 v[52:55], v[52:53], off
	v_addc_co_u32_e32 v57, vcc, 0, v109, vcc
	v_add_co_u32_e32 v60, vcc, s42, v108
	s_and_b32 s4, s26, 32
	s_nop 0
	v_addc_co_u32_e32 v61, vcc, 0, v109, vcc
	v_add_co_u32_e32 v64, vcc, s66, v108
	global_load_dwordx4 v[56:59], v[56:57], off
	s_nop 0
	global_load_dwordx4 v[60:63], v[60:61], off
	v_addc_co_u32_e32 v65, vcc, 0, v109, vcc
	v_add_co_u32_e32 v68, vcc, s67, v108
	s_or_b32 s4, s4, s33
	s_nop 0
	v_addc_co_u32_e32 v69, vcc, 0, v109, vcc
	v_add_co_u32_e32 v72, vcc, s68, v108
	global_load_dwordx4 v[64:67], v[64:65], off
	s_nop 0
	global_load_dwordx4 v[68:71], v[68:69], off
	v_addc_co_u32_e32 v73, vcc, 0, v109, vcc
	v_add_co_u32_e32 v76, vcc, s69, v108
	s_add_i32 s0, s4, s0
	s_nop 0
	v_addc_co_u32_e32 v77, vcc, 0, v109, vcc
	v_add_co_u32_e32 v80, vcc, s70, v108
	global_load_dwordx4 v[72:75], v[72:73], off
	s_nop 0
	global_load_dwordx4 v[76:79], v[76:77], off
	v_addc_co_u32_e32 v81, vcc, 0, v109, vcc
	v_add_co_u32_e32 v84, vcc, s71, v108
	s_lshl_b32 s4, s63, 1
	s_nop 0
	v_addc_co_u32_e32 v85, vcc, 0, v109, vcc
	v_add_co_u32_e32 v88, vcc, s72, v108
	global_load_dwordx4 v[80:83], v[80:81], off
	s_nop 0
	global_load_dwordx4 v[84:87], v[84:85], off
	v_addc_co_u32_e32 v89, vcc, 0, v109, vcc
	v_add_co_u32_e32 v92, vcc, s73, v108
	s_add_u32 s33, s15, s4
	s_nop 0
	v_addc_co_u32_e32 v93, vcc, 0, v109, vcc
	global_load_dwordx4 v[88:91], v[88:89], off
	s_nop 0
	global_load_dwordx4 v[92:95], v[92:93], off
	v_add_co_u32_e32 v96, vcc, s74, v108
	v_add_u32_e32 v31, 0xc800, v9
	s_nop 0
	v_addc_co_u32_e32 v97, vcc, 0, v109, vcc
	global_load_dwordx4 v[96:99], v[96:97], off
	v_add_co_u32_e32 v100, vcc, s75, v108
	s_addc_u32 s62, s36, 0
	s_nop 0
	v_addc_co_u32_e32 v101, vcc, 0, v109, vcc
	global_load_dwordx4 v[100:103], v[100:101], off
	v_add_co_u32_e32 v104, vcc, s76, v108
	s_lshl_b64 s[4:5], s[0:1], 15
	s_nop 0
	v_addc_co_u32_e32 v105, vcc, 0, v109, vcc
	global_load_dwordx4 v[104:107], v[104:105], off
	v_add_co_u32_e32 v108, vcc, s77, v108
	s_add_u32 s4, s33, s4
	s_nop 0
	v_addc_co_u32_e32 v109, vcc, 0, v109, vcc
	global_load_dwordx4 v[108:111], v[108:109], off
	v_add_u32_e32 v47, 0xcc00, v9
	s_addc_u32 s5, s62, s5
	s_waitcnt vmcnt(15)
	ds_write2_b32 v7, v48, v49 offset1:1
	ds_write2_b32 v11, v50, v51 offset1:1
	s_waitcnt vmcnt(14)
	ds_write2_b32 v13, v52, v53 offset1:1
	ds_write2_b32 v15, v54, v55 offset1:1
	s_waitcnt vmcnt(13)
	ds_write2_b32 v17, v56, v57 offset1:1
	ds_write2_b32 v19, v58, v59 offset1:1
	s_waitcnt vmcnt(12)
	ds_write2_b32 v32, v60, v61 offset1:1
	ds_write2_b32 v33, v62, v63 offset1:1
	s_waitcnt vmcnt(11)
	ds_write2_b32 v34, v64, v65 offset1:1
	ds_write2_b32 v36, v66, v67 offset1:1
	s_waitcnt vmcnt(10)
	ds_write2_b32 v37, v68, v69 offset1:1
	ds_write2_b32 v38, v70, v71 offset1:1
	s_waitcnt vmcnt(9)
	ds_write2_b32 v39, v72, v73 offset1:1
	ds_write2_b32 v40, v74, v75 offset1:1
	s_waitcnt vmcnt(8)
	ds_write2_b32 v41, v76, v77 offset1:1
	ds_write2_b32 v42, v78, v79 offset1:1
	s_waitcnt vmcnt(7)
	ds_write2_b32 v43, v80, v81 offset1:1
	ds_write2_b32 v44, v82, v83 offset1:1
	s_waitcnt vmcnt(6)
	ds_write2_b32 v45, v84, v85 offset1:1
	ds_write2_b32 v46, v86, v87 offset1:1
	s_waitcnt vmcnt(5)
	ds_write2_b32 v0, v88, v89 offset1:1
	v_add_u32_e32 v0, 0xf0a8, v5
	ds_write2_b32 v0, v90, v91 offset1:1
	v_add_u32_e32 v0, 0xf4b0, v5
	s_waitcnt vmcnt(4)
	ds_write2_b32 v0, v92, v93 offset1:1
	v_add_u32_e32 v0, 0xf4b8, v5
	ds_write2_b32 v0, v94, v95 offset1:1
	v_add_u32_e32 v0, 0xf8c0, v5
	s_waitcnt vmcnt(3)
	ds_write2_b32 v0, v96, v97 offset1:1
	v_add_u32_e32 v0, 0xf8c8, v5
	ds_write2_b32 v0, v98, v99 offset1:1
	v_add_u32_e32 v0, 0xfcd0, v5
	s_waitcnt vmcnt(2)
	ds_write2_b32 v0, v100, v101 offset1:1
	v_add_u32_e32 v0, 0xfcd8, v5
	ds_write2_b32 v0, v102, v103 offset1:1
	v_add_u32_e32 v0, 0x38e0, v7
	s_waitcnt vmcnt(1)
	ds_write2_b32 v0, v104, v105 offset1:1
	v_add_u32_e32 v0, 0x38e8, v7
	ds_write2_b32 v0, v106, v107 offset1:1
	v_add_u32_e32 v0, 0x3cf0, v7
	s_waitcnt vmcnt(0)
; #define LAS __attribute__((address_space(3)))
; __device__ __forceinline__ unsigned cvt_pk_bf16(float lo, float hi) { unsigned r; asm volatile("v_cvt_pk_bf16_f32 %0, %1, %2" : "=v"(r) : "v"(lo), "v"(hi)); return r; }
; #define LDS_WAIT() asm volatile("s_waitcnt lgkmcnt(0)" ::: "memory")
; __device__ __forceinline__ void transpose_item(const float* W, int N, bf16_t* WT, int nkt, int k0, int n0, int r0, int kbd, LAS float* scr, int lane) {
;     ...
;     const int c = lane & 7;
; #pragma unroll
;     for (int j = 0; j < 8; ++j) { const int n = (lane >> 3) + 8 * j; const LAS float* s = scr + (8 * c) * 65 + n;
;         u32x4 o; o.x = cvt_pk_bf16(s[0], s[65]); o.y = cvt_pk_bf16(s[2 * 65], s[3 * 65]); o.z = cvt_pk_bf16(s[4 * 65], s[5 * 65]); o.w = cvt_pk_bf16(s[6 * 65], s[7 * 65]);
;         *(u32x4*)(WT + dst_off + (size_t)n * 64 + 8 * c) = o; }
;     LDS_WAIT();
	ds_write2_b32 v0, v108, v109 offset1:1
	v_add_u32_e32 v0, 0x3cf8, v7
	ds_write2_b32 v0, v110, v111 offset1:1
	s_waitcnt lgkmcnt(0)
	ds_read2_b32 v[48:49], v31 offset1:65
	s_waitcnt lgkmcnt(0)
	v_cvt_pk_bf16_f32 v48, v48, v49
	ds_read2_b32 v[50:51], v31 offset0:130 offset1:195
	v_lshlrev_b32_e32 v0, 1, v2
	s_waitcnt lgkmcnt(0)
	v_cvt_pk_bf16_f32 v49, v50, v51
	ds_read2_b32 v[50:51], v47 offset0:4 offset1:69
	v_lshl_add_u64 v[54:55], s[4:5], 0, v[0:1]
	v_lshlrev_b32_e32 v0, 1, v4
	s_waitcnt lgkmcnt(0)
	v_cvt_pk_bf16_f32 v50, v50, v51
	ds_read2_b32 v[52:53], v47 offset0:134 offset1:199
	s_waitcnt lgkmcnt(0)
	v_cvt_pk_bf16_f32 v51, v52, v53
	v_lshl_add_u64 v[56:57], v[54:55], 0, v[0:1]
	ds_read2_b32 v[52:53], v31 offset0:8 offset1:73
	global_store_dwordx4 v[56:57], v[48:51], off sc1
	v_lshlrev_b32_e32 v0, 1, v6
	v_lshl_add_u64 v[56:57], v[54:55], 0, v[0:1]
	s_waitcnt lgkmcnt(0)
	v_cvt_pk_bf16_f32 v48, v52, v53
	ds_read2_b32 v[50:51], v31 offset0:138 offset1:203
	s_waitcnt lgkmcnt(0)
	v_cvt_pk_bf16_f32 v49, v50, v51
	ds_read2_b32 v[50:51], v47 offset0:12 offset1:77
	s_waitcnt lgkmcnt(0)
	v_cvt_pk_bf16_f32 v50, v50, v51
	ds_read2_b32 v[52:53], v47 offset0:142 offset1:207
	s_waitcnt lgkmcnt(0)
	v_cvt_pk_bf16_f32 v51, v52, v53
	ds_read2_b32 v[52:53], v31 offset0:16 offset1:81
	global_store_dwordx4 v[56:57], v[48:51], off sc1
	v_lshlrev_b32_e32 v0, 1, v8
	v_lshl_add_u64 v[56:57], v[54:55], 0, v[0:1]
	s_waitcnt lgkmcnt(0)
	v_cvt_pk_bf16_f32 v48, v52, v53
	ds_read2_b32 v[50:51], v31 offset0:146 offset1:211
	s_waitcnt lgkmcnt(0)
	v_cvt_pk_bf16_f32 v49, v50, v51
	ds_read2_b32 v[50:51], v47 offset0:20 offset1:85
	s_waitcnt lgkmcnt(0)
	v_cvt_pk_bf16_f32 v50, v50, v51
	ds_read2_b32 v[52:53], v47 offset0:150 offset1:215
	s_waitcnt lgkmcnt(0)
	v_cvt_pk_bf16_f32 v51, v52, v53
	ds_read2_b32 v[52:53], v31 offset0:24 offset1:89
	global_store_dwordx4 v[56:57], v[48:51], off sc1
	v_lshlrev_b32_e32 v0, 1, v10
	v_lshl_add_u64 v[56:57], v[54:55], 0, v[0:1]
	s_waitcnt lgkmcnt(0)
	v_cvt_pk_bf16_f32 v48, v52, v53
	ds_read2_b32 v[50:51], v31 offset0:154 offset1:219
	s_waitcnt lgkmcnt(0)
	v_cvt_pk_bf16_f32 v49, v50, v51
	ds_read2_b32 v[50:51], v47 offset0:28 offset1:93
	s_waitcnt lgkmcnt(0)
	v_cvt_pk_bf16_f32 v50, v50, v51
	ds_read2_b32 v[52:53], v47 offset0:158 offset1:223
	s_waitcnt lgkmcnt(0)
	v_cvt_pk_bf16_f32 v51, v52, v53
	ds_read2_b32 v[52:53], v31 offset0:32 offset1:97
	global_store_dwordx4 v[56:57], v[48:51], off sc1
	v_lshlrev_b32_e32 v0, 1, v12
	v_lshl_add_u64 v[56:57], v[54:55], 0, v[0:1]
	s_waitcnt lgkmcnt(0)
	v_cvt_pk_bf16_f32 v48, v52, v53
	ds_read2_b32 v[50:51], v31 offset0:162 offset1:227
	s_waitcnt lgkmcnt(0)
	v_cvt_pk_bf16_f32 v49, v50, v51
	ds_read2_b32 v[50:51], v47 offset0:36 offset1:101
	s_waitcnt lgkmcnt(0)
	v_cvt_pk_bf16_f32 v50, v50, v51
	ds_read2_b32 v[52:53], v47 offset0:166 offset1:231
	s_waitcnt lgkmcnt(0)
	v_cvt_pk_bf16_f32 v51, v52, v53
	ds_read2_b32 v[52:53], v31 offset0:40 offset1:105
	global_store_dwordx4 v[56:57], v[48:51], off sc1
	v_lshlrev_b32_e32 v0, 1, v14
	v_lshl_add_u64 v[56:57], v[54:55], 0, v[0:1]
	s_waitcnt lgkmcnt(0)
	v_cvt_pk_bf16_f32 v48, v52, v53
	ds_read2_b32 v[50:51], v31 offset0:170 offset1:235
	s_waitcnt lgkmcnt(0)
	v_cvt_pk_bf16_f32 v49, v50, v51
	ds_read2_b32 v[50:51], v47 offset0:44 offset1:109
	s_waitcnt lgkmcnt(0)
	v_cvt_pk_bf16_f32 v50, v50, v51
	ds_read2_b32 v[52:53], v47 offset0:174 offset1:239
	s_waitcnt lgkmcnt(0)
	v_cvt_pk_bf16_f32 v51, v52, v53
	ds_read2_b32 v[52:53], v31 offset0:48 offset1:113
	global_store_dwordx4 v[56:57], v[48:51], off sc1
	v_lshlrev_b32_e32 v0, 1, v16
	v_lshl_add_u64 v[56:57], v[54:55], 0, v[0:1]
	s_waitcnt lgkmcnt(0)
	v_cvt_pk_bf16_f32 v48, v52, v53
	ds_read2_b32 v[50:51], v31 offset0:178 offset1:243
	s_waitcnt lgkmcnt(0)
	v_cvt_pk_bf16_f32 v49, v50, v51
	ds_read2_b32 v[50:51], v47 offset0:52 offset1:117
	s_waitcnt lgkmcnt(0)
	v_cvt_pk_bf16_f32 v50, v50, v51
	ds_read2_b32 v[52:53], v47 offset0:182 offset1:247
	s_waitcnt lgkmcnt(0)
	v_cvt_pk_bf16_f32 v51, v52, v53
	ds_read2_b32 v[52:53], v31 offset0:56 offset1:121
	global_store_dwordx4 v[56:57], v[48:51], off sc1
	v_lshlrev_b32_e32 v0, 1, v18
	s_waitcnt lgkmcnt(0)
	v_cvt_pk_bf16_f32 v48, v52, v53
	ds_read2_b32 v[50:51], v31 offset0:186 offset1:251
	s_waitcnt lgkmcnt(0)
	v_cvt_pk_bf16_f32 v49, v50, v51
	ds_read2_b32 v[50:51], v47 offset0:60 offset1:125
	s_waitcnt lgkmcnt(0)
	v_cvt_pk_bf16_f32 v50, v50, v51
	ds_read2_b32 v[52:53], v47 offset0:190 offset1:255
	s_waitcnt lgkmcnt(0)
	v_cvt_pk_bf16_f32 v51, v52, v53
	v_lshl_add_u64 v[52:53], v[54:55], 0, v[0:1]
	global_store_dwordx4 v[52:53], v[48:51], off sc1
	s_waitcnt lgkmcnt(0)

; #define LAS __attribute__((address_space(3)))
; #define LDS_WAIT() asm volatile("s_waitcnt lgkmcnt(0)" ::: "memory")
; __device__ __forceinline__ void transpose_item(const float* W, int N, bf16_t* WT, int nkt, int k0, int n0, int r0, int kbd, LAS float* scr, int lane) {
;     const size_t dst_off = ((size_t)(r0 >> 8) * nkt + kbd) * 16384 + (size_t)(r0 & 255) * 64;
;     const int l15 = lane & 15, lq = lane >> 4;
;     f32x4 v[16];
; #pragma unroll
;     for (int i = 0; i < 16; ++i) v[i] = *(const f32x4*)(W + (size_t)(k0 + 4 * i + lq) * N + n0 + 4 * l15);
; #pragma unroll
;     for (int i = 0; i < 16; ++i) { LAS float* d = scr + (4 * i + lq) * 65 + 4 * l15; d[0] = v[i][0]; d[1] = v[i][1]; d[2] = v[i][2]; d[3] = v[i][3]; }
;     LDS_WAIT();
; __device__ __forceinline__ void phase_convert_late(const Params& p, LAS float* scr, int cw, int NCW, int lane) {
;     ...
;         if (r < I1) { const int nb = r % 32, kb = r / 32; transpose_item(p.in[11], 2048, (bf16_t*)(ws + WS_W_GLU), 32, kb * 64, nb * 64, nb * 64, kb, scr, lane); continue; } r -= I1;
.LBB0_329:
	s_andn2_b64 vcc, exec, s[4:5]
	s_cbranch_vccnz .LBB0_331
	s_add_i32 s0, s35, 0xffffaa00
	s_lshr_b32 s4, s0, 5
	s_and_b32 s0, s16, 0x7c0
	v_lshl_or_b32 v0, s4, 6, v3
	s_lshl_b32 s0, s0, 2
	v_or_b32_e32 v50, 4, v0
	v_mov_b32_e32 v51, v1
	v_or_b32_e32 v56, 8, v0
	v_mov_b32_e32 v57, v1
	v_or_b32_e32 v58, 12, v0
	v_mov_b32_e32 v59, v1
	v_or_b32_e32 v64, 16, v0
	v_mov_b32_e32 v65, v1
	v_or_b32_e32 v66, 20, v0
	v_mov_b32_e32 v67, v1
	v_or_b32_e32 v72, 24, v0
	v_mov_b32_e32 v73, v1
	v_or_b32_e32 v74, 28, v0
	v_mov_b32_e32 v75, v1
	v_or_b32_e32 v80, 32, v0
	v_mov_b32_e32 v81, v1
	v_or_b32_e32 v82, 36, v0
	v_mov_b32_e32 v83, v1
	v_lshl_add_u64 v[108:109], v[26:27], 0, s[0:1]
	v_lshlrev_b64 v[48:49], 13, v[0:1]
	v_lshlrev_b64 v[50:51], 13, v[50:51]
	v_lshlrev_b64 v[56:57], 13, v[56:57]
	v_lshlrev_b64 v[58:59], 13, v[58:59]
	v_lshlrev_b64 v[64:65], 13, v[64:65]
	v_lshlrev_b64 v[66:67], 13, v[66:67]
	v_lshlrev_b64 v[72:73], 13, v[72:73]
	v_lshlrev_b64 v[74:75], 13, v[74:75]
	v_lshlrev_b64 v[80:81], 13, v[80:81]
	v_lshlrev_b64 v[82:83], 13, v[82:83]
	v_or_b32_e32 v88, 40, v0
	v_mov_b32_e32 v89, v1
	v_or_b32_e32 v90, 44, v0
	v_mov_b32_e32 v91, v1
	v_lshl_add_u64 v[48:49], v[108:109], 0, v[48:49]
	v_lshl_add_u64 v[52:53], v[108:109], 0, v[50:51]
	v_lshl_add_u64 v[56:57], v[108:109], 0, v[56:57]
	v_lshl_add_u64 v[60:61], v[108:109], 0, v[58:59]
	v_lshl_add_u64 v[64:65], v[108:109], 0, v[64:65]
	v_lshl_add_u64 v[68:69], v[108:109], 0, v[66:67]
	v_lshl_add_u64 v[72:73], v[108:109], 0, v[72:73]
	v_lshl_add_u64 v[76:77], v[108:109], 0, v[74:75]
	v_lshl_add_u64 v[80:81], v[108:109], 0, v[80:81]
	v_lshl_add_u64 v[84:85], v[108:109], 0, v[82:83]
	v_lshlrev_b64 v[88:89], 13, v[88:89]
	v_lshlrev_b64 v[90:91], 13, v[90:91]
	global_load_dwordx4 v[48:51], v[48:49], off
	s_nop 0
	global_load_dwordx4 v[52:55], v[52:53], off
	s_nop 0
	global_load_dwordx4 v[56:59], v[56:57], off
	s_nop 0
	global_load_dwordx4 v[60:63], v[60:61], off
	s_nop 0
	global_load_dwordx4 v[64:67], v[64:65], off
	s_nop 0
	global_load_dwordx4 v[68:71], v[68:69], off
	s_nop 0
	global_load_dwordx4 v[72:75], v[72:73], off
	s_nop 0
	global_load_dwordx4 v[76:79], v[76:77], off
	s_nop 0
	global_load_dwordx4 v[80:83], v[80:81], off
	s_nop 0
	global_load_dwordx4 v[84:87], v[84:85], off
	v_lshl_add_u64 v[88:89], v[108:109], 0, v[88:89]
	v_lshl_add_u64 v[92:93], v[108:109], 0, v[90:91]
	global_load_dwordx4 v[88:91], v[88:89], off
	s_nop 0
	global_load_dwordx4 v[92:95], v[92:93], off
	v_or_b32_e32 v96, 48, v0
	v_mov_b32_e32 v97, v1
	v_lshlrev_b64 v[96:97], 13, v[96:97]
	v_lshl_add_u64 v[96:97], v[108:109], 0, v[96:97]
	v_or_b32_e32 v100, 52, v0
	v_mov_b32_e32 v101, v1
	global_load_dwordx4 v[96:99], v[96:97], off
	v_lshlrev_b64 v[100:101], 13, v[100:101]
	v_lshl_add_u64 v[100:101], v[108:109], 0, v[100:101]
	v_or_b32_e32 v104, 56, v0
	v_mov_b32_e32 v105, v1
	global_load_dwordx4 v[100:103], v[100:101], off
	v_lshlrev_b64 v[104:105], 13, v[104:105]
	v_lshl_add_u64 v[104:105], v[108:109], 0, v[104:105]
	v_or_b32_e32 v0, 60, v0
	global_load_dwordx4 v[104:107], v[104:105], off
	v_lshlrev_b64 v[110:111], 13, v[0:1]
	v_lshl_add_u64 v[108:109], v[108:109], 0, v[110:111]
	global_load_dwordx4 v[108:111], v[108:109], off
	v_add_u32_e32 v0, 0xf0a0, v5
	s_and_b32 s5, s20, 0x3000
	s_and_b32 s0, s26, 0xe0
	s_add_i32 s0, s0, s4
	s_lshl_b32 s4, s5, 1
	s_add_u32 s33, s37, s4
	v_add_u32_e32 v31, 0xc800, v9
	s_addc_u32 s62, s38, 0
	s_lshl_b64 s[4:5], s[0:1], 15
	s_waitcnt vmcnt(15)
	ds_write2_b32 v7, v48, v49 offset1:1
	ds_write2_b32 v11, v50, v51 offset1:1
	s_waitcnt vmcnt(14)
	ds_write2_b32 v13, v52, v53 offset1:1
	ds_write2_b32 v15, v54, v55 offset1:1
	s_waitcnt vmcnt(13)
	ds_write2_b32 v17, v56, v57 offset1:1
	ds_write2_b32 v19, v58, v59 offset1:1
	s_waitcnt vmcnt(12)
	ds_write2_b32 v32, v60, v61 offset1:1
	ds_write2_b32 v33, v62, v63 offset1:1
	s_waitcnt vmcnt(11)
	ds_write2_b32 v34, v64, v65 offset1:1
	ds_write2_b32 v36, v66, v67 offset1:1
	s_waitcnt vmcnt(10)
	ds_write2_b32 v37, v68, v69 offset1:1
	ds_write2_b32 v38, v70, v71 offset1:1
	s_waitcnt vmcnt(9)
	ds_write2_b32 v39, v72, v73 offset1:1
	ds_write2_b32 v40, v74, v75 offset1:1
	s_waitcnt vmcnt(8)
	ds_write2_b32 v41, v76, v77 offset1:1
	ds_write2_b32 v42, v78, v79 offset1:1
	s_waitcnt vmcnt(7)
	ds_write2_b32 v43, v80, v81 offset1:1
	ds_write2_b32 v44, v82, v83 offset1:1
	s_waitcnt vmcnt(6)
	ds_write2_b32 v45, v84, v85 offset1:1
	ds_write2_b32 v46, v86, v87 offset1:1
	s_add_u32 s4, s33, s4
	s_waitcnt vmcnt(5)
	ds_write2_b32 v0, v88, v89 offset1:1
	v_add_u32_e32 v0, 0xf0a8, v5
	ds_write2_b32 v0, v90, v91 offset1:1
	v_add_u32_e32 v0, 0xf4b0, v5
	s_waitcnt vmcnt(4)
	ds_write2_b32 v0, v92, v93 offset1:1
	v_add_u32_e32 v0, 0xf4b8, v5
	ds_write2_b32 v0, v94, v95 offset1:1
	v_add_u32_e32 v0, 0xf8c0, v5
	s_waitcnt vmcnt(3)
	ds_write2_b32 v0, v96, v97 offset1:1
	v_add_u32_e32 v0, 0xf8c8, v5
	ds_write2_b32 v0, v98, v99 offset1:1
	v_add_u32_e32 v0, 0xfcd0, v5
	v_add_u32_e32 v47, 0xcc00, v9
	s_waitcnt vmcnt(2)
; #define LAS __attribute__((address_space(3)))
; __device__ __forceinline__ unsigned cvt_pk_bf16(float lo, float hi) { unsigned r; asm volatile("v_cvt_pk_bf16_f32 %0, %1, %2" : "=v"(r) : "v"(lo), "v"(hi)); return r; }
; #define LDS_WAIT() asm volatile("s_waitcnt lgkmcnt(0)" ::: "memory")
; __device__ __forceinline__ void transpose_item(const float* W, int N, bf16_t* WT, int nkt, int k0, int n0, int r0, int kbd, LAS float* scr, int lane) {
;     ...
;     const int c = lane & 7;
; #pragma unroll
;     for (int j = 0; j < 8; ++j) { const int n = (lane >> 3) + 8 * j; const LAS float* s = scr + (8 * c) * 65 + n;
;         u32x4 o; o.x = cvt_pk_bf16(s[0], s[65]); o.y = cvt_pk_bf16(s[2 * 65], s[3 * 65]); o.z = cvt_pk_bf16(s[4 * 65], s[5 * 65]); o.w = cvt_pk_bf16(s[6 * 65], s[7 * 65]);
;         *(u32x4*)(WT + dst_off + (size_t)n * 64 + 8 * c) = o; }
;     LDS_WAIT();
	ds_write2_b32 v0, v100, v101 offset1:1
	v_add_u32_e32 v0, 0xfcd8, v5
	ds_write2_b32 v0, v102, v103 offset1:1
	v_add_u32_e32 v0, 0x38e0, v7
	s_waitcnt vmcnt(1)
	ds_write2_b32 v0, v104, v105 offset1:1
	v_add_u32_e32 v0, 0x38e8, v7
	ds_write2_b32 v0, v106, v107 offset1:1
	v_add_u32_e32 v0, 0x3cf0, v7
	s_waitcnt vmcnt(0)
	ds_write2_b32 v0, v108, v109 offset1:1
	v_add_u32_e32 v0, 0x3cf8, v7
	ds_write2_b32 v0, v110, v111 offset1:1
	s_waitcnt lgkmcnt(0)
	ds_read2_b32 v[48:49], v31 offset1:65
	s_waitcnt lgkmcnt(0)
	v_cvt_pk_bf16_f32 v48, v48, v49
	ds_read2_b32 v[50:51], v31 offset0:130 offset1:195
	s_addc_u32 s5, s62, s5
	v_lshlrev_b32_e32 v0, 1, v2
	s_waitcnt lgkmcnt(0)
	v_cvt_pk_bf16_f32 v49, v50, v51
	ds_read2_b32 v[50:51], v47 offset0:4 offset1:69
	v_lshl_add_u64 v[54:55], s[4:5], 0, v[0:1]
	v_lshlrev_b32_e32 v0, 1, v4
	s_waitcnt lgkmcnt(0)
	v_cvt_pk_bf16_f32 v50, v50, v51
	ds_read2_b32 v[52:53], v47 offset0:134 offset1:199
	s_waitcnt lgkmcnt(0)
	v_cvt_pk_bf16_f32 v51, v52, v53
	v_lshl_add_u64 v[56:57], v[54:55], 0, v[0:1]
	ds_read2_b32 v[52:53], v31 offset0:8 offset1:73
	global_store_dwordx4 v[56:57], v[48:51], off sc1
	v_lshlrev_b32_e32 v0, 1, v6
	v_lshl_add_u64 v[56:57], v[54:55], 0, v[0:1]
	s_waitcnt lgkmcnt(0)
	v_cvt_pk_bf16_f32 v48, v52, v53
	ds_read2_b32 v[50:51], v31 offset0:138 offset1:203
	s_waitcnt lgkmcnt(0)
	v_cvt_pk_bf16_f32 v49, v50, v51
	ds_read2_b32 v[50:51], v47 offset0:12 offset1:77
	s_waitcnt lgkmcnt(0)
	v_cvt_pk_bf16_f32 v50, v50, v51
	ds_read2_b32 v[52:53], v47 offset0:142 offset1:207
	s_waitcnt lgkmcnt(0)
	v_cvt_pk_bf16_f32 v51, v52, v53
	ds_read2_b32 v[52:53], v31 offset0:16 offset1:81
	global_store_dwordx4 v[56:57], v[48:51], off sc1
	v_lshlrev_b32_e32 v0, 1, v8
	v_lshl_add_u64 v[56:57], v[54:55], 0, v[0:1]
	s_waitcnt lgkmcnt(0)
	v_cvt_pk_bf16_f32 v48, v52, v53
	ds_read2_b32 v[50:51], v31 offset0:146 offset1:211
	s_waitcnt lgkmcnt(0)
	v_cvt_pk_bf16_f32 v49, v50, v51
	ds_read2_b32 v[50:51], v47 offset0:20 offset1:85
	s_waitcnt lgkmcnt(0)
	v_cvt_pk_bf16_f32 v50, v50, v51
	ds_read2_b32 v[52:53], v47 offset0:150 offset1:215
	s_waitcnt lgkmcnt(0)
	v_cvt_pk_bf16_f32 v51, v52, v53
	ds_read2_b32 v[52:53], v31 offset0:24 offset1:89
	global_store_dwordx4 v[56:57], v[48:51], off sc1
	v_lshlrev_b32_e32 v0, 1, v10
	v_lshl_add_u64 v[56:57], v[54:55], 0, v[0:1]
	s_waitcnt lgkmcnt(0)
	v_cvt_pk_bf16_f32 v48, v52, v53
	ds_read2_b32 v[50:51], v31 offset0:154 offset1:219
	s_waitcnt lgkmcnt(0)
	v_cvt_pk_bf16_f32 v49, v50, v51
	ds_read2_b32 v[50:51], v47 offset0:28 offset1:93
	s_waitcnt lgkmcnt(0)
	v_cvt_pk_bf16_f32 v50, v50, v51
	ds_read2_b32 v[52:53], v47 offset0:158 offset1:223
	s_waitcnt lgkmcnt(0)
	v_cvt_pk_bf16_f32 v51, v52, v53
	ds_read2_b32 v[52:53], v31 offset0:32 offset1:97
	global_store_dwordx4 v[56:57], v[48:51], off sc1
	v_lshlrev_b32_e32 v0, 1, v12
	v_lshl_add_u64 v[56:57], v[54:55], 0, v[0:1]
	s_waitcnt lgkmcnt(0)
	v_cvt_pk_bf16_f32 v48, v52, v53
	ds_read2_b32 v[50:51], v31 offset0:162 offset1:227
	s_waitcnt lgkmcnt(0)
	v_cvt_pk_bf16_f32 v49, v50, v51
	ds_read2_b32 v[50:51], v47 offset0:36 offset1:101
	s_waitcnt lgkmcnt(0)
	v_cvt_pk_bf16_f32 v50, v50, v51
	ds_read2_b32 v[52:53], v47 offset0:166 offset1:231
	s_waitcnt lgkmcnt(0)
	v_cvt_pk_bf16_f32 v51, v52, v53
	ds_read2_b32 v[52:53], v31 offset0:40 offset1:105
	global_store_dwordx4 v[56:57], v[48:51], off sc1
	v_lshlrev_b32_e32 v0, 1, v14
	v_lshl_add_u64 v[56:57], v[54:55], 0, v[0:1]
	s_waitcnt lgkmcnt(0)
	v_cvt_pk_bf16_f32 v48, v52, v53
	ds_read2_b32 v[50:51], v31 offset0:170 offset1:235
	s_waitcnt lgkmcnt(0)
	v_cvt_pk_bf16_f32 v49, v50, v51
	ds_read2_b32 v[50:51], v47 offset0:44 offset1:109
	s_waitcnt lgkmcnt(0)
	v_cvt_pk_bf16_f32 v50, v50, v51
	ds_read2_b32 v[52:53], v47 offset0:174 offset1:239
	s_waitcnt lgkmcnt(0)
	v_cvt_pk_bf16_f32 v51, v52, v53
	ds_read2_b32 v[52:53], v31 offset0:48 offset1:113
	global_store_dwordx4 v[56:57], v[48:51], off sc1
	v_lshlrev_b32_e32 v0, 1, v16
	v_lshl_add_u64 v[56:57], v[54:55], 0, v[0:1]
	s_waitcnt lgkmcnt(0)
	v_cvt_pk_bf16_f32 v48, v52, v53
	ds_read2_b32 v[50:51], v31 offset0:178 offset1:243
	s_waitcnt lgkmcnt(0)
	v_cvt_pk_bf16_f32 v49, v50, v51
	ds_read2_b32 v[50:51], v47 offset0:52 offset1:117
	s_waitcnt lgkmcnt(0)
	v_cvt_pk_bf16_f32 v50, v50, v51
	ds_read2_b32 v[52:53], v47 offset0:182 offset1:247
	s_waitcnt lgkmcnt(0)
	v_cvt_pk_bf16_f32 v51, v52, v53
	ds_read2_b32 v[52:53], v31 offset0:56 offset1:121
	global_store_dwordx4 v[56:57], v[48:51], off sc1
	v_lshlrev_b32_e32 v0, 1, v18
	s_waitcnt lgkmcnt(0)
	v_cvt_pk_bf16_f32 v48, v52, v53
	ds_read2_b32 v[50:51], v31 offset0:186 offset1:251
	s_waitcnt lgkmcnt(0)
	v_cvt_pk_bf16_f32 v49, v50, v51
	ds_read2_b32 v[50:51], v47 offset0:60 offset1:125
	s_waitcnt lgkmcnt(0)
	v_cvt_pk_bf16_f32 v50, v50, v51
	ds_read2_b32 v[52:53], v47 offset0:190 offset1:255
	s_waitcnt lgkmcnt(0)
	v_cvt_pk_bf16_f32 v51, v52, v53
	v_lshl_add_u64 v[52:53], v[54:55], 0, v[0:1]
	global_store_dwordx4 v[52:53], v[48:51], off sc1
	s_waitcnt lgkmcnt(0)

; #define LAS __attribute__((address_space(3)))
; #define LDS_WAIT() asm volatile("s_waitcnt lgkmcnt(0)" ::: "memory")
; __device__ __forceinline__ void transpose_item(const float* W, int N, bf16_t* WT, int nkt, int k0, int n0, int r0, int kbd, LAS float* scr, int lane) {
;     const size_t dst_off = ((size_t)(r0 >> 8) * nkt + kbd) * 16384 + (size_t)(r0 & 255) * 64;
;     const int l15 = lane & 15, lq = lane >> 4;
;     f32x4 v[16];
; #pragma unroll
;     for (int i = 0; i < 16; ++i) v[i] = *(const f32x4*)(W + (size_t)(k0 + 4 * i + lq) * N + n0 + 4 * l15);
; #pragma unroll
;     for (int i = 0; i < 16; ++i) { LAS float* d = scr + (4 * i + lq) * 65 + 4 * l15; d[0] = v[i][0]; d[1] = v[i][1]; d[2] = v[i][2]; d[3] = v[i][3]; }
;     LDS_WAIT();
; __device__ __forceinline__ void phase_convert_late(const Params& p, LAS float* scr, int cw, int NCW, int lane) {
;     ...
;         if (r < I6) { const int nb = r % 344, kb = r / 344; const int n0 = nb * 64; const int nn = n0 < FF ? n0 : n0 - FF; const int r0 = (nn >> 7) * 256 + (n0 < FF ? 0 : 128) + (nn & 127);
;             transpose_item(p.in[21], FF2, (bf16_t*)(ws + WS_W_UP), 64, kb * 64, n0, r0, kb, scr, lane); continue; } r -= I6;
.LBB0_332:
	s_andn2_b64 vcc, exec, s[4:5]
	s_cbranch_vccnz .LBB0_313
	s_mul_hi_i32 s0, s35, 0x2fa0be83
	s_lshr_b32 s4, s0, 31
	s_ashr_i32 s0, s0, 6
	s_add_i32 s4, s0, s4
	s_mul_i32 s5, s4, 0xffffaa00
	s_mul_i32 s0, s4, 0xfffffea8
	s_add_i32 s62, s16, s5
	s_add_i32 s0, s35, s0
	s_add_i32 s5, s62, 0xffffd500
	s_cmpk_lt_i32 s0, 0xac
	s_cselect_b32 s0, s62, s5
	s_cselect_b32 s5, 0, 0xac
	v_lshl_or_b32 v0, s4, 6, v3
	s_ashr_i32 s63, s62, 31
	v_lshl_add_u64 v[108:109], s[62:63], 2, v[28:29]
	v_or_b32_e32 v31, 4, v0
	v_mad_i64_i32 v[52:53], s[62:63], v31, s78, v[108:109]
	v_or_b32_e32 v31, 8, v0
	v_mad_i64_i32 v[56:57], s[62:63], v31, s78, v[108:109]
	v_or_b32_e32 v31, 12, v0
	v_mad_i64_i32 v[60:61], s[62:63], v31, s78, v[108:109]
	v_or_b32_e32 v31, 16, v0
	v_mad_i64_i32 v[64:65], s[62:63], v31, s78, v[108:109]
	v_or_b32_e32 v31, 20, v0
	v_mad_i64_i32 v[68:69], s[62:63], v31, s78, v[108:109]
	v_or_b32_e32 v31, 24, v0
	v_mad_i64_i32 v[72:73], s[62:63], v31, s78, v[108:109]
	v_or_b32_e32 v31, 28, v0
	v_mad_i64_i32 v[76:77], s[62:63], v31, s78, v[108:109]
	v_or_b32_e32 v31, 32, v0
	v_mad_i64_i32 v[80:81], s[62:63], v31, s78, v[108:109]
	v_or_b32_e32 v31, 36, v0
	v_mad_i64_i32 v[84:85], s[62:63], v31, s78, v[108:109]
	v_or_b32_e32 v31, 40, v0
	v_mad_i64_i32 v[48:49], s[62:63], v0, s78, v[108:109]
	v_mad_i64_i32 v[88:89], s[62:63], v31, s78, v[108:109]
	global_load_dwordx4 v[48:51], v[48:49], off
	s_nop 0
	global_load_dwordx4 v[52:55], v[52:53], off
	s_nop 0
	global_load_dwordx4 v[56:59], v[56:57], off
	s_nop 0
	global_load_dwordx4 v[60:63], v[60:61], off
	s_nop 0
	global_load_dwordx4 v[64:67], v[64:65], off
	s_nop 0
	global_load_dwordx4 v[68:71], v[68:69], off
	s_nop 0
	global_load_dwordx4 v[72:75], v[72:73], off
	s_nop 0
	global_load_dwordx4 v[76:79], v[76:77], off
	s_nop 0
	global_load_dwordx4 v[80:83], v[80:81], off
	s_nop 0
	global_load_dwordx4 v[84:87], v[84:85], off
	v_or_b32_e32 v31, 44, v0
	global_load_dwordx4 v[88:91], v[88:89], off
	v_mad_i64_i32 v[92:93], s[62:63], v31, s78, v[108:109]
	global_load_dwordx4 v[92:95], v[92:93], off
	v_or_b32_e32 v31, 48, v0
	v_mad_i64_i32 v[96:97], s[62:63], v31, s78, v[108:109]
	global_load_dwordx4 v[96:99], v[96:97], off
	v_or_b32_e32 v31, 52, v0
	v_mad_i64_i32 v[100:101], s[62:63], v31, s78, v[108:109]
	global_load_dwordx4 v[100:103], v[100:101], off
	v_or_b32_e32 v31, 56, v0
	v_mad_i64_i32 v[104:105], s[62:63], v31, s78, v[108:109]
	global_load_dwordx4 v[104:107], v[104:105], off
	v_or_b32_e32 v0, 60, v0
	v_mad_i64_i32 v[108:109], s[62:63], v0, s78, v[108:109]
	global_load_dwordx4 v[108:111], v[108:109], off
	v_add_u32_e32 v0, 0xf0a0, v5
	s_and_b32 s33, s0, 64
	s_or_b32 s33, s33, s5
	s_ashr_i32 s62, s0, 7
	s_lshl_b32 s0, s33, 7
	s_ashr_i32 s5, s4, 31
	s_ashr_i32 s63, s62, 31
	s_and_b32 s0, s0, 0x6000
	s_add_u32 s0, s39, s0
	s_addc_u32 s33, s41, 0
	s_lshl_b64 s[62:63], s[62:63], 21
	s_lshl_b64 s[4:5], s[4:5], 15
	s_add_u32 s0, s0, s62
	v_add_u32_e32 v31, 0xc800, v9
	s_addc_u32 s33, s33, s63
	s_add_u32 s4, s0, s4
	v_add_u32_e32 v47, 0xcc00, v9
	s_addc_u32 s5, s33, s5
	s_waitcnt vmcnt(15)
	ds_write2_b32 v7, v48, v49 offset1:1
	ds_write2_b32 v11, v50, v51 offset1:1
	s_waitcnt vmcnt(14)
	ds_write2_b32 v13, v52, v53 offset1:1
	ds_write2_b32 v15, v54, v55 offset1:1
	s_waitcnt vmcnt(13)
	ds_write2_b32 v17, v56, v57 offset1:1
	ds_write2_b32 v19, v58, v59 offset1:1
	s_waitcnt vmcnt(12)
	ds_write2_b32 v32, v60, v61 offset1:1
	ds_write2_b32 v33, v62, v63 offset1:1
	s_waitcnt vmcnt(11)
	ds_write2_b32 v34, v64, v65 offset1:1
	ds_write2_b32 v36, v66, v67 offset1:1
	s_waitcnt vmcnt(10)
	ds_write2_b32 v37, v68, v69 offset1:1
	ds_write2_b32 v38, v70, v71 offset1:1
	s_waitcnt vmcnt(9)
	ds_write2_b32 v39, v72, v73 offset1:1
	ds_write2_b32 v40, v74, v75 offset1:1
	s_waitcnt vmcnt(8)
	ds_write2_b32 v41, v76, v77 offset1:1
	ds_write2_b32 v42, v78, v79 offset1:1
	s_waitcnt vmcnt(7)
	ds_write2_b32 v43, v80, v81 offset1:1
	ds_write2_b32 v44, v82, v83 offset1:1
	s_waitcnt vmcnt(6)
	ds_write2_b32 v45, v84, v85 offset1:1
	ds_write2_b32 v46, v86, v87 offset1:1
	s_waitcnt vmcnt(5)
	ds_write2_b32 v0, v88, v89 offset1:1
	v_add_u32_e32 v0, 0xf0a8, v5
	ds_write2_b32 v0, v90, v91 offset1:1
	v_add_u32_e32 v0, 0xf4b0, v5
	s_waitcnt vmcnt(4)
	ds_write2_b32 v0, v92, v93 offset1:1
	v_add_u32_e32 v0, 0xf4b8, v5
	ds_write2_b32 v0, v94, v95 offset1:1
	v_add_u32_e32 v0, 0xf8c0, v5
	s_waitcnt vmcnt(3)
	ds_write2_b32 v0, v96, v97 offset1:1
	v_add_u32_e32 v0, 0xf8c8, v5
	ds_write2_b32 v0, v98, v99 offset1:1
	v_add_u32_e32 v0, 0xfcd0, v5
	s_waitcnt vmcnt(2)
	ds_write2_b32 v0, v100, v101 offset1:1
	v_add_u32_e32 v0, 0xfcd8, v5
	ds_write2_b32 v0, v102, v103 offset1:1
	v_add_u32_e32 v0, 0x38e0, v7
	s_waitcnt vmcnt(1)
; #define LAS __attribute__((address_space(3)))
; __device__ __forceinline__ unsigned cvt_pk_bf16(float lo, float hi) { unsigned r; asm volatile("v_cvt_pk_bf16_f32 %0, %1, %2" : "=v"(r) : "v"(lo), "v"(hi)); return r; }
; #define LDS_WAIT() asm volatile("s_waitcnt lgkmcnt(0)" ::: "memory")
; __device__ __forceinline__ void transpose_item(const float* W, int N, bf16_t* WT, int nkt, int k0, int n0, int r0, int kbd, LAS float* scr, int lane) {
;     ...
;     const int c = lane & 7;
; #pragma unroll
;     for (int j = 0; j < 8; ++j) { const int n = (lane >> 3) + 8 * j; const LAS float* s = scr + (8 * c) * 65 + n;
;         u32x4 o; o.x = cvt_pk_bf16(s[0], s[65]); o.y = cvt_pk_bf16(s[2 * 65], s[3 * 65]); o.z = cvt_pk_bf16(s[4 * 65], s[5 * 65]); o.w = cvt_pk_bf16(s[6 * 65], s[7 * 65]);
;         *(u32x4*)(WT + dst_off + (size_t)n * 64 + 8 * c) = o; }
;     LDS_WAIT();
	ds_write2_b32 v0, v104, v105 offset1:1
	v_add_u32_e32 v0, 0x38e8, v7
	ds_write2_b32 v0, v106, v107 offset1:1
	v_add_u32_e32 v0, 0x3cf0, v7
	s_waitcnt vmcnt(0)
	ds_write2_b32 v0, v108, v109 offset1:1
	v_add_u32_e32 v0, 0x3cf8, v7
	ds_write2_b32 v0, v110, v111 offset1:1
	s_waitcnt lgkmcnt(0)
	ds_read2_b32 v[48:49], v31 offset1:65
	s_waitcnt lgkmcnt(0)
	v_cvt_pk_bf16_f32 v48, v48, v49
	ds_read2_b32 v[50:51], v31 offset0:130 offset1:195
	v_lshlrev_b32_e32 v0, 1, v2
	s_waitcnt lgkmcnt(0)
	v_cvt_pk_bf16_f32 v49, v50, v51
	ds_read2_b32 v[50:51], v47 offset0:4 offset1:69
	v_lshl_add_u64 v[54:55], s[4:5], 0, v[0:1]
	v_lshlrev_b32_e32 v0, 1, v4
	s_waitcnt lgkmcnt(0)
	v_cvt_pk_bf16_f32 v50, v50, v51
	ds_read2_b32 v[52:53], v47 offset0:134 offset1:199
	s_waitcnt lgkmcnt(0)
	v_cvt_pk_bf16_f32 v51, v52, v53
	v_lshl_add_u64 v[56:57], v[54:55], 0, v[0:1]
	ds_read2_b32 v[52:53], v31 offset0:8 offset1:73
	global_store_dwordx4 v[56:57], v[48:51], off sc1
	v_lshlrev_b32_e32 v0, 1, v6
	v_lshl_add_u64 v[56:57], v[54:55], 0, v[0:1]
	s_waitcnt lgkmcnt(0)
	v_cvt_pk_bf16_f32 v48, v52, v53
	ds_read2_b32 v[50:51], v31 offset0:138 offset1:203
	s_waitcnt lgkmcnt(0)
	v_cvt_pk_bf16_f32 v49, v50, v51
	ds_read2_b32 v[50:51], v47 offset0:12 offset1:77
	s_waitcnt lgkmcnt(0)
	v_cvt_pk_bf16_f32 v50, v50, v51
	ds_read2_b32 v[52:53], v47 offset0:142 offset1:207
	s_waitcnt lgkmcnt(0)
	v_cvt_pk_bf16_f32 v51, v52, v53
	ds_read2_b32 v[52:53], v31 offset0:16 offset1:81
	global_store_dwordx4 v[56:57], v[48:51], off sc1
	v_lshlrev_b32_e32 v0, 1, v8
	v_lshl_add_u64 v[56:57], v[54:55], 0, v[0:1]
	s_waitcnt lgkmcnt(0)
	v_cvt_pk_bf16_f32 v48, v52, v53
	ds_read2_b32 v[50:51], v31 offset0:146 offset1:211
	s_waitcnt lgkmcnt(0)
	v_cvt_pk_bf16_f32 v49, v50, v51
	ds_read2_b32 v[50:51], v47 offset0:20 offset1:85
	s_waitcnt lgkmcnt(0)
	v_cvt_pk_bf16_f32 v50, v50, v51
	ds_read2_b32 v[52:53], v47 offset0:150 offset1:215
	s_waitcnt lgkmcnt(0)
	v_cvt_pk_bf16_f32 v51, v52, v53
	ds_read2_b32 v[52:53], v31 offset0:24 offset1:89
	global_store_dwordx4 v[56:57], v[48:51], off sc1
	v_lshlrev_b32_e32 v0, 1, v10
	v_lshl_add_u64 v[56:57], v[54:55], 0, v[0:1]
	s_waitcnt lgkmcnt(0)
	v_cvt_pk_bf16_f32 v48, v52, v53
	ds_read2_b32 v[50:51], v31 offset0:154 offset1:219
	s_waitcnt lgkmcnt(0)
	v_cvt_pk_bf16_f32 v49, v50, v51
	ds_read2_b32 v[50:51], v47 offset0:28 offset1:93
	s_waitcnt lgkmcnt(0)
	v_cvt_pk_bf16_f32 v50, v50, v51
	ds_read2_b32 v[52:53], v47 offset0:158 offset1:223
	s_waitcnt lgkmcnt(0)
	v_cvt_pk_bf16_f32 v51, v52, v53
	ds_read2_b32 v[52:53], v31 offset0:32 offset1:97
	global_store_dwordx4 v[56:57], v[48:51], off sc1
	v_lshlrev_b32_e32 v0, 1, v12
	v_lshl_add_u64 v[56:57], v[54:55], 0, v[0:1]
	s_waitcnt lgkmcnt(0)
	v_cvt_pk_bf16_f32 v48, v52, v53
	ds_read2_b32 v[50:51], v31 offset0:162 offset1:227
	s_waitcnt lgkmcnt(0)
	v_cvt_pk_bf16_f32 v49, v50, v51
	ds_read2_b32 v[50:51], v47 offset0:36 offset1:101
	s_waitcnt lgkmcnt(0)
	v_cvt_pk_bf16_f32 v50, v50, v51
	ds_read2_b32 v[52:53], v47 offset0:166 offset1:231
	s_waitcnt lgkmcnt(0)
	v_cvt_pk_bf16_f32 v51, v52, v53
	ds_read2_b32 v[52:53], v31 offset0:40 offset1:105
	global_store_dwordx4 v[56:57], v[48:51], off sc1
	v_lshlrev_b32_e32 v0, 1, v14
	v_lshl_add_u64 v[56:57], v[54:55], 0, v[0:1]
	s_waitcnt lgkmcnt(0)
	v_cvt_pk_bf16_f32 v48, v52, v53
	ds_read2_b32 v[50:51], v31 offset0:170 offset1:235
	s_waitcnt lgkmcnt(0)
	v_cvt_pk_bf16_f32 v49, v50, v51
	ds_read2_b32 v[50:51], v47 offset0:44 offset1:109
	s_waitcnt lgkmcnt(0)
	v_cvt_pk_bf16_f32 v50, v50, v51
	ds_read2_b32 v[52:53], v47 offset0:174 offset1:239
	s_waitcnt lgkmcnt(0)
	v_cvt_pk_bf16_f32 v51, v52, v53
	ds_read2_b32 v[52:53], v31 offset0:48 offset1:113
	global_store_dwordx4 v[56:57], v[48:51], off sc1
	v_lshlrev_b32_e32 v0, 1, v16
	v_lshl_add_u64 v[56:57], v[54:55], 0, v[0:1]
	s_waitcnt lgkmcnt(0)
	v_cvt_pk_bf16_f32 v48, v52, v53
	ds_read2_b32 v[50:51], v31 offset0:178 offset1:243
	s_waitcnt lgkmcnt(0)
	v_cvt_pk_bf16_f32 v49, v50, v51
	ds_read2_b32 v[50:51], v47 offset0:52 offset1:117
	s_waitcnt lgkmcnt(0)
	v_cvt_pk_bf16_f32 v50, v50, v51
	ds_read2_b32 v[52:53], v47 offset0:182 offset1:247
	s_waitcnt lgkmcnt(0)
	v_cvt_pk_bf16_f32 v51, v52, v53
	ds_read2_b32 v[52:53], v31 offset0:56 offset1:121
	global_store_dwordx4 v[56:57], v[48:51], off sc1
	v_lshlrev_b32_e32 v0, 1, v18
	s_waitcnt lgkmcnt(0)
	v_cvt_pk_bf16_f32 v48, v52, v53
	ds_read2_b32 v[50:51], v31 offset0:186 offset1:251
	s_waitcnt lgkmcnt(0)
	v_cvt_pk_bf16_f32 v49, v50, v51
	ds_read2_b32 v[50:51], v47 offset0:60 offset1:125
	s_waitcnt lgkmcnt(0)
	v_cvt_pk_bf16_f32 v50, v50, v51
	ds_read2_b32 v[52:53], v47 offset0:190 offset1:255
	s_waitcnt lgkmcnt(0)
	v_cvt_pk_bf16_f32 v51, v52, v53
	v_lshl_add_u64 v[52:53], v[54:55], 0, v[0:1]
	global_store_dwordx4 v[52:53], v[48:51], off sc1
	s_waitcnt lgkmcnt(0)
	s_branch .LBB0_313

; __device__ __forceinline__ u32x4 pack8(const f32x4 v0, const f32x4 v1) { u32x4 w; w.x = cvt_pk_bf16(v0[0], v0[1]); w.y = cvt_pk_bf16(v0[2], v0[3]); w.z = cvt_pk_bf16(v1[0], v1[1]); w.w = cvt_pk_bf16(v1[2], v1[3]); return w; }
;     __device__ __forceinline__ void operator()(AccT& acc, const Unit& u, int wr, int wc, int fr, int fq) const {
;     ...
; #pragma unroll
;             for (int bj = 0; bj < 2; ++bj) { const f32x4 b0 = *(const f32x4*)(pool_b + col0 + bj * 128), b1 = *(const f32x4*)(pool_b + col0 + bj * 128 + 4);
;                 const f32x4 s0 = *(const f32x4*)(pool_scale + col0 + bj * 128), s1 = *(const f32x4*)(pool_scale + col0 + bj * 128 + 4);
; #pragma unroll
;                 for (int ai = 0; ai < 2; ++ai)
; #pragma unroll
;                     for (int m = 0; m < 4; ++m) { const size_t off = (size_t)(row0 + ai * 128 + m * 16) * DSS + col0 + bj * 128;
;                         *(u32x4*)(ZP + off) = pack8((acc[ai][bj][m][0] + b0) * s0, (acc[ai][bj][m][1] + b1) * s1); } }
.LBB0_411:
	v_mov_b32_e32 v104, v254
	s_lshl_b32 s4, s8, 8
	s_add_i32 s4, s4, s84
	v_and_or_b32 v150, v104, 15, s4
	s_lshl_b32 s3, s3, 8
	v_lshrrev_b32_e32 v104, 1, v104
	v_and_or_b32 v104, v104, 24, s3
	v_or_b32_e32 v148, s85, v104
	v_or_b32_e32 v156, 16, v150
	v_or_b32_e32 v154, 32, v150
	v_or_b32_e32 v152, 48, v150
	s_cmp_eq_u32 s33, 0
	v_ashrrev_i32_e32 v149, 31, v148
	v_ashrrev_i32_e32 v151, 31, v150
	v_ashrrev_i32_e32 v157, 31, v156
	v_ashrrev_i32_e32 v155, 31, v154
	v_ashrrev_i32_e32 v153, 31, v152
	s_cbranch_scc1 .LBB0_417
	v_lshlrev_b64 v[136:137], 2, v[148:149]
	v_lshl_add_u64 v[158:159], s[48:49], 0, v[136:137]
	global_load_dwordx4 v[108:111], v[158:159], off
	global_load_dwordx4 v[104:107], v[158:159], off offset:16
	v_lshl_add_u64 v[160:161], s[50:51], 0, v[136:137]
	global_load_dwordx4 v[140:143], v[160:161], off
	global_load_dwordx4 v[136:139], v[160:161], off offset:16
	v_lshlrev_b64 v[164:165], 12, v[150:151]
	v_lshlrev_b64 v[166:167], 12, v[156:157]
	v_lshlrev_b64 v[168:169], 12, v[154:155]
	v_lshlrev_b64 v[170:171], 12, v[152:153]
	v_lshlrev_b64 v[162:163], 1, v[148:149]
	v_lshl_add_u64 v[164:165], s[46:47], 0, v[164:165]
	v_lshl_add_u64 v[166:167], s[46:47], 0, v[166:167]
	v_lshl_add_u64 v[172:173], s[46:47], 0, v[168:169]
	v_lshl_add_u64 v[170:171], s[46:47], 0, v[170:171]
	v_lshl_add_u64 v[168:169], v[164:165], 0, v[162:163]
	v_lshl_add_u64 v[166:167], v[166:167], 0, v[162:163]
	v_lshl_add_u64 v[164:165], v[172:173], 0, v[162:163]
	v_lshl_add_u64 v[162:163], v[170:171], 0, v[162:163]
	s_mov_b32 s3, 0x80000
	v_add_co_u32_e32 v174, vcc, s3, v168
	s_mov_b32 s3, 0x90000
	s_nop 0
	v_addc_co_u32_e32 v175, vcc, 0, v169, vcc
	s_mov_b64 s[4:5], 0x80000
	s_mov_b64 s[8:9], 0x90000
	s_mov_b64 s[16:17], 0xa0000
	s_mov_b64 s[18:19], 0xb0000
	s_waitcnt vmcnt(3)
	v_pk_add_f32 v[170:171], v[134:135], v[110:111]
	v_pk_add_f32 v[172:173], v[132:133], v[108:109]
	s_waitcnt vmcnt(2)
	v_pk_add_f32 v[188:189], v[128:129], v[104:105]
	v_pk_add_f32 v[186:187], v[130:131], v[106:107]
	s_waitcnt vmcnt(1)
	v_pk_mul_f32 v[222:223], v[170:171], v[142:143]
	v_pk_mul_f32 v[170:171], v[172:173], v[140:141]
	s_waitcnt vmcnt(0)
	v_pk_mul_f32 v[172:173], v[188:189], v[136:137]
	v_pk_add_f32 v[190:191], v[126:127], v[110:111]
	v_pk_add_f32 v[192:193], v[124:125], v[108:109]
	v_pk_add_f32 v[194:195], v[122:123], v[106:107]
	v_pk_add_f32 v[196:197], v[120:121], v[104:105]
	v_pk_mul_f32 v[186:187], v[186:187], v[138:139]
	v_cvt_pk_bf16_f32 v170, v170, v171
	v_cvt_pk_bf16_f32 v171, v222, v223
	v_cvt_pk_bf16_f32 v172, v172, v173
	v_pk_add_f32 v[198:199], v[118:119], v[110:111]
	v_cvt_pk_bf16_f32 v173, v186, v187
	v_pk_add_f32 v[200:201], v[116:117], v[108:109]
	v_pk_add_f32 v[202:203], v[114:115], v[106:107]
	v_pk_add_f32 v[204:205], v[112:113], v[104:105]
	v_pk_mul_f32 v[188:189], v[190:191], v[142:143]
	v_pk_mul_f32 v[190:191], v[192:193], v[140:141]
	v_pk_mul_f32 v[192:193], v[194:195], v[138:139]
	v_pk_mul_f32 v[194:195], v[196:197], v[136:137]
	global_store_dwordx4 v[168:169], v[170:173], off sc1
	v_pk_add_f32 v[206:207], v[102:103], v[110:111]
	v_pk_add_f32 v[208:209], v[100:101], v[108:109]
	v_cvt_pk_bf16_f32 v170, v190, v191
	v_cvt_pk_bf16_f32 v171, v188, v189
	v_cvt_pk_bf16_f32 v172, v194, v195
	v_cvt_pk_bf16_f32 v173, v192, v193
	v_pk_add_f32 v[210:211], v[98:99], v[106:107]
	v_pk_add_f32 v[212:213], v[96:97], v[104:105]
	v_pk_mul_f32 v[196:197], v[198:199], v[142:143]
	v_pk_mul_f32 v[198:199], v[200:201], v[140:141]
	v_pk_mul_f32 v[200:201], v[202:203], v[138:139]
	v_pk_mul_f32 v[202:203], v[204:205], v[136:137]
	global_store_dwordx4 v[166:167], v[170:173], off sc1
	v_pk_add_f32 v[214:215], v[94:95], v[110:111]
	v_pk_add_f32 v[216:217], v[92:93], v[108:109]
	v_cvt_pk_bf16_f32 v170, v198, v199
	v_cvt_pk_bf16_f32 v171, v196, v197
	v_cvt_pk_bf16_f32 v172, v202, v203
	v_cvt_pk_bf16_f32 v173, v200, v201
	v_pk_add_f32 v[218:219], v[90:91], v[106:107]
	v_pk_add_f32 v[220:221], v[88:89], v[104:105]
	v_pk_mul_f32 v[204:205], v[206:207], v[142:143]
	v_pk_mul_f32 v[206:207], v[208:209], v[140:141]
	v_pk_mul_f32 v[208:209], v[210:211], v[138:139]
	v_pk_mul_f32 v[210:211], v[212:213], v[136:137]
	global_store_dwordx4 v[164:165], v[170:173], off sc1
	v_pk_mul_f32 v[212:213], v[214:215], v[142:143]
	v_pk_mul_f32 v[214:215], v[216:217], v[140:141]
	v_cvt_pk_bf16_f32 v170, v206, v207
	v_cvt_pk_bf16_f32 v171, v204, v205
	v_cvt_pk_bf16_f32 v172, v210, v211
	v_cvt_pk_bf16_f32 v173, v208, v209
	v_pk_mul_f32 v[216:217], v[218:219], v[138:139]
	v_pk_mul_f32 v[218:219], v[220:221], v[136:137]
	global_store_dwordx4 v[162:163], v[170:173], off sc1
	v_pk_add_f32 v[186:187], v[80:81], v[104:105]
	s_nop 0
	v_cvt_pk_bf16_f32 v170, v214, v215
	v_cvt_pk_bf16_f32 v171, v212, v213
	v_cvt_pk_bf16_f32 v172, v218, v219
	v_cvt_pk_bf16_f32 v173, v216, v217
	global_store_dwordx4 v[174:175], v[170:173], off sc1
	s_nop 1
	v_pk_add_f32 v[170:171], v[86:87], v[110:111]
	v_pk_add_f32 v[172:173], v[84:85], v[108:109]
	v_pk_mul_f32 v[174:175], v[170:171], v[142:143]
	v_pk_mul_f32 v[170:171], v[172:173], v[140:141]
	v_pk_add_f32 v[172:173], v[82:83], v[106:107]
	v_cvt_pk_bf16_f32 v170, v170, v171
	v_cvt_pk_bf16_f32 v171, v174, v175
	v_add_co_u32_e32 v174, vcc, s3, v168
	v_pk_mul_f32 v[188:189], v[172:173], v[138:139]
	v_pk_mul_f32 v[172:173], v[186:187], v[136:137]
	v_addc_co_u32_e32 v175, vcc, 0, v169, vcc
	v_cvt_pk_bf16_f32 v172, v172, v173
	v_cvt_pk_bf16_f32 v173, v188, v189
	global_store_dwordx4 v[174:175], v[170:173], off sc1
	s_mov_b32 s3, 0xa0000
	v_pk_add_f32 v[186:187], v[72:73], v[104:105]
	v_pk_add_f32 v[170:171], v[78:79], v[110:111]
	v_pk_add_f32 v[172:173], v[76:77], v[108:109]
; __device__ __forceinline__ u32x4 pack8(const f32x4 v0, const f32x4 v1) { u32x4 w; w.x = cvt_pk_bf16(v0[0], v0[1]); w.y = cvt_pk_bf16(v0[2], v0[3]); w.z = cvt_pk_bf16(v1[0], v1[1]); w.w = cvt_pk_bf16(v1[2], v1[3]); return w; }
;     __device__ __forceinline__ void operator()(AccT& acc, const Unit& u, int wr, int wc, int fr, int fq) const {
;     ...
; #pragma unroll
;             for (int bj = 0; bj < 2; ++bj) { const f32x4 b0 = *(const f32x4*)(pool_b + col0 + bj * 128), b1 = *(const f32x4*)(pool_b + col0 + bj * 128 + 4);
;                 const f32x4 s0 = *(const f32x4*)(pool_scale + col0 + bj * 128), s1 = *(const f32x4*)(pool_scale + col0 + bj * 128 + 4);
; #pragma unroll
;                 for (int ai = 0; ai < 2; ++ai)
; #pragma unroll
;                     for (int m = 0; m < 4; ++m) { const size_t off = (size_t)(row0 + ai * 128 + m * 16) * DSS + col0 + bj * 128;
;                         *(u32x4*)(ZP + off) = pack8((acc[ai][bj][m][0] + b0) * s0, (acc[ai][bj][m][1] + b1) * s1); } }
	v_pk_mul_f32 v[174:175], v[170:171], v[142:143]
	v_pk_mul_f32 v[170:171], v[172:173], v[140:141]
	v_pk_add_f32 v[172:173], v[74:75], v[106:107]
	v_cvt_pk_bf16_f32 v170, v170, v171
	v_cvt_pk_bf16_f32 v171, v174, v175
	v_add_co_u32_e32 v174, vcc, s3, v168
	v_pk_add_f32 v[108:109], v[68:69], v[108:109]
	v_pk_mul_f32 v[188:189], v[172:173], v[138:139]
	v_pk_mul_f32 v[172:173], v[186:187], v[136:137]
	v_addc_co_u32_e32 v175, vcc, 0, v169, vcc
	v_pk_mul_f32 v[108:109], v[108:109], v[140:141]
	v_pk_add_f32 v[106:107], v[66:67], v[106:107]
	v_pk_add_f32 v[104:105], v[64:65], v[104:105]
	s_mov_b32 s3, 0xb0000
	v_cvt_pk_bf16_f32 v172, v172, v173
	v_cvt_pk_bf16_f32 v173, v188, v189
	global_store_dwordx4 v[174:175], v[170:173], off sc1
	v_pk_mul_f32 v[138:139], v[106:107], v[138:139]
	v_pk_mul_f32 v[106:107], v[104:105], v[136:137]
	v_cvt_pk_bf16_f32 v104, v108, v109
	v_add_co_u32_e32 v108, vcc, s3, v168
	v_pk_add_f32 v[110:111], v[70:71], v[110:111]
	s_nop 0
	v_addc_co_u32_e32 v109, vcc, 0, v169, vcc
	v_pk_mul_f32 v[110:111], v[110:111], v[142:143]
	v_lshl_add_u64 v[174:175], v[168:169], 0, s[4:5]
	v_cvt_pk_bf16_f32 v105, v110, v111
	v_cvt_pk_bf16_f32 v106, v106, v107
	v_cvt_pk_bf16_f32 v107, v138, v139
	global_store_dwordx4 v[108:109], v[104:107], off sc1
	global_load_dwordx4 v[108:111], v[158:159], off offset:512
	s_nop 0
	global_load_dwordx4 v[104:107], v[158:159], off offset:528
	global_load_dwordx4 v[140:143], v[160:161], off offset:512
	global_load_dwordx4 v[136:139], v[160:161], off offset:528
	v_lshl_add_u64 v[170:171], v[168:169], 0, s[8:9]
	v_lshl_add_u64 v[160:161], v[168:169], 0, s[16:17]
	v_lshl_add_u64 v[158:159], v[168:169], 0, s[18:19]
	s_waitcnt vmcnt(3)
	v_pk_add_f32 v[186:187], v[60:61], v[108:109]
	s_waitcnt vmcnt(2)
	v_pk_add_f32 v[188:189], v[58:59], v[106:107]
	v_pk_add_f32 v[190:191], v[56:57], v[104:105]
	v_pk_add_f32 v[172:173], v[62:63], v[110:111]
	s_waitcnt vmcnt(1)
	v_pk_mul_f32 v[186:187], v[186:187], v[140:141]
	s_waitcnt vmcnt(0)
	v_pk_mul_f32 v[196:197], v[188:189], v[138:139]
	v_pk_mul_f32 v[188:189], v[190:191], v[136:137]
	v_pk_mul_f32 v[172:173], v[172:173], v[142:143]
	v_cvt_pk_bf16_f32 v186, v186, v187
	v_pk_add_f32 v[192:193], v[54:55], v[110:111]
	v_cvt_pk_bf16_f32 v187, v172, v173
	v_cvt_pk_bf16_f32 v188, v188, v189
	v_cvt_pk_bf16_f32 v189, v196, v197
	global_store_dwordx4 v[168:169], v[186:189], off offset:256 sc1
	v_pk_add_f32 v[168:169], v[50:51], v[106:107]
	v_pk_add_f32 v[194:195], v[52:53], v[108:109]
	v_pk_add_f32 v[172:173], v[48:49], v[104:105]
	v_pk_mul_f32 v[168:169], v[168:169], v[138:139]
	v_pk_mul_f32 v[190:191], v[192:193], v[142:143]
	v_pk_mul_f32 v[192:193], v[194:195], v[140:141]
	v_pk_mul_f32 v[172:173], v[172:173], v[136:137]
	v_cvt_pk_bf16_f32 v186, v192, v193
	v_cvt_pk_bf16_f32 v187, v190, v191
	s_nop 0
	v_cvt_pk_bf16_f32 v188, v172, v173
	v_cvt_pk_bf16_f32 v189, v168, v169
	global_store_dwordx4 v[166:167], v[186:189], off offset:256 sc1
	v_pk_add_f32 v[166:167], v[46:47], v[110:111]
	v_pk_add_f32 v[168:169], v[44:45], v[108:109]
	v_pk_mul_f32 v[172:173], v[166:167], v[142:143]
	v_pk_mul_f32 v[166:167], v[168:169], v[140:141]
	v_pk_add_f32 v[168:169], v[42:43], v[106:107]
	v_pk_add_f32 v[186:187], v[40:41], v[104:105]
	v_pk_mul_f32 v[188:189], v[168:169], v[138:139]
	v_pk_mul_f32 v[168:169], v[186:187], v[136:137]
	v_cvt_pk_bf16_f32 v166, v166, v167
	v_cvt_pk_bf16_f32 v167, v172, v173
	v_pk_add_f32 v[172:173], v[32:33], v[104:105]
	v_cvt_pk_bf16_f32 v168, v168, v169
	v_cvt_pk_bf16_f32 v169, v188, v189
	global_store_dwordx4 v[164:165], v[166:169], off offset:256 sc1
	v_pk_add_f32 v[164:165], v[38:39], v[110:111]
	s_nop 0
	v_pk_add_f32 v[166:167], v[36:37], v[108:109]
	v_pk_mul_f32 v[168:169], v[164:165], v[142:143]
	v_pk_mul_f32 v[164:165], v[166:167], v[140:141]
	v_pk_add_f32 v[166:167], v[34:35], v[106:107]
	v_cvt_pk_bf16_f32 v164, v164, v165
	v_cvt_pk_bf16_f32 v165, v168, v169
	v_pk_add_f32 v[168:169], v[24:25], v[104:105]
	v_pk_mul_f32 v[186:187], v[166:167], v[138:139]
	v_pk_mul_f32 v[166:167], v[172:173], v[136:137]
	s_nop 0
	v_cvt_pk_bf16_f32 v166, v166, v167
	v_cvt_pk_bf16_f32 v167, v186, v187
	global_store_dwordx4 v[162:163], v[164:167], off offset:256 sc1
	v_pk_add_f32 v[162:163], v[30:31], v[110:111]
	s_nop 0
	v_pk_add_f32 v[164:165], v[28:29], v[108:109]
	v_pk_mul_f32 v[166:167], v[162:163], v[142:143]
	v_pk_mul_f32 v[162:163], v[164:165], v[140:141]
	v_pk_add_f32 v[164:165], v[26:27], v[106:107]
	v_cvt_pk_bf16_f32 v162, v162, v163
	v_cvt_pk_bf16_f32 v163, v166, v167
	s_nop 0
	v_pk_mul_f32 v[172:173], v[164:165], v[138:139]
	v_pk_mul_f32 v[164:165], v[168:169], v[136:137]
	v_pk_add_f32 v[168:169], v[16:17], v[104:105]
	v_cvt_pk_bf16_f32 v164, v164, v165
	v_cvt_pk_bf16_f32 v165, v172, v173
	global_store_dwordx4 v[174:175], v[162:165], off offset:256 sc1
	s_nop 1
	v_pk_add_f32 v[162:163], v[22:23], v[110:111]
	v_pk_add_f32 v[164:165], v[20:21], v[108:109]
	v_pk_mul_f32 v[166:167], v[162:163], v[142:143]
	v_pk_mul_f32 v[162:163], v[164:165], v[140:141]
	v_pk_add_f32 v[164:165], v[18:19], v[106:107]
	v_cvt_pk_bf16_f32 v162, v162, v163
	v_cvt_pk_bf16_f32 v163, v166, v167
	s_nop 0
	v_pk_mul_f32 v[172:173], v[164:165], v[138:139]
	v_pk_mul_f32 v[164:165], v[168:169], v[136:137]
	v_pk_add_f32 v[168:169], v[8:9], v[104:105]
	v_cvt_pk_bf16_f32 v164, v164, v165
	v_cvt_pk_bf16_f32 v165, v172, v173
	global_store_dwordx4 v[170:171], v[162:165], off offset:256 sc1
	v_pk_add_f32 v[104:105], v[0:1], v[104:105]
	s_nop 0
	v_pk_add_f32 v[162:163], v[14:15], v[110:111]
	v_pk_add_f32 v[164:165], v[12:13], v[108:109]
	v_pk_mul_f32 v[166:167], v[162:163], v[142:143]
	v_pk_mul_f32 v[162:163], v[164:165], v[140:141]
	v_pk_add_f32 v[164:165], v[10:11], v[106:107]
	v_pk_add_f32 v[106:107], v[2:3], v[106:107]
	v_pk_mul_f32 v[170:171], v[164:165], v[138:139]
	v_pk_mul_f32 v[164:165], v[168:169], v[136:137]
	v_pk_add_f32 v[110:111], v[6:7], v[110:111]
	v_pk_add_f32 v[108:109], v[4:5], v[108:109]
	v_pk_mul_f32 v[138:139], v[106:107], v[138:139]
	v_pk_mul_f32 v[106:107], v[104:105], v[136:137]
	v_cvt_pk_bf16_f32 v162, v162, v163
	v_cvt_pk_bf16_f32 v163, v166, v167
	v_cvt_pk_bf16_f32 v164, v164, v165
	v_cvt_pk_bf16_f32 v165, v170, v171
	global_store_dwordx4 v[160:161], v[162:165], off offset:256 sc1
	v_pk_mul_f32 v[110:111], v[110:111], v[142:143]
	v_pk_mul_f32 v[108:109], v[108:109], v[140:141]
	s_nop 0
	v_cvt_pk_bf16_f32 v104, v108, v109
	v_cvt_pk_bf16_f32 v105, v110, v111
	v_cvt_pk_bf16_f32 v106, v106, v107
	v_cvt_pk_bf16_f32 v107, v138, v139
	global_store_dwordx4 v[158:159], v[104:107], off offset:256 sc1
	s_cbranch_execnz .LBB0_414
; __device__ __forceinline__ float sigm(float x) { return __builtin_amdgcn_rcpf(1.f + __builtin_amdgcn_exp2f(-1.4426950409f * x)); }
; __device__ __forceinline__ u32x4 pack8(const f32x4 v0, const f32x4 v1) { u32x4 w; w.x = cvt_pk_bf16(v0[0], v0[1]); w.y = cvt_pk_bf16(v0[2], v0[3]); w.z = cvt_pk_bf16(v1[0], v1[1]); w.w = cvt_pk_bf16(v1[2], v1[3]); return w; }
; __device__ __forceinline__ void unpack8(const u32x4 w, f32x4& lo, f32x4& hi) { lo = (f32x4){bf_lo(w.x), bf_hi(w.x), bf_lo(w.y), bf_hi(w.y)}; hi = (f32x4){bf_lo(w.z), bf_hi(w.z), bf_lo(w.w), bf_hi(w.w)}; }
;     __device__ __forceinline__ void operator()(AccT& acc, const Unit& u, int wr, int wc, int fr, int fq) const {
;     ...
;         if (u.kind == 0) {
; #pragma unroll
;             for (int bj = 0; bj < 2; ++bj) { const f32x4 b0 = *(const f32x4*)(glu_b + col0 + bj * 128), b1 = *(const f32x4*)(glu_b + col0 + bj * 128 + 4);
; #pragma unroll
;                 for (int ai = 0; ai < 2; ++ai)
; #pragma unroll
;                     for (int m = 0; m < 4; ++m) { const size_t off = (size_t)(row0 + ai * 128 + m * 16) * DSS + col0 + bj * 128;
;                         f32x4 y0, y1; unpack8(*(const u32x4*)(YG + off), y0, y1);
;                         f32x4 v0 = acc[ai][bj][m][0] + b0, v1 = acc[ai][bj][m][1] + b1;
; #pragma unroll
;                         for (int j = 0; j < 4; ++j) { v0[j] = y0[j] * sigm(v0[j]); v1[j] = y1[j] * sigm(v1[j]); }
;                         *(u32x4*)(YS + off) = pack8(v0, v1); } }
.LBB0_413:
	v_lshl_add_u64 v[140:141], v[148:149], 2, s[44:45]
	global_load_dwordx4 v[108:111], v[140:141], off
	global_load_dwordx4 v[104:107], v[140:141], off offset:16
	v_lshlrev_b64 v[150:151], 11, v[150:151]
	v_lshl_add_u64 v[136:137], v[150:151], 0, v[148:149]
	v_lshlrev_b64 v[158:159], 1, v[136:137]
	v_lshl_add_u64 v[136:137], s[14:15], 0, v[158:159]
	global_load_dwordx4 v[136:139], v[136:137], off
	v_lshlrev_b64 v[142:143], 11, v[156:157]
	v_lshl_add_u64 v[156:157], v[142:143], 0, v[148:149]
	v_lshlrev_b64 v[156:157], 1, v[156:157]
	v_lshl_add_u64 v[158:159], s[26:27], 0, v[158:159]
	v_lshl_add_u64 v[160:161], s[14:15], 0, v[156:157]
	s_mov_b64 s[4:5], 0x40000
	s_waitcnt vmcnt(2)
	v_pk_add_f32 v[134:135], v[134:135], v[110:111]
	v_pk_add_f32 v[132:133], v[132:133], v[108:109]
	s_waitcnt vmcnt(1)
	v_pk_add_f32 v[130:131], v[130:131], v[106:107]
	v_pk_add_f32 v[128:129], v[128:129], v[104:105]
	v_mul_f32_e32 v132, 0xbfb8aa3b, v132
	v_mul_f32_e32 v128, 0xbfb8aa3b, v128
	v_mul_f32_e32 v133, 0xbfb8aa3b, v133
	v_mul_f32_e32 v129, 0xbfb8aa3b, v129
	v_mul_f32_e32 v134, 0xbfb8aa3b, v134
	v_mul_f32_e32 v130, 0xbfb8aa3b, v130
	v_mul_f32_e32 v135, 0xbfb8aa3b, v135
	v_mul_f32_e32 v131, 0xbfb8aa3b, v131
	v_exp_f32_e32 v132, v132
	v_exp_f32_e32 v128, v128
	v_exp_f32_e32 v133, v133
	v_exp_f32_e32 v129, v129
	v_exp_f32_e32 v134, v134
	v_exp_f32_e32 v130, v130
	v_exp_f32_e32 v135, v135
	v_exp_f32_e32 v131, v131
	v_add_f32_e32 v132, 1.0, v132
	v_add_f32_e32 v128, 1.0, v128
	v_add_f32_e32 v133, 1.0, v133
	v_add_f32_e32 v129, 1.0, v129
	v_add_f32_e32 v134, 1.0, v134
	v_add_f32_e32 v130, 1.0, v130
	v_add_f32_e32 v135, 1.0, v135
	v_add_f32_e32 v131, 1.0, v131
	v_rcp_f32_e32 v132, v132
	v_rcp_f32_e32 v128, v128
	v_rcp_f32_e32 v133, v133
	v_rcp_f32_e32 v129, v129
	v_rcp_f32_e32 v134, v134
	v_rcp_f32_e32 v130, v130
	v_rcp_f32_e32 v135, v135
	v_rcp_f32_e32 v131, v131
	s_waitcnt vmcnt(0)
	v_lshlrev_b32_e32 v162, 16, v136
	v_and_b32_e32 v136, 0xffff0000, v136
	v_lshlrev_b32_e32 v163, 16, v137
	v_and_b32_e32 v137, 0xffff0000, v137
	v_lshlrev_b32_e32 v164, 16, v138
	v_and_b32_e32 v138, 0xffff0000, v138
	v_lshlrev_b32_e32 v165, 16, v139
	v_and_b32_e32 v139, 0xffff0000, v139
	v_mul_f32_e32 v132, v132, v162
	v_mul_f32_e32 v162, v128, v164
	v_mul_f32_e32 v128, v133, v136
	v_mul_f32_e32 v133, v129, v138
	v_mul_f32_e32 v129, v134, v163
	v_mul_f32_e32 v134, v130, v165
	v_mul_f32_e32 v130, v135, v137
	v_mul_f32_e32 v131, v131, v139
	v_cvt_pk_bf16_f32 v128, v132, v128
	v_cvt_pk_bf16_f32 v129, v129, v130
	v_cvt_pk_bf16_f32 v130, v162, v133
	v_cvt_pk_bf16_f32 v131, v134, v131
	global_store_dwordx4 v[158:159], v[128:131], off sc1
	global_load_dwordx4 v[128:131], v[160:161], off
	v_pk_add_f32 v[126:127], v[126:127], v[110:111]
	v_pk_add_f32 v[124:125], v[124:125], v[108:109]
	v_pk_add_f32 v[122:123], v[122:123], v[106:107]
	v_pk_add_f32 v[120:121], v[120:121], v[104:105]
	v_mul_f32_e32 v124, 0xbfb8aa3b, v124
	v_mul_f32_e32 v120, 0xbfb8aa3b, v120
	v_mul_f32_e32 v125, 0xbfb8aa3b, v125
	v_mul_f32_e32 v121, 0xbfb8aa3b, v121
	v_mul_f32_e32 v126, 0xbfb8aa3b, v126
	v_mul_f32_e32 v122, 0xbfb8aa3b, v122
	v_mul_f32_e32 v127, 0xbfb8aa3b, v127
	v_mul_f32_e32 v123, 0xbfb8aa3b, v123
	v_exp_f32_e32 v124, v124
	v_exp_f32_e32 v120, v120
	v_exp_f32_e32 v125, v125
	v_exp_f32_e32 v121, v121
	v_exp_f32_e32 v126, v126
	v_exp_f32_e32 v122, v122
	v_exp_f32_e32 v127, v127
	v_exp_f32_e32 v123, v123
	v_add_f32_e32 v124, 1.0, v124
	v_add_f32_e32 v120, 1.0, v120
	v_add_f32_e32 v125, 1.0, v125
	v_add_f32_e32 v121, 1.0, v121
	v_add_f32_e32 v126, 1.0, v126
	v_add_f32_e32 v122, 1.0, v122
	v_add_f32_e32 v127, 1.0, v127
	v_add_f32_e32 v123, 1.0, v123
	v_rcp_f32_e32 v124, v124
	v_rcp_f32_e32 v120, v120
	v_rcp_f32_e32 v125, v125
	v_rcp_f32_e32 v121, v121
	v_rcp_f32_e32 v126, v126
	v_rcp_f32_e32 v122, v122
	v_rcp_f32_e32 v127, v127
	v_rcp_f32_e32 v123, v123
	v_lshlrev_b64 v[132:133], 11, v[154:155]
	v_lshl_add_u64 v[134:135], v[132:133], 0, v[148:149]
	v_lshl_add_u64 v[136:137], s[26:27], 0, v[156:157]
	v_lshlrev_b64 v[134:135], 1, v[134:135]
	v_lshl_add_u64 v[138:139], s[14:15], 0, v[134:135]
	v_pk_add_f32 v[118:119], v[118:119], v[110:111]
	v_pk_add_f32 v[116:117], v[116:117], v[108:109]
	v_pk_add_f32 v[114:115], v[114:115], v[106:107]
	v_pk_add_f32 v[112:113], v[112:113], v[104:105]
	v_mul_f32_e32 v116, 0xbfb8aa3b, v116
	v_mul_f32_e32 v112, 0xbfb8aa3b, v112
	v_mul_f32_e32 v117, 0xbfb8aa3b, v117
	v_mul_f32_e32 v113, 0xbfb8aa3b, v113
	v_mul_f32_e32 v118, 0xbfb8aa3b, v118
	v_mul_f32_e32 v114, 0xbfb8aa3b, v114
	v_mul_f32_e32 v119, 0xbfb8aa3b, v119
	v_mul_f32_e32 v115, 0xbfb8aa3b, v115
	v_exp_f32_e32 v116, v116
	v_exp_f32_e32 v112, v112
	v_exp_f32_e32 v117, v117
	v_exp_f32_e32 v113, v113
	v_exp_f32_e32 v118, v118
	v_exp_f32_e32 v114, v114
	v_exp_f32_e32 v119, v119
	v_exp_f32_e32 v115, v115
	v_add_f32_e32 v116, 1.0, v116
	v_add_f32_e32 v112, 1.0, v112
	v_add_f32_e32 v117, 1.0, v117
	v_add_f32_e32 v113, 1.0, v113
	v_add_f32_e32 v118, 1.0, v118
	v_add_f32_e32 v114, 1.0, v114
	v_add_f32_e32 v119, 1.0, v119
	v_add_f32_e32 v115, 1.0, v115
	v_rcp_f32_e32 v116, v116
	v_rcp_f32_e32 v112, v112
	v_rcp_f32_e32 v117, v117
	v_rcp_f32_e32 v113, v113
	v_rcp_f32_e32 v118, v118
	v_rcp_f32_e32 v114, v114
	v_rcp_f32_e32 v119, v119
	v_rcp_f32_e32 v115, v115
	v_pk_add_f32 v[102:103], v[102:103], v[110:111]
	v_pk_add_f32 v[100:101], v[100:101], v[108:109]
	s_waitcnt vmcnt(0)
; __device__ __forceinline__ float sigm(float x) { return __builtin_amdgcn_rcpf(1.f + __builtin_amdgcn_exp2f(-1.4426950409f * x)); }
; __device__ __forceinline__ u32x4 pack8(const f32x4 v0, const f32x4 v1) { u32x4 w; w.x = cvt_pk_bf16(v0[0], v0[1]); w.y = cvt_pk_bf16(v0[2], v0[3]); w.z = cvt_pk_bf16(v1[0], v1[1]); w.w = cvt_pk_bf16(v1[2], v1[3]); return w; }
; __device__ __forceinline__ void unpack8(const u32x4 w, f32x4& lo, f32x4& hi) { lo = (f32x4){bf_lo(w.x), bf_hi(w.x), bf_lo(w.y), bf_hi(w.y)}; hi = (f32x4){bf_lo(w.z), bf_hi(w.z), bf_lo(w.w), bf_hi(w.w)}; }
;     __device__ __forceinline__ void operator()(AccT& acc, const Unit& u, int wr, int wc, int fr, int fq) const {
;     ...
;         if (u.kind == 0) {
; #pragma unroll
;             for (int bj = 0; bj < 2; ++bj) { const f32x4 b0 = *(const f32x4*)(glu_b + col0 + bj * 128), b1 = *(const f32x4*)(glu_b + col0 + bj * 128 + 4);
; #pragma unroll
;                 for (int ai = 0; ai < 2; ++ai)
; #pragma unroll
;                     for (int m = 0; m < 4; ++m) { const size_t off = (size_t)(row0 + ai * 128 + m * 16) * DSS + col0 + bj * 128;
;                         f32x4 y0, y1; unpack8(*(const u32x4*)(YG + off), y0, y1);
;                         f32x4 v0 = acc[ai][bj][m][0] + b0, v1 = acc[ai][bj][m][1] + b1;
; #pragma unroll
;                         for (int j = 0; j < 4; ++j) { v0[j] = y0[j] * sigm(v0[j]); v1[j] = y1[j] * sigm(v1[j]); }
;                         *(u32x4*)(YS + off) = pack8(v0, v1); } }
	v_lshlrev_b32_e32 v154, 16, v128
	v_and_b32_e32 v128, 0xffff0000, v128
	v_lshlrev_b32_e32 v155, 16, v129
	v_and_b32_e32 v129, 0xffff0000, v129
	v_lshlrev_b32_e32 v156, 16, v130
	v_and_b32_e32 v130, 0xffff0000, v130
	v_lshlrev_b32_e32 v157, 16, v131
	v_and_b32_e32 v131, 0xffff0000, v131
	v_mul_f32_e32 v124, v124, v154
	v_mul_f32_e32 v154, v120, v156
	v_mul_f32_e32 v120, v125, v128
	v_mul_f32_e32 v125, v121, v130
	v_mul_f32_e32 v121, v126, v155
	v_mul_f32_e32 v126, v122, v157
	v_mul_f32_e32 v122, v127, v129
	v_mul_f32_e32 v123, v123, v131
	v_cvt_pk_bf16_f32 v120, v124, v120
	v_cvt_pk_bf16_f32 v121, v121, v122
	v_cvt_pk_bf16_f32 v122, v154, v125
	v_cvt_pk_bf16_f32 v123, v126, v123
	global_store_dwordx4 v[136:137], v[120:123], off sc1
	global_load_dwordx4 v[120:123], v[138:139], off
	v_lshlrev_b64 v[124:125], 11, v[152:153]
	v_lshl_add_u64 v[126:127], v[124:125], 0, v[148:149]
	v_lshl_add_u64 v[128:129], s[26:27], 0, v[134:135]
	v_lshlrev_b64 v[126:127], 1, v[126:127]
	v_lshl_add_u64 v[130:131], s[14:15], 0, v[126:127]
	v_pk_add_f32 v[98:99], v[98:99], v[106:107]
	v_pk_add_f32 v[96:97], v[96:97], v[104:105]
	v_mul_f32_e32 v100, 0xbfb8aa3b, v100
	v_mul_f32_e32 v96, 0xbfb8aa3b, v96
	v_mul_f32_e32 v101, 0xbfb8aa3b, v101
	v_mul_f32_e32 v97, 0xbfb8aa3b, v97
	v_mul_f32_e32 v102, 0xbfb8aa3b, v102
	v_mul_f32_e32 v98, 0xbfb8aa3b, v98
	v_mul_f32_e32 v103, 0xbfb8aa3b, v103
	v_mul_f32_e32 v99, 0xbfb8aa3b, v99
	v_exp_f32_e32 v100, v100
	v_exp_f32_e32 v96, v96
	v_exp_f32_e32 v101, v101
	v_exp_f32_e32 v97, v97
	v_exp_f32_e32 v102, v102
	v_exp_f32_e32 v98, v98
	v_exp_f32_e32 v103, v103
	v_exp_f32_e32 v99, v99
	v_add_f32_e32 v100, 1.0, v100
	v_add_f32_e32 v96, 1.0, v96
	v_add_f32_e32 v101, 1.0, v101
	v_add_f32_e32 v97, 1.0, v97
	v_add_f32_e32 v102, 1.0, v102
	v_add_f32_e32 v98, 1.0, v98
	v_add_f32_e32 v103, 1.0, v103
	v_add_f32_e32 v99, 1.0, v99
	v_rcp_f32_e32 v100, v100
	v_rcp_f32_e32 v96, v96
	v_rcp_f32_e32 v101, v101
	v_rcp_f32_e32 v97, v97
	v_rcp_f32_e32 v102, v102
	v_rcp_f32_e32 v98, v98
	v_rcp_f32_e32 v103, v103
	v_rcp_f32_e32 v99, v99
	v_pk_add_f32 v[94:95], v[94:95], v[110:111]
	v_pk_add_f32 v[92:93], v[92:93], v[108:109]
	v_pk_add_f32 v[90:91], v[90:91], v[106:107]
	v_pk_add_f32 v[88:89], v[88:89], v[104:105]
	v_mul_f32_e32 v92, 0xbfb8aa3b, v92
	v_mul_f32_e32 v88, 0xbfb8aa3b, v88
	v_mul_f32_e32 v93, 0xbfb8aa3b, v93
	v_mul_f32_e32 v89, 0xbfb8aa3b, v89
	v_mul_f32_e32 v94, 0xbfb8aa3b, v94
	v_mul_f32_e32 v90, 0xbfb8aa3b, v90
	v_mul_f32_e32 v95, 0xbfb8aa3b, v95
	v_mul_f32_e32 v91, 0xbfb8aa3b, v91
	v_exp_f32_e32 v92, v92
	v_exp_f32_e32 v88, v88
	v_exp_f32_e32 v93, v93
	v_exp_f32_e32 v89, v89
	v_exp_f32_e32 v94, v94
	v_exp_f32_e32 v90, v90
	v_exp_f32_e32 v95, v95
	v_exp_f32_e32 v91, v91
	v_add_f32_e32 v92, 1.0, v92
	v_add_f32_e32 v88, 1.0, v88
	v_add_f32_e32 v93, 1.0, v93
	v_add_f32_e32 v89, 1.0, v89
	v_add_f32_e32 v94, 1.0, v94
	v_add_f32_e32 v90, 1.0, v90
	v_add_f32_e32 v95, 1.0, v95
	v_add_f32_e32 v91, 1.0, v91
	v_rcp_f32_e32 v92, v92
	v_rcp_f32_e32 v88, v88
	v_rcp_f32_e32 v93, v93
	v_rcp_f32_e32 v89, v89
	v_rcp_f32_e32 v94, v94
	v_rcp_f32_e32 v90, v90
	v_rcp_f32_e32 v95, v95
	v_rcp_f32_e32 v91, v91
	v_pk_add_f32 v[86:87], v[86:87], v[110:111]
	v_pk_add_f32 v[84:85], v[84:85], v[108:109]
	v_pk_add_f32 v[82:83], v[82:83], v[106:107]
	v_pk_add_f32 v[80:81], v[80:81], v[104:105]
	s_waitcnt vmcnt(0)
	v_lshlrev_b32_e32 v134, 16, v120
	v_and_b32_e32 v120, 0xffff0000, v120
	v_lshlrev_b32_e32 v135, 16, v121
	v_and_b32_e32 v121, 0xffff0000, v121
	v_lshlrev_b32_e32 v136, 16, v122
	v_and_b32_e32 v122, 0xffff0000, v122
	v_lshlrev_b32_e32 v137, 16, v123
	v_and_b32_e32 v123, 0xffff0000, v123
	v_mul_f32_e32 v116, v116, v134
	v_mul_f32_e32 v134, v112, v136
	v_mul_f32_e32 v112, v117, v120
	v_mul_f32_e32 v117, v113, v122
	v_mul_f32_e32 v113, v118, v135
	v_mul_f32_e32 v118, v114, v137
	v_mul_f32_e32 v114, v119, v121
	v_mul_f32_e32 v115, v115, v123
	v_cvt_pk_bf16_f32 v112, v116, v112
	v_cvt_pk_bf16_f32 v113, v113, v114
	v_cvt_pk_bf16_f32 v114, v134, v117
	v_cvt_pk_bf16_f32 v115, v118, v115
	global_store_dwordx4 v[128:129], v[112:115], off sc1
	global_load_dwordx4 v[112:115], v[130:131], off
	v_lshl_add_u64 v[116:117], v[150:151], 0, s[4:5]
	v_lshl_add_u64 v[118:119], v[116:117], 0, v[148:149]
	v_lshl_add_u64 v[120:121], s[26:27], 0, v[126:127]
	v_lshlrev_b64 v[118:119], 1, v[118:119]
	v_lshl_add_u64 v[122:123], s[14:15], 0, v[118:119]
	s_mov_b64 s[4:5], 0x48000
	v_mul_f32_e32 v84, 0xbfb8aa3b, v84
	v_mul_f32_e32 v80, 0xbfb8aa3b, v80
	v_mul_f32_e32 v85, 0xbfb8aa3b, v85
	v_mul_f32_e32 v81, 0xbfb8aa3b, v81
	v_mul_f32_e32 v86, 0xbfb8aa3b, v86
	v_mul_f32_e32 v82, 0xbfb8aa3b, v82
	v_mul_f32_e32 v87, 0xbfb8aa3b, v87
	v_mul_f32_e32 v83, 0xbfb8aa3b, v83
	v_exp_f32_e32 v84, v84
	v_exp_f32_e32 v80, v80
	v_exp_f32_e32 v85, v85
	v_exp_f32_e32 v81, v81
	v_exp_f32_e32 v86, v86
	v_exp_f32_e32 v82, v82
	v_exp_f32_e32 v87, v87
	v_exp_f32_e32 v83, v83
	v_add_f32_e32 v84, 1.0, v84
	v_add_f32_e32 v80, 1.0, v80
	v_add_f32_e32 v85, 1.0, v85
	v_add_f32_e32 v81, 1.0, v81
	v_add_f32_e32 v86, 1.0, v86
	v_add_f32_e32 v82, 1.0, v82
	v_add_f32_e32 v87, 1.0, v87
	v_add_f32_e32 v83, 1.0, v83
	v_rcp_f32_e32 v84, v84
	v_rcp_f32_e32 v80, v80
	v_rcp_f32_e32 v85, v85
	v_rcp_f32_e32 v81, v81
	v_rcp_f32_e32 v86, v86
	v_rcp_f32_e32 v82, v82
	v_rcp_f32_e32 v87, v87
	v_rcp_f32_e32 v83, v83
	v_pk_add_f32 v[78:79], v[78:79], v[110:111]
	v_pk_add_f32 v[76:77], v[76:77], v[108:109]
	v_pk_add_f32 v[74:75], v[74:75], v[106:107]
	v_pk_add_f32 v[72:73], v[72:73], v[104:105]
	v_mul_f32_e32 v76, 0xbfb8aa3b, v76
	v_mul_f32_e32 v72, 0xbfb8aa3b, v72
	v_mul_f32_e32 v77, 0xbfb8aa3b, v77
	v_mul_f32_e32 v73, 0xbfb8aa3b, v73
	v_mul_f32_e32 v78, 0xbfb8aa3b, v78
	v_mul_f32_e32 v74, 0xbfb8aa3b, v74
	v_mul_f32_e32 v79, 0xbfb8aa3b, v79
	v_mul_f32_e32 v75, 0xbfb8aa3b, v75
	v_exp_f32_e32 v76, v76
	v_exp_f32_e32 v72, v72
	v_exp_f32_e32 v77, v77
	v_exp_f32_e32 v73, v73
	v_exp_f32_e32 v78, v78
	v_exp_f32_e32 v74, v74
	v_exp_f32_e32 v79, v79
	v_exp_f32_e32 v75, v75
	v_add_f32_e32 v76, 1.0, v76
	v_add_f32_e32 v72, 1.0, v72
	v_add_f32_e32 v77, 1.0, v77
	v_add_f32_e32 v73, 1.0, v73
	v_add_f32_e32 v78, 1.0, v78
	v_add_f32_e32 v74, 1.0, v74
	v_add_f32_e32 v79, 1.0, v79
	v_add_f32_e32 v75, 1.0, v75
	v_rcp_f32_e32 v76, v76
	v_rcp_f32_e32 v72, v72
	v_rcp_f32_e32 v77, v77
	v_rcp_f32_e32 v73, v73
	v_rcp_f32_e32 v78, v78
	v_rcp_f32_e32 v74, v74
	v_rcp_f32_e32 v79, v79
	v_rcp_f32_e32 v75, v75
	v_pk_add_f32 v[70:71], v[70:71], v[110:111]
	v_pk_add_f32 v[68:69], v[68:69], v[108:109]
	v_pk_add_f32 v[66:67], v[66:67], v[106:107]
	v_pk_add_f32 v[64:65], v[64:65], v[104:105]
	v_mul_f32_e32 v68, 0xbfb8aa3b, v68
	s_waitcnt vmcnt(0)
; __device__ __forceinline__ float sigm(float x) { return __builtin_amdgcn_rcpf(1.f + __builtin_amdgcn_exp2f(-1.4426950409f * x)); }
; __device__ __forceinline__ u32x4 pack8(const f32x4 v0, const f32x4 v1) { u32x4 w; w.x = cvt_pk_bf16(v0[0], v0[1]); w.y = cvt_pk_bf16(v0[2], v0[3]); w.z = cvt_pk_bf16(v1[0], v1[1]); w.w = cvt_pk_bf16(v1[2], v1[3]); return w; }
; __device__ __forceinline__ void unpack8(const u32x4 w, f32x4& lo, f32x4& hi) { lo = (f32x4){bf_lo(w.x), bf_hi(w.x), bf_lo(w.y), bf_hi(w.y)}; hi = (f32x4){bf_lo(w.z), bf_hi(w.z), bf_lo(w.w), bf_hi(w.w)}; }
;     __device__ __forceinline__ void operator()(AccT& acc, const Unit& u, int wr, int wc, int fr, int fq) const {
;     ...
;         if (u.kind == 0) {
; #pragma unroll
;             for (int bj = 0; bj < 2; ++bj) { const f32x4 b0 = *(const f32x4*)(glu_b + col0 + bj * 128), b1 = *(const f32x4*)(glu_b + col0 + bj * 128 + 4);
; #pragma unroll
;                 for (int ai = 0; ai < 2; ++ai)
; #pragma unroll
;                     for (int m = 0; m < 4; ++m) { const size_t off = (size_t)(row0 + ai * 128 + m * 16) * DSS + col0 + bj * 128;
;                         f32x4 y0, y1; unpack8(*(const u32x4*)(YG + off), y0, y1);
;                         f32x4 v0 = acc[ai][bj][m][0] + b0, v1 = acc[ai][bj][m][1] + b1;
; #pragma unroll
;                         for (int j = 0; j < 4; ++j) { v0[j] = y0[j] * sigm(v0[j]); v1[j] = y1[j] * sigm(v1[j]); }
;                         *(u32x4*)(YS + off) = pack8(v0, v1); } }
	v_lshlrev_b32_e32 v126, 16, v112
	v_and_b32_e32 v112, 0xffff0000, v112
	v_lshlrev_b32_e32 v127, 16, v113
	v_and_b32_e32 v113, 0xffff0000, v113
	v_lshlrev_b32_e32 v128, 16, v114
	v_and_b32_e32 v114, 0xffff0000, v114
	v_lshlrev_b32_e32 v129, 16, v115
	v_and_b32_e32 v115, 0xffff0000, v115
	v_mul_f32_e32 v100, v100, v126
	v_mul_f32_e32 v126, v96, v128
	v_mul_f32_e32 v96, v101, v112
	v_mul_f32_e32 v101, v97, v114
	v_mul_f32_e32 v97, v102, v127
	v_mul_f32_e32 v102, v98, v129
	v_mul_f32_e32 v98, v103, v113
	v_mul_f32_e32 v99, v99, v115
	v_cvt_pk_bf16_f32 v96, v100, v96
	v_cvt_pk_bf16_f32 v97, v97, v98
	v_cvt_pk_bf16_f32 v98, v126, v101
	v_cvt_pk_bf16_f32 v99, v102, v99
	global_store_dwordx4 v[120:121], v[96:99], off sc1
	global_load_dwordx4 v[96:99], v[122:123], off
	v_lshl_add_u64 v[100:101], v[150:151], 0, s[4:5]
	v_lshl_add_u64 v[102:103], v[100:101], 0, v[148:149]
	v_lshl_add_u64 v[112:113], s[26:27], 0, v[118:119]
	v_lshlrev_b64 v[102:103], 1, v[102:103]
	v_lshl_add_u64 v[114:115], s[14:15], 0, v[102:103]
	s_mov_b64 s[4:5], 0x50000
	v_mul_f32_e32 v64, 0xbfb8aa3b, v64
	v_mul_f32_e32 v69, 0xbfb8aa3b, v69
	v_mul_f32_e32 v65, 0xbfb8aa3b, v65
	v_mul_f32_e32 v70, 0xbfb8aa3b, v70
	v_mul_f32_e32 v66, 0xbfb8aa3b, v66
	v_mul_f32_e32 v71, 0xbfb8aa3b, v71
	v_mul_f32_e32 v67, 0xbfb8aa3b, v67
	v_exp_f32_e32 v68, v68
	v_exp_f32_e32 v64, v64
	v_exp_f32_e32 v69, v69
	v_exp_f32_e32 v65, v65
	v_exp_f32_e32 v70, v70
	v_exp_f32_e32 v66, v66
	v_exp_f32_e32 v71, v71
	v_exp_f32_e32 v67, v67
	v_add_f32_e32 v68, 1.0, v68
	v_add_f32_e32 v64, 1.0, v64
	v_add_f32_e32 v69, 1.0, v69
	v_add_f32_e32 v65, 1.0, v65
	v_add_f32_e32 v70, 1.0, v70
	v_add_f32_e32 v66, 1.0, v66
	v_add_f32_e32 v71, 1.0, v71
	v_add_f32_e32 v67, 1.0, v67
	v_rcp_f32_e32 v68, v68
	v_rcp_f32_e32 v64, v64
	v_rcp_f32_e32 v69, v69
	v_rcp_f32_e32 v65, v65
	v_rcp_f32_e32 v70, v70
	v_rcp_f32_e32 v66, v66
	v_rcp_f32_e32 v71, v71
	v_rcp_f32_e32 v67, v67
	s_waitcnt vmcnt(0)
	v_lshlrev_b32_e32 v118, 16, v96
	v_and_b32_e32 v96, 0xffff0000, v96
	v_lshlrev_b32_e32 v119, 16, v97
	v_and_b32_e32 v97, 0xffff0000, v97
	v_lshlrev_b32_e32 v120, 16, v98
	v_and_b32_e32 v98, 0xffff0000, v98
	v_lshlrev_b32_e32 v121, 16, v99
	v_and_b32_e32 v99, 0xffff0000, v99
	v_mul_f32_e32 v92, v92, v118
	v_mul_f32_e32 v118, v88, v120
	v_mul_f32_e32 v88, v93, v96
	v_mul_f32_e32 v93, v89, v98
	v_mul_f32_e32 v89, v94, v119
	v_mul_f32_e32 v94, v90, v121
	v_mul_f32_e32 v90, v95, v97
	v_mul_f32_e32 v91, v91, v99
	v_cvt_pk_bf16_f32 v88, v92, v88
	v_cvt_pk_bf16_f32 v89, v89, v90
	v_cvt_pk_bf16_f32 v90, v118, v93
	v_cvt_pk_bf16_f32 v91, v94, v91
	global_store_dwordx4 v[112:113], v[88:91], off sc1
	global_load_dwordx4 v[88:91], v[114:115], off
	v_lshl_add_u64 v[92:93], v[150:151], 0, s[4:5]
	v_lshl_add_u64 v[94:95], v[92:93], 0, v[148:149]
	v_lshl_add_u64 v[96:97], s[26:27], 0, v[102:103]
	v_lshlrev_b64 v[94:95], 1, v[94:95]
	v_lshl_add_u64 v[98:99], s[14:15], 0, v[94:95]
	s_mov_b64 s[4:5], 0x58000
	s_waitcnt vmcnt(0)
	v_lshlrev_b32_e32 v102, 16, v88
	v_and_b32_e32 v88, 0xffff0000, v88
	v_lshlrev_b32_e32 v103, 16, v89
	v_and_b32_e32 v89, 0xffff0000, v89
	v_lshlrev_b32_e32 v112, 16, v90
	v_and_b32_e32 v90, 0xffff0000, v90
	v_lshlrev_b32_e32 v113, 16, v91
	v_and_b32_e32 v91, 0xffff0000, v91
	v_mul_f32_e32 v84, v84, v102
	v_mul_f32_e32 v102, v80, v112
	v_mul_f32_e32 v80, v85, v88
	v_mul_f32_e32 v85, v81, v90
	v_mul_f32_e32 v81, v86, v103
	v_mul_f32_e32 v86, v82, v113
	v_mul_f32_e32 v82, v87, v89
	v_mul_f32_e32 v83, v83, v91
	v_cvt_pk_bf16_f32 v80, v84, v80
	v_cvt_pk_bf16_f32 v81, v81, v82
	v_cvt_pk_bf16_f32 v82, v102, v85
	v_cvt_pk_bf16_f32 v83, v86, v83
	global_store_dwordx4 v[96:97], v[80:83], off sc1
	global_load_dwordx4 v[80:83], v[98:99], off
	v_lshl_add_u64 v[84:85], v[150:151], 0, s[4:5]
	v_lshl_add_u64 v[86:87], v[84:85], 0, v[148:149]
	v_lshl_add_u64 v[88:89], s[26:27], 0, v[94:95]
	v_lshlrev_b64 v[86:87], 1, v[86:87]
	v_lshl_add_u64 v[90:91], s[14:15], 0, v[86:87]
	v_or_b32_e32 v148, 0x80, v148
	s_waitcnt vmcnt(0)
	v_lshlrev_b32_e32 v94, 16, v80
	v_and_b32_e32 v80, 0xffff0000, v80
	v_lshlrev_b32_e32 v95, 16, v81
	v_and_b32_e32 v81, 0xffff0000, v81
	v_lshlrev_b32_e32 v96, 16, v82
	v_and_b32_e32 v82, 0xffff0000, v82
	v_lshlrev_b32_e32 v97, 16, v83
	v_and_b32_e32 v83, 0xffff0000, v83
	v_mul_f32_e32 v76, v76, v94
	v_mul_f32_e32 v94, v72, v96
	v_mul_f32_e32 v72, v77, v80
	v_mul_f32_e32 v77, v73, v82
	v_mul_f32_e32 v73, v78, v95
	v_mul_f32_e32 v78, v74, v97
	v_mul_f32_e32 v74, v79, v81
	v_mul_f32_e32 v75, v75, v83
	v_cvt_pk_bf16_f32 v72, v76, v72
	v_cvt_pk_bf16_f32 v73, v73, v74
	v_cvt_pk_bf16_f32 v74, v94, v77
	v_cvt_pk_bf16_f32 v75, v78, v75
	global_store_dwordx4 v[88:89], v[72:75], off sc1
	global_load_dwordx4 v[72:75], v[90:91], off
	v_lshl_add_u64 v[76:77], v[148:149], 0, v[150:151]
	v_lshl_add_u64 v[78:79], s[26:27], 0, v[86:87]
	v_lshlrev_b64 v[76:77], 1, v[76:77]
	v_lshl_add_u64 v[80:81], s[14:15], 0, v[76:77]
	v_lshl_add_u64 v[76:77], s[26:27], 0, v[76:77]
	s_waitcnt vmcnt(0)
	v_lshlrev_b32_e32 v82, 16, v72
	v_and_b32_e32 v72, 0xffff0000, v72
	v_lshlrev_b32_e32 v83, 16, v73
	v_and_b32_e32 v73, 0xffff0000, v73
	v_lshlrev_b32_e32 v86, 16, v74
	v_and_b32_e32 v74, 0xffff0000, v74
	v_lshlrev_b32_e32 v87, 16, v75
	v_and_b32_e32 v75, 0xffff0000, v75
	v_mul_f32_e32 v68, v68, v82
	v_mul_f32_e32 v82, v64, v86
	v_mul_f32_e32 v64, v69, v72
	v_mul_f32_e32 v69, v65, v74
	v_mul_f32_e32 v65, v70, v83
	v_mul_f32_e32 v70, v66, v87
	v_mul_f32_e32 v66, v71, v73
	v_mul_f32_e32 v67, v67, v75
	v_cvt_pk_bf16_f32 v64, v68, v64
	v_cvt_pk_bf16_f32 v65, v65, v66
	v_cvt_pk_bf16_f32 v66, v82, v69
	v_cvt_pk_bf16_f32 v67, v70, v67
	global_store_dwordx4 v[78:79], v[64:67], off sc1
	global_load_dwordx4 v[72:75], v[80:81], off
	global_load_dwordx4 v[68:71], v[140:141], off offset:512
	s_nop 0
	global_load_dwordx4 v[64:67], v[140:141], off offset:528
	v_lshl_add_u64 v[78:79], v[148:149], 0, v[142:143]
	v_lshlrev_b64 v[78:79], 1, v[78:79]
	v_lshl_add_u64 v[80:81], s[14:15], 0, v[78:79]
	s_waitcnt vmcnt(2)
; __device__ __forceinline__ float sigm(float x) { return __builtin_amdgcn_rcpf(1.f + __builtin_amdgcn_exp2f(-1.4426950409f * x)); }
; __device__ __forceinline__ u32x4 pack8(const f32x4 v0, const f32x4 v1) { u32x4 w; w.x = cvt_pk_bf16(v0[0], v0[1]); w.y = cvt_pk_bf16(v0[2], v0[3]); w.z = cvt_pk_bf16(v1[0], v1[1]); w.w = cvt_pk_bf16(v1[2], v1[3]); return w; }
; __device__ __forceinline__ void unpack8(const u32x4 w, f32x4& lo, f32x4& hi) { lo = (f32x4){bf_lo(w.x), bf_hi(w.x), bf_lo(w.y), bf_hi(w.y)}; hi = (f32x4){bf_lo(w.z), bf_hi(w.z), bf_lo(w.w), bf_hi(w.w)}; }
;     __device__ __forceinline__ void operator()(AccT& acc, const Unit& u, int wr, int wc, int fr, int fq) const {
;     ...
;         if (u.kind == 0) {
; #pragma unroll
;             for (int bj = 0; bj < 2; ++bj) { const f32x4 b0 = *(const f32x4*)(glu_b + col0 + bj * 128), b1 = *(const f32x4*)(glu_b + col0 + bj * 128 + 4);
; #pragma unroll
;                 for (int ai = 0; ai < 2; ++ai)
; #pragma unroll
;                     for (int m = 0; m < 4; ++m) { const size_t off = (size_t)(row0 + ai * 128 + m * 16) * DSS + col0 + bj * 128;
;                         f32x4 y0, y1; unpack8(*(const u32x4*)(YG + off), y0, y1);
;                         f32x4 v0 = acc[ai][bj][m][0] + b0, v1 = acc[ai][bj][m][1] + b1;
; #pragma unroll
;                         for (int j = 0; j < 4; ++j) { v0[j] = y0[j] * sigm(v0[j]); v1[j] = y1[j] * sigm(v1[j]); }
;                         *(u32x4*)(YS + off) = pack8(v0, v1); } }
	v_lshlrev_b32_e32 v82, 16, v72
	s_waitcnt vmcnt(1)
	v_pk_add_f32 v[62:63], v[62:63], v[70:71]
	v_pk_add_f32 v[60:61], v[60:61], v[68:69]
	s_waitcnt vmcnt(0)
	v_pk_add_f32 v[58:59], v[58:59], v[66:67]
	v_pk_add_f32 v[56:57], v[56:57], v[64:65]
	v_mul_f32_e32 v60, 0xbfb8aa3b, v60
	v_mul_f32_e32 v56, 0xbfb8aa3b, v56
	v_mul_f32_e32 v61, 0xbfb8aa3b, v61
	v_mul_f32_e32 v57, 0xbfb8aa3b, v57
	v_mul_f32_e32 v62, 0xbfb8aa3b, v62
	v_mul_f32_e32 v58, 0xbfb8aa3b, v58
	v_mul_f32_e32 v63, 0xbfb8aa3b, v63
	v_mul_f32_e32 v59, 0xbfb8aa3b, v59
	v_exp_f32_e32 v60, v60
	v_exp_f32_e32 v56, v56
	v_exp_f32_e32 v61, v61
	v_exp_f32_e32 v57, v57
	v_exp_f32_e32 v62, v62
	v_exp_f32_e32 v58, v58
	v_exp_f32_e32 v63, v63
	v_exp_f32_e32 v59, v59
	v_add_f32_e32 v60, 1.0, v60
	v_add_f32_e32 v56, 1.0, v56
	v_add_f32_e32 v61, 1.0, v61
	v_add_f32_e32 v57, 1.0, v57
	v_add_f32_e32 v62, 1.0, v62
	v_add_f32_e32 v58, 1.0, v58
	v_add_f32_e32 v63, 1.0, v63
	v_add_f32_e32 v59, 1.0, v59
	v_rcp_f32_e32 v60, v60
	v_rcp_f32_e32 v56, v56
	v_rcp_f32_e32 v61, v61
	v_rcp_f32_e32 v57, v57
	v_rcp_f32_e32 v62, v62
	v_rcp_f32_e32 v58, v58
	v_rcp_f32_e32 v63, v63
	v_rcp_f32_e32 v59, v59
	v_and_b32_e32 v72, 0xffff0000, v72
	v_lshlrev_b32_e32 v83, 16, v73
	v_and_b32_e32 v73, 0xffff0000, v73
	v_lshlrev_b32_e32 v86, 16, v74
	v_and_b32_e32 v74, 0xffff0000, v74
	v_lshlrev_b32_e32 v87, 16, v75
	v_and_b32_e32 v75, 0xffff0000, v75
	v_mul_f32_e32 v60, v60, v82
	v_mul_f32_e32 v82, v56, v86
	v_mul_f32_e32 v56, v61, v72
	v_mul_f32_e32 v61, v57, v74
	v_mul_f32_e32 v57, v62, v83
	v_mul_f32_e32 v62, v58, v87
	v_mul_f32_e32 v58, v63, v73
	v_mul_f32_e32 v59, v59, v75
	v_cvt_pk_bf16_f32 v56, v60, v56
	v_cvt_pk_bf16_f32 v57, v57, v58
	v_cvt_pk_bf16_f32 v58, v82, v61
	v_cvt_pk_bf16_f32 v59, v62, v59
	global_store_dwordx4 v[76:77], v[56:59], off sc1
	global_load_dwordx4 v[56:59], v[80:81], off
	v_pk_add_f32 v[54:55], v[54:55], v[70:71]
	v_pk_add_f32 v[52:53], v[52:53], v[68:69]
	v_pk_add_f32 v[50:51], v[50:51], v[66:67]
	v_pk_add_f32 v[48:49], v[48:49], v[64:65]
	v_mul_f32_e32 v52, 0xbfb8aa3b, v52
	v_mul_f32_e32 v48, 0xbfb8aa3b, v48
	v_mul_f32_e32 v53, 0xbfb8aa3b, v53
	v_mul_f32_e32 v49, 0xbfb8aa3b, v49
	v_mul_f32_e32 v54, 0xbfb8aa3b, v54
	v_mul_f32_e32 v50, 0xbfb8aa3b, v50
	v_mul_f32_e32 v55, 0xbfb8aa3b, v55
	v_mul_f32_e32 v51, 0xbfb8aa3b, v51
	v_exp_f32_e32 v52, v52
	v_exp_f32_e32 v48, v48
	v_exp_f32_e32 v53, v53
	v_exp_f32_e32 v49, v49
	v_exp_f32_e32 v54, v54
	v_exp_f32_e32 v50, v50
	v_exp_f32_e32 v55, v55
	v_exp_f32_e32 v51, v51
	v_add_f32_e32 v52, 1.0, v52
	v_add_f32_e32 v48, 1.0, v48
	v_add_f32_e32 v53, 1.0, v53
	v_add_f32_e32 v49, 1.0, v49
	v_add_f32_e32 v54, 1.0, v54
	v_add_f32_e32 v50, 1.0, v50
	v_add_f32_e32 v55, 1.0, v55
	v_add_f32_e32 v51, 1.0, v51
	v_rcp_f32_e32 v52, v52
	v_rcp_f32_e32 v48, v48
	v_rcp_f32_e32 v53, v53
	v_rcp_f32_e32 v49, v49
	v_rcp_f32_e32 v54, v54
	v_rcp_f32_e32 v50, v50
	v_rcp_f32_e32 v55, v55
	v_rcp_f32_e32 v51, v51
	v_lshl_add_u64 v[60:61], v[148:149], 0, v[132:133]
	v_lshlrev_b64 v[60:61], 1, v[60:61]
	v_lshl_add_u64 v[62:63], s[26:27], 0, v[78:79]
	v_lshl_add_u64 v[72:73], s[14:15], 0, v[60:61]
	v_pk_add_f32 v[46:47], v[46:47], v[70:71]
	v_pk_add_f32 v[44:45], v[44:45], v[68:69]
	v_pk_add_f32 v[42:43], v[42:43], v[66:67]
	v_pk_add_f32 v[40:41], v[40:41], v[64:65]
	v_mul_f32_e32 v44, 0xbfb8aa3b, v44
	v_mul_f32_e32 v40, 0xbfb8aa3b, v40
	v_mul_f32_e32 v45, 0xbfb8aa3b, v45
	v_mul_f32_e32 v41, 0xbfb8aa3b, v41
	v_mul_f32_e32 v46, 0xbfb8aa3b, v46
	v_mul_f32_e32 v42, 0xbfb8aa3b, v42
	v_mul_f32_e32 v47, 0xbfb8aa3b, v47
	v_mul_f32_e32 v43, 0xbfb8aa3b, v43
	v_exp_f32_e32 v44, v44
	v_exp_f32_e32 v40, v40
	v_exp_f32_e32 v45, v45
	v_exp_f32_e32 v41, v41
	v_exp_f32_e32 v46, v46
	v_exp_f32_e32 v42, v42
	v_exp_f32_e32 v47, v47
	v_exp_f32_e32 v43, v43
	v_add_f32_e32 v44, 1.0, v44
	v_add_f32_e32 v40, 1.0, v40
	v_add_f32_e32 v45, 1.0, v45
	v_add_f32_e32 v41, 1.0, v41
	v_add_f32_e32 v46, 1.0, v46
	v_add_f32_e32 v42, 1.0, v42
	v_add_f32_e32 v47, 1.0, v47
	v_add_f32_e32 v43, 1.0, v43
	v_rcp_f32_e32 v44, v44
	v_rcp_f32_e32 v40, v40
	v_rcp_f32_e32 v45, v45
	v_rcp_f32_e32 v41, v41
	v_rcp_f32_e32 v46, v46
	v_rcp_f32_e32 v42, v42
	v_rcp_f32_e32 v47, v47
	v_rcp_f32_e32 v43, v43
	v_pk_add_f32 v[38:39], v[38:39], v[70:71]
	v_pk_add_f32 v[36:37], v[36:37], v[68:69]
	v_pk_add_f32 v[34:35], v[34:35], v[66:67]
	s_waitcnt vmcnt(0)
; __device__ __forceinline__ float sigm(float x) { return __builtin_amdgcn_rcpf(1.f + __builtin_amdgcn_exp2f(-1.4426950409f * x)); }
; __device__ __forceinline__ u32x4 pack8(const f32x4 v0, const f32x4 v1) { u32x4 w; w.x = cvt_pk_bf16(v0[0], v0[1]); w.y = cvt_pk_bf16(v0[2], v0[3]); w.z = cvt_pk_bf16(v1[0], v1[1]); w.w = cvt_pk_bf16(v1[2], v1[3]); return w; }
; __device__ __forceinline__ void unpack8(const u32x4 w, f32x4& lo, f32x4& hi) { lo = (f32x4){bf_lo(w.x), bf_hi(w.x), bf_lo(w.y), bf_hi(w.y)}; hi = (f32x4){bf_lo(w.z), bf_hi(w.z), bf_lo(w.w), bf_hi(w.w)}; }
;     __device__ __forceinline__ void operator()(AccT& acc, const Unit& u, int wr, int wc, int fr, int fq) const {
;     ...
;         if (u.kind == 0) {
; #pragma unroll
;             for (int bj = 0; bj < 2; ++bj) { const f32x4 b0 = *(const f32x4*)(glu_b + col0 + bj * 128), b1 = *(const f32x4*)(glu_b + col0 + bj * 128 + 4);
; #pragma unroll
;                 for (int ai = 0; ai < 2; ++ai)
; #pragma unroll
;                     for (int m = 0; m < 4; ++m) { const size_t off = (size_t)(row0 + ai * 128 + m * 16) * DSS + col0 + bj * 128;
;                         f32x4 y0, y1; unpack8(*(const u32x4*)(YG + off), y0, y1);
;                         f32x4 v0 = acc[ai][bj][m][0] + b0, v1 = acc[ai][bj][m][1] + b1;
; #pragma unroll
;                         for (int j = 0; j < 4; ++j) { v0[j] = y0[j] * sigm(v0[j]); v1[j] = y1[j] * sigm(v1[j]); }
;                         *(u32x4*)(YS + off) = pack8(v0, v1); } }
	v_lshlrev_b32_e32 v74, 16, v56
	v_and_b32_e32 v56, 0xffff0000, v56
	v_lshlrev_b32_e32 v75, 16, v57
	v_and_b32_e32 v57, 0xffff0000, v57
	v_lshlrev_b32_e32 v76, 16, v58
	v_and_b32_e32 v58, 0xffff0000, v58
	v_lshlrev_b32_e32 v77, 16, v59
	v_and_b32_e32 v59, 0xffff0000, v59
	v_mul_f32_e32 v52, v52, v74
	v_mul_f32_e32 v74, v48, v76
	v_mul_f32_e32 v48, v53, v56
	v_mul_f32_e32 v53, v49, v58
	v_mul_f32_e32 v49, v54, v75
	v_mul_f32_e32 v54, v50, v77
	v_mul_f32_e32 v50, v55, v57
	v_mul_f32_e32 v51, v51, v59
	v_cvt_pk_bf16_f32 v48, v52, v48
	v_cvt_pk_bf16_f32 v49, v49, v50
	v_cvt_pk_bf16_f32 v50, v74, v53
	v_cvt_pk_bf16_f32 v51, v54, v51
	global_store_dwordx4 v[62:63], v[48:51], off sc1
	global_load_dwordx4 v[48:51], v[72:73], off
	v_lshl_add_u64 v[52:53], v[148:149], 0, v[124:125]
	v_lshl_add_u64 v[54:55], s[26:27], 0, v[60:61]
	v_lshlrev_b64 v[52:53], 1, v[52:53]
	v_lshl_add_u64 v[56:57], s[14:15], 0, v[52:53]
	v_pk_add_f32 v[32:33], v[32:33], v[64:65]
	v_mul_f32_e32 v36, 0xbfb8aa3b, v36
	v_mul_f32_e32 v32, 0xbfb8aa3b, v32
	v_mul_f32_e32 v37, 0xbfb8aa3b, v37
	v_mul_f32_e32 v33, 0xbfb8aa3b, v33
	v_mul_f32_e32 v38, 0xbfb8aa3b, v38
	v_mul_f32_e32 v34, 0xbfb8aa3b, v34
	v_mul_f32_e32 v39, 0xbfb8aa3b, v39
	v_mul_f32_e32 v35, 0xbfb8aa3b, v35
	v_exp_f32_e32 v36, v36
	v_exp_f32_e32 v32, v32
	v_exp_f32_e32 v37, v37
	v_exp_f32_e32 v33, v33
	v_exp_f32_e32 v38, v38
	v_exp_f32_e32 v34, v34
	v_exp_f32_e32 v39, v39
	v_exp_f32_e32 v35, v35
	v_add_f32_e32 v36, 1.0, v36
	v_add_f32_e32 v32, 1.0, v32
	v_add_f32_e32 v37, 1.0, v37
	v_add_f32_e32 v33, 1.0, v33
	v_add_f32_e32 v38, 1.0, v38
	v_add_f32_e32 v34, 1.0, v34
	v_add_f32_e32 v39, 1.0, v39
	v_add_f32_e32 v35, 1.0, v35
	v_rcp_f32_e32 v36, v36
	v_rcp_f32_e32 v32, v32
	v_rcp_f32_e32 v37, v37
	v_rcp_f32_e32 v33, v33
	v_rcp_f32_e32 v38, v38
	v_rcp_f32_e32 v34, v34
	v_rcp_f32_e32 v39, v39
	v_rcp_f32_e32 v35, v35
	v_pk_add_f32 v[30:31], v[30:31], v[70:71]
	v_pk_add_f32 v[28:29], v[28:29], v[68:69]
	v_pk_add_f32 v[26:27], v[26:27], v[66:67]
	v_pk_add_f32 v[24:25], v[24:25], v[64:65]
	v_mul_f32_e32 v28, 0xbfb8aa3b, v28
	v_mul_f32_e32 v24, 0xbfb8aa3b, v24
	v_mul_f32_e32 v29, 0xbfb8aa3b, v29
	v_mul_f32_e32 v25, 0xbfb8aa3b, v25
	v_mul_f32_e32 v30, 0xbfb8aa3b, v30
	v_mul_f32_e32 v26, 0xbfb8aa3b, v26
	v_mul_f32_e32 v31, 0xbfb8aa3b, v31
	v_mul_f32_e32 v27, 0xbfb8aa3b, v27
	v_exp_f32_e32 v28, v28
	v_exp_f32_e32 v24, v24
	v_exp_f32_e32 v29, v29
	v_exp_f32_e32 v25, v25
	v_exp_f32_e32 v30, v30
	v_exp_f32_e32 v26, v26
	v_exp_f32_e32 v31, v31
	v_exp_f32_e32 v27, v27
	v_add_f32_e32 v28, 1.0, v28
	v_add_f32_e32 v24, 1.0, v24
	v_add_f32_e32 v29, 1.0, v29
	v_add_f32_e32 v25, 1.0, v25
	v_add_f32_e32 v30, 1.0, v30
	v_add_f32_e32 v26, 1.0, v26
	v_add_f32_e32 v31, 1.0, v31
	v_add_f32_e32 v27, 1.0, v27
	v_rcp_f32_e32 v28, v28
	v_rcp_f32_e32 v24, v24
	v_rcp_f32_e32 v29, v29
	v_rcp_f32_e32 v25, v25
	v_rcp_f32_e32 v30, v30
	v_rcp_f32_e32 v26, v26
	v_rcp_f32_e32 v31, v31
	v_rcp_f32_e32 v27, v27
	v_pk_add_f32 v[22:23], v[22:23], v[70:71]
	v_pk_add_f32 v[20:21], v[20:21], v[68:69]
	v_pk_add_f32 v[18:19], v[18:19], v[66:67]
	v_pk_add_f32 v[16:17], v[16:17], v[64:65]
	v_mul_f32_e32 v20, 0xbfb8aa3b, v20
	v_mul_f32_e32 v16, 0xbfb8aa3b, v16
	s_waitcnt vmcnt(0)
	v_lshlrev_b32_e32 v58, 16, v48
	v_and_b32_e32 v48, 0xffff0000, v48
	v_lshlrev_b32_e32 v59, 16, v49
	v_and_b32_e32 v49, 0xffff0000, v49
	v_lshlrev_b32_e32 v60, 16, v50
	v_and_b32_e32 v50, 0xffff0000, v50
	v_lshlrev_b32_e32 v61, 16, v51
	v_and_b32_e32 v51, 0xffff0000, v51
	v_mul_f32_e32 v44, v44, v58
	v_mul_f32_e32 v58, v40, v60
	v_mul_f32_e32 v40, v45, v48
	v_mul_f32_e32 v45, v41, v50
	v_mul_f32_e32 v41, v46, v59
	v_mul_f32_e32 v46, v42, v61
	v_mul_f32_e32 v42, v47, v49
	v_mul_f32_e32 v43, v43, v51
	v_cvt_pk_bf16_f32 v40, v44, v40
	v_cvt_pk_bf16_f32 v41, v41, v42
	v_cvt_pk_bf16_f32 v42, v58, v45
	v_cvt_pk_bf16_f32 v43, v46, v43
	global_store_dwordx4 v[54:55], v[40:43], off sc1
	global_load_dwordx4 v[40:43], v[56:57], off
	v_lshl_add_u64 v[44:45], v[148:149], 0, v[116:117]
	v_lshl_add_u64 v[46:47], s[26:27], 0, v[52:53]
	v_lshlrev_b64 v[44:45], 1, v[44:45]
	v_lshl_add_u64 v[48:49], s[14:15], 0, v[44:45]
	v_mul_f32_e32 v21, 0xbfb8aa3b, v21
	v_mul_f32_e32 v17, 0xbfb8aa3b, v17
	v_mul_f32_e32 v22, 0xbfb8aa3b, v22
	v_mul_f32_e32 v18, 0xbfb8aa3b, v18
	v_mul_f32_e32 v23, 0xbfb8aa3b, v23
	v_mul_f32_e32 v19, 0xbfb8aa3b, v19
	v_exp_f32_e32 v20, v20
	v_exp_f32_e32 v16, v16
	v_exp_f32_e32 v21, v21
	v_exp_f32_e32 v17, v17
	v_exp_f32_e32 v22, v22
	v_exp_f32_e32 v18, v18
	v_exp_f32_e32 v23, v23
	v_exp_f32_e32 v19, v19
	v_add_f32_e32 v20, 1.0, v20
	v_add_f32_e32 v16, 1.0, v16
	v_add_f32_e32 v21, 1.0, v21
	v_add_f32_e32 v17, 1.0, v17
	v_add_f32_e32 v22, 1.0, v22
	v_add_f32_e32 v18, 1.0, v18
	v_add_f32_e32 v23, 1.0, v23
	v_add_f32_e32 v19, 1.0, v19
	v_rcp_f32_e32 v20, v20
	v_rcp_f32_e32 v16, v16
	v_rcp_f32_e32 v21, v21
	v_rcp_f32_e32 v17, v17
	v_rcp_f32_e32 v22, v22
	v_rcp_f32_e32 v18, v18
	v_rcp_f32_e32 v23, v23
	v_rcp_f32_e32 v19, v19
	v_pk_add_f32 v[14:15], v[14:15], v[70:71]
	v_pk_add_f32 v[12:13], v[12:13], v[68:69]
	v_pk_add_f32 v[10:11], v[10:11], v[66:67]
	v_pk_add_f32 v[8:9], v[8:9], v[64:65]
	v_mul_f32_e32 v12, 0xbfb8aa3b, v12
	v_mul_f32_e32 v8, 0xbfb8aa3b, v8
	v_mul_f32_e32 v13, 0xbfb8aa3b, v13
	v_mul_f32_e32 v9, 0xbfb8aa3b, v9
	v_mul_f32_e32 v14, 0xbfb8aa3b, v14
	v_mul_f32_e32 v10, 0xbfb8aa3b, v10
	v_mul_f32_e32 v15, 0xbfb8aa3b, v15
	v_mul_f32_e32 v11, 0xbfb8aa3b, v11
	v_exp_f32_e32 v12, v12
	v_exp_f32_e32 v8, v8
	v_exp_f32_e32 v13, v13
	v_exp_f32_e32 v9, v9
	v_exp_f32_e32 v14, v14
	v_exp_f32_e32 v10, v10
	v_exp_f32_e32 v15, v15
	v_exp_f32_e32 v11, v11
	v_add_f32_e32 v12, 1.0, v12
	v_add_f32_e32 v8, 1.0, v8
	v_add_f32_e32 v13, 1.0, v13
	v_add_f32_e32 v9, 1.0, v9
	v_add_f32_e32 v14, 1.0, v14
	v_add_f32_e32 v10, 1.0, v10
	v_add_f32_e32 v15, 1.0, v15
	v_add_f32_e32 v11, 1.0, v11
	v_rcp_f32_e32 v12, v12
	v_rcp_f32_e32 v8, v8
	v_rcp_f32_e32 v13, v13
	v_rcp_f32_e32 v9, v9
	v_rcp_f32_e32 v14, v14
	v_rcp_f32_e32 v10, v10
	v_rcp_f32_e32 v15, v15
	v_rcp_f32_e32 v11, v11
	v_pk_add_f32 v[6:7], v[6:7], v[70:71]
	v_pk_add_f32 v[4:5], v[4:5], v[68:69]
	v_pk_add_f32 v[2:3], v[2:3], v[66:67]
	v_pk_add_f32 v[0:1], v[0:1], v[64:65]
	v_mul_f32_e32 v4, 0xbfb8aa3b, v4
	v_mul_f32_e32 v0, 0xbfb8aa3b, v0
	v_mul_f32_e32 v5, 0xbfb8aa3b, v5
	v_mul_f32_e32 v1, 0xbfb8aa3b, v1
	v_mul_f32_e32 v6, 0xbfb8aa3b, v6
	s_waitcnt vmcnt(0)
; __device__ __forceinline__ float sigm(float x) { return __builtin_amdgcn_rcpf(1.f + __builtin_amdgcn_exp2f(-1.4426950409f * x)); }
; __device__ __forceinline__ u32x4 pack8(const f32x4 v0, const f32x4 v1) { u32x4 w; w.x = cvt_pk_bf16(v0[0], v0[1]); w.y = cvt_pk_bf16(v0[2], v0[3]); w.z = cvt_pk_bf16(v1[0], v1[1]); w.w = cvt_pk_bf16(v1[2], v1[3]); return w; }
; __device__ __forceinline__ void unpack8(const u32x4 w, f32x4& lo, f32x4& hi) { lo = (f32x4){bf_lo(w.x), bf_hi(w.x), bf_lo(w.y), bf_hi(w.y)}; hi = (f32x4){bf_lo(w.z), bf_hi(w.z), bf_lo(w.w), bf_hi(w.w)}; }
;     __device__ __forceinline__ void operator()(AccT& acc, const Unit& u, int wr, int wc, int fr, int fq) const {
;     ...
;         if (u.kind == 0) {
; #pragma unroll
;             for (int bj = 0; bj < 2; ++bj) { const f32x4 b0 = *(const f32x4*)(glu_b + col0 + bj * 128), b1 = *(const f32x4*)(glu_b + col0 + bj * 128 + 4);
; #pragma unroll
;                 for (int ai = 0; ai < 2; ++ai)
; #pragma unroll
;                     for (int m = 0; m < 4; ++m) { const size_t off = (size_t)(row0 + ai * 128 + m * 16) * DSS + col0 + bj * 128;
;                         f32x4 y0, y1; unpack8(*(const u32x4*)(YG + off), y0, y1);
;                         f32x4 v0 = acc[ai][bj][m][0] + b0, v1 = acc[ai][bj][m][1] + b1;
; #pragma unroll
;                         for (int j = 0; j < 4; ++j) { v0[j] = y0[j] * sigm(v0[j]); v1[j] = y1[j] * sigm(v1[j]); }
;                         *(u32x4*)(YS + off) = pack8(v0, v1); } }
	v_lshlrev_b32_e32 v50, 16, v40
	v_and_b32_e32 v40, 0xffff0000, v40
	v_lshlrev_b32_e32 v51, 16, v41
	v_and_b32_e32 v41, 0xffff0000, v41
	v_lshlrev_b32_e32 v52, 16, v42
	v_and_b32_e32 v42, 0xffff0000, v42
	v_lshlrev_b32_e32 v53, 16, v43
	v_and_b32_e32 v43, 0xffff0000, v43
	v_mul_f32_e32 v36, v36, v50
	v_mul_f32_e32 v50, v32, v52
	v_mul_f32_e32 v32, v37, v40
	v_mul_f32_e32 v37, v33, v42
	v_mul_f32_e32 v33, v38, v51
	v_mul_f32_e32 v38, v34, v53
	v_mul_f32_e32 v34, v39, v41
	v_mul_f32_e32 v35, v35, v43
	v_cvt_pk_bf16_f32 v32, v36, v32
	v_cvt_pk_bf16_f32 v33, v33, v34
	v_cvt_pk_bf16_f32 v34, v50, v37
	v_cvt_pk_bf16_f32 v35, v38, v35
	global_store_dwordx4 v[46:47], v[32:35], off sc1
	global_load_dwordx4 v[32:35], v[48:49], off
	v_lshl_add_u64 v[36:37], v[148:149], 0, v[100:101]
	v_lshl_add_u64 v[38:39], s[26:27], 0, v[44:45]
	v_lshlrev_b64 v[36:37], 1, v[36:37]
	v_lshl_add_u64 v[40:41], s[14:15], 0, v[36:37]
	v_mul_f32_e32 v2, 0xbfb8aa3b, v2
	v_mul_f32_e32 v7, 0xbfb8aa3b, v7
	v_mul_f32_e32 v3, 0xbfb8aa3b, v3
	v_exp_f32_e32 v4, v4
	v_exp_f32_e32 v0, v0
	v_exp_f32_e32 v5, v5
	v_exp_f32_e32 v1, v1
	v_exp_f32_e32 v6, v6
	v_exp_f32_e32 v2, v2
	v_exp_f32_e32 v7, v7
	v_exp_f32_e32 v3, v3
	v_add_f32_e32 v4, 1.0, v4
	v_add_f32_e32 v0, 1.0, v0
	v_add_f32_e32 v5, 1.0, v5
	v_add_f32_e32 v1, 1.0, v1
	v_add_f32_e32 v6, 1.0, v6
	v_add_f32_e32 v2, 1.0, v2
	v_add_f32_e32 v7, 1.0, v7
	v_add_f32_e32 v3, 1.0, v3
	v_rcp_f32_e32 v4, v4
	v_rcp_f32_e32 v0, v0
	v_rcp_f32_e32 v5, v5
	v_rcp_f32_e32 v1, v1
	v_rcp_f32_e32 v6, v6
	v_rcp_f32_e32 v2, v2
	v_rcp_f32_e32 v7, v7
	v_rcp_f32_e32 v3, v3
	s_waitcnt vmcnt(0)
	v_lshlrev_b32_e32 v42, 16, v32
	v_and_b32_e32 v32, 0xffff0000, v32
	v_lshlrev_b32_e32 v43, 16, v33
	v_and_b32_e32 v33, 0xffff0000, v33
	v_lshlrev_b32_e32 v44, 16, v34
	v_and_b32_e32 v34, 0xffff0000, v34
	v_lshlrev_b32_e32 v45, 16, v35
	v_and_b32_e32 v35, 0xffff0000, v35
	v_mul_f32_e32 v28, v28, v42
	v_mul_f32_e32 v42, v24, v44
	v_mul_f32_e32 v24, v29, v32
	v_mul_f32_e32 v29, v25, v34
	v_mul_f32_e32 v25, v30, v43
	v_mul_f32_e32 v30, v26, v45
	v_mul_f32_e32 v26, v31, v33
	v_mul_f32_e32 v27, v27, v35
	v_cvt_pk_bf16_f32 v24, v28, v24
	v_cvt_pk_bf16_f32 v25, v25, v26
	v_cvt_pk_bf16_f32 v26, v42, v29
	v_cvt_pk_bf16_f32 v27, v30, v27
	global_store_dwordx4 v[38:39], v[24:27], off sc1
	global_load_dwordx4 v[24:27], v[40:41], off
	v_lshl_add_u64 v[28:29], v[148:149], 0, v[92:93]
	v_lshl_add_u64 v[30:31], s[26:27], 0, v[36:37]
	v_lshlrev_b64 v[28:29], 1, v[28:29]
	v_lshl_add_u64 v[32:33], s[14:15], 0, v[28:29]
	s_waitcnt vmcnt(0)
	v_lshlrev_b32_e32 v34, 16, v24
	v_and_b32_e32 v24, 0xffff0000, v24
	v_lshlrev_b32_e32 v35, 16, v25
	v_and_b32_e32 v25, 0xffff0000, v25
	v_lshlrev_b32_e32 v36, 16, v26
	v_and_b32_e32 v26, 0xffff0000, v26
	v_lshlrev_b32_e32 v37, 16, v27
	v_and_b32_e32 v27, 0xffff0000, v27
	v_mul_f32_e32 v20, v20, v34
	v_mul_f32_e32 v34, v16, v36
	v_mul_f32_e32 v16, v21, v24
	v_mul_f32_e32 v21, v17, v26
	v_mul_f32_e32 v17, v22, v35
	v_mul_f32_e32 v22, v18, v37
	v_mul_f32_e32 v18, v23, v25
	v_mul_f32_e32 v19, v19, v27
	v_cvt_pk_bf16_f32 v16, v20, v16
	v_cvt_pk_bf16_f32 v17, v17, v18
	v_cvt_pk_bf16_f32 v18, v34, v21
	v_cvt_pk_bf16_f32 v19, v22, v19
	global_store_dwordx4 v[30:31], v[16:19], off sc1
	global_load_dwordx4 v[16:19], v[32:33], off
	v_lshl_add_u64 v[20:21], v[148:149], 0, v[84:85]
	v_lshl_add_u64 v[22:23], s[26:27], 0, v[28:29]
	v_lshlrev_b64 v[20:21], 1, v[20:21]
	v_lshl_add_u64 v[24:25], s[14:15], 0, v[20:21]
	s_waitcnt vmcnt(0)
	v_lshlrev_b32_e32 v26, 16, v16
	v_and_b32_e32 v16, 0xffff0000, v16
	v_lshlrev_b32_e32 v27, 16, v17
	v_and_b32_e32 v17, 0xffff0000, v17
	v_lshlrev_b32_e32 v28, 16, v18
	v_and_b32_e32 v18, 0xffff0000, v18
	v_lshlrev_b32_e32 v29, 16, v19
	v_and_b32_e32 v19, 0xffff0000, v19
	v_mul_f32_e32 v12, v12, v26
	v_mul_f32_e32 v26, v8, v28
	v_mul_f32_e32 v8, v13, v16
	v_mul_f32_e32 v13, v9, v18
	v_mul_f32_e32 v9, v14, v27
	v_mul_f32_e32 v14, v10, v29
	v_mul_f32_e32 v10, v15, v17
	v_mul_f32_e32 v11, v11, v19
	v_cvt_pk_bf16_f32 v8, v12, v8
	v_cvt_pk_bf16_f32 v9, v9, v10
	v_cvt_pk_bf16_f32 v10, v26, v13
	v_cvt_pk_bf16_f32 v11, v14, v11
	global_store_dwordx4 v[22:23], v[8:11], off sc1
	global_load_dwordx4 v[8:11], v[24:25], off
	s_waitcnt vmcnt(0)
	v_lshlrev_b32_e32 v12, 16, v8
	v_and_b32_e32 v8, 0xffff0000, v8
	v_lshlrev_b32_e32 v13, 16, v9
	v_and_b32_e32 v9, 0xffff0000, v9
	v_lshlrev_b32_e32 v14, 16, v10
	v_and_b32_e32 v10, 0xffff0000, v10
	v_lshlrev_b32_e32 v15, 16, v11
	v_and_b32_e32 v11, 0xffff0000, v11
	v_mul_f32_e32 v4, v4, v12
	v_mul_f32_e32 v12, v0, v14
	v_mul_f32_e32 v0, v5, v8
	v_mul_f32_e32 v5, v1, v10
	v_mul_f32_e32 v1, v6, v13
	v_mul_f32_e32 v6, v2, v15
	v_mul_f32_e32 v2, v7, v9
	v_mul_f32_e32 v3, v3, v11
	v_cvt_pk_bf16_f32 v0, v4, v0
	v_cvt_pk_bf16_f32 v1, v1, v2
	v_cvt_pk_bf16_f32 v2, v12, v5
	v_lshl_add_u64 v[4:5], s[26:27], 0, v[20:21]
	v_cvt_pk_bf16_f32 v3, v6, v3
	global_store_dwordx4 v[4:5], v[0:3], off sc1

; __device__ __forceinline__ u32x4 pack8(const f32x4 v0, const f32x4 v1) { u32x4 w; w.x = cvt_pk_bf16(v0[0], v0[1]); w.y = cvt_pk_bf16(v0[2], v0[3]); w.z = cvt_pk_bf16(v1[0], v1[1]); w.w = cvt_pk_bf16(v1[2], v1[3]); return w; }
; __device__ __forceinline__ void unpack8(const u32x4 w, f32x4& lo, f32x4& hi) { lo = (f32x4){bf_lo(w.x), bf_hi(w.x), bf_lo(w.y), bf_hi(w.y)}; hi = (f32x4){bf_lo(w.z), bf_hi(w.z), bf_lo(w.w), bf_hi(w.w)}; }
;     __device__ __forceinline__ void operator()(AccT& acc, const Unit& u, int wr, int wc, int fr, int fq) const {
;     ...
;             for (int m = 0; m < 4; ++m) { const size_t row = (size_t)(row0 + ai * 128 + m * 16);
; #pragma unroll
;                 for (int bj = 0; bj < 2; ++bj) { f32x4 p0, p1; unpack8(*(const u32x4*)(PROJ + row * DIN + 8192 + col0 + bj * 128), p0, p1);
; #pragma unroll
;                     for (int j = 0; j < 4; ++j) { p0[j] = fmaxf(p0[j], TINY); p1[j] = fmaxf(p1[j], TINY); }
;                     if (u.kind == 0) { f32x4 s0, s1; unpack8(*(const u32x4*)(PROJ + row * DIN + 4096 + col0 + bj * 128), s0, s1);
; #pragma unroll
;                         for (int j = 0; j < 4; ++j) { acc[ai][bj][m][0][j] *= s0[j] * __builtin_amdgcn_rcpf(p0[j]); acc[ai][bj][m][1][j] *= s1[j] * __builtin_amdgcn_rcpf(p1[j]); } }
;                     else *(u32x4*)(MG + row * DM + col0 + bj * 128) = pack8(acc[ai][bj][m][0] * p0, acc[ai][bj][m][1] * p1); } }
.LBB0_488:
	v_mov_b32_e32 v133, v254
	s_lshl_b32 s4, s66, 8
	v_lshrrev_b32_e32 v132, 1, v133
	v_and_or_b32 v132, v132, 24, s4
	v_and_or_b32 v133, v133, 15, s83
	v_or_b32_e32 v132, s84, v132
	v_lshl_add_u32 v134, s3, 8, v133
	v_mov_b64_e32 v[136:137], s[20:21]
	v_ashrrev_i32_e32 v133, 31, v132
	v_mad_i64_i32 v[136:137], s[4:5], v134, s78, v[136:137]
	v_lshl_add_u64 v[136:137], v[132:133], 1, v[136:137]
	v_add_co_u32_e32 v138, vcc, s77, v136
	v_ashrrev_i32_e32 v135, 31, v134
	s_nop 0
	v_addc_co_u32_e32 v139, vcc, 0, v137, vcc
	global_load_dwordx4 v[140:143], v[138:139], off
	s_cmp_lg_u32 s8, 0
	v_lshlrev_b64 v[138:139], 13, v[134:135]
	s_cselect_b64 s[16:17], -1, 0
	v_lshl_add_u64 v[138:139], s[26:27], 0, v[138:139]
	s_and_b64 vcc, exec, s[16:17]
	v_lshl_add_u64 v[138:139], v[132:133], 1, v[138:139]
	s_waitcnt vmcnt(0)
	v_lshlrev_b32_e32 v135, 16, v140
	v_and_b32_e32 v140, 0xffff0000, v140
	v_lshlrev_b32_e32 v144, 16, v141
	v_and_b32_e32 v141, 0xffff0000, v141
	v_lshlrev_b32_e32 v145, 16, v142
	v_and_b32_e32 v142, 0xffff0000, v142
	v_lshlrev_b32_e32 v146, 16, v143
	v_and_b32_e32 v143, 0xffff0000, v143
	v_max_f32_e32 v135, v135, v135
	v_max_f32_e32 v145, v145, v145
	v_max_f32_e32 v140, v140, v140
	v_max_f32_e32 v142, v142, v142
	v_max_f32_e32 v154, v144, v144
	v_max_f32_e32 v155, v146, v146
	v_max_f32_e32 v141, v141, v141
	v_max_f32_e32 v156, v143, v143
	v_max_f32_e32 v146, 0xda24260, v135
	v_max_f32_e32 v144, 0xda24260, v145
	v_max_f32_e32 v147, 0xda24260, v140
	v_max_f32_e32 v145, 0xda24260, v142
	v_max_f32_e32 v142, 0xda24260, v154
	v_max_f32_e32 v140, 0xda24260, v155
	v_max_f32_e32 v143, 0xda24260, v141
	v_max_f32_e32 v141, 0xda24260, v156
	s_cbranch_vccz .LBB0_541
	v_pk_mul_f32 v[156:157], v[126:127], v[142:143]
	v_pk_mul_f32 v[154:155], v[124:125], v[146:147]
	v_pk_mul_f32 v[158:159], v[122:123], v[140:141]
	v_pk_mul_f32 v[160:161], v[120:121], v[144:145]
	v_cvt_pk_bf16_f32 v154, v154, v155
	v_cvt_pk_bf16_f32 v155, v156, v157
	s_nop 0
	v_cvt_pk_bf16_f32 v156, v160, v161
	v_cvt_pk_bf16_f32 v157, v158, v159
	global_store_dwordx4 v[138:139], v[154:157], off sc1
	s_cbranch_execnz .LBB0_491

; __device__ __forceinline__ u32x4 pack8(const f32x4 v0, const f32x4 v1) { u32x4 w; w.x = cvt_pk_bf16(v0[0], v0[1]); w.y = cvt_pk_bf16(v0[2], v0[3]); w.z = cvt_pk_bf16(v1[0], v1[1]); w.w = cvt_pk_bf16(v1[2], v1[3]); return w; }
; __device__ __forceinline__ void unpack8(const u32x4 w, f32x4& lo, f32x4& hi) { lo = (f32x4){bf_lo(w.x), bf_hi(w.x), bf_lo(w.y), bf_hi(w.y)}; hi = (f32x4){bf_lo(w.z), bf_hi(w.z), bf_lo(w.w), bf_hi(w.w)}; }
;     __device__ __forceinline__ void operator()(AccT& acc, const Unit& u, int wr, int wc, int fr, int fq) const {
;     ...
;             for (int m = 0; m < 4; ++m) { const size_t row = (size_t)(row0 + ai * 128 + m * 16);
; #pragma unroll
;                 for (int bj = 0; bj < 2; ++bj) { f32x4 p0, p1; unpack8(*(const u32x4*)(PROJ + row * DIN + 8192 + col0 + bj * 128), p0, p1);
; #pragma unroll
;                     for (int j = 0; j < 4; ++j) { p0[j] = fmaxf(p0[j], TINY); p1[j] = fmaxf(p1[j], TINY); }
;                     if (u.kind == 0) { f32x4 s0, s1; unpack8(*(const u32x4*)(PROJ + row * DIN + 4096 + col0 + bj * 128), s0, s1);
; #pragma unroll
;                         for (int j = 0; j < 4; ++j) { acc[ai][bj][m][0][j] *= s0[j] * __builtin_amdgcn_rcpf(p0[j]); acc[ai][bj][m][1][j] *= s1[j] * __builtin_amdgcn_rcpf(p1[j]); } }
;                     else *(u32x4*)(MG + row * DM + col0 + bj * 128) = pack8(acc[ai][bj][m][0] * p0, acc[ai][bj][m][1] * p1); } }
.LBB0_491:
	v_add_co_u32_e32 v140, vcc, 0x4000, v136
	v_cndmask_b32_e64 v135, 0, 1, s[16:17]
	s_nop 0
	v_addc_co_u32_e32 v141, vcc, 0, v137, vcc
	global_load_dwordx4 v[140:143], v[140:141], off offset:256
	v_cmp_ne_u32_e64 s[4:5], 1, v135
	s_andn2_b64 vcc, exec, s[16:17]
	s_waitcnt vmcnt(0)
	v_lshlrev_b32_e32 v135, 16, v140
	v_and_b32_e32 v140, 0xffff0000, v140
	v_lshlrev_b32_e32 v144, 16, v141
	v_and_b32_e32 v141, 0xffff0000, v141
	v_lshlrev_b32_e32 v145, 16, v142
	v_and_b32_e32 v142, 0xffff0000, v142
	v_lshlrev_b32_e32 v146, 16, v143
	v_and_b32_e32 v143, 0xffff0000, v143
	v_max_f32_e32 v135, v135, v135
	v_max_f32_e32 v145, v145, v145
	v_max_f32_e32 v140, v140, v140
	v_max_f32_e32 v142, v142, v142
	v_max_f32_e32 v154, v144, v144
	v_max_f32_e32 v155, v146, v146
	v_max_f32_e32 v141, v141, v141
	v_max_f32_e32 v156, v143, v143
	v_max_f32_e32 v146, 0xda24260, v135
	v_max_f32_e32 v144, 0xda24260, v145
	v_max_f32_e32 v147, 0xda24260, v140
	v_max_f32_e32 v145, 0xda24260, v142
	v_max_f32_e32 v142, 0xda24260, v154
	v_max_f32_e32 v140, 0xda24260, v155
	v_max_f32_e32 v143, 0xda24260, v141
	v_max_f32_e32 v141, 0xda24260, v156
	s_cbranch_vccnz .LBB0_542
	v_pk_mul_f32 v[156:157], v[94:95], v[142:143]
	v_pk_mul_f32 v[154:155], v[92:93], v[146:147]
	v_pk_mul_f32 v[158:159], v[90:91], v[140:141]
	v_pk_mul_f32 v[160:161], v[88:89], v[144:145]
	v_cvt_pk_bf16_f32 v154, v154, v155
	v_cvt_pk_bf16_f32 v155, v156, v157
	s_nop 0
	v_cvt_pk_bf16_f32 v156, v160, v161
	v_cvt_pk_bf16_f32 v157, v158, v159
	global_store_dwordx4 v[138:139], v[154:157], off offset:256 sc1
	s_cbranch_execnz .LBB0_494

; __device__ __forceinline__ u32x4 pack8(const f32x4 v0, const f32x4 v1) { u32x4 w; w.x = cvt_pk_bf16(v0[0], v0[1]); w.y = cvt_pk_bf16(v0[2], v0[3]); w.z = cvt_pk_bf16(v1[0], v1[1]); w.w = cvt_pk_bf16(v1[2], v1[3]); return w; }
; __device__ __forceinline__ void unpack8(const u32x4 w, f32x4& lo, f32x4& hi) { lo = (f32x4){bf_lo(w.x), bf_hi(w.x), bf_lo(w.y), bf_hi(w.y)}; hi = (f32x4){bf_lo(w.z), bf_hi(w.z), bf_lo(w.w), bf_hi(w.w)}; }
;     __device__ __forceinline__ void operator()(AccT& acc, const Unit& u, int wr, int wc, int fr, int fq) const {
;     ...
;             for (int m = 0; m < 4; ++m) { const size_t row = (size_t)(row0 + ai * 128 + m * 16);
; #pragma unroll
;                 for (int bj = 0; bj < 2; ++bj) { f32x4 p0, p1; unpack8(*(const u32x4*)(PROJ + row * DIN + 8192 + col0 + bj * 128), p0, p1);
; #pragma unroll
;                     for (int j = 0; j < 4; ++j) { p0[j] = fmaxf(p0[j], TINY); p1[j] = fmaxf(p1[j], TINY); }
;                     if (u.kind == 0) { f32x4 s0, s1; unpack8(*(const u32x4*)(PROJ + row * DIN + 4096 + col0 + bj * 128), s0, s1);
; #pragma unroll
;                         for (int j = 0; j < 4; ++j) { acc[ai][bj][m][0][j] *= s0[j] * __builtin_amdgcn_rcpf(p0[j]); acc[ai][bj][m][1][j] *= s1[j] * __builtin_amdgcn_rcpf(p1[j]); } }
;                     else *(u32x4*)(MG + row * DM + col0 + bj * 128) = pack8(acc[ai][bj][m][0] * p0, acc[ai][bj][m][1] * p1); } }
.LBB0_494:
	v_or_b32_e32 v142, 16, v134
	v_mov_b64_e32 v[136:137], s[20:21]
	v_mad_i64_i32 v[136:137], s[8:9], v142, s78, v[136:137]
	v_lshl_add_u64 v[136:137], v[132:133], 1, v[136:137]
	v_add_co_u32_e32 v138, vcc, 0x4000, v136
	v_ashrrev_i32_e32 v143, 31, v142
	s_nop 0
	v_addc_co_u32_e32 v139, vcc, 0, v137, vcc
	global_load_dwordx4 v[138:141], v[138:139], off
	v_lshlrev_b64 v[142:143], 13, v[142:143]
	v_lshl_add_u64 v[154:155], s[26:27], 0, v[142:143]
	s_and_b64 vcc, exec, s[4:5]
	s_waitcnt vmcnt(0)
	v_lshlrev_b32_e32 v135, 16, v138
	v_and_b32_e32 v138, 0xffff0000, v138
	v_lshlrev_b32_e32 v142, 16, v139
	v_and_b32_e32 v139, 0xffff0000, v139
	v_lshlrev_b32_e32 v143, 16, v140
	v_and_b32_e32 v140, 0xffff0000, v140
	v_lshlrev_b32_e32 v144, 16, v141
	v_and_b32_e32 v141, 0xffff0000, v141
	v_max_f32_e32 v135, v135, v135
	v_max_f32_e32 v143, v143, v143
	v_max_f32_e32 v138, v138, v138
	v_max_f32_e32 v140, v140, v140
	v_max_f32_e32 v142, v142, v142
	v_max_f32_e32 v156, v144, v144
	v_max_f32_e32 v139, v139, v139
	v_max_f32_e32 v141, v141, v141
	v_max_f32_e32 v146, 0xda24260, v135
	v_max_f32_e32 v144, 0xda24260, v143
	v_max_f32_e32 v147, 0xda24260, v138
	v_max_f32_e32 v145, 0xda24260, v140
	v_max_f32_e32 v142, 0xda24260, v142
	v_max_f32_e32 v140, 0xda24260, v156
	v_max_f32_e32 v143, 0xda24260, v139
	v_max_f32_e32 v141, 0xda24260, v141
	v_lshl_add_u64 v[138:139], v[132:133], 1, v[154:155]
	s_cbranch_vccnz .LBB0_543
	v_pk_mul_f32 v[156:157], v[118:119], v[142:143]
	v_pk_mul_f32 v[154:155], v[116:117], v[146:147]
	v_pk_mul_f32 v[158:159], v[114:115], v[140:141]
	v_pk_mul_f32 v[160:161], v[112:113], v[144:145]
	v_cvt_pk_bf16_f32 v154, v154, v155
	v_cvt_pk_bf16_f32 v155, v156, v157
	s_nop 0
	v_cvt_pk_bf16_f32 v156, v160, v161
	v_cvt_pk_bf16_f32 v157, v158, v159
	global_store_dwordx4 v[138:139], v[154:157], off sc1
	s_cbranch_execnz .LBB0_497

; __device__ __forceinline__ u32x4 pack8(const f32x4 v0, const f32x4 v1) { u32x4 w; w.x = cvt_pk_bf16(v0[0], v0[1]); w.y = cvt_pk_bf16(v0[2], v0[3]); w.z = cvt_pk_bf16(v1[0], v1[1]); w.w = cvt_pk_bf16(v1[2], v1[3]); return w; }
; __device__ __forceinline__ void unpack8(const u32x4 w, f32x4& lo, f32x4& hi) { lo = (f32x4){bf_lo(w.x), bf_hi(w.x), bf_lo(w.y), bf_hi(w.y)}; hi = (f32x4){bf_lo(w.z), bf_hi(w.z), bf_lo(w.w), bf_hi(w.w)}; }
;     __device__ __forceinline__ void operator()(AccT& acc, const Unit& u, int wr, int wc, int fr, int fq) const {
;     ...
;             for (int m = 0; m < 4; ++m) { const size_t row = (size_t)(row0 + ai * 128 + m * 16);
; #pragma unroll
;                 for (int bj = 0; bj < 2; ++bj) { f32x4 p0, p1; unpack8(*(const u32x4*)(PROJ + row * DIN + 8192 + col0 + bj * 128), p0, p1);
; #pragma unroll
;                     for (int j = 0; j < 4; ++j) { p0[j] = fmaxf(p0[j], TINY); p1[j] = fmaxf(p1[j], TINY); }
;                     if (u.kind == 0) { f32x4 s0, s1; unpack8(*(const u32x4*)(PROJ + row * DIN + 4096 + col0 + bj * 128), s0, s1);
; #pragma unroll
;                         for (int j = 0; j < 4; ++j) { acc[ai][bj][m][0][j] *= s0[j] * __builtin_amdgcn_rcpf(p0[j]); acc[ai][bj][m][1][j] *= s1[j] * __builtin_amdgcn_rcpf(p1[j]); } }
;                     else *(u32x4*)(MG + row * DM + col0 + bj * 128) = pack8(acc[ai][bj][m][0] * p0, acc[ai][bj][m][1] * p1); } }
.LBB0_497:
	v_add_co_u32_e32 v140, vcc, 0x4000, v136
	s_nop 1
	v_addc_co_u32_e32 v141, vcc, 0, v137, vcc
	global_load_dwordx4 v[140:143], v[140:141], off offset:256
	s_and_b64 vcc, exec, s[4:5]
	s_waitcnt vmcnt(0)
	v_lshlrev_b32_e32 v135, 16, v140
	v_and_b32_e32 v140, 0xffff0000, v140
	v_lshlrev_b32_e32 v144, 16, v141
	v_and_b32_e32 v141, 0xffff0000, v141
	v_lshlrev_b32_e32 v145, 16, v142
	v_and_b32_e32 v142, 0xffff0000, v142
	v_lshlrev_b32_e32 v146, 16, v143
	v_and_b32_e32 v143, 0xffff0000, v143
	v_max_f32_e32 v135, v135, v135
	v_max_f32_e32 v145, v145, v145
	v_max_f32_e32 v140, v140, v140
	v_max_f32_e32 v142, v142, v142
	v_max_f32_e32 v154, v144, v144
	v_max_f32_e32 v155, v146, v146
	v_max_f32_e32 v141, v141, v141
	v_max_f32_e32 v156, v143, v143
	v_max_f32_e32 v146, 0xda24260, v135
	v_max_f32_e32 v144, 0xda24260, v145
	v_max_f32_e32 v147, 0xda24260, v140
	v_max_f32_e32 v145, 0xda24260, v142
	v_max_f32_e32 v142, 0xda24260, v154
	v_max_f32_e32 v140, 0xda24260, v155
	v_max_f32_e32 v143, 0xda24260, v141
	v_max_f32_e32 v141, 0xda24260, v156
	s_cbranch_vccnz .LBB0_544
	v_pk_mul_f32 v[156:157], v[86:87], v[142:143]
	v_pk_mul_f32 v[154:155], v[84:85], v[146:147]
	v_pk_mul_f32 v[158:159], v[82:83], v[140:141]
	v_pk_mul_f32 v[160:161], v[80:81], v[144:145]
	v_cvt_pk_bf16_f32 v154, v154, v155
	v_cvt_pk_bf16_f32 v155, v156, v157
	s_nop 0
	v_cvt_pk_bf16_f32 v156, v160, v161
	v_cvt_pk_bf16_f32 v157, v158, v159
	global_store_dwordx4 v[138:139], v[154:157], off offset:256 sc1
	s_cbranch_execnz .LBB0_500

; __device__ __forceinline__ u32x4 pack8(const f32x4 v0, const f32x4 v1) { u32x4 w; w.x = cvt_pk_bf16(v0[0], v0[1]); w.y = cvt_pk_bf16(v0[2], v0[3]); w.z = cvt_pk_bf16(v1[0], v1[1]); w.w = cvt_pk_bf16(v1[2], v1[3]); return w; }
; __device__ __forceinline__ void unpack8(const u32x4 w, f32x4& lo, f32x4& hi) { lo = (f32x4){bf_lo(w.x), bf_hi(w.x), bf_lo(w.y), bf_hi(w.y)}; hi = (f32x4){bf_lo(w.z), bf_hi(w.z), bf_lo(w.w), bf_hi(w.w)}; }
;     __device__ __forceinline__ void operator()(AccT& acc, const Unit& u, int wr, int wc, int fr, int fq) const {
;     ...
;             for (int m = 0; m < 4; ++m) { const size_t row = (size_t)(row0 + ai * 128 + m * 16);
; #pragma unroll
;                 for (int bj = 0; bj < 2; ++bj) { f32x4 p0, p1; unpack8(*(const u32x4*)(PROJ + row * DIN + 8192 + col0 + bj * 128), p0, p1);
; #pragma unroll
;                     for (int j = 0; j < 4; ++j) { p0[j] = fmaxf(p0[j], TINY); p1[j] = fmaxf(p1[j], TINY); }
;                     if (u.kind == 0) { f32x4 s0, s1; unpack8(*(const u32x4*)(PROJ + row * DIN + 4096 + col0 + bj * 128), s0, s1);
; #pragma unroll
;                         for (int j = 0; j < 4; ++j) { acc[ai][bj][m][0][j] *= s0[j] * __builtin_amdgcn_rcpf(p0[j]); acc[ai][bj][m][1][j] *= s1[j] * __builtin_amdgcn_rcpf(p1[j]); } }
;                     else *(u32x4*)(MG + row * DM + col0 + bj * 128) = pack8(acc[ai][bj][m][0] * p0, acc[ai][bj][m][1] * p1); } }
.LBB0_500:
	v_or_b32_e32 v142, 32, v134
	v_mov_b64_e32 v[136:137], s[20:21]
	v_mad_i64_i32 v[136:137], s[8:9], v142, s78, v[136:137]
	v_lshl_add_u64 v[136:137], v[132:133], 1, v[136:137]
	v_add_co_u32_e32 v138, vcc, 0x4000, v136
	v_ashrrev_i32_e32 v143, 31, v142
	s_nop 0
	v_addc_co_u32_e32 v139, vcc, 0, v137, vcc
	global_load_dwordx4 v[138:141], v[138:139], off
	v_lshlrev_b64 v[142:143], 13, v[142:143]
	v_lshl_add_u64 v[154:155], s[26:27], 0, v[142:143]
	s_and_b64 vcc, exec, s[4:5]
	s_waitcnt vmcnt(0)
	v_lshlrev_b32_e32 v135, 16, v138
	v_and_b32_e32 v138, 0xffff0000, v138
	v_lshlrev_b32_e32 v142, 16, v139
	v_and_b32_e32 v139, 0xffff0000, v139
	v_lshlrev_b32_e32 v143, 16, v140
	v_and_b32_e32 v140, 0xffff0000, v140
	v_lshlrev_b32_e32 v144, 16, v141
	v_and_b32_e32 v141, 0xffff0000, v141
	v_max_f32_e32 v135, v135, v135
	v_max_f32_e32 v143, v143, v143
	v_max_f32_e32 v138, v138, v138
	v_max_f32_e32 v140, v140, v140
	v_max_f32_e32 v142, v142, v142
	v_max_f32_e32 v156, v144, v144
	v_max_f32_e32 v139, v139, v139
	v_max_f32_e32 v141, v141, v141
	v_max_f32_e32 v146, 0xda24260, v135
	v_max_f32_e32 v144, 0xda24260, v143
	v_max_f32_e32 v147, 0xda24260, v138
	v_max_f32_e32 v145, 0xda24260, v140
	v_max_f32_e32 v142, 0xda24260, v142
	v_max_f32_e32 v140, 0xda24260, v156
	v_max_f32_e32 v143, 0xda24260, v139
	v_max_f32_e32 v141, 0xda24260, v141
	v_lshl_add_u64 v[138:139], v[132:133], 1, v[154:155]
	s_cbranch_vccnz .LBB0_545
	v_pk_mul_f32 v[156:157], v[110:111], v[142:143]
	v_pk_mul_f32 v[154:155], v[108:109], v[146:147]
	v_pk_mul_f32 v[158:159], v[106:107], v[140:141]
	v_pk_mul_f32 v[160:161], v[104:105], v[144:145]
	v_cvt_pk_bf16_f32 v154, v154, v155
	v_cvt_pk_bf16_f32 v155, v156, v157
	s_nop 0
	v_cvt_pk_bf16_f32 v156, v160, v161
	v_cvt_pk_bf16_f32 v157, v158, v159
	global_store_dwordx4 v[138:139], v[154:157], off sc1
	s_cbranch_execnz .LBB0_503

; __device__ __forceinline__ u32x4 pack8(const f32x4 v0, const f32x4 v1) { u32x4 w; w.x = cvt_pk_bf16(v0[0], v0[1]); w.y = cvt_pk_bf16(v0[2], v0[3]); w.z = cvt_pk_bf16(v1[0], v1[1]); w.w = cvt_pk_bf16(v1[2], v1[3]); return w; }
; __device__ __forceinline__ void unpack8(const u32x4 w, f32x4& lo, f32x4& hi) { lo = (f32x4){bf_lo(w.x), bf_hi(w.x), bf_lo(w.y), bf_hi(w.y)}; hi = (f32x4){bf_lo(w.z), bf_hi(w.z), bf_lo(w.w), bf_hi(w.w)}; }
;     __device__ __forceinline__ void operator()(AccT& acc, const Unit& u, int wr, int wc, int fr, int fq) const {
;     ...
;             for (int m = 0; m < 4; ++m) { const size_t row = (size_t)(row0 + ai * 128 + m * 16);
; #pragma unroll
;                 for (int bj = 0; bj < 2; ++bj) { f32x4 p0, p1; unpack8(*(const u32x4*)(PROJ + row * DIN + 8192 + col0 + bj * 128), p0, p1);
; #pragma unroll
;                     for (int j = 0; j < 4; ++j) { p0[j] = fmaxf(p0[j], TINY); p1[j] = fmaxf(p1[j], TINY); }
;                     if (u.kind == 0) { f32x4 s0, s1; unpack8(*(const u32x4*)(PROJ + row * DIN + 4096 + col0 + bj * 128), s0, s1);
; #pragma unroll
;                         for (int j = 0; j < 4; ++j) { acc[ai][bj][m][0][j] *= s0[j] * __builtin_amdgcn_rcpf(p0[j]); acc[ai][bj][m][1][j] *= s1[j] * __builtin_amdgcn_rcpf(p1[j]); } }
;                     else *(u32x4*)(MG + row * DM + col0 + bj * 128) = pack8(acc[ai][bj][m][0] * p0, acc[ai][bj][m][1] * p1); } }
.LBB0_503:
	v_add_co_u32_e32 v140, vcc, 0x4000, v136
	s_nop 1
	v_addc_co_u32_e32 v141, vcc, 0, v137, vcc
	global_load_dwordx4 v[140:143], v[140:141], off offset:256
	s_and_b64 vcc, exec, s[4:5]
	s_waitcnt vmcnt(0)
	v_lshlrev_b32_e32 v135, 16, v140
	v_and_b32_e32 v140, 0xffff0000, v140
	v_lshlrev_b32_e32 v144, 16, v141
	v_and_b32_e32 v141, 0xffff0000, v141
	v_lshlrev_b32_e32 v145, 16, v142
	v_and_b32_e32 v142, 0xffff0000, v142
	v_lshlrev_b32_e32 v146, 16, v143
	v_and_b32_e32 v143, 0xffff0000, v143
	v_max_f32_e32 v135, v135, v135
	v_max_f32_e32 v145, v145, v145
	v_max_f32_e32 v140, v140, v140
	v_max_f32_e32 v142, v142, v142
	v_max_f32_e32 v154, v144, v144
	v_max_f32_e32 v155, v146, v146
	v_max_f32_e32 v141, v141, v141
	v_max_f32_e32 v156, v143, v143
	v_max_f32_e32 v146, 0xda24260, v135
	v_max_f32_e32 v144, 0xda24260, v145
	v_max_f32_e32 v147, 0xda24260, v140
	v_max_f32_e32 v145, 0xda24260, v142
	v_max_f32_e32 v142, 0xda24260, v154
	v_max_f32_e32 v140, 0xda24260, v155
	v_max_f32_e32 v143, 0xda24260, v141
	v_max_f32_e32 v141, 0xda24260, v156
	s_cbranch_vccnz .LBB0_546
	v_pk_mul_f32 v[156:157], v[78:79], v[142:143]
	v_pk_mul_f32 v[154:155], v[76:77], v[146:147]
	v_pk_mul_f32 v[158:159], v[74:75], v[140:141]
	v_pk_mul_f32 v[160:161], v[72:73], v[144:145]
	v_cvt_pk_bf16_f32 v154, v154, v155
	v_cvt_pk_bf16_f32 v155, v156, v157
	s_nop 0
	v_cvt_pk_bf16_f32 v156, v160, v161
	v_cvt_pk_bf16_f32 v157, v158, v159
	global_store_dwordx4 v[138:139], v[154:157], off offset:256 sc1
	s_cbranch_execnz .LBB0_506

; __device__ __forceinline__ u32x4 pack8(const f32x4 v0, const f32x4 v1) { u32x4 w; w.x = cvt_pk_bf16(v0[0], v0[1]); w.y = cvt_pk_bf16(v0[2], v0[3]); w.z = cvt_pk_bf16(v1[0], v1[1]); w.w = cvt_pk_bf16(v1[2], v1[3]); return w; }
; __device__ __forceinline__ void unpack8(const u32x4 w, f32x4& lo, f32x4& hi) { lo = (f32x4){bf_lo(w.x), bf_hi(w.x), bf_lo(w.y), bf_hi(w.y)}; hi = (f32x4){bf_lo(w.z), bf_hi(w.z), bf_lo(w.w), bf_hi(w.w)}; }
;     __device__ __forceinline__ void operator()(AccT& acc, const Unit& u, int wr, int wc, int fr, int fq) const {
;     ...
;             for (int m = 0; m < 4; ++m) { const size_t row = (size_t)(row0 + ai * 128 + m * 16);
; #pragma unroll
;                 for (int bj = 0; bj < 2; ++bj) { f32x4 p0, p1; unpack8(*(const u32x4*)(PROJ + row * DIN + 8192 + col0 + bj * 128), p0, p1);
; #pragma unroll
;                     for (int j = 0; j < 4; ++j) { p0[j] = fmaxf(p0[j], TINY); p1[j] = fmaxf(p1[j], TINY); }
;                     if (u.kind == 0) { f32x4 s0, s1; unpack8(*(const u32x4*)(PROJ + row * DIN + 4096 + col0 + bj * 128), s0, s1);
; #pragma unroll
;                         for (int j = 0; j < 4; ++j) { acc[ai][bj][m][0][j] *= s0[j] * __builtin_amdgcn_rcpf(p0[j]); acc[ai][bj][m][1][j] *= s1[j] * __builtin_amdgcn_rcpf(p1[j]); } }
;                     else *(u32x4*)(MG + row * DM + col0 + bj * 128) = pack8(acc[ai][bj][m][0] * p0, acc[ai][bj][m][1] * p1); } }
.LBB0_506:
	v_or_b32_e32 v142, 48, v134
	v_mov_b64_e32 v[136:137], s[20:21]
	v_mad_i64_i32 v[136:137], s[8:9], v142, s78, v[136:137]
	v_lshl_add_u64 v[136:137], v[132:133], 1, v[136:137]
	v_add_co_u32_e32 v138, vcc, 0x4000, v136
	v_ashrrev_i32_e32 v143, 31, v142
	s_nop 0
	v_addc_co_u32_e32 v139, vcc, 0, v137, vcc
	global_load_dwordx4 v[138:141], v[138:139], off
	v_lshlrev_b64 v[142:143], 13, v[142:143]
	v_lshl_add_u64 v[154:155], s[26:27], 0, v[142:143]
	s_and_b64 vcc, exec, s[4:5]
	s_waitcnt vmcnt(0)
	v_lshlrev_b32_e32 v135, 16, v138
	v_and_b32_e32 v138, 0xffff0000, v138
	v_lshlrev_b32_e32 v142, 16, v139
	v_and_b32_e32 v139, 0xffff0000, v139
	v_lshlrev_b32_e32 v143, 16, v140
	v_and_b32_e32 v140, 0xffff0000, v140
	v_lshlrev_b32_e32 v144, 16, v141
	v_and_b32_e32 v141, 0xffff0000, v141
	v_max_f32_e32 v135, v135, v135
	v_max_f32_e32 v143, v143, v143
	v_max_f32_e32 v138, v138, v138
	v_max_f32_e32 v140, v140, v140
	v_max_f32_e32 v142, v142, v142
	v_max_f32_e32 v156, v144, v144
	v_max_f32_e32 v139, v139, v139
	v_max_f32_e32 v141, v141, v141
	v_max_f32_e32 v146, 0xda24260, v135
	v_max_f32_e32 v144, 0xda24260, v143
	v_max_f32_e32 v147, 0xda24260, v138
	v_max_f32_e32 v145, 0xda24260, v140
	v_max_f32_e32 v142, 0xda24260, v142
	v_max_f32_e32 v140, 0xda24260, v156
	v_max_f32_e32 v143, 0xda24260, v139
	v_max_f32_e32 v141, 0xda24260, v141
	v_lshl_add_u64 v[138:139], v[132:133], 1, v[154:155]
	s_cbranch_vccnz .LBB0_547
	v_pk_mul_f32 v[156:157], v[102:103], v[142:143]
	v_pk_mul_f32 v[154:155], v[100:101], v[146:147]
	v_pk_mul_f32 v[158:159], v[98:99], v[140:141]
	v_pk_mul_f32 v[160:161], v[96:97], v[144:145]
	v_cvt_pk_bf16_f32 v154, v154, v155
	v_cvt_pk_bf16_f32 v155, v156, v157
	s_nop 0
	v_cvt_pk_bf16_f32 v156, v160, v161
	v_cvt_pk_bf16_f32 v157, v158, v159
	global_store_dwordx4 v[138:139], v[154:157], off sc1
	s_cbranch_execnz .LBB0_509

; __device__ __forceinline__ u32x4 pack8(const f32x4 v0, const f32x4 v1) { u32x4 w; w.x = cvt_pk_bf16(v0[0], v0[1]); w.y = cvt_pk_bf16(v0[2], v0[3]); w.z = cvt_pk_bf16(v1[0], v1[1]); w.w = cvt_pk_bf16(v1[2], v1[3]); return w; }
; __device__ __forceinline__ void unpack8(const u32x4 w, f32x4& lo, f32x4& hi) { lo = (f32x4){bf_lo(w.x), bf_hi(w.x), bf_lo(w.y), bf_hi(w.y)}; hi = (f32x4){bf_lo(w.z), bf_hi(w.z), bf_lo(w.w), bf_hi(w.w)}; }
;     __device__ __forceinline__ void operator()(AccT& acc, const Unit& u, int wr, int wc, int fr, int fq) const {
;     ...
;             for (int m = 0; m < 4; ++m) { const size_t row = (size_t)(row0 + ai * 128 + m * 16);
; #pragma unroll
;                 for (int bj = 0; bj < 2; ++bj) { f32x4 p0, p1; unpack8(*(const u32x4*)(PROJ + row * DIN + 8192 + col0 + bj * 128), p0, p1);
; #pragma unroll
;                     for (int j = 0; j < 4; ++j) { p0[j] = fmaxf(p0[j], TINY); p1[j] = fmaxf(p1[j], TINY); }
;                     if (u.kind == 0) { f32x4 s0, s1; unpack8(*(const u32x4*)(PROJ + row * DIN + 4096 + col0 + bj * 128), s0, s1);
; #pragma unroll
;                         for (int j = 0; j < 4; ++j) { acc[ai][bj][m][0][j] *= s0[j] * __builtin_amdgcn_rcpf(p0[j]); acc[ai][bj][m][1][j] *= s1[j] * __builtin_amdgcn_rcpf(p1[j]); } }
;                     else *(u32x4*)(MG + row * DM + col0 + bj * 128) = pack8(acc[ai][bj][m][0] * p0, acc[ai][bj][m][1] * p1); } }
.LBB0_509:
	v_add_co_u32_e32 v140, vcc, 0x4000, v136
	s_nop 1
	v_addc_co_u32_e32 v141, vcc, 0, v137, vcc
	global_load_dwordx4 v[140:143], v[140:141], off offset:256
	s_and_b64 vcc, exec, s[4:5]
	s_waitcnt vmcnt(0)
	v_lshlrev_b32_e32 v135, 16, v140
	v_and_b32_e32 v140, 0xffff0000, v140
	v_lshlrev_b32_e32 v144, 16, v141
	v_and_b32_e32 v141, 0xffff0000, v141
	v_lshlrev_b32_e32 v145, 16, v142
	v_and_b32_e32 v142, 0xffff0000, v142
	v_lshlrev_b32_e32 v146, 16, v143
	v_and_b32_e32 v143, 0xffff0000, v143
	v_max_f32_e32 v135, v135, v135
	v_max_f32_e32 v145, v145, v145
	v_max_f32_e32 v140, v140, v140
	v_max_f32_e32 v142, v142, v142
	v_max_f32_e32 v154, v144, v144
	v_max_f32_e32 v155, v146, v146
	v_max_f32_e32 v141, v141, v141
	v_max_f32_e32 v156, v143, v143
	v_max_f32_e32 v146, 0xda24260, v135
	v_max_f32_e32 v144, 0xda24260, v145
	v_max_f32_e32 v147, 0xda24260, v140
	v_max_f32_e32 v145, 0xda24260, v142
	v_max_f32_e32 v142, 0xda24260, v154
	v_max_f32_e32 v140, 0xda24260, v155
	v_max_f32_e32 v143, 0xda24260, v141
	v_max_f32_e32 v141, 0xda24260, v156
	s_cbranch_vccnz .LBB0_548
	v_pk_mul_f32 v[156:157], v[70:71], v[142:143]
	v_pk_mul_f32 v[154:155], v[68:69], v[146:147]
	v_pk_mul_f32 v[158:159], v[66:67], v[140:141]
	v_pk_mul_f32 v[160:161], v[64:65], v[144:145]
	v_cvt_pk_bf16_f32 v154, v154, v155
	v_cvt_pk_bf16_f32 v155, v156, v157
	s_nop 0
	v_cvt_pk_bf16_f32 v156, v160, v161
	v_cvt_pk_bf16_f32 v157, v158, v159
	global_store_dwordx4 v[138:139], v[154:157], off offset:256 sc1
	s_cbranch_execnz .LBB0_512

; __device__ __forceinline__ u32x4 pack8(const f32x4 v0, const f32x4 v1) { u32x4 w; w.x = cvt_pk_bf16(v0[0], v0[1]); w.y = cvt_pk_bf16(v0[2], v0[3]); w.z = cvt_pk_bf16(v1[0], v1[1]); w.w = cvt_pk_bf16(v1[2], v1[3]); return w; }
; __device__ __forceinline__ void unpack8(const u32x4 w, f32x4& lo, f32x4& hi) { lo = (f32x4){bf_lo(w.x), bf_hi(w.x), bf_lo(w.y), bf_hi(w.y)}; hi = (f32x4){bf_lo(w.z), bf_hi(w.z), bf_lo(w.w), bf_hi(w.w)}; }
;     __device__ __forceinline__ void operator()(AccT& acc, const Unit& u, int wr, int wc, int fr, int fq) const {
;     ...
;             for (int m = 0; m < 4; ++m) { const size_t row = (size_t)(row0 + ai * 128 + m * 16);
; #pragma unroll
;                 for (int bj = 0; bj < 2; ++bj) { f32x4 p0, p1; unpack8(*(const u32x4*)(PROJ + row * DIN + 8192 + col0 + bj * 128), p0, p1);
; #pragma unroll
;                     for (int j = 0; j < 4; ++j) { p0[j] = fmaxf(p0[j], TINY); p1[j] = fmaxf(p1[j], TINY); }
;                     if (u.kind == 0) { f32x4 s0, s1; unpack8(*(const u32x4*)(PROJ + row * DIN + 4096 + col0 + bj * 128), s0, s1);
; #pragma unroll
;                         for (int j = 0; j < 4; ++j) { acc[ai][bj][m][0][j] *= s0[j] * __builtin_amdgcn_rcpf(p0[j]); acc[ai][bj][m][1][j] *= s1[j] * __builtin_amdgcn_rcpf(p1[j]); } }
;                     else *(u32x4*)(MG + row * DM + col0 + bj * 128) = pack8(acc[ai][bj][m][0] * p0, acc[ai][bj][m][1] * p1); } }
.LBB0_512:
	v_add_u32_e32 v142, 0x80, v134
	v_mov_b64_e32 v[136:137], s[20:21]
	v_mad_i64_i32 v[136:137], s[8:9], v142, s78, v[136:137]
	v_lshl_add_u64 v[136:137], v[132:133], 1, v[136:137]
	v_add_co_u32_e32 v138, vcc, 0x4000, v136
	v_ashrrev_i32_e32 v143, 31, v142
	s_nop 0
	v_addc_co_u32_e32 v139, vcc, 0, v137, vcc
	global_load_dwordx4 v[138:141], v[138:139], off
	v_lshlrev_b64 v[142:143], 13, v[142:143]
	v_lshl_add_u64 v[154:155], s[26:27], 0, v[142:143]
	s_and_b64 vcc, exec, s[4:5]
	s_waitcnt vmcnt(0)
	v_lshlrev_b32_e32 v135, 16, v138
	v_and_b32_e32 v138, 0xffff0000, v138
	v_lshlrev_b32_e32 v142, 16, v139
	v_and_b32_e32 v139, 0xffff0000, v139
	v_lshlrev_b32_e32 v143, 16, v140
	v_and_b32_e32 v140, 0xffff0000, v140
	v_lshlrev_b32_e32 v144, 16, v141
	v_and_b32_e32 v141, 0xffff0000, v141
	v_max_f32_e32 v135, v135, v135
	v_max_f32_e32 v143, v143, v143
	v_max_f32_e32 v138, v138, v138
	v_max_f32_e32 v140, v140, v140
	v_max_f32_e32 v142, v142, v142
	v_max_f32_e32 v156, v144, v144
	v_max_f32_e32 v139, v139, v139
	v_max_f32_e32 v141, v141, v141
	v_max_f32_e32 v146, 0xda24260, v135
	v_max_f32_e32 v144, 0xda24260, v143
	v_max_f32_e32 v147, 0xda24260, v138
	v_max_f32_e32 v145, 0xda24260, v140
	v_max_f32_e32 v142, 0xda24260, v142
	v_max_f32_e32 v140, 0xda24260, v156
	v_max_f32_e32 v143, 0xda24260, v139
	v_max_f32_e32 v141, 0xda24260, v141
	v_lshl_add_u64 v[138:139], v[132:133], 1, v[154:155]
	s_cbranch_vccnz .LBB0_549
	v_pk_mul_f32 v[156:157], v[62:63], v[142:143]
	v_pk_mul_f32 v[154:155], v[60:61], v[146:147]
	v_pk_mul_f32 v[158:159], v[58:59], v[140:141]
	v_pk_mul_f32 v[160:161], v[56:57], v[144:145]
	v_cvt_pk_bf16_f32 v154, v154, v155
	v_cvt_pk_bf16_f32 v155, v156, v157
	s_nop 0
	v_cvt_pk_bf16_f32 v156, v160, v161
	v_cvt_pk_bf16_f32 v157, v158, v159
	global_store_dwordx4 v[138:139], v[154:157], off sc1
	s_cbranch_execnz .LBB0_515

; __device__ __forceinline__ u32x4 pack8(const f32x4 v0, const f32x4 v1) { u32x4 w; w.x = cvt_pk_bf16(v0[0], v0[1]); w.y = cvt_pk_bf16(v0[2], v0[3]); w.z = cvt_pk_bf16(v1[0], v1[1]); w.w = cvt_pk_bf16(v1[2], v1[3]); return w; }
; __device__ __forceinline__ void unpack8(const u32x4 w, f32x4& lo, f32x4& hi) { lo = (f32x4){bf_lo(w.x), bf_hi(w.x), bf_lo(w.y), bf_hi(w.y)}; hi = (f32x4){bf_lo(w.z), bf_hi(w.z), bf_lo(w.w), bf_hi(w.w)}; }
;     __device__ __forceinline__ void operator()(AccT& acc, const Unit& u, int wr, int wc, int fr, int fq) const {
;     ...
;             for (int m = 0; m < 4; ++m) { const size_t row = (size_t)(row0 + ai * 128 + m * 16);
; #pragma unroll
;                 for (int bj = 0; bj < 2; ++bj) { f32x4 p0, p1; unpack8(*(const u32x4*)(PROJ + row * DIN + 8192 + col0 + bj * 128), p0, p1);
; #pragma unroll
;                     for (int j = 0; j < 4; ++j) { p0[j] = fmaxf(p0[j], TINY); p1[j] = fmaxf(p1[j], TINY); }
;                     if (u.kind == 0) { f32x4 s0, s1; unpack8(*(const u32x4*)(PROJ + row * DIN + 4096 + col0 + bj * 128), s0, s1);
; #pragma unroll
;                         for (int j = 0; j < 4; ++j) { acc[ai][bj][m][0][j] *= s0[j] * __builtin_amdgcn_rcpf(p0[j]); acc[ai][bj][m][1][j] *= s1[j] * __builtin_amdgcn_rcpf(p1[j]); } }
;                     else *(u32x4*)(MG + row * DM + col0 + bj * 128) = pack8(acc[ai][bj][m][0] * p0, acc[ai][bj][m][1] * p1); } }
.LBB0_515:
	v_add_co_u32_e32 v140, vcc, 0x4000, v136
	s_nop 1
	v_addc_co_u32_e32 v141, vcc, 0, v137, vcc
	global_load_dwordx4 v[140:143], v[140:141], off offset:256
	s_and_b64 vcc, exec, s[4:5]
	s_waitcnt vmcnt(0)
	v_lshlrev_b32_e32 v135, 16, v140
	v_and_b32_e32 v140, 0xffff0000, v140
	v_lshlrev_b32_e32 v144, 16, v141
	v_and_b32_e32 v141, 0xffff0000, v141
	v_lshlrev_b32_e32 v145, 16, v142
	v_and_b32_e32 v142, 0xffff0000, v142
	v_lshlrev_b32_e32 v146, 16, v143
	v_and_b32_e32 v143, 0xffff0000, v143
	v_max_f32_e32 v135, v135, v135
	v_max_f32_e32 v145, v145, v145
	v_max_f32_e32 v140, v140, v140
	v_max_f32_e32 v142, v142, v142
	v_max_f32_e32 v154, v144, v144
	v_max_f32_e32 v155, v146, v146
	v_max_f32_e32 v141, v141, v141
	v_max_f32_e32 v156, v143, v143
	v_max_f32_e32 v146, 0xda24260, v135
	v_max_f32_e32 v144, 0xda24260, v145
	v_max_f32_e32 v147, 0xda24260, v140
	v_max_f32_e32 v145, 0xda24260, v142
	v_max_f32_e32 v142, 0xda24260, v154
	v_max_f32_e32 v140, 0xda24260, v155
	v_max_f32_e32 v143, 0xda24260, v141
	v_max_f32_e32 v141, 0xda24260, v156
	s_cbranch_vccnz .LBB0_550
	v_pk_mul_f32 v[156:157], v[30:31], v[142:143]
	v_pk_mul_f32 v[154:155], v[28:29], v[146:147]
	v_pk_mul_f32 v[158:159], v[26:27], v[140:141]
	v_pk_mul_f32 v[160:161], v[24:25], v[144:145]
	v_cvt_pk_bf16_f32 v154, v154, v155
	v_cvt_pk_bf16_f32 v155, v156, v157
	s_nop 0
	v_cvt_pk_bf16_f32 v156, v160, v161
	v_cvt_pk_bf16_f32 v157, v158, v159
	global_store_dwordx4 v[138:139], v[154:157], off offset:256 sc1
	s_cbranch_execnz .LBB0_518

; __device__ __forceinline__ u32x4 pack8(const f32x4 v0, const f32x4 v1) { u32x4 w; w.x = cvt_pk_bf16(v0[0], v0[1]); w.y = cvt_pk_bf16(v0[2], v0[3]); w.z = cvt_pk_bf16(v1[0], v1[1]); w.w = cvt_pk_bf16(v1[2], v1[3]); return w; }
; __device__ __forceinline__ void unpack8(const u32x4 w, f32x4& lo, f32x4& hi) { lo = (f32x4){bf_lo(w.x), bf_hi(w.x), bf_lo(w.y), bf_hi(w.y)}; hi = (f32x4){bf_lo(w.z), bf_hi(w.z), bf_lo(w.w), bf_hi(w.w)}; }
;     __device__ __forceinline__ void operator()(AccT& acc, const Unit& u, int wr, int wc, int fr, int fq) const {
;     ...
;             for (int m = 0; m < 4; ++m) { const size_t row = (size_t)(row0 + ai * 128 + m * 16);
; #pragma unroll
;                 for (int bj = 0; bj < 2; ++bj) { f32x4 p0, p1; unpack8(*(const u32x4*)(PROJ + row * DIN + 8192 + col0 + bj * 128), p0, p1);
; #pragma unroll
;                     for (int j = 0; j < 4; ++j) { p0[j] = fmaxf(p0[j], TINY); p1[j] = fmaxf(p1[j], TINY); }
;                     if (u.kind == 0) { f32x4 s0, s1; unpack8(*(const u32x4*)(PROJ + row * DIN + 4096 + col0 + bj * 128), s0, s1);
; #pragma unroll
;                         for (int j = 0; j < 4; ++j) { acc[ai][bj][m][0][j] *= s0[j] * __builtin_amdgcn_rcpf(p0[j]); acc[ai][bj][m][1][j] *= s1[j] * __builtin_amdgcn_rcpf(p1[j]); } }
;                     else *(u32x4*)(MG + row * DM + col0 + bj * 128) = pack8(acc[ai][bj][m][0] * p0, acc[ai][bj][m][1] * p1); } }
.LBB0_518:
	v_add_u32_e32 v142, 0x90, v134
	v_mov_b64_e32 v[136:137], s[20:21]
	v_mad_i64_i32 v[136:137], s[8:9], v142, s78, v[136:137]
	v_lshl_add_u64 v[136:137], v[132:133], 1, v[136:137]
	v_add_co_u32_e32 v138, vcc, 0x4000, v136
	v_ashrrev_i32_e32 v143, 31, v142
	s_nop 0
	v_addc_co_u32_e32 v139, vcc, 0, v137, vcc
	global_load_dwordx4 v[138:141], v[138:139], off
	v_lshlrev_b64 v[142:143], 13, v[142:143]
	v_lshl_add_u64 v[154:155], s[26:27], 0, v[142:143]
	s_and_b64 vcc, exec, s[4:5]
	s_waitcnt vmcnt(0)
	v_lshlrev_b32_e32 v135, 16, v138
	v_and_b32_e32 v138, 0xffff0000, v138
	v_lshlrev_b32_e32 v142, 16, v139
	v_and_b32_e32 v139, 0xffff0000, v139
	v_lshlrev_b32_e32 v143, 16, v140
	v_and_b32_e32 v140, 0xffff0000, v140
	v_lshlrev_b32_e32 v144, 16, v141
	v_and_b32_e32 v141, 0xffff0000, v141
	v_max_f32_e32 v135, v135, v135
	v_max_f32_e32 v143, v143, v143
	v_max_f32_e32 v138, v138, v138
	v_max_f32_e32 v140, v140, v140
	v_max_f32_e32 v142, v142, v142
	v_max_f32_e32 v156, v144, v144
	v_max_f32_e32 v139, v139, v139
	v_max_f32_e32 v141, v141, v141
	v_max_f32_e32 v146, 0xda24260, v135
	v_max_f32_e32 v144, 0xda24260, v143
	v_max_f32_e32 v147, 0xda24260, v138
	v_max_f32_e32 v145, 0xda24260, v140
	v_max_f32_e32 v142, 0xda24260, v142
	v_max_f32_e32 v140, 0xda24260, v156
	v_max_f32_e32 v143, 0xda24260, v139
	v_max_f32_e32 v141, 0xda24260, v141
	v_lshl_add_u64 v[138:139], v[132:133], 1, v[154:155]
	s_cbranch_vccnz .LBB0_551
	v_pk_mul_f32 v[156:157], v[54:55], v[142:143]
	v_pk_mul_f32 v[154:155], v[52:53], v[146:147]
	v_pk_mul_f32 v[158:159], v[50:51], v[140:141]
	v_pk_mul_f32 v[160:161], v[48:49], v[144:145]
	v_cvt_pk_bf16_f32 v154, v154, v155
	v_cvt_pk_bf16_f32 v155, v156, v157
	s_nop 0
	v_cvt_pk_bf16_f32 v156, v160, v161
	v_cvt_pk_bf16_f32 v157, v158, v159
	global_store_dwordx4 v[138:139], v[154:157], off sc1
	s_cbranch_execnz .LBB0_521

; __device__ __forceinline__ u32x4 pack8(const f32x4 v0, const f32x4 v1) { u32x4 w; w.x = cvt_pk_bf16(v0[0], v0[1]); w.y = cvt_pk_bf16(v0[2], v0[3]); w.z = cvt_pk_bf16(v1[0], v1[1]); w.w = cvt_pk_bf16(v1[2], v1[3]); return w; }
; __device__ __forceinline__ void unpack8(const u32x4 w, f32x4& lo, f32x4& hi) { lo = (f32x4){bf_lo(w.x), bf_hi(w.x), bf_lo(w.y), bf_hi(w.y)}; hi = (f32x4){bf_lo(w.z), bf_hi(w.z), bf_lo(w.w), bf_hi(w.w)}; }
;     __device__ __forceinline__ void operator()(AccT& acc, const Unit& u, int wr, int wc, int fr, int fq) const {
;     ...
;             for (int m = 0; m < 4; ++m) { const size_t row = (size_t)(row0 + ai * 128 + m * 16);
; #pragma unroll
;                 for (int bj = 0; bj < 2; ++bj) { f32x4 p0, p1; unpack8(*(const u32x4*)(PROJ + row * DIN + 8192 + col0 + bj * 128), p0, p1);
; #pragma unroll
;                     for (int j = 0; j < 4; ++j) { p0[j] = fmaxf(p0[j], TINY); p1[j] = fmaxf(p1[j], TINY); }
;                     if (u.kind == 0) { f32x4 s0, s1; unpack8(*(const u32x4*)(PROJ + row * DIN + 4096 + col0 + bj * 128), s0, s1);
; #pragma unroll
;                         for (int j = 0; j < 4; ++j) { acc[ai][bj][m][0][j] *= s0[j] * __builtin_amdgcn_rcpf(p0[j]); acc[ai][bj][m][1][j] *= s1[j] * __builtin_amdgcn_rcpf(p1[j]); } }
;                     else *(u32x4*)(MG + row * DM + col0 + bj * 128) = pack8(acc[ai][bj][m][0] * p0, acc[ai][bj][m][1] * p1); } }
.LBB0_521:
	v_add_co_u32_e32 v140, vcc, 0x4000, v136
	s_nop 1
	v_addc_co_u32_e32 v141, vcc, 0, v137, vcc
	global_load_dwordx4 v[140:143], v[140:141], off offset:256
	s_and_b64 vcc, exec, s[4:5]
	s_waitcnt vmcnt(0)
	v_lshlrev_b32_e32 v135, 16, v140
	v_and_b32_e32 v140, 0xffff0000, v140
	v_lshlrev_b32_e32 v144, 16, v141
	v_and_b32_e32 v141, 0xffff0000, v141
	v_lshlrev_b32_e32 v145, 16, v142
	v_and_b32_e32 v142, 0xffff0000, v142
	v_lshlrev_b32_e32 v146, 16, v143
	v_and_b32_e32 v143, 0xffff0000, v143
	v_max_f32_e32 v135, v135, v135
	v_max_f32_e32 v145, v145, v145
	v_max_f32_e32 v140, v140, v140
	v_max_f32_e32 v142, v142, v142
	v_max_f32_e32 v154, v144, v144
	v_max_f32_e32 v155, v146, v146
	v_max_f32_e32 v141, v141, v141
	v_max_f32_e32 v156, v143, v143
	v_max_f32_e32 v146, 0xda24260, v135
	v_max_f32_e32 v144, 0xda24260, v145
	v_max_f32_e32 v147, 0xda24260, v140
	v_max_f32_e32 v145, 0xda24260, v142
	v_max_f32_e32 v142, 0xda24260, v154
	v_max_f32_e32 v140, 0xda24260, v155
	v_max_f32_e32 v143, 0xda24260, v141
	v_max_f32_e32 v141, 0xda24260, v156
	s_cbranch_vccnz .LBB0_552
	v_pk_mul_f32 v[156:157], v[22:23], v[142:143]
	v_pk_mul_f32 v[154:155], v[20:21], v[146:147]
	v_pk_mul_f32 v[158:159], v[18:19], v[140:141]
	v_pk_mul_f32 v[160:161], v[16:17], v[144:145]
	v_cvt_pk_bf16_f32 v154, v154, v155
	v_cvt_pk_bf16_f32 v155, v156, v157
	s_nop 0
	v_cvt_pk_bf16_f32 v156, v160, v161
	v_cvt_pk_bf16_f32 v157, v158, v159
	global_store_dwordx4 v[138:139], v[154:157], off offset:256 sc1
	s_cbranch_execnz .LBB0_524

; __device__ __forceinline__ u32x4 pack8(const f32x4 v0, const f32x4 v1) { u32x4 w; w.x = cvt_pk_bf16(v0[0], v0[1]); w.y = cvt_pk_bf16(v0[2], v0[3]); w.z = cvt_pk_bf16(v1[0], v1[1]); w.w = cvt_pk_bf16(v1[2], v1[3]); return w; }
; __device__ __forceinline__ void unpack8(const u32x4 w, f32x4& lo, f32x4& hi) { lo = (f32x4){bf_lo(w.x), bf_hi(w.x), bf_lo(w.y), bf_hi(w.y)}; hi = (f32x4){bf_lo(w.z), bf_hi(w.z), bf_lo(w.w), bf_hi(w.w)}; }
;     __device__ __forceinline__ void operator()(AccT& acc, const Unit& u, int wr, int wc, int fr, int fq) const {
;     ...
;             for (int m = 0; m < 4; ++m) { const size_t row = (size_t)(row0 + ai * 128 + m * 16);
; #pragma unroll
;                 for (int bj = 0; bj < 2; ++bj) { f32x4 p0, p1; unpack8(*(const u32x4*)(PROJ + row * DIN + 8192 + col0 + bj * 128), p0, p1);
; #pragma unroll
;                     for (int j = 0; j < 4; ++j) { p0[j] = fmaxf(p0[j], TINY); p1[j] = fmaxf(p1[j], TINY); }
;                     if (u.kind == 0) { f32x4 s0, s1; unpack8(*(const u32x4*)(PROJ + row * DIN + 4096 + col0 + bj * 128), s0, s1);
; #pragma unroll
;                         for (int j = 0; j < 4; ++j) { acc[ai][bj][m][0][j] *= s0[j] * __builtin_amdgcn_rcpf(p0[j]); acc[ai][bj][m][1][j] *= s1[j] * __builtin_amdgcn_rcpf(p1[j]); } }
;                     else *(u32x4*)(MG + row * DM + col0 + bj * 128) = pack8(acc[ai][bj][m][0] * p0, acc[ai][bj][m][1] * p1); } }
.LBB0_524:
	v_add_u32_e32 v142, 0xa0, v134
	v_mov_b64_e32 v[136:137], s[20:21]
	v_mad_i64_i32 v[136:137], s[8:9], v142, s78, v[136:137]
	v_lshl_add_u64 v[136:137], v[132:133], 1, v[136:137]
	v_add_co_u32_e32 v138, vcc, 0x4000, v136
	v_ashrrev_i32_e32 v143, 31, v142
	s_nop 0
	v_addc_co_u32_e32 v139, vcc, 0, v137, vcc
	global_load_dwordx4 v[138:141], v[138:139], off
	v_lshlrev_b64 v[142:143], 13, v[142:143]
	v_lshl_add_u64 v[154:155], s[26:27], 0, v[142:143]
	s_and_b64 vcc, exec, s[4:5]
	s_waitcnt vmcnt(0)
	v_lshlrev_b32_e32 v135, 16, v138
	v_and_b32_e32 v138, 0xffff0000, v138
	v_lshlrev_b32_e32 v142, 16, v139
	v_and_b32_e32 v139, 0xffff0000, v139
	v_lshlrev_b32_e32 v143, 16, v140
	v_and_b32_e32 v140, 0xffff0000, v140
	v_lshlrev_b32_e32 v144, 16, v141
	v_and_b32_e32 v141, 0xffff0000, v141
	v_max_f32_e32 v135, v135, v135
	v_max_f32_e32 v143, v143, v143
	v_max_f32_e32 v138, v138, v138
	v_max_f32_e32 v140, v140, v140
	v_max_f32_e32 v142, v142, v142
	v_max_f32_e32 v156, v144, v144
	v_max_f32_e32 v139, v139, v139
	v_max_f32_e32 v141, v141, v141
	v_max_f32_e32 v146, 0xda24260, v135
	v_max_f32_e32 v144, 0xda24260, v143
	v_max_f32_e32 v147, 0xda24260, v138
	v_max_f32_e32 v145, 0xda24260, v140
	v_max_f32_e32 v142, 0xda24260, v142
	v_max_f32_e32 v140, 0xda24260, v156
	v_max_f32_e32 v143, 0xda24260, v139
	v_max_f32_e32 v141, 0xda24260, v141
	v_lshl_add_u64 v[138:139], v[132:133], 1, v[154:155]
	s_cbranch_vccnz .LBB0_553
	v_pk_mul_f32 v[156:157], v[46:47], v[142:143]
	v_pk_mul_f32 v[154:155], v[44:45], v[146:147]
	v_pk_mul_f32 v[158:159], v[42:43], v[140:141]
	v_pk_mul_f32 v[160:161], v[40:41], v[144:145]
	v_cvt_pk_bf16_f32 v154, v154, v155
	v_cvt_pk_bf16_f32 v155, v156, v157
	s_nop 0
	v_cvt_pk_bf16_f32 v156, v160, v161
	v_cvt_pk_bf16_f32 v157, v158, v159
	global_store_dwordx4 v[138:139], v[154:157], off sc1
	s_cbranch_execnz .LBB0_527

; __device__ __forceinline__ u32x4 pack8(const f32x4 v0, const f32x4 v1) { u32x4 w; w.x = cvt_pk_bf16(v0[0], v0[1]); w.y = cvt_pk_bf16(v0[2], v0[3]); w.z = cvt_pk_bf16(v1[0], v1[1]); w.w = cvt_pk_bf16(v1[2], v1[3]); return w; }
; __device__ __forceinline__ void unpack8(const u32x4 w, f32x4& lo, f32x4& hi) { lo = (f32x4){bf_lo(w.x), bf_hi(w.x), bf_lo(w.y), bf_hi(w.y)}; hi = (f32x4){bf_lo(w.z), bf_hi(w.z), bf_lo(w.w), bf_hi(w.w)}; }
;     __device__ __forceinline__ void operator()(AccT& acc, const Unit& u, int wr, int wc, int fr, int fq) const {
;     ...
;             for (int m = 0; m < 4; ++m) { const size_t row = (size_t)(row0 + ai * 128 + m * 16);
; #pragma unroll
;                 for (int bj = 0; bj < 2; ++bj) { f32x4 p0, p1; unpack8(*(const u32x4*)(PROJ + row * DIN + 8192 + col0 + bj * 128), p0, p1);
; #pragma unroll
;                     for (int j = 0; j < 4; ++j) { p0[j] = fmaxf(p0[j], TINY); p1[j] = fmaxf(p1[j], TINY); }
;                     if (u.kind == 0) { f32x4 s0, s1; unpack8(*(const u32x4*)(PROJ + row * DIN + 4096 + col0 + bj * 128), s0, s1);
; #pragma unroll
;                         for (int j = 0; j < 4; ++j) { acc[ai][bj][m][0][j] *= s0[j] * __builtin_amdgcn_rcpf(p0[j]); acc[ai][bj][m][1][j] *= s1[j] * __builtin_amdgcn_rcpf(p1[j]); } }
;                     else *(u32x4*)(MG + row * DM + col0 + bj * 128) = pack8(acc[ai][bj][m][0] * p0, acc[ai][bj][m][1] * p1); } }
.LBB0_527:
	v_add_co_u32_e32 v140, vcc, 0x4000, v136
	s_nop 1
	v_addc_co_u32_e32 v141, vcc, 0, v137, vcc
	global_load_dwordx4 v[140:143], v[140:141], off offset:256
	s_and_b64 vcc, exec, s[4:5]
	s_waitcnt vmcnt(0)
	v_lshlrev_b32_e32 v135, 16, v140
	v_and_b32_e32 v140, 0xffff0000, v140
	v_lshlrev_b32_e32 v144, 16, v141
	v_and_b32_e32 v141, 0xffff0000, v141
	v_lshlrev_b32_e32 v145, 16, v142
	v_and_b32_e32 v142, 0xffff0000, v142
	v_lshlrev_b32_e32 v146, 16, v143
	v_and_b32_e32 v143, 0xffff0000, v143
	v_max_f32_e32 v135, v135, v135
	v_max_f32_e32 v145, v145, v145
	v_max_f32_e32 v140, v140, v140
	v_max_f32_e32 v142, v142, v142
	v_max_f32_e32 v154, v144, v144
	v_max_f32_e32 v155, v146, v146
	v_max_f32_e32 v141, v141, v141
	v_max_f32_e32 v156, v143, v143
	v_max_f32_e32 v146, 0xda24260, v135
	v_max_f32_e32 v144, 0xda24260, v145
	v_max_f32_e32 v147, 0xda24260, v140
	v_max_f32_e32 v145, 0xda24260, v142
	v_max_f32_e32 v142, 0xda24260, v154
	v_max_f32_e32 v140, 0xda24260, v155
	v_max_f32_e32 v143, 0xda24260, v141
	v_max_f32_e32 v141, 0xda24260, v156
	s_cbranch_vccnz .LBB0_554
	v_pk_mul_f32 v[156:157], v[14:15], v[142:143]
	v_pk_mul_f32 v[154:155], v[12:13], v[146:147]
	v_pk_mul_f32 v[158:159], v[10:11], v[140:141]
	v_pk_mul_f32 v[160:161], v[8:9], v[144:145]
	v_cvt_pk_bf16_f32 v154, v154, v155
	v_cvt_pk_bf16_f32 v155, v156, v157
	s_nop 0
	v_cvt_pk_bf16_f32 v156, v160, v161
	v_cvt_pk_bf16_f32 v157, v158, v159
	global_store_dwordx4 v[138:139], v[154:157], off offset:256 sc1
	s_cbranch_execnz .LBB0_530

; __device__ __forceinline__ u32x4 pack8(const f32x4 v0, const f32x4 v1) { u32x4 w; w.x = cvt_pk_bf16(v0[0], v0[1]); w.y = cvt_pk_bf16(v0[2], v0[3]); w.z = cvt_pk_bf16(v1[0], v1[1]); w.w = cvt_pk_bf16(v1[2], v1[3]); return w; }
; __device__ __forceinline__ void unpack8(const u32x4 w, f32x4& lo, f32x4& hi) { lo = (f32x4){bf_lo(w.x), bf_hi(w.x), bf_lo(w.y), bf_hi(w.y)}; hi = (f32x4){bf_lo(w.z), bf_hi(w.z), bf_lo(w.w), bf_hi(w.w)}; }
;     __device__ __forceinline__ void operator()(AccT& acc, const Unit& u, int wr, int wc, int fr, int fq) const {
;     ...
;             for (int m = 0; m < 4; ++m) { const size_t row = (size_t)(row0 + ai * 128 + m * 16);
; #pragma unroll
;                 for (int bj = 0; bj < 2; ++bj) { f32x4 p0, p1; unpack8(*(const u32x4*)(PROJ + row * DIN + 8192 + col0 + bj * 128), p0, p1);
; #pragma unroll
;                     for (int j = 0; j < 4; ++j) { p0[j] = fmaxf(p0[j], TINY); p1[j] = fmaxf(p1[j], TINY); }
;                     if (u.kind == 0) { f32x4 s0, s1; unpack8(*(const u32x4*)(PROJ + row * DIN + 4096 + col0 + bj * 128), s0, s1);
; #pragma unroll
;                         for (int j = 0; j < 4; ++j) { acc[ai][bj][m][0][j] *= s0[j] * __builtin_amdgcn_rcpf(p0[j]); acc[ai][bj][m][1][j] *= s1[j] * __builtin_amdgcn_rcpf(p1[j]); } }
;                     else *(u32x4*)(MG + row * DM + col0 + bj * 128) = pack8(acc[ai][bj][m][0] * p0, acc[ai][bj][m][1] * p1); } }
.LBB0_530:
	v_add_u32_e32 v140, 0xb0, v134
	v_mov_b64_e32 v[134:135], s[20:21]
	v_mad_i64_i32 v[134:135], s[8:9], v140, s78, v[134:135]
	v_lshl_add_u64 v[134:135], v[132:133], 1, v[134:135]
	v_add_co_u32_e32 v136, vcc, 0x4000, v134
	v_ashrrev_i32_e32 v141, 31, v140
	s_nop 0
	v_addc_co_u32_e32 v137, vcc, 0, v135, vcc
	global_load_dwordx4 v[136:139], v[136:137], off
	v_lshlrev_b64 v[140:141], 13, v[140:141]
	v_lshl_add_u64 v[144:145], s[26:27], 0, v[140:141]
	s_and_b64 vcc, exec, s[4:5]
	v_lshl_add_u64 v[132:133], v[132:133], 1, v[144:145]
	s_waitcnt vmcnt(0)
	v_lshlrev_b32_e32 v140, 16, v136
	v_and_b32_e32 v136, 0xffff0000, v136
	v_lshlrev_b32_e32 v141, 16, v137
	v_and_b32_e32 v137, 0xffff0000, v137
	v_lshlrev_b32_e32 v142, 16, v138
	v_and_b32_e32 v138, 0xffff0000, v138
	v_lshlrev_b32_e32 v143, 16, v139
	v_and_b32_e32 v139, 0xffff0000, v139
	v_max_f32_e32 v140, v140, v140
	v_max_f32_e32 v146, v142, v142
	v_max_f32_e32 v136, v136, v136
	v_max_f32_e32 v138, v138, v138
	v_max_f32_e32 v147, v141, v141
	v_max_f32_e32 v154, v143, v143
	v_max_f32_e32 v137, v137, v137
	v_max_f32_e32 v155, v139, v139
	v_max_f32_e32 v142, 0xda24260, v140
	v_max_f32_e32 v140, 0xda24260, v146
	v_max_f32_e32 v143, 0xda24260, v136
	v_max_f32_e32 v141, 0xda24260, v138
	v_max_f32_e32 v138, 0xda24260, v147
	v_max_f32_e32 v136, 0xda24260, v154
	v_max_f32_e32 v139, 0xda24260, v137
	v_max_f32_e32 v137, 0xda24260, v155
	s_cbranch_vccnz .LBB0_555
	v_pk_mul_f32 v[146:147], v[38:39], v[138:139]
	v_pk_mul_f32 v[144:145], v[36:37], v[142:143]
	v_pk_mul_f32 v[154:155], v[34:35], v[136:137]
	v_pk_mul_f32 v[156:157], v[32:33], v[140:141]
	v_cvt_pk_bf16_f32 v144, v144, v145
	v_cvt_pk_bf16_f32 v145, v146, v147
	s_nop 0
	v_cvt_pk_bf16_f32 v146, v156, v157
	v_cvt_pk_bf16_f32 v147, v154, v155
	global_store_dwordx4 v[132:133], v[144:147], off sc1
	s_cbranch_execnz .LBB0_533

; __device__ __forceinline__ u32x4 pack8(const f32x4 v0, const f32x4 v1) { u32x4 w; w.x = cvt_pk_bf16(v0[0], v0[1]); w.y = cvt_pk_bf16(v0[2], v0[3]); w.z = cvt_pk_bf16(v1[0], v1[1]); w.w = cvt_pk_bf16(v1[2], v1[3]); return w; }
; __device__ __forceinline__ void unpack8(const u32x4 w, f32x4& lo, f32x4& hi) { lo = (f32x4){bf_lo(w.x), bf_hi(w.x), bf_lo(w.y), bf_hi(w.y)}; hi = (f32x4){bf_lo(w.z), bf_hi(w.z), bf_lo(w.w), bf_hi(w.w)}; }
;     __device__ __forceinline__ void operator()(AccT& acc, const Unit& u, int wr, int wc, int fr, int fq) const {
;     ...
;             for (int m = 0; m < 4; ++m) { const size_t row = (size_t)(row0 + ai * 128 + m * 16);
; #pragma unroll
;                 for (int bj = 0; bj < 2; ++bj) { f32x4 p0, p1; unpack8(*(const u32x4*)(PROJ + row * DIN + 8192 + col0 + bj * 128), p0, p1);
; #pragma unroll
;                     for (int j = 0; j < 4; ++j) { p0[j] = fmaxf(p0[j], TINY); p1[j] = fmaxf(p1[j], TINY); }
;                     if (u.kind == 0) { f32x4 s0, s1; unpack8(*(const u32x4*)(PROJ + row * DIN + 4096 + col0 + bj * 128), s0, s1);
; #pragma unroll
;                         for (int j = 0; j < 4; ++j) { acc[ai][bj][m][0][j] *= s0[j] * __builtin_amdgcn_rcpf(p0[j]); acc[ai][bj][m][1][j] *= s1[j] * __builtin_amdgcn_rcpf(p1[j]); } }
;                     else *(u32x4*)(MG + row * DM + col0 + bj * 128) = pack8(acc[ai][bj][m][0] * p0, acc[ai][bj][m][1] * p1); } }
.LBB0_533:
	v_add_co_u32_e32 v136, vcc, 0x4000, v134
	s_nop 1
	v_addc_co_u32_e32 v137, vcc, 0, v135, vcc
	global_load_dwordx4 v[136:139], v[136:137], off offset:256
	s_and_b64 vcc, exec, s[4:5]
	s_waitcnt vmcnt(0)
	v_lshlrev_b32_e32 v140, 16, v136
	v_and_b32_e32 v136, 0xffff0000, v136
	v_lshlrev_b32_e32 v141, 16, v137
	v_and_b32_e32 v137, 0xffff0000, v137
	v_lshlrev_b32_e32 v142, 16, v138
	v_and_b32_e32 v138, 0xffff0000, v138
	v_lshlrev_b32_e32 v143, 16, v139
	v_and_b32_e32 v139, 0xffff0000, v139
	v_max_f32_e32 v140, v140, v140
	v_max_f32_e32 v144, v142, v142
	v_max_f32_e32 v136, v136, v136
	v_max_f32_e32 v138, v138, v138
	v_max_f32_e32 v145, v141, v141
	v_max_f32_e32 v146, v143, v143
	v_max_f32_e32 v137, v137, v137
	v_max_f32_e32 v147, v139, v139
	v_max_f32_e32 v142, 0xda24260, v140
	v_max_f32_e32 v140, 0xda24260, v144
	v_max_f32_e32 v143, 0xda24260, v136
	v_max_f32_e32 v141, 0xda24260, v138
	v_max_f32_e32 v138, 0xda24260, v145
	v_max_f32_e32 v136, 0xda24260, v146
	v_max_f32_e32 v139, 0xda24260, v137
	v_max_f32_e32 v137, 0xda24260, v147
	s_cbranch_vccnz .LBB0_556
	v_pk_mul_f32 v[146:147], v[6:7], v[138:139]
	v_pk_mul_f32 v[144:145], v[4:5], v[142:143]
	v_pk_mul_f32 v[154:155], v[2:3], v[136:137]
	v_pk_mul_f32 v[156:157], v[0:1], v[140:141]
	v_cvt_pk_bf16_f32 v144, v144, v145
	v_cvt_pk_bf16_f32 v145, v146, v147
	s_nop 0
	v_cvt_pk_bf16_f32 v146, v156, v157
	v_cvt_pk_bf16_f32 v147, v154, v155
	global_store_dwordx4 v[132:133], v[144:147], off offset:256 sc1
	s_cbranch_execnz .LBB0_536

; __device__ __forceinline__ u32x4 pack8(const f32x4 v0, const f32x4 v1) { u32x4 w; w.x = cvt_pk_bf16(v0[0], v0[1]); w.y = cvt_pk_bf16(v0[2], v0[3]); w.z = cvt_pk_bf16(v1[0], v1[1]); w.w = cvt_pk_bf16(v1[2], v1[3]); return w; }
;     __device__ __forceinline__ void operator()(AccT& acc, const Unit& u, int wr, int wc, int fr, int fq) const {
;         const int row0 = u.pm * 256 + wr * 64 + fr, col0 = u.pn * 256 + wc * 32 + 8 * fq;
; #pragma unroll
;         for (int ai = 0; ai < 2; ++ai)
; #pragma unroll
;             for (int m = 0; m < 4; ++m) { const int row = row0 + ai * 128 + m * 16; bf16_t* rowp = O + (size_t)row * DM + col0; float ss = 0.f;
; #pragma unroll
;                 for (int bj = 0; bj < 2; ++bj) { const f32x4 v0 = acc[ai][bj][m][0], v1 = acc[ai][bj][m][1];
;                     ss += (v0[0] * v0[0] + v0[1] * v0[1]) + (v0[2] * v0[2] + v0[3] * v0[3]) + (v1[0] * v1[0] + v1[1] * v1[1]) + (v1[2] * v1[2] + v1[3] * v1[3]);
;                     *(u32x4*)(rowp + bj * 128) = pack8(v0, v1); }
;                 ss += __shfl_xor(ss, 16); ss += __shfl_xor(ss, 32);
;                 if (fq == 0) SSQ[(size_t)(u.pn * 4 + wc) * MT + row] = ss; }
.LBB0_635:
	v_mul_f32_e32 v148, v125, v125
	v_mul_f32_e32 v149, v127, v127
	v_fmac_f32_e32 v148, v124, v124
	v_fmac_f32_e32 v149, v126, v126
	v_add_f32_e32 v148, v148, v149
	v_mul_f32_e32 v149, v121, v121
	v_fmac_f32_e32 v149, v120, v120
	v_add_f32_e32 v148, v149, v148
	v_mul_f32_e32 v149, v123, v123
	v_mov_b32_e32 v132, v254
	v_fmac_f32_e32 v149, v122, v122
	v_add_f32_e32 v150, v149, v148
	v_cvt_pk_bf16_f32 v148, v124, v125
	v_mul_f32_e32 v124, v117, v117
	v_mul_f32_e32 v125, v119, v119
	s_lshl_b32 s4, s72, 8
	v_fmac_f32_e32 v124, v116, v116
	v_fmac_f32_e32 v125, v118, v118
	s_add_i32 s4, s4, s84
	v_add_f32_e32 v124, v124, v125
	v_mul_f32_e32 v125, v113, v113
	v_bfe_u32 v133, v132, 4, 2
	v_and_or_b32 v132, v132, 15, s4
	s_lshl_b32 s4, s63, 8
	v_fmac_f32_e32 v125, v112, v112
	s_or_b32 s4, s4, s85
	v_add_f32_e32 v124, v125, v124
	v_mul_f32_e32 v125, v115, v115
	v_lshl_or_b32 v136, v133, 3, s4
	s_lshl_b32 s4, s63, 2
	v_fmac_f32_e32 v125, v114, v114
	s_or_b32 s4, s4, s83
	v_cvt_pk_bf16_f32 v149, v126, v127
	v_add_f32_e32 v124, v125, v124
	v_and_b32_e32 v126, 64, v147
	s_ashr_i32 s5, s4, 31
	v_add_f32_e32 v125, v124, v150
	v_xor_b32_e32 v124, 16, v147
	v_add_u32_e32 v126, 64, v126
	s_lshl_b64 s[16:17], s[4:5], 15
	v_cmp_lt_i32_e64 s[4:5], v124, v126
	v_cmp_eq_u32_e32 vcc, 0, v133
	v_ashrrev_i32_e32 v133, 31, v132
	v_cndmask_b32_e64 v124, v147, v124, s[4:5]
	v_lshlrev_b64 v[134:135], 13, v[132:133]
	v_lshlrev_b32_e32 v124, 2, v124
	v_ashrrev_i32_e32 v137, 31, v136
	v_lshl_add_u64 v[134:135], s[20:21], 0, v[134:135]
	ds_bpermute_b32 v127, v124, v125
	v_lshl_add_u64 v[134:135], v[136:137], 1, v[134:135]
	v_cvt_pk_bf16_f32 v150, v120, v121
	v_cvt_pk_bf16_f32 v151, v122, v123
	global_store_dwordx4 v[134:135], v[148:151], off sc1
	s_nop 1
	v_cvt_pk_bf16_f32 v148, v116, v117
	v_xor_b32_e32 v116, 32, v147
	v_cmp_lt_i32_e64 s[4:5], v116, v126
	s_waitcnt lgkmcnt(0)
	v_add_f32_e32 v117, v125, v127
	v_cvt_pk_bf16_f32 v149, v118, v119
	v_cvt_pk_bf16_f32 v150, v112, v113
	v_cvt_pk_bf16_f32 v151, v114, v115
	global_store_dwordx4 v[134:135], v[148:151], off offset:256 sc1
	v_cndmask_b32_e64 v116, v147, v116, s[4:5]
	v_lshlrev_b32_e32 v116, 2, v116
	ds_bpermute_b32 v120, v116, v117
	s_and_saveexec_b64 s[4:5], vcc
	s_cbranch_execz .LBB0_637
	s_add_u32 s18, s81, s16
	s_addc_u32 s19, s82, s17
	s_waitcnt lgkmcnt(0)
	v_add_f32_e32 v114, v117, v120
	v_lshl_add_u64 v[112:113], v[132:133], 2, s[18:19]
	global_store_dword v[112:113], v114, off
.LBB0_637:
	s_or_b64 exec, exec, s[4:5]
	v_mul_f32_e32 v114, v109, v109
	v_mul_f32_e32 v115, v111, v111
	v_fmac_f32_e32 v114, v108, v108
	v_fmac_f32_e32 v115, v110, v110
	v_cvt_pk_bf16_f32 v108, v108, v109
	v_cvt_pk_bf16_f32 v109, v110, v111
	v_mul_f32_e32 v110, v101, v101
	v_mul_f32_e32 v111, v103, v103
	v_fmac_f32_e32 v110, v100, v100
	v_fmac_f32_e32 v111, v102, v102
	v_add_f32_e32 v114, v114, v115
	v_mul_f32_e32 v115, v105, v105
	v_add_f32_e32 v110, v110, v111
	v_mul_f32_e32 v111, v97, v97
	v_fmac_f32_e32 v115, v104, v104
	v_fmac_f32_e32 v111, v96, v96
	v_add_f32_e32 v114, v115, v114
	v_mul_f32_e32 v115, v107, v107
	v_add_f32_e32 v110, v111, v110
	v_mul_f32_e32 v111, v99, v99
	v_fmac_f32_e32 v115, v106, v106
	v_fmac_f32_e32 v111, v98, v98
	v_add_f32_e32 v114, v115, v114
	v_add_f32_e32 v110, v111, v110
	v_add_f32_e32 v114, v110, v114
	v_or_b32_e32 v112, 16, v132
	ds_bpermute_b32 v115, v124, v114
	v_ashrrev_i32_e32 v113, 31, v112
	v_lshlrev_b64 v[112:113], 13, v[112:113]
	v_lshl_add_u64 v[112:113], s[20:21], 0, v[112:113]
	v_lshl_add_u64 v[112:113], v[136:137], 1, v[112:113]
	v_cvt_pk_bf16_f32 v110, v104, v105
	v_cvt_pk_bf16_f32 v111, v106, v107
	global_store_dwordx4 v[112:113], v[108:111], off sc1
	v_cvt_pk_bf16_f32 v104, v100, v101
	s_waitcnt lgkmcnt(0)
	v_add_f32_e32 v100, v114, v115
	ds_bpermute_b32 v101, v116, v100
	v_cvt_pk_bf16_f32 v105, v102, v103
	v_cvt_pk_bf16_f32 v106, v96, v97
	v_cvt_pk_bf16_f32 v107, v98, v99
	global_store_dwordx4 v[112:113], v[104:107], off offset:256 sc1
	s_and_saveexec_b64 s[4:5], vcc
	s_cbranch_execz .LBB0_639
	s_add_u32 s18, s81, s16
	s_addc_u32 s19, s82, s17
	s_waitcnt lgkmcnt(0)
	v_add_f32_e32 v98, v100, v101
	v_lshl_add_u64 v[96:97], v[132:133], 2, s[18:19]
	global_store_dword v[96:97], v98, off offset:64
.LBB0_639:
	s_or_b64 exec, exec, s[4:5]
	v_mul_f32_e32 v98, v93, v93
	v_mul_f32_e32 v99, v95, v95
	v_fmac_f32_e32 v98, v92, v92
	v_fmac_f32_e32 v99, v94, v94
	v_cvt_pk_bf16_f32 v92, v92, v93
	v_cvt_pk_bf16_f32 v93, v94, v95
	v_mul_f32_e32 v94, v85, v85
	v_mul_f32_e32 v95, v87, v87
	v_fmac_f32_e32 v94, v84, v84
	v_fmac_f32_e32 v95, v86, v86
	v_add_f32_e32 v98, v98, v99
	v_mul_f32_e32 v99, v89, v89
	v_add_f32_e32 v94, v94, v95
	v_mul_f32_e32 v95, v81, v81
	v_fmac_f32_e32 v99, v88, v88
	v_fmac_f32_e32 v95, v80, v80
	v_add_f32_e32 v98, v99, v98
	v_mul_f32_e32 v99, v91, v91
	v_add_f32_e32 v94, v95, v94
	v_mul_f32_e32 v95, v83, v83
	v_fmac_f32_e32 v99, v90, v90
	v_fmac_f32_e32 v95, v82, v82
	v_add_f32_e32 v98, v99, v98
	v_add_f32_e32 v94, v95, v94
	v_add_f32_e32 v98, v94, v98
	v_or_b32_e32 v96, 32, v132
	ds_bpermute_b32 v99, v124, v98
	v_ashrrev_i32_e32 v97, 31, v96
	v_lshlrev_b64 v[96:97], 13, v[96:97]
	v_lshl_add_u64 v[96:97], s[20:21], 0, v[96:97]
	v_lshl_add_u64 v[96:97], v[136:137], 1, v[96:97]
	v_cvt_pk_bf16_f32 v94, v88, v89
	v_cvt_pk_bf16_f32 v95, v90, v91
	global_store_dwordx4 v[96:97], v[92:95], off sc1
	v_cvt_pk_bf16_f32 v88, v84, v85
	s_waitcnt lgkmcnt(0)
	v_add_f32_e32 v84, v98, v99
	ds_bpermute_b32 v85, v116, v84
	v_cvt_pk_bf16_f32 v89, v86, v87
	v_cvt_pk_bf16_f32 v90, v80, v81
	v_cvt_pk_bf16_f32 v91, v82, v83
	global_store_dwordx4 v[96:97], v[88:91], off offset:256 sc1
	s_and_saveexec_b64 s[4:5], vcc
	s_cbranch_execz .LBB0_641
	s_add_u32 s18, s81, s16
	s_addc_u32 s19, s82, s17
	s_waitcnt lgkmcnt(0)
	v_add_f32_e32 v82, v84, v85
	v_lshl_add_u64 v[80:81], v[132:133], 2, s[18:19]
	global_store_dword v[80:81], v82, off offset:128
; __device__ __forceinline__ u32x4 pack8(const f32x4 v0, const f32x4 v1) { u32x4 w; w.x = cvt_pk_bf16(v0[0], v0[1]); w.y = cvt_pk_bf16(v0[2], v0[3]); w.z = cvt_pk_bf16(v1[0], v1[1]); w.w = cvt_pk_bf16(v1[2], v1[3]); return w; }
;     __device__ __forceinline__ void operator()(AccT& acc, const Unit& u, int wr, int wc, int fr, int fq) const {
;         const int row0 = u.pm * 256 + wr * 64 + fr, col0 = u.pn * 256 + wc * 32 + 8 * fq;
; #pragma unroll
;         for (int ai = 0; ai < 2; ++ai)
; #pragma unroll
;             for (int m = 0; m < 4; ++m) { const int row = row0 + ai * 128 + m * 16; bf16_t* rowp = O + (size_t)row * DM + col0; float ss = 0.f;
; #pragma unroll
;                 for (int bj = 0; bj < 2; ++bj) { const f32x4 v0 = acc[ai][bj][m][0], v1 = acc[ai][bj][m][1];
;                     ss += (v0[0] * v0[0] + v0[1] * v0[1]) + (v0[2] * v0[2] + v0[3] * v0[3]) + (v1[0] * v1[0] + v1[1] * v1[1]) + (v1[2] * v1[2] + v1[3] * v1[3]);
;                     *(u32x4*)(rowp + bj * 128) = pack8(v0, v1); }
;                 ss += __shfl_xor(ss, 16); ss += __shfl_xor(ss, 32);
;                 if (fq == 0) SSQ[(size_t)(u.pn * 4 + wc) * MT + row] = ss; }
.LBB0_641:
	s_or_b64 exec, exec, s[4:5]
	v_mul_f32_e32 v82, v77, v77
	v_mul_f32_e32 v83, v79, v79
	v_fmac_f32_e32 v82, v76, v76
	v_fmac_f32_e32 v83, v78, v78
	v_cvt_pk_bf16_f32 v76, v76, v77
	v_cvt_pk_bf16_f32 v77, v78, v79
	v_mul_f32_e32 v78, v69, v69
	v_mul_f32_e32 v79, v71, v71
	v_fmac_f32_e32 v78, v68, v68
	v_fmac_f32_e32 v79, v70, v70
	v_add_f32_e32 v82, v82, v83
	v_mul_f32_e32 v83, v73, v73
	v_add_f32_e32 v78, v78, v79
	v_mul_f32_e32 v79, v65, v65
	v_fmac_f32_e32 v83, v72, v72
	v_fmac_f32_e32 v79, v64, v64
	v_add_f32_e32 v82, v83, v82
	v_mul_f32_e32 v83, v75, v75
	v_add_f32_e32 v78, v79, v78
	v_mul_f32_e32 v79, v67, v67
	v_fmac_f32_e32 v83, v74, v74
	v_fmac_f32_e32 v79, v66, v66
	v_add_f32_e32 v82, v83, v82
	v_add_f32_e32 v78, v79, v78
	v_add_f32_e32 v82, v78, v82
	v_or_b32_e32 v80, 48, v132
	ds_bpermute_b32 v83, v124, v82
	v_ashrrev_i32_e32 v81, 31, v80
	v_lshlrev_b64 v[80:81], 13, v[80:81]
	v_lshl_add_u64 v[80:81], s[20:21], 0, v[80:81]
	v_lshl_add_u64 v[80:81], v[136:137], 1, v[80:81]
	v_cvt_pk_bf16_f32 v78, v72, v73
	v_cvt_pk_bf16_f32 v79, v74, v75
	global_store_dwordx4 v[80:81], v[76:79], off sc1
	v_cvt_pk_bf16_f32 v72, v68, v69
	s_waitcnt lgkmcnt(0)
	v_add_f32_e32 v68, v82, v83
	ds_bpermute_b32 v69, v116, v68
	v_cvt_pk_bf16_f32 v73, v70, v71
	v_cvt_pk_bf16_f32 v74, v64, v65
	v_cvt_pk_bf16_f32 v75, v66, v67
	global_store_dwordx4 v[80:81], v[72:75], off offset:256 sc1
	s_and_saveexec_b64 s[4:5], vcc
	s_cbranch_execz .LBB0_643
	s_add_u32 s18, s81, s16
	s_addc_u32 s19, s82, s17
	s_waitcnt lgkmcnt(0)
	v_add_f32_e32 v66, v68, v69
	v_lshl_add_u64 v[64:65], v[132:133], 2, s[18:19]
	global_store_dword v[64:65], v66, off offset:192
.LBB0_643:
	s_or_b64 exec, exec, s[4:5]
	v_mul_f32_e32 v66, v61, v61
	v_mul_f32_e32 v67, v63, v63
	v_fmac_f32_e32 v66, v60, v60
	v_fmac_f32_e32 v67, v62, v62
	v_add_f32_e32 v66, v66, v67
	v_mul_f32_e32 v67, v57, v57
	v_fmac_f32_e32 v67, v56, v56
	v_cvt_pk_bf16_f32 v60, v60, v61
	v_cvt_pk_bf16_f32 v61, v62, v63
	v_cvt_pk_bf16_f32 v62, v56, v57
	v_mul_f32_e32 v56, v53, v53
	v_mul_f32_e32 v57, v55, v55
	v_fmac_f32_e32 v56, v52, v52
	v_fmac_f32_e32 v57, v54, v54
	v_add_f32_e32 v56, v56, v57
	v_mul_f32_e32 v57, v49, v49
	v_fmac_f32_e32 v57, v48, v48
	v_add_f32_e32 v66, v67, v66
	v_mul_f32_e32 v67, v59, v59
	v_add_f32_e32 v56, v57, v56
	v_mul_f32_e32 v57, v51, v51
	v_fmac_f32_e32 v67, v58, v58
	v_fmac_f32_e32 v57, v50, v50
	v_add_f32_e32 v66, v67, v66
	v_add_f32_e32 v56, v57, v56
	v_cvt_pk_bf16_f32 v63, v58, v59
	v_add_f32_e32 v58, v56, v66
	ds_bpermute_b32 v59, v124, v58
	s_mov_b64 s[4:5], 0x100000
	v_lshl_add_u64 v[64:65], v[134:135], 0, s[4:5]
	s_mov_b32 s4, 0x100000
	v_add_co_u32_e64 v56, s[4:5], s4, v134
	s_nop 1
	v_addc_co_u32_e64 v57, s[4:5], 0, v135, s[4:5]
	global_store_dwordx4 v[56:57], v[60:63], off sc1
	v_cvt_pk_bf16_f32 v56, v52, v53
	s_waitcnt lgkmcnt(0)
	v_add_f32_e32 v52, v58, v59
	ds_bpermute_b32 v53, v116, v52
	v_cvt_pk_bf16_f32 v57, v54, v55
	v_cvt_pk_bf16_f32 v58, v48, v49
	v_cvt_pk_bf16_f32 v59, v50, v51
	global_store_dwordx4 v[64:65], v[56:59], off offset:256 sc1
	s_and_saveexec_b64 s[4:5], vcc
	s_cbranch_execz .LBB0_645
	s_add_u32 s18, s81, s16
	s_addc_u32 s19, s82, s17
	s_waitcnt lgkmcnt(0)
	v_add_f32_e32 v50, v52, v53
	v_lshl_add_u64 v[48:49], v[132:133], 2, s[18:19]
	global_store_dword v[48:49], v50, off offset:512
; __device__ __forceinline__ u32x4 pack8(const f32x4 v0, const f32x4 v1) { u32x4 w; w.x = cvt_pk_bf16(v0[0], v0[1]); w.y = cvt_pk_bf16(v0[2], v0[3]); w.z = cvt_pk_bf16(v1[0], v1[1]); w.w = cvt_pk_bf16(v1[2], v1[3]); return w; }
;     __device__ __forceinline__ void operator()(AccT& acc, const Unit& u, int wr, int wc, int fr, int fq) const {
;         const int row0 = u.pm * 256 + wr * 64 + fr, col0 = u.pn * 256 + wc * 32 + 8 * fq;
; #pragma unroll
;         for (int ai = 0; ai < 2; ++ai)
; #pragma unroll
;             for (int m = 0; m < 4; ++m) { const int row = row0 + ai * 128 + m * 16; bf16_t* rowp = O + (size_t)row * DM + col0; float ss = 0.f;
; #pragma unroll
;                 for (int bj = 0; bj < 2; ++bj) { const f32x4 v0 = acc[ai][bj][m][0], v1 = acc[ai][bj][m][1];
;                     ss += (v0[0] * v0[0] + v0[1] * v0[1]) + (v0[2] * v0[2] + v0[3] * v0[3]) + (v1[0] * v1[0] + v1[1] * v1[1]) + (v1[2] * v1[2] + v1[3] * v1[3]);
;                     *(u32x4*)(rowp + bj * 128) = pack8(v0, v1); }
;                 ss += __shfl_xor(ss, 16); ss += __shfl_xor(ss, 32);
;                 if (fq == 0) SSQ[(size_t)(u.pn * 4 + wc) * MT + row] = ss; }
.LBB0_645:
	s_or_b64 exec, exec, s[4:5]
	v_mul_f32_e32 v50, v45, v45
	v_mul_f32_e32 v51, v47, v47
	v_fmac_f32_e32 v50, v44, v44
	v_fmac_f32_e32 v51, v46, v46
	v_add_f32_e32 v50, v50, v51
	v_mul_f32_e32 v51, v41, v41
	v_fmac_f32_e32 v51, v40, v40
	v_cvt_pk_bf16_f32 v44, v44, v45
	v_cvt_pk_bf16_f32 v45, v46, v47
	v_cvt_pk_bf16_f32 v46, v40, v41
	v_mul_f32_e32 v40, v37, v37
	v_mul_f32_e32 v41, v39, v39
	v_fmac_f32_e32 v40, v36, v36
	v_fmac_f32_e32 v41, v38, v38
	v_add_f32_e32 v40, v40, v41
	v_mul_f32_e32 v41, v33, v33
	v_fmac_f32_e32 v41, v32, v32
	v_add_f32_e32 v50, v51, v50
	v_mul_f32_e32 v51, v43, v43
	v_add_f32_e32 v40, v41, v40
	v_mul_f32_e32 v41, v35, v35
	v_fmac_f32_e32 v51, v42, v42
	v_fmac_f32_e32 v41, v34, v34
	v_add_f32_e32 v50, v51, v50
	v_add_f32_e32 v40, v41, v40
	v_cvt_pk_bf16_f32 v47, v42, v43
	v_add_f32_e32 v42, v40, v50
	ds_bpermute_b32 v43, v124, v42
	v_add_co_u32_e64 v40, s[4:5], s97, v134
	v_lshl_add_u64 v[48:49], v[134:135], 0, s[44:45]
	s_nop 0
	v_addc_co_u32_e64 v41, s[4:5], 0, v135, s[4:5]
	global_store_dwordx4 v[40:41], v[44:47], off sc1
	v_cvt_pk_bf16_f32 v40, v36, v37
	s_waitcnt lgkmcnt(0)
	v_add_f32_e32 v36, v42, v43
	ds_bpermute_b32 v37, v116, v36
	v_cvt_pk_bf16_f32 v41, v38, v39
	v_cvt_pk_bf16_f32 v42, v32, v33
	v_cvt_pk_bf16_f32 v43, v34, v35
	global_store_dwordx4 v[48:49], v[40:43], off offset:256 sc1
	s_and_saveexec_b64 s[4:5], vcc
	s_cbranch_execz .LBB0_647
	s_add_u32 s18, s81, s16
	s_addc_u32 s19, s82, s17
	s_waitcnt lgkmcnt(0)
	v_add_f32_e32 v34, v36, v37
	v_lshl_add_u64 v[32:33], v[132:133], 2, s[18:19]
	global_store_dword v[32:33], v34, off offset:576
.LBB0_647:
	s_or_b64 exec, exec, s[4:5]
	v_mul_f32_e32 v34, v29, v29
	v_mul_f32_e32 v35, v31, v31
	v_fmac_f32_e32 v34, v28, v28
	v_fmac_f32_e32 v35, v30, v30
	v_add_f32_e32 v34, v34, v35
	v_mul_f32_e32 v35, v25, v25
	v_fmac_f32_e32 v35, v24, v24
	v_cvt_pk_bf16_f32 v28, v28, v29
	v_cvt_pk_bf16_f32 v29, v30, v31
	v_cvt_pk_bf16_f32 v30, v24, v25
	v_mul_f32_e32 v24, v21, v21
	v_mul_f32_e32 v25, v23, v23
	v_fmac_f32_e32 v24, v20, v20
	v_fmac_f32_e32 v25, v22, v22
	v_add_f32_e32 v24, v24, v25
	v_mul_f32_e32 v25, v17, v17
	v_fmac_f32_e32 v25, v16, v16
	v_add_f32_e32 v34, v35, v34
	v_mul_f32_e32 v35, v27, v27
	v_add_f32_e32 v24, v25, v24
	v_mul_f32_e32 v25, v19, v19
	v_fmac_f32_e32 v35, v26, v26
	v_fmac_f32_e32 v25, v18, v18
	v_add_f32_e32 v34, v35, v34
	v_add_f32_e32 v24, v25, v24
	v_cvt_pk_bf16_f32 v31, v26, v27
	v_add_f32_e32 v26, v24, v34
	ds_bpermute_b32 v27, v124, v26
	v_add_co_u32_e64 v24, s[4:5], s33, v134
	v_lshl_add_u64 v[32:33], v[134:135], 0, s[46:47]
	s_nop 0
	v_addc_co_u32_e64 v25, s[4:5], 0, v135, s[4:5]
	global_store_dwordx4 v[24:25], v[28:31], off sc1
	v_cvt_pk_bf16_f32 v24, v20, v21
	s_waitcnt lgkmcnt(0)
	v_add_f32_e32 v20, v26, v27
	ds_bpermute_b32 v21, v116, v20
	v_cvt_pk_bf16_f32 v25, v22, v23
	v_cvt_pk_bf16_f32 v26, v16, v17
	v_cvt_pk_bf16_f32 v27, v18, v19
	global_store_dwordx4 v[32:33], v[24:27], off offset:256 sc1
	s_and_saveexec_b64 s[4:5], vcc
	s_cbranch_execz .LBB0_649
	s_add_u32 s18, s81, s16
	s_addc_u32 s19, s82, s17
	s_waitcnt lgkmcnt(0)
	v_add_f32_e32 v18, v20, v21
	v_lshl_add_u64 v[16:17], v[132:133], 2, s[18:19]
	global_store_dword v[16:17], v18, off offset:640
.LBB0_649:
	s_or_b64 exec, exec, s[4:5]
	v_mul_f32_e32 v18, v13, v13
	v_mul_f32_e32 v19, v15, v15
	v_fmac_f32_e32 v18, v12, v12
	v_fmac_f32_e32 v19, v14, v14
	v_add_f32_e32 v18, v18, v19
	v_mul_f32_e32 v19, v9, v9
	v_fmac_f32_e32 v19, v8, v8
	v_cvt_pk_bf16_f32 v12, v12, v13
	v_cvt_pk_bf16_f32 v13, v14, v15
	v_cvt_pk_bf16_f32 v14, v8, v9
	v_mul_f32_e32 v8, v5, v5
	v_mul_f32_e32 v9, v7, v7
	v_fmac_f32_e32 v8, v4, v4
	v_fmac_f32_e32 v9, v6, v6
	v_add_f32_e32 v8, v8, v9
	v_mul_f32_e32 v9, v1, v1
	v_fmac_f32_e32 v9, v0, v0
	v_add_f32_e32 v18, v19, v18
	v_mul_f32_e32 v19, v11, v11
	v_add_f32_e32 v8, v9, v8
	v_mul_f32_e32 v9, v3, v3
	v_fmac_f32_e32 v19, v10, v10
	v_fmac_f32_e32 v9, v2, v2
	v_add_f32_e32 v18, v19, v18
	v_add_f32_e32 v8, v9, v8
	v_cvt_pk_bf16_f32 v15, v10, v11
	v_add_f32_e32 v10, v8, v18
	ds_bpermute_b32 v11, v124, v10
	v_add_co_u32_e64 v8, s[4:5], s62, v134
	v_lshl_add_u64 v[16:17], v[134:135], 0, s[48:49]
	s_nop 0
	v_addc_co_u32_e64 v9, s[4:5], 0, v135, s[4:5]
	global_store_dwordx4 v[8:9], v[12:15], off sc1
	v_cvt_pk_bf16_f32 v8, v4, v5
	s_waitcnt lgkmcnt(0)
	v_add_f32_e32 v4, v10, v11
	ds_bpermute_b32 v5, v116, v4
	v_cvt_pk_bf16_f32 v9, v6, v7
	v_cvt_pk_bf16_f32 v10, v0, v1
	v_cvt_pk_bf16_f32 v11, v2, v3
	global_store_dwordx4 v[16:17], v[8:11], off offset:256 sc1
	s_and_saveexec_b64 s[4:5], vcc
	s_cbranch_execz .LBB0_651
	s_add_u32 s16, s81, s16
	s_addc_u32 s17, s82, s17
	s_waitcnt lgkmcnt(0)
	v_add_f32_e32 v2, v4, v5
	v_lshl_add_u64 v[0:1], v[132:133], 2, s[16:17]
	global_store_dword v[0:1], v2, off offset:704

; #define LAS __attribute__((address_space(3)))
;     __device__ __forceinline__ int xidx(int ai, int w_r, int wc, int rsel, int fq, int bj, int n) const { return (((((ai * 2 + w_r) * 4 + wc) * 2 + rsel) * 4 + fq) * 4 + bj * 2 + n) * 16; }
;     __device__ __forceinline__ void operator()(AccT& acc, const Unit& u, int wr, int wc, int fr, int fq) const {
;         const int t0 = u.pm * 256, lcol = 32 * wc + 8 * fq;
;         if (fr >= 14) {
; #pragma unroll
;             for (int ai = 0; ai < 2; ++ai)
; #pragma unroll
;                 for (int bj = 0; bj < 2; ++bj)
; #pragma unroll
;                     for (int n = 0; n < 2; ++n) *(LAS f32x4*)(xl + xidx(ai, wr, wc, fr - 14, fq, bj, n)) = acc[ai][bj][3][n];
;             if (wr == 1) {
; #pragma unroll
;                 for (int bj = 0; bj < 2; ++bj)
; #pragma unroll
;                     for (int n = 0; n < 2; ++n) *(f32x4*)(HB + (size_t)(u.pm * 4 + fr - 14) * FF2 + u.pn * 256 + bj * 128 + lcol + 4 * n) = acc[1][bj][3][n]; }
;         }
;         if (wr == 0 && fr < 2) {
; #pragma unroll
;             for (int bj = 0; bj < 2; ++bj)
; #pragma unroll
;                 for (int n = 0; n < 2; ++n) *(f32x4*)(HB + (size_t)(u.pm * 4 + 2 + fr) * FF2 + u.pn * 256 + bj * 128 + lcol + 4 * n) = acc[0][bj][0][n]; }
.LBB0_781:
	v_mov_b32_e32 v108, v254
	v_cndmask_b32_e64 v118, 0, 1, s[26:27]
	v_and_b32_e32 v199, 15, v108
	v_bfe_u32 v108, v108, 4, 2
	v_lshl_or_b32 v109, v108, 3, s77
	v_cmp_lt_u32_e64 s[6:7], 13, v199
	v_lshl_or_b32 v108, v199, 2, v108
	v_cmp_ne_u32_e64 s[4:5], 1, v118
	s_and_saveexec_b64 s[12:13], s[6:7]
	s_cbranch_execz .LBB0_784
	v_add_u32_e32 v118, s85, v108
	v_lshl_add_u32 v118, v118, 6, 0
	v_add_u32_e32 v118, 0x1f200, v118
	s_and_b64 vcc, exec, s[4:5]
	ds_write_b128 v118, v[110:113]
	ds_write_b128 v118, v[36:39] offset:16
	ds_write_b128 v118, v[96:99] offset:32
	ds_write_b128 v118, v[32:35] offset:48
	ds_write_b128 v118, v[72:75] offset:4096
	ds_write_b128 v118, v[4:7] offset:4112
	ds_write_b128 v118, v[64:67] offset:4128
	ds_write_b128 v118, v[0:3] offset:4144
	s_cbranch_vccnz .LBB0_784
	s_lshl_b32 s8, s50, 2
	v_add3_u32 v120, s8, -14, v199
	s_lshl_b32 s8, s3, 8
	v_mov_b64_e32 v[118:119], s[38:39]
	s_ashr_i32 s9, s8, 31
	v_mad_i64_i32 v[118:119], s[16:17], v120, s93, v[118:119]
	v_lshl_add_u64 v[118:119], s[8:9], 2, v[118:119]
	v_lshlrev_b32_e32 v184, 2, v109
	v_lshl_add_u64 v[118:119], v[118:119], 0, v[184:185]
	global_store_dwordx4 v[118:119], v[72:75], off sc1
	global_store_dwordx4 v[118:119], v[4:7], off offset:16 sc1
	global_store_dwordx4 v[118:119], v[64:67], off offset:512 sc1
	global_store_dwordx4 v[118:119], v[0:3], off offset:528 sc1
.LBB0_784:
	s_or_b64 exec, exec, s[12:13]
	v_cmp_gt_u32_e32 vcc, 2, v199
	s_and_b64 s[8:9], s[40:41], vcc
	s_and_saveexec_b64 s[12:13], s[8:9]
	s_cbranch_execz .LBB0_786
	s_lshl_b32 s8, s50, 2
	v_or3_b32 v120, v199, s8, 2
	s_lshl_b32 s8, s3, 8
	v_mov_b64_e32 v[118:119], s[38:39]
	s_ashr_i32 s9, s8, 31
	v_mad_i64_i32 v[118:119], s[16:17], v120, s93, v[118:119]
	v_lshl_add_u64 v[118:119], s[8:9], 2, v[118:119]
	v_lshlrev_b32_e32 v184, 2, v109
	v_lshl_add_u64 v[118:119], v[118:119], 0, v[184:185]
	global_store_dwordx4 v[118:119], v[158:161], off sc1
	global_store_dwordx4 v[118:119], v[60:63], off offset:16 sc1
	global_store_dwordx4 v[118:119], v[104:107], off offset:512 sc1
	global_store_dwordx4 v[118:119], v[56:59], off offset:528 sc1

; #define LAS __attribute__((address_space(3)))
; __device__ __forceinline__ unsigned cvt_pk_bf16(float lo, float hi) { unsigned r; asm volatile("v_cvt_pk_bf16_f32 %0, %1, %2" : "=v"(r) : "v"(lo), "v"(hi)); return r; }
; __device__ __forceinline__ float gelu_t(float x) { const float u = 1.5957691216f * (x + 0.044715f * x * x * x); return x * sigm(u); }
; __device__ __forceinline__ float dpp_shr1(float old, float src) { return __int_as_float(__builtin_amdgcn_update_dpp(__float_as_int(old), __float_as_int(src), 0x111, 0xf, 0xf, false)); }
; __device__ __forceinline__ float dpp_shr2(float old, float src) { return __int_as_float(__builtin_amdgcn_update_dpp(__float_as_int(old), __float_as_int(src), 0x112, 0xf, 0xf, false)); }
;     __device__ __forceinline__ void operator()(AccT& acc, const Unit& u, int wr, int wc, int fr, int fq) const {
;     ...
;             for (int ai = 0; ai < 2; ++ai) {
;                 f32x4 hv[2]; hv[0] = (f32x4){0.f, 0.f, 0.f, 0.f}; hv[1] = hv[0];
;                 const bool has_pred = (wr == 1) || (ai == 1);
;                 const int pa = (wr == 1) ? ai : 0, pw = (wr == 1) ? 0 : 1;
;                 if (has_pred && fr >= 14) { hv[0] = *(const LAS f32x4*)(xl + xidx(pa, pw, wc, fr - 14, fq, 0, n)); hv[1] = *(const LAS f32x4*)(xl + xidx(pa, pw, wc, fr - 14, fq, 1, n)); }
; #pragma unroll
;                 for (int m = 0; m < 4; ++m) {
;                     f32x4 c2[2];
; #pragma unroll
;                     for (int bj = 0; bj < 2; ++bj) { const f32x4 cur = acc[ai][bj][m][n]; const f32x4 pv = (m == 0) ? hv[bj] : acc[ai][bj][m == 0 ? 0 : m - 1][n];
; #pragma unroll
;                         for (int j = 0; j < 4; ++j) { const float p1 = dpp_shr1(dpp_ror1(pv[j]), cur[j]), p2 = dpp_shr2(dpp_ror2(pv[j]), cur[j]);
;                             c2[bj][j] = bia[bj][j] + wgt[bj][0][j] * p2 + wgt[bj][1][j] * p1 + wgt[bj][2][j] * cur[j]; } }
;                     u32x2 w; w.x = cvt_pk_bf16(gelu_t(c2[0][0]) * c2[1][0], gelu_t(c2[0][1]) * c2[1][1]); w.y = cvt_pk_bf16(gelu_t(c2[0][2]) * c2[1][2], gelu_t(c2[0][3]) * c2[1][3]);
;                     if (n == 0) pend[ai][m] = w;
;                     else { u32x4 w4; w4.x = pend[ai][m].x; w4.y = pend[ai][m].y; w4.z = w.x; w4.w = w.y;
;                         *(u32x4*)(F + (size_t)(t0 + ai * 128 + wr * 64 + m * 16 + fr) * FF + cg - 4) = w4; }
.LBB0_792:
	s_or_b64 exec, exec, s[16:17]
	v_mov_b32_e32 v126, 0
	v_mov_b32_e32 v127, 0
	v_mov_b32_e32 v82, 0
	s_waitcnt lgkmcnt(1)
	v_mov_b32_dpp v126, v122 row_ror:2 row_mask:0xf bank_mask:0xf
	v_mov_b32_e32 v128, 0
	v_mov_b32_e32 v130, 0
	v_mov_b32_e32 v83, 0
	s_waitcnt lgkmcnt(0)
	v_mov_b32_dpp v127, v118 row_ror:2 row_mask:0xf bank_mask:0xf
	v_mov_b32_dpp v82, v122 row_ror:1 row_mask:0xf bank_mask:0xf
	v_mov_b32_dpp v126, v60 row_shr:2 row_mask:0xf bank_mask:0xf
	v_mov_b32_dpp v128, v123 row_ror:1 row_mask:0xf bank_mask:0xf
	v_mov_b32_dpp v130, v123 row_ror:2 row_mask:0xf bank_mask:0xf
	v_mov_b32_e32 v134, 0
	v_mov_b32_e32 v136, 0
	v_mov_b32_e32 v138, 0
	v_mov_b32_e32 v140, 0
	v_mov_b32_dpp v83, v118 row_ror:1 row_mask:0xf bank_mask:0xf
	v_mov_b32_dpp v127, v56 row_shr:2 row_mask:0xf bank_mask:0xf
	s_waitcnt vmcnt(6)
	v_mov_b32_e32 v78, v114
	s_waitcnt vmcnt(2)
	v_mov_b32_e32 v79, v74
	v_mov_b32_e32 v122, v100
	v_mov_b32_e32 v123, v70
	v_mov_b32_dpp v82, v60 row_shr:1 row_mask:0xf bank_mask:0xf
	v_mov_b32_dpp v134, v124 row_ror:1 row_mask:0xf bank_mask:0xf
	v_mov_b32_dpp v136, v124 row_ror:2 row_mask:0xf bank_mask:0xf
	v_mov_b32_dpp v138, v125 row_ror:1 row_mask:0xf bank_mask:0xf
	v_mov_b32_dpp v140, v125 row_ror:2 row_mask:0xf bank_mask:0xf
	v_mov_b32_dpp v83, v56 row_shr:1 row_mask:0xf bank_mask:0xf
	v_pk_fma_f32 v[126:127], v[78:79], v[126:127], v[122:123]
	v_mov_b32_e32 v124, v110
	s_waitcnt vmcnt(1)
	v_mov_b32_e32 v125, v84
	v_mov_b32_e32 v131, 0
	v_pk_fma_f32 v[82:83], v[124:125], v[82:83], v[126:127]
	v_mov_b32_e32 v142, v60
	v_mov_b32_e32 v143, v56
	v_mov_b32_e32 v126, v92
	s_waitcnt vmcnt(0)
	v_mov_b32_e32 v127, v66
	v_mov_b32_dpp v131, v119 row_ror:2 row_mask:0xf bank_mask:0xf
	v_mov_b32_dpp v130, v61 row_shr:2 row_mask:0xf bank_mask:0xf
	v_pk_fma_f32 v[82:83], v[142:143], v[126:127], v[82:83]
	v_mov_b32_dpp v131, v57 row_shr:2 row_mask:0xf bank_mask:0xf
	v_mov_b32_e32 v74, v115
	v_mov_b32_e32 v70, v101
	v_mov_b32_e32 v129, 0
	v_pk_fma_f32 v[100:101], v[74:75], v[130:131], v[70:71]
	v_mov_b32_e32 v131, v68
	v_mul_f32_e32 v68, 0x3d372713, v82
	v_mov_b32_dpp v129, v119 row_ror:1 row_mask:0xf bank_mask:0xf
	v_mul_f32_e32 v68, v82, v68
	v_mov_b32_dpp v128, v61 row_shr:1 row_mask:0xf bank_mask:0xf
	v_mov_b32_dpp v129, v57 row_shr:1 row_mask:0xf bank_mask:0xf
	v_mov_b32_e32 v84, v111
	v_fma_f32 v68, v82, v68, v82
	v_pk_fma_f32 v[100:101], v[84:85], v[128:129], v[100:101]
	v_mov_b32_e32 v110, v61
	v_mov_b32_e32 v111, v57
	v_mov_b32_e32 v66, v93
	v_mul_f32_e32 v68, 0x3fcc422a, v68
	v_pk_fma_f32 v[92:93], v[110:111], v[66:67], v[100:101]
	v_mul_f32_e32 v68, 0xbfb8aa3b, v68
	v_exp_f32_e32 v91, v68
	v_mul_f32_e32 v68, 0x3d372713, v92
	v_mul_f32_e32 v68, v92, v68
	v_fma_f32 v68, v92, v68, v92
	v_mul_f32_e32 v68, 0x3fcc422a, v68
	v_mul_f32_e32 v68, 0xbfb8aa3b, v68
	v_mov_b32_e32 v130, v94
	v_exp_f32_e32 v94, v68
	v_mov_b32_e32 v137, 0
	v_mov_b32_e32 v135, 0
	v_mov_b32_e32 v141, 0
	v_mov_b32_dpp v137, v120 row_ror:2 row_mask:0xf bank_mask:0xf
	v_add_f32_e32 v91, 1.0, v91
	v_mov_b32_dpp v136, v62 row_shr:2 row_mask:0xf bank_mask:0xf
	v_mov_b32_dpp v135, v120 row_ror:1 row_mask:0xf bank_mask:0xf
	v_mov_b32_dpp v137, v58 row_shr:2 row_mask:0xf bank_mask:0xf
	v_mov_b32_e32 v114, v116
	v_mov_b32_e32 v115, v76
	v_mov_b32_e32 v118, v102
	v_mov_b32_e32 v119, v72
	v_mov_b32_e32 v139, 0
	v_mov_b32_dpp v141, v121 row_ror:2 row_mask:0xf bank_mask:0xf
	v_rcp_f32_e32 v91, v91
	v_add_f32_e32 v94, 1.0, v94
	v_mov_b32_dpp v134, v62 row_shr:1 row_mask:0xf bank_mask:0xf
	v_mov_b32_dpp v140, v63 row_shr:2 row_mask:0xf bank_mask:0xf
	v_mov_b32_dpp v135, v58 row_shr:1 row_mask:0xf bank_mask:0xf
	v_pk_fma_f32 v[100:101], v[114:115], v[136:137], v[118:119]
	v_mov_b32_e32 v128, v112
	v_mov_b32_e32 v129, v86
	v_mov_b32_dpp v139, v121 row_ror:1 row_mask:0xf bank_mask:0xf
	v_mov_b32_dpp v141, v59 row_shr:2 row_mask:0xf bank_mask:0xf
	v_mov_b32_e32 v76, v117
	v_mov_b32_e32 v72, v103
	v_rcp_f32_e32 v112, v94
	v_mov_b32_dpp v138, v63 row_shr:1 row_mask:0xf bank_mask:0xf
	v_pk_fma_f32 v[100:101], v[128:129], v[134:135], v[100:101]
	v_mov_b32_e32 v110, v62
	v_mov_b32_e32 v111, v58
	v_mov_b32_dpp v139, v59 row_shr:1 row_mask:0xf bank_mask:0xf
	v_pk_fma_f32 v[102:103], v[76:77], v[140:141], v[72:73]
	v_mov_b32_e32 v86, v113
	v_pk_fma_f32 v[100:101], v[110:111], v[130:131], v[100:101]
	v_pk_fma_f32 v[102:103], v[86:87], v[138:139], v[102:103]
	v_mov_b32_e32 v110, v63
	v_mov_b32_e32 v111, v59
	v_mov_b32_e32 v68, v95
	v_pk_fma_f32 v[94:95], v[110:111], v[68:69], v[102:103]
	v_mul_f32_e32 v82, v82, v91
	v_mul_f32_e32 v82, v82, v83
	v_mul_f32_e32 v83, v92, v112
	v_mul_f32_e32 v91, 0x3d372713, v100
	v_mul_f32_e32 v92, 0x3d372713, v94
	v_mul_f32_e32 v91, v100, v91
	v_mul_f32_e32 v92, v94, v92
	v_fma_f32 v91, v100, v91, v100
	v_fma_f32 v92, v94, v92, v94
	v_mul_f32_e32 v91, 0x3fcc422a, v91
	v_mul_f32_e32 v92, 0x3fcc422a, v92
	v_mul_f32_e32 v91, 0xbfb8aa3b, v91
	v_mul_f32_e32 v92, 0xbfb8aa3b, v92
	v_exp_f32_e32 v91, v91
	v_exp_f32_e32 v92, v92
	v_mul_f32_e32 v83, v83, v93
	s_lshl_b32 s3, s50, 8
	v_add_f32_e32 v91, 1.0, v91
	v_add_f32_e32 v92, 1.0, v92
	v_rcp_f32_e32 v91, v91
	v_rcp_f32_e32 v92, v92
	v_cvt_pk_bf16_f32 v110, v82, v83
	s_add_i32 s3, s3, s76
	v_mul_f32_e32 v82, v100, v91
	v_mul_f32_e32 v83, v94, v92
	v_mul_f32_e32 v82, v82, v101
	v_mul_f32_e32 v83, v83, v95
	v_or_b32_e32 v132, s3, v199
	v_cvt_pk_bf16_f32 v111, v82, v83
	v_mov_b64_e32 v[82:83], s[36:37]
	v_mad_i64_i32 v[92:93], s[8:9], v132, s94, v[82:83]
	v_lshlrev_b64 v[94:95], 1, v[186:187]
	v_lshl_add_u64 v[92:93], v[92:93], 0, v[94:95]
	v_mov_b32_e32 v100, 0
	v_mov_b32_e32 v101, 0
	global_store_dwordx4 v[92:93], v[108:111], off sc1
; __device__ __forceinline__ unsigned cvt_pk_bf16(float lo, float hi) { unsigned r; asm volatile("v_cvt_pk_bf16_f32 %0, %1, %2" : "=v"(r) : "v"(lo), "v"(hi)); return r; }
; __device__ __forceinline__ float gelu_t(float x) { const float u = 1.5957691216f * (x + 0.044715f * x * x * x); return x * sigm(u); }
; __device__ __forceinline__ float dpp_shr1(float old, float src) { return __int_as_float(__builtin_amdgcn_update_dpp(__float_as_int(old), __float_as_int(src), 0x111, 0xf, 0xf, false)); }
; __device__ __forceinline__ float dpp_shr2(float old, float src) { return __int_as_float(__builtin_amdgcn_update_dpp(__float_as_int(old), __float_as_int(src), 0x112, 0xf, 0xf, false)); }
; __device__ __forceinline__ float dpp_ror1(float src) { return __int_as_float(__builtin_amdgcn_update_dpp(0, __float_as_int(src), 0x121, 0xf, 0xf, false)); }
; __device__ __forceinline__ float dpp_ror2(float src) { return __int_as_float(__builtin_amdgcn_update_dpp(0, __float_as_int(src), 0x122, 0xf, 0xf, false)); }
;     __device__ __forceinline__ void operator()(AccT& acc, const Unit& u, int wr, int wc, int fr, int fq) const {
;     ...
;                 for (int m = 0; m < 4; ++m) {
;                     f32x4 c2[2];
; #pragma unroll
;                     for (int bj = 0; bj < 2; ++bj) { const f32x4 cur = acc[ai][bj][m][n]; const f32x4 pv = (m == 0) ? hv[bj] : acc[ai][bj][m == 0 ? 0 : m - 1][n];
; #pragma unroll
;                         for (int j = 0; j < 4; ++j) { const float p1 = dpp_shr1(dpp_ror1(pv[j]), cur[j]), p2 = dpp_shr2(dpp_ror2(pv[j]), cur[j]);
;                             c2[bj][j] = bia[bj][j] + wgt[bj][0][j] * p2 + wgt[bj][1][j] * p1 + wgt[bj][2][j] * cur[j]; } }
;                     u32x2 w; w.x = cvt_pk_bf16(gelu_t(c2[0][0]) * c2[1][0], gelu_t(c2[0][1]) * c2[1][1]); w.y = cvt_pk_bf16(gelu_t(c2[0][2]) * c2[1][2], gelu_t(c2[0][3]) * c2[1][3]);
;                     if (n == 0) pend[ai][m] = w;
;                     else { u32x4 w4; w4.x = pend[ai][m].x; w4.y = pend[ai][m].y; w4.z = w.x; w4.w = w.y;
;                         *(u32x4*)(F + (size_t)(t0 + ai * 128 + wr * 64 + m * 16 + fr) * FF + cg - 4) = w4; }
	v_mov_b32_e32 v92, 0
	v_mov_b32_dpp v100, v60 row_ror:2 row_mask:0xf bank_mask:0xf
	v_mov_b32_e32 v108, 0
	v_mov_b32_e32 v110, 0
	v_mov_b32_e32 v93, 0
	v_mov_b32_dpp v101, v56 row_ror:2 row_mask:0xf bank_mask:0xf
	v_mov_b32_dpp v92, v60 row_ror:1 row_mask:0xf bank_mask:0xf
	v_mov_b32_dpp v100, v52 row_shr:2 row_mask:0xf bank_mask:0xf
	v_mov_b32_dpp v108, v62 row_ror:1 row_mask:0xf bank_mask:0xf
	v_mov_b32_dpp v110, v62 row_ror:2 row_mask:0xf bank_mask:0xf
	v_mov_b32_e32 v62, 0
	v_mov_b32_e32 v112, 0
	v_mov_b32_dpp v93, v56 row_ror:1 row_mask:0xf bank_mask:0xf
	v_mov_b32_dpp v101, v48 row_shr:2 row_mask:0xf bank_mask:0xf
	v_mov_b32_e32 v113, 0
	v_mov_b32_dpp v92, v52 row_shr:1 row_mask:0xf bank_mask:0xf
	v_mov_b32_dpp v62, v63 row_ror:1 row_mask:0xf bank_mask:0xf
	v_mov_b32_dpp v112, v63 row_ror:2 row_mask:0xf bank_mask:0xf
	v_mov_b32_dpp v93, v48 row_shr:1 row_mask:0xf bank_mask:0xf
	v_pk_fma_f32 v[100:101], v[78:79], v[100:101], v[122:123]
	v_mov_b32_e32 v63, 0
	v_mov_b32_dpp v113, v59 row_ror:2 row_mask:0xf bank_mask:0xf
	v_mov_b32_dpp v112, v55 row_shr:2 row_mask:0xf bank_mask:0xf
	v_pk_fma_f32 v[92:93], v[124:125], v[92:93], v[100:101]
	v_mov_b32_e32 v100, v52
	v_mov_b32_e32 v101, v48
	v_mov_b32_e32 v109, 0
	v_mov_b32_e32 v111, 0
	v_mov_b32_dpp v63, v59 row_ror:1 row_mask:0xf bank_mask:0xf
	v_mov_b32_dpp v113, v51 row_shr:2 row_mask:0xf bank_mask:0xf
	v_mov_b32_dpp v62, v55 row_shr:1 row_mask:0xf bank_mask:0xf
	v_pk_fma_f32 v[92:93], v[100:101], v[126:127], v[92:93]
	v_mov_b32_dpp v109, v58 row_ror:1 row_mask:0xf bank_mask:0xf
	v_mov_b32_dpp v111, v58 row_ror:2 row_mask:0xf bank_mask:0xf
	v_mov_b32_dpp v63, v51 row_shr:1 row_mask:0xf bank_mask:0xf
	v_pk_fma_f32 v[58:59], v[76:77], v[112:113], v[72:73]
	v_mov_b32_e32 v60, 0
	v_pk_fma_f32 v[58:59], v[86:87], v[62:63], v[58:59]
	v_mul_f32_e32 v63, 0x3d372713, v92
	v_mov_b32_e32 v102, 0
	v_mov_b32_e32 v103, 0
	v_mul_f32_e32 v63, v92, v63
	v_mov_b32_dpp v60, v61 row_ror:1 row_mask:0xf bank_mask:0xf
	v_mov_b32_dpp v102, v61 row_ror:2 row_mask:0xf bank_mask:0xf
	v_mov_b32_e32 v61, 0
	v_mov_b32_dpp v103, v57 row_ror:2 row_mask:0xf bank_mask:0xf
	v_fma_f32 v63, v92, v63, v92
	v_mov_b32_dpp v102, v53 row_shr:2 row_mask:0xf bank_mask:0xf
	v_mov_b32_dpp v61, v57 row_ror:1 row_mask:0xf bank_mask:0xf
	v_mov_b32_dpp v103, v49 row_shr:2 row_mask:0xf bank_mask:0xf
	v_mul_f32_e32 v63, 0x3fcc422a, v63
	v_mov_b32_dpp v60, v53 row_shr:1 row_mask:0xf bank_mask:0xf
	v_mov_b32_dpp v61, v49 row_shr:1 row_mask:0xf bank_mask:0xf
	v_pk_fma_f32 v[56:57], v[74:75], v[102:103], v[70:71]
	v_mul_f32_e32 v63, 0xbfb8aa3b, v63
	v_pk_fma_f32 v[56:57], v[84:85], v[60:61], v[56:57]
	v_mov_b32_e32 v60, v53
	v_mov_b32_e32 v61, v49
	v_exp_f32_e32 v91, v63
	v_pk_fma_f32 v[56:57], v[60:61], v[66:67], v[56:57]
	v_mov_b32_dpp v110, v54 row_shr:2 row_mask:0xf bank_mask:0xf
	v_mul_f32_e32 v63, 0x3d372713, v56
	v_mul_f32_e32 v63, v56, v63
	v_mov_b32_dpp v111, v50 row_shr:2 row_mask:0xf bank_mask:0xf
	v_fma_f32 v63, v56, v63, v56
	v_add_f32_e32 v91, 1.0, v91
	v_mov_b32_dpp v108, v54 row_shr:1 row_mask:0xf bank_mask:0xf
	v_mov_b32_dpp v109, v50 row_shr:1 row_mask:0xf bank_mask:0xf
	v_pk_fma_f32 v[60:61], v[114:115], v[110:111], v[118:119]
	v_mul_f32_e32 v63, 0x3fcc422a, v63
	v_rcp_f32_e32 v91, v91
	v_pk_fma_f32 v[60:61], v[128:129], v[108:109], v[60:61]
	v_mov_b32_e32 v100, v54
	v_mov_b32_e32 v101, v50
	v_mul_f32_e32 v63, 0xbfb8aa3b, v63
	v_pk_fma_f32 v[60:61], v[100:101], v[130:131], v[60:61]
	v_mov_b32_e32 v62, v55
	v_exp_f32_e32 v100, v63
	v_mov_b32_e32 v63, v51
	v_pk_fma_f32 v[58:59], v[62:63], v[68:69], v[58:59]
	v_mul_f32_e32 v63, 0x3d372713, v60
	v_mul_f32_e32 v62, v92, v91
	v_mul_f32_e32 v63, v60, v63
	v_mul_f32_e32 v91, 0x3d372713, v58
	v_fma_f32 v63, v60, v63, v60
	v_mul_f32_e32 v91, v58, v91
	v_add_f32_e32 v100, 1.0, v100
	v_mul_f32_e32 v63, 0x3fcc422a, v63
	v_fma_f32 v91, v58, v91, v58
	v_rcp_f32_e32 v100, v100
	v_mul_f32_e32 v63, 0xbfb8aa3b, v63
	v_mul_f32_e32 v91, 0x3fcc422a, v91
	v_exp_f32_e32 v63, v63
	v_mul_f32_e32 v91, 0xbfb8aa3b, v91
	v_exp_f32_e32 v91, v91
	v_mul_f32_e32 v56, v56, v100
	v_mul_f32_e32 v56, v56, v57
	v_add_f32_e32 v57, 1.0, v63
	v_rcp_f32_e32 v57, v57
	v_add_f32_e32 v63, 1.0, v91
	v_rcp_f32_e32 v63, v63
	v_mul_f32_e32 v62, v62, v93
	v_cvt_pk_bf16_f32 v108, v62, v56
	v_mul_f32_e32 v56, v60, v57
	v_mul_f32_e32 v56, v56, v61
	v_mul_f32_e32 v57, v58, v63
	v_mul_f32_e32 v57, v57, v59
	v_cvt_pk_bf16_f32 v109, v56, v57
	v_or_b32_e32 v56, 16, v132
	v_mad_i64_i32 v[56:57], s[8:9], v56, s94, v[82:83]
	v_lshl_add_u64 v[56:57], v[56:57], 0, v[94:95]
	v_mov_b32_e32 v58, 0
	v_mov_b32_e32 v59, 0
	global_store_dwordx4 v[56:57], v[106:109], off sc1
	v_mov_b32_e32 v56, 0
	v_mov_b32_dpp v58, v52 row_ror:2 row_mask:0xf bank_mask:0xf
	v_mov_b32_e32 v62, 0
	v_mov_b32_e32 v92, 0
	v_mov_b32_e32 v57, 0
	v_mov_b32_dpp v59, v48 row_ror:2 row_mask:0xf bank_mask:0xf
	v_mov_b32_dpp v56, v52 row_ror:1 row_mask:0xf bank_mask:0xf
	v_mov_b32_dpp v58, v44 row_shr:2 row_mask:0xf bank_mask:0xf
	v_mov_b32_dpp v62, v54 row_ror:1 row_mask:0xf bank_mask:0xf
	v_mov_b32_dpp v92, v54 row_ror:2 row_mask:0xf bank_mask:0xf
	v_mov_b32_e32 v54, 0
	v_mov_b32_e32 v100, 0
	v_mov_b32_dpp v57, v48 row_ror:1 row_mask:0xf bank_mask:0xf
	v_mov_b32_dpp v59, v40 row_shr:2 row_mask:0xf bank_mask:0xf
	v_mov_b32_e32 v101, 0
	v_mov_b32_dpp v56, v44 row_shr:1 row_mask:0xf bank_mask:0xf
	v_mov_b32_dpp v54, v55 row_ror:1 row_mask:0xf bank_mask:0xf
	v_mov_b32_dpp v100, v55 row_ror:2 row_mask:0xf bank_mask:0xf
	v_mov_b32_dpp v57, v40 row_shr:1 row_mask:0xf bank_mask:0xf
	v_pk_fma_f32 v[58:59], v[78:79], v[58:59], v[122:123]
	v_mov_b32_e32 v55, 0
; __device__ __forceinline__ unsigned cvt_pk_bf16(float lo, float hi) { unsigned r; asm volatile("v_cvt_pk_bf16_f32 %0, %1, %2" : "=v"(r) : "v"(lo), "v"(hi)); return r; }
; __device__ __forceinline__ float gelu_t(float x) { const float u = 1.5957691216f * (x + 0.044715f * x * x * x); return x * sigm(u); }
; __device__ __forceinline__ float dpp_shr1(float old, float src) { return __int_as_float(__builtin_amdgcn_update_dpp(__float_as_int(old), __float_as_int(src), 0x111, 0xf, 0xf, false)); }
; __device__ __forceinline__ float dpp_shr2(float old, float src) { return __int_as_float(__builtin_amdgcn_update_dpp(__float_as_int(old), __float_as_int(src), 0x112, 0xf, 0xf, false)); }
; __device__ __forceinline__ float dpp_ror1(float src) { return __int_as_float(__builtin_amdgcn_update_dpp(0, __float_as_int(src), 0x121, 0xf, 0xf, false)); }
; __device__ __forceinline__ float dpp_ror2(float src) { return __int_as_float(__builtin_amdgcn_update_dpp(0, __float_as_int(src), 0x122, 0xf, 0xf, false)); }
;     __device__ __forceinline__ void operator()(AccT& acc, const Unit& u, int wr, int wc, int fr, int fq) const {
;     ...
;                 for (int m = 0; m < 4; ++m) {
;                     f32x4 c2[2];
; #pragma unroll
;                     for (int bj = 0; bj < 2; ++bj) { const f32x4 cur = acc[ai][bj][m][n]; const f32x4 pv = (m == 0) ? hv[bj] : acc[ai][bj][m == 0 ? 0 : m - 1][n];
; #pragma unroll
;                         for (int j = 0; j < 4; ++j) { const float p1 = dpp_shr1(dpp_ror1(pv[j]), cur[j]), p2 = dpp_shr2(dpp_ror2(pv[j]), cur[j]);
;                             c2[bj][j] = bia[bj][j] + wgt[bj][0][j] * p2 + wgt[bj][1][j] * p1 + wgt[bj][2][j] * cur[j]; } }
;                     u32x2 w; w.x = cvt_pk_bf16(gelu_t(c2[0][0]) * c2[1][0], gelu_t(c2[0][1]) * c2[1][1]); w.y = cvt_pk_bf16(gelu_t(c2[0][2]) * c2[1][2], gelu_t(c2[0][3]) * c2[1][3]);
;                     if (n == 0) pend[ai][m] = w;
;                     else { u32x4 w4; w4.x = pend[ai][m].x; w4.y = pend[ai][m].y; w4.z = w.x; w4.w = w.y;
;                         *(u32x4*)(F + (size_t)(t0 + ai * 128 + wr * 64 + m * 16 + fr) * FF + cg - 4) = w4; }
	v_mov_b32_dpp v101, v51 row_ror:2 row_mask:0xf bank_mask:0xf
	v_mov_b32_e32 v52, 0
	v_mov_b32_e32 v60, 0
	v_mov_b32_dpp v100, v47 row_shr:2 row_mask:0xf bank_mask:0xf
	v_pk_fma_f32 v[56:57], v[124:125], v[56:57], v[58:59]
	v_mov_b32_e32 v58, v44
	v_mov_b32_e32 v59, v40
	v_mov_b32_e32 v61, 0
	v_mov_b32_e32 v63, 0
	v_mov_b32_e32 v93, 0
	v_mov_b32_dpp v55, v51 row_ror:1 row_mask:0xf bank_mask:0xf
	v_mov_b32_dpp v101, v43 row_shr:2 row_mask:0xf bank_mask:0xf
	v_mov_b32_dpp v52, v53 row_ror:1 row_mask:0xf bank_mask:0xf
	v_mov_b32_dpp v60, v53 row_ror:2 row_mask:0xf bank_mask:0xf
	v_mov_b32_dpp v54, v47 row_shr:1 row_mask:0xf bank_mask:0xf
	v_pk_fma_f32 v[56:57], v[58:59], v[126:127], v[56:57]
	v_mov_b32_e32 v53, 0
	v_mov_b32_dpp v61, v49 row_ror:2 row_mask:0xf bank_mask:0xf
	v_mov_b32_dpp v63, v50 row_ror:1 row_mask:0xf bank_mask:0xf
	v_mov_b32_dpp v93, v50 row_ror:2 row_mask:0xf bank_mask:0xf
	v_mov_b32_dpp v55, v43 row_shr:1 row_mask:0xf bank_mask:0xf
	v_pk_fma_f32 v[50:51], v[76:77], v[100:101], v[72:73]
	v_mov_b32_dpp v60, v45 row_shr:2 row_mask:0xf bank_mask:0xf
	v_mov_b32_dpp v53, v49 row_ror:1 row_mask:0xf bank_mask:0xf
	v_mov_b32_dpp v61, v41 row_shr:2 row_mask:0xf bank_mask:0xf
	v_pk_fma_f32 v[50:51], v[86:87], v[54:55], v[50:51]
	v_mul_f32_e32 v55, 0x3d372713, v56
	v_mov_b32_dpp v52, v45 row_shr:1 row_mask:0xf bank_mask:0xf
	v_mov_b32_dpp v53, v41 row_shr:1 row_mask:0xf bank_mask:0xf
	v_pk_fma_f32 v[48:49], v[74:75], v[60:61], v[70:71]
	v_mul_f32_e32 v55, v56, v55
	v_mov_b32_dpp v92, v46 row_shr:2 row_mask:0xf bank_mask:0xf
	v_pk_fma_f32 v[48:49], v[84:85], v[52:53], v[48:49]
	v_mov_b32_e32 v52, v45
	v_mov_b32_e32 v53, v41
	v_mov_b32_dpp v93, v42 row_shr:2 row_mask:0xf bank_mask:0xf
	v_fma_f32 v55, v56, v55, v56
	v_mov_b32_dpp v62, v46 row_shr:1 row_mask:0xf bank_mask:0xf
	v_pk_fma_f32 v[48:49], v[52:53], v[66:67], v[48:49]
	v_mov_b32_dpp v63, v42 row_shr:1 row_mask:0xf bank_mask:0xf
	v_pk_fma_f32 v[52:53], v[114:115], v[92:93], v[118:119]
	v_mul_f32_e32 v55, 0x3fcc422a, v55
	v_pk_fma_f32 v[52:53], v[128:129], v[62:63], v[52:53]
	v_mov_b32_e32 v58, v46
	v_mov_b32_e32 v59, v42
	v_mul_f32_e32 v55, 0xbfb8aa3b, v55
	v_pk_fma_f32 v[52:53], v[58:59], v[130:131], v[52:53]
	v_exp_f32_e32 v58, v55
	v_mul_f32_e32 v55, 0x3d372713, v48
	v_mul_f32_e32 v55, v48, v55
	v_fma_f32 v55, v48, v55, v48
	v_add_f32_e32 v58, 1.0, v58
	v_mul_f32_e32 v55, 0x3fcc422a, v55
	v_rcp_f32_e32 v58, v58
	v_mul_f32_e32 v55, 0xbfb8aa3b, v55
	v_mov_b32_e32 v54, v47
	v_exp_f32_e32 v59, v55
	v_mov_b32_e32 v55, v43
	v_pk_fma_f32 v[50:51], v[54:55], v[68:69], v[50:51]
	v_mul_f32_e32 v55, 0x3d372713, v52
	v_mul_f32_e32 v54, v56, v58
	v_mul_f32_e32 v55, v52, v55
	v_mul_f32_e32 v56, 0x3d372713, v50
	v_fma_f32 v55, v52, v55, v52
	v_mul_f32_e32 v56, v50, v56
	v_add_f32_e32 v59, 1.0, v59
	v_mul_f32_e32 v55, 0x3fcc422a, v55
	v_fma_f32 v56, v50, v56, v50
	v_rcp_f32_e32 v59, v59
	v_mul_f32_e32 v55, 0xbfb8aa3b, v55
	v_mul_f32_e32 v56, 0x3fcc422a, v56
	v_exp_f32_e32 v55, v55
	v_mul_f32_e32 v56, 0xbfb8aa3b, v56
	v_exp_f32_e32 v56, v56
	v_mul_f32_e32 v48, v48, v59
	v_mul_f32_e32 v48, v48, v49
	v_add_f32_e32 v49, 1.0, v55
	v_rcp_f32_e32 v49, v49
	v_add_f32_e32 v55, 1.0, v56
	v_rcp_f32_e32 v55, v55
	v_mul_f32_e32 v54, v54, v57
	v_cvt_pk_bf16_f32 v106, v54, v48
	v_mul_f32_e32 v48, v52, v49
	v_mul_f32_e32 v48, v48, v53
	v_mul_f32_e32 v49, v50, v55
	v_mul_f32_e32 v49, v49, v51
	v_cvt_pk_bf16_f32 v107, v48, v49
	v_or_b32_e32 v48, 32, v132
	v_mad_i64_i32 v[48:49], s[8:9], v48, s94, v[82:83]
	v_lshl_add_u64 v[48:49], v[48:49], 0, v[94:95]
	global_store_dwordx4 v[48:49], v[104:107], off sc1
	v_mov_b32_e32 v48, 0
	v_mov_b32_e32 v50, 0
	v_mov_b32_e32 v51, 0
	v_mov_b32_dpp v48, v44 row_ror:1 row_mask:0xf bank_mask:0xf
	v_mov_b32_dpp v50, v44 row_ror:2 row_mask:0xf bank_mask:0xf
	v_mov_b32_e32 v44, 0
	v_mov_b32_e32 v52, 0
	v_mov_b32_e32 v49, 0
	v_mov_b32_dpp v51, v40 row_ror:2 row_mask:0xf bank_mask:0xf
	v_mov_b32_e32 v53, 0
	v_mov_b32_dpp v50, v36 row_shr:2 row_mask:0xf bank_mask:0xf
	v_mov_b32_dpp v44, v45 row_ror:1 row_mask:0xf bank_mask:0xf
	v_mov_b32_dpp v52, v45 row_ror:2 row_mask:0xf bank_mask:0xf
	v_mov_b32_dpp v49, v40 row_ror:1 row_mask:0xf bank_mask:0xf
	v_mov_b32_dpp v51, v32 row_shr:2 row_mask:0xf bank_mask:0xf
	v_mov_b32_e32 v45, 0
	v_mov_b32_dpp v53, v41 row_ror:2 row_mask:0xf bank_mask:0xf
	v_mov_b32_dpp v48, v36 row_shr:1 row_mask:0xf bank_mask:0xf
	v_mov_b32_dpp v52, v37 row_shr:2 row_mask:0xf bank_mask:0xf
	v_mov_b32_dpp v49, v32 row_shr:1 row_mask:0xf bank_mask:0xf
	v_pk_fma_f32 v[50:51], v[78:79], v[50:51], v[122:123]
	v_mov_b32_dpp v45, v41 row_ror:1 row_mask:0xf bank_mask:0xf
	v_mov_b32_dpp v53, v33 row_shr:2 row_mask:0xf bank_mask:0xf
	v_mov_b32_dpp v44, v37 row_shr:1 row_mask:0xf bank_mask:0xf
	v_pk_fma_f32 v[48:49], v[124:125], v[48:49], v[50:51]
	v_mov_b32_e32 v50, v36
	v_mov_b32_e32 v51, v32
	v_mov_b32_dpp v45, v33 row_shr:1 row_mask:0xf bank_mask:0xf
	v_pk_fma_f32 v[40:41], v[74:75], v[52:53], v[70:71]
	v_mov_b32_e32 v55, 0
	v_mov_b32_e32 v57, 0
	v_pk_fma_f32 v[48:49], v[50:51], v[126:127], v[48:49]
	v_pk_fma_f32 v[40:41], v[84:85], v[44:45], v[40:41]
	v_mov_b32_e32 v32, v37
	v_mov_b32_dpp v55, v42 row_ror:1 row_mask:0xf bank_mask:0xf
	v_mov_b32_dpp v57, v42 row_ror:2 row_mask:0xf bank_mask:0xf
	v_pk_fma_f32 v[32:33], v[32:33], v[66:67], v[40:41]
	v_mov_b32_dpp v55, v34 row_shr:1 row_mask:0xf bank_mask:0xf
	v_mov_b32_dpp v57, v34 row_shr:2 row_mask:0xf bank_mask:0xf
	v_mov_b32_e32 v41, v34
	v_mul_f32_e32 v34, 0x3d372713, v48
	v_mul_f32_e32 v34, v48, v34
	v_fma_f32 v34, v48, v34, v48
	v_mov_b32_e32 v54, 0
	v_mov_b32_e32 v56, 0
	v_mul_f32_e32 v34, 0x3fcc422a, v34
; #define LAS __attribute__((address_space(3)))
; __device__ __forceinline__ unsigned cvt_pk_bf16(float lo, float hi) { unsigned r; asm volatile("v_cvt_pk_bf16_f32 %0, %1, %2" : "=v"(r) : "v"(lo), "v"(hi)); return r; }
; __device__ __forceinline__ float gelu_t(float x) { const float u = 1.5957691216f * (x + 0.044715f * x * x * x); return x * sigm(u); }
; __device__ __forceinline__ float dpp_shr1(float old, float src) { return __int_as_float(__builtin_amdgcn_update_dpp(__float_as_int(old), __float_as_int(src), 0x111, 0xf, 0xf, false)); }
; __device__ __forceinline__ float dpp_shr2(float old, float src) { return __int_as_float(__builtin_amdgcn_update_dpp(__float_as_int(old), __float_as_int(src), 0x112, 0xf, 0xf, false)); }
;     __device__ __forceinline__ void operator()(AccT& acc, const Unit& u, int wr, int wc, int fr, int fq) const {
;     ...
;             for (int ai = 0; ai < 2; ++ai) {
;                 f32x4 hv[2]; hv[0] = (f32x4){0.f, 0.f, 0.f, 0.f}; hv[1] = hv[0];
;                 const bool has_pred = (wr == 1) || (ai == 1);
;                 const int pa = (wr == 1) ? ai : 0, pw = (wr == 1) ? 0 : 1;
;                 if (has_pred && fr >= 14) { hv[0] = *(const LAS f32x4*)(xl + xidx(pa, pw, wc, fr - 14, fq, 0, n)); hv[1] = *(const LAS f32x4*)(xl + xidx(pa, pw, wc, fr - 14, fq, 1, n)); }
; #pragma unroll
;                 for (int m = 0; m < 4; ++m) {
;                     f32x4 c2[2];
; #pragma unroll
;                     for (int bj = 0; bj < 2; ++bj) { const f32x4 cur = acc[ai][bj][m][n]; const f32x4 pv = (m == 0) ? hv[bj] : acc[ai][bj][m == 0 ? 0 : m - 1][n];
; #pragma unroll
;                         for (int j = 0; j < 4; ++j) { const float p1 = dpp_shr1(dpp_ror1(pv[j]), cur[j]), p2 = dpp_shr2(dpp_ror2(pv[j]), cur[j]);
;                             c2[bj][j] = bia[bj][j] + wgt[bj][0][j] * p2 + wgt[bj][1][j] * p1 + wgt[bj][2][j] * cur[j]; } }
;                     u32x2 w; w.x = cvt_pk_bf16(gelu_t(c2[0][0]) * c2[1][0], gelu_t(c2[0][1]) * c2[1][1]); w.y = cvt_pk_bf16(gelu_t(c2[0][2]) * c2[1][2], gelu_t(c2[0][3]) * c2[1][3]);
;                     if (n == 0) pend[ai][m] = w;
;                     else { u32x4 w4; w4.x = pend[ai][m].x; w4.y = pend[ai][m].y; w4.z = w.x; w4.w = w.y;
;                         *(u32x4*)(F + (size_t)(t0 + ai * 128 + wr * 64 + m * 16 + fr) * FF + cg - 4) = w4; }
	v_mov_b32_dpp v54, v46 row_ror:1 row_mask:0xf bank_mask:0xf
	v_mov_b32_dpp v56, v46 row_ror:2 row_mask:0xf bank_mask:0xf
	v_mul_f32_e32 v34, 0xbfb8aa3b, v34
	v_mov_b32_dpp v54, v38 row_shr:1 row_mask:0xf bank_mask:0xf
	v_mov_b32_dpp v56, v38 row_shr:2 row_mask:0xf bank_mask:0xf
	v_mov_b32_e32 v40, v38
	v_exp_f32_e32 v38, v34
	v_mul_f32_e32 v34, 0x3d372713, v32
	v_mul_f32_e32 v34, v32, v34
	v_fma_f32 v34, v32, v34, v32
	v_mul_f32_e32 v34, 0x3fcc422a, v34
	v_mul_f32_e32 v34, 0xbfb8aa3b, v34
	v_exp_f32_e32 v42, v34
	v_mov_b32_e32 v46, 0
	v_mov_b32_e32 v58, 0
	v_mov_b32_e32 v59, 0
	v_mov_b32_dpp v46, v47 row_ror:1 row_mask:0xf bank_mask:0xf
	v_mov_b32_dpp v58, v47 row_ror:2 row_mask:0xf bank_mask:0xf
	v_mov_b32_e32 v34, v39
	v_mov_b32_dpp v46, v39 row_shr:1 row_mask:0xf bank_mask:0xf
	v_mov_b32_dpp v58, v39 row_shr:2 row_mask:0xf bank_mask:0xf
	v_add_f32_e32 v39, 1.0, v42
	v_pk_fma_f32 v[36:37], v[114:115], v[56:57], v[118:119]
	v_mov_b32_e32 v47, 0
	v_mov_b32_dpp v59, v43 row_ror:2 row_mask:0xf bank_mask:0xf
	v_rcp_f32_e32 v39, v39
	v_pk_fma_f32 v[36:37], v[128:129], v[54:55], v[36:37]
	v_mov_b32_dpp v47, v43 row_ror:1 row_mask:0xf bank_mask:0xf
	v_mov_b32_dpp v59, v35 row_shr:2 row_mask:0xf bank_mask:0xf
	v_pk_fma_f32 v[36:37], v[40:41], v[130:131], v[36:37]
	v_mov_b32_dpp v47, v35 row_shr:1 row_mask:0xf bank_mask:0xf
	v_pk_fma_f32 v[40:41], v[76:77], v[58:59], v[72:73]
	v_mul_f32_e32 v32, v32, v39
	v_pk_fma_f32 v[40:41], v[86:87], v[46:47], v[40:41]
	v_mul_f32_e32 v39, 0x3d372713, v36
	v_pk_fma_f32 v[34:35], v[34:35], v[68:69], v[40:41]
	v_mul_f32_e32 v39, v36, v39
	v_mul_f32_e32 v40, 0x3d372713, v34
	v_fma_f32 v39, v36, v39, v36
	v_mul_f32_e32 v40, v34, v40
	v_mul_f32_e32 v39, 0x3fcc422a, v39
	v_fma_f32 v40, v34, v40, v34
	v_mul_f32_e32 v39, 0xbfb8aa3b, v39
	v_mul_f32_e32 v40, 0x3fcc422a, v40
	v_exp_f32_e32 v39, v39
	v_mul_f32_e32 v40, 0xbfb8aa3b, v40
	v_exp_f32_e32 v40, v40
	v_add_f32_e32 v38, 1.0, v38
	v_rcp_f32_e32 v38, v38
	v_mul_f32_e32 v32, v32, v33
	v_add_f32_e32 v33, 1.0, v39
	v_rcp_f32_e32 v33, v33
	v_add_f32_e32 v39, 1.0, v40
	v_rcp_f32_e32 v39, v39
	v_mul_f32_e32 v38, v48, v38
	v_mul_f32_e32 v38, v38, v49
	v_cvt_pk_bf16_f32 v100, v38, v32
	v_mul_f32_e32 v32, v36, v33
	v_mul_f32_e32 v32, v32, v37
	v_mul_f32_e32 v33, v34, v39
	v_mul_f32_e32 v33, v33, v35
	v_cvt_pk_bf16_f32 v101, v32, v33
	v_or_b32_e32 v32, 48, v132
	v_mad_i64_i32 v[32:33], s[8:9], v32, s94, v[82:83]
	v_lshl_add_u64 v[32:33], v[32:33], 0, v[94:95]
	global_store_dwordx4 v[32:33], v[98:101], off sc1
	v_mov_b32_e32 v91, 0
	v_mov_b32_e32 v92, 0
	v_mov_b32_e32 v93, 0
	v_mov_b32_e32 v32, 0
	v_mov_b32_e32 v33, 0
	v_mov_b32_e32 v34, 0
	v_mov_b32_e32 v35, 0
	s_and_saveexec_b64 s[12:13], s[6:7]
	s_cbranch_execz .LBB0_794
	ds_read_b128 v[32:35], v154 offset:16
	ds_read_b128 v[90:93], v154 offset:48
.LBB0_794:
	s_or_b64 exec, exec, s[12:13]
	v_mov_b32_e32 v38, 0
	v_mov_b32_e32 v39, 0
	v_mov_b32_e32 v36, 0
	s_waitcnt lgkmcnt(1)
	v_mov_b32_dpp v38, v32 row_ror:2 row_mask:0xf bank_mask:0xf
	v_mov_b32_e32 v37, 0
	s_waitcnt lgkmcnt(0)
	v_mov_b32_dpp v39, v90 row_ror:2 row_mask:0xf bank_mask:0xf
	v_mov_b32_dpp v36, v32 row_ror:1 row_mask:0xf bank_mask:0xf
	v_mov_b32_dpp v38, v28 row_shr:2 row_mask:0xf bank_mask:0xf
	v_mov_b32_e32 v32, 0
	v_mov_b32_e32 v40, 0
	v_mov_b32_dpp v37, v90 row_ror:1 row_mask:0xf bank_mask:0xf
	v_mov_b32_dpp v39, v24 row_shr:2 row_mask:0xf bank_mask:0xf
	v_mov_b32_e32 v41, 0
	v_mov_b32_dpp v36, v28 row_shr:1 row_mask:0xf bank_mask:0xf
	v_mov_b32_dpp v32, v33 row_ror:1 row_mask:0xf bank_mask:0xf
	v_mov_b32_dpp v40, v33 row_ror:2 row_mask:0xf bank_mask:0xf
	v_mov_b32_dpp v37, v24 row_shr:1 row_mask:0xf bank_mask:0xf
	v_pk_fma_f32 v[38:39], v[78:79], v[38:39], v[122:123]
	v_mov_b32_e32 v33, 0
	v_mov_b32_dpp v41, v91 row_ror:2 row_mask:0xf bank_mask:0xf
	v_mov_b32_dpp v40, v29 row_shr:2 row_mask:0xf bank_mask:0xf
	v_mov_b32_e32 v44, 0
	v_pk_fma_f32 v[36:37], v[124:125], v[36:37], v[38:39]
	v_mov_b32_e32 v38, v28
	v_mov_b32_e32 v39, v24
	v_mov_b32_dpp v33, v91 row_ror:1 row_mask:0xf bank_mask:0xf
	v_mov_b32_dpp v41, v25 row_shr:2 row_mask:0xf bank_mask:0xf
	v_mov_b32_e32 v45, 0
	v_mov_b32_dpp v32, v29 row_shr:1 row_mask:0xf bank_mask:0xf
	v_mov_b32_e32 v42, 0
	v_mov_b32_dpp v44, v34 row_ror:2 row_mask:0xf bank_mask:0xf
	v_pk_fma_f32 v[36:37], v[38:39], v[126:127], v[36:37]
	v_mov_b32_dpp v33, v25 row_shr:1 row_mask:0xf bank_mask:0xf
	v_pk_fma_f32 v[38:39], v[74:75], v[40:41], v[70:71]
	v_mov_b32_e32 v43, 0
	v_mov_b32_dpp v45, v92 row_ror:2 row_mask:0xf bank_mask:0xf
	v_mov_b32_dpp v42, v34 row_ror:1 row_mask:0xf bank_mask:0xf
	v_mov_b32_dpp v44, v30 row_shr:2 row_mask:0xf bank_mask:0xf
	v_mov_b32_e32 v34, 0
	v_mov_b32_e32 v46, 0
	v_pk_fma_f32 v[32:33], v[84:85], v[32:33], v[38:39]
	v_mov_b32_e32 v38, v29
	v_mov_b32_e32 v39, v25
	v_mov_b32_dpp v43, v92 row_ror:1 row_mask:0xf bank_mask:0xf
	v_mov_b32_dpp v45, v26 row_shr:2 row_mask:0xf bank_mask:0xf
	v_mov_b32_e32 v47, 0
	v_mov_b32_dpp v42, v30 row_shr:1 row_mask:0xf bank_mask:0xf
	v_mov_b32_dpp v34, v35 row_ror:1 row_mask:0xf bank_mask:0xf
	v_mov_b32_dpp v46, v35 row_ror:2 row_mask:0xf bank_mask:0xf
	v_pk_fma_f32 v[32:33], v[38:39], v[66:67], v[32:33]
	v_mov_b32_dpp v43, v26 row_shr:1 row_mask:0xf bank_mask:0xf
	v_pk_fma_f32 v[38:39], v[114:115], v[44:45], v[118:119]
	v_mov_b32_e32 v35, 0
	v_mov_b32_dpp v47, v93 row_ror:2 row_mask:0xf bank_mask:0xf
	v_mov_b32_dpp v46, v31 row_shr:2 row_mask:0xf bank_mask:0xf
	v_pk_fma_f32 v[38:39], v[128:129], v[42:43], v[38:39]
	v_mov_b32_e32 v40, v30
	v_mov_b32_e32 v41, v26
	v_mov_b32_dpp v35, v93 row_ror:1 row_mask:0xf bank_mask:0xf
	v_mov_b32_dpp v47, v27 row_shr:2 row_mask:0xf bank_mask:0xf
; __device__ __forceinline__ unsigned cvt_pk_bf16(float lo, float hi) { unsigned r; asm volatile("v_cvt_pk_bf16_f32 %0, %1, %2" : "=v"(r) : "v"(lo), "v"(hi)); return r; }
; __device__ __forceinline__ float gelu_t(float x) { const float u = 1.5957691216f * (x + 0.044715f * x * x * x); return x * sigm(u); }
; __device__ __forceinline__ float dpp_shr1(float old, float src) { return __int_as_float(__builtin_amdgcn_update_dpp(__float_as_int(old), __float_as_int(src), 0x111, 0xf, 0xf, false)); }
; __device__ __forceinline__ float dpp_shr2(float old, float src) { return __int_as_float(__builtin_amdgcn_update_dpp(__float_as_int(old), __float_as_int(src), 0x112, 0xf, 0xf, false)); }
; __device__ __forceinline__ float dpp_ror1(float src) { return __int_as_float(__builtin_amdgcn_update_dpp(0, __float_as_int(src), 0x121, 0xf, 0xf, false)); }
; __device__ __forceinline__ float dpp_ror2(float src) { return __int_as_float(__builtin_amdgcn_update_dpp(0, __float_as_int(src), 0x122, 0xf, 0xf, false)); }
;     __device__ __forceinline__ void operator()(AccT& acc, const Unit& u, int wr, int wc, int fr, int fq) const {
;     ...
;                 for (int m = 0; m < 4; ++m) {
;                     f32x4 c2[2];
; #pragma unroll
;                     for (int bj = 0; bj < 2; ++bj) { const f32x4 cur = acc[ai][bj][m][n]; const f32x4 pv = (m == 0) ? hv[bj] : acc[ai][bj][m == 0 ? 0 : m - 1][n];
; #pragma unroll
;                         for (int j = 0; j < 4; ++j) { const float p1 = dpp_shr1(dpp_ror1(pv[j]), cur[j]), p2 = dpp_shr2(dpp_ror2(pv[j]), cur[j]);
;                             c2[bj][j] = bia[bj][j] + wgt[bj][0][j] * p2 + wgt[bj][1][j] * p1 + wgt[bj][2][j] * cur[j]; } }
;                     u32x2 w; w.x = cvt_pk_bf16(gelu_t(c2[0][0]) * c2[1][0], gelu_t(c2[0][1]) * c2[1][1]); w.y = cvt_pk_bf16(gelu_t(c2[0][2]) * c2[1][2], gelu_t(c2[0][3]) * c2[1][3]);
;                     if (n == 0) pend[ai][m] = w;
;                     else { u32x4 w4; w4.x = pend[ai][m].x; w4.y = pend[ai][m].y; w4.z = w.x; w4.w = w.y;
;                         *(u32x4*)(F + (size_t)(t0 + ai * 128 + wr * 64 + m * 16 + fr) * FF + cg - 4) = w4; }
	v_mov_b32_dpp v34, v31 row_shr:1 row_mask:0xf bank_mask:0xf
	v_pk_fma_f32 v[38:39], v[40:41], v[130:131], v[38:39]
	v_mov_b32_dpp v35, v27 row_shr:1 row_mask:0xf bank_mask:0xf
	v_pk_fma_f32 v[40:41], v[76:77], v[46:47], v[72:73]
	v_add_u32_e32 v48, 0x80, v132
	v_pk_fma_f32 v[34:35], v[86:87], v[34:35], v[40:41]
	v_mul_f32_e32 v41, 0x3d372713, v36
	v_mul_f32_e32 v41, v36, v41
	v_fma_f32 v41, v36, v41, v36
	v_mul_f32_e32 v41, 0x3fcc422a, v41
	v_mul_f32_e32 v41, 0xbfb8aa3b, v41
	v_exp_f32_e32 v42, v41
	v_mul_f32_e32 v41, 0x3d372713, v32
	v_mul_f32_e32 v41, v32, v41
	v_fma_f32 v41, v32, v41, v32
	v_add_f32_e32 v42, 1.0, v42
	v_rcp_f32_e32 v42, v42
	v_mul_f32_e32 v41, 0x3fcc422a, v41
	v_mul_f32_e32 v41, 0xbfb8aa3b, v41
	v_mov_b32_e32 v40, v31
	v_exp_f32_e32 v43, v41
	v_mov_b32_e32 v41, v27
	v_pk_fma_f32 v[34:35], v[40:41], v[68:69], v[34:35]
	v_mul_f32_e32 v36, v36, v42
	v_mul_f32_e32 v36, v36, v37
	v_mul_f32_e32 v37, 0x3d372713, v38
	v_mul_f32_e32 v40, 0x3d372713, v34
	v_mul_f32_e32 v37, v38, v37
	v_mul_f32_e32 v40, v34, v40
	v_fma_f32 v37, v38, v37, v38
	v_fma_f32 v40, v34, v40, v34
	v_add_f32_e32 v43, 1.0, v43
	v_mul_f32_e32 v37, 0x3fcc422a, v37
	v_mul_f32_e32 v40, 0x3fcc422a, v40
	v_rcp_f32_e32 v43, v43
	v_mul_f32_e32 v37, 0xbfb8aa3b, v37
	v_mul_f32_e32 v40, 0xbfb8aa3b, v40
	v_exp_f32_e32 v37, v37
	v_exp_f32_e32 v40, v40
	v_mul_f32_e32 v32, v32, v43
	v_mul_f32_e32 v32, v32, v33
	v_add_f32_e32 v33, 1.0, v37
	v_add_f32_e32 v37, 1.0, v40
	v_rcp_f32_e32 v33, v33
	v_rcp_f32_e32 v37, v37
	v_cvt_pk_bf16_f32 v98, v36, v32
	v_mov_b32_e32 v36, 0
	v_mul_f32_e32 v32, v38, v33
	v_mul_f32_e32 v33, v34, v37
	v_mul_f32_e32 v32, v32, v39
	v_mul_f32_e32 v33, v33, v35
	v_cvt_pk_bf16_f32 v99, v32, v33
	v_mov_b64_e32 v[32:33], s[36:37]
	v_mad_i64_i32 v[34:35], s[6:7], v48, s94, v[32:33]
	v_lshl_add_u64 v[34:35], v[34:35], 0, v[94:95]
	v_mov_b32_e32 v37, 0
	global_store_dwordx4 v[34:35], v[96:99], off sc1
	v_mov_b32_e32 v34, 0
	v_mov_b32_dpp v36, v28 row_ror:2 row_mask:0xf bank_mask:0xf
	v_mov_b32_e32 v40, 0
	v_mov_b32_e32 v42, 0
	v_mov_b32_e32 v35, 0
	v_mov_b32_dpp v37, v24 row_ror:2 row_mask:0xf bank_mask:0xf
	v_mov_b32_dpp v34, v28 row_ror:1 row_mask:0xf bank_mask:0xf
	v_mov_b32_dpp v36, v20 row_shr:2 row_mask:0xf bank_mask:0xf
	v_mov_b32_dpp v40, v30 row_ror:1 row_mask:0xf bank_mask:0xf
	v_mov_b32_dpp v42, v30 row_ror:2 row_mask:0xf bank_mask:0xf
	v_mov_b32_e32 v30, 0
	v_mov_b32_e32 v44, 0
	v_mov_b32_dpp v35, v24 row_ror:1 row_mask:0xf bank_mask:0xf
	v_mov_b32_dpp v37, v16 row_shr:2 row_mask:0xf bank_mask:0xf
	v_mov_b32_e32 v45, 0
	v_mov_b32_dpp v34, v20 row_shr:1 row_mask:0xf bank_mask:0xf
	v_mov_b32_dpp v30, v31 row_ror:1 row_mask:0xf bank_mask:0xf
	v_mov_b32_dpp v44, v31 row_ror:2 row_mask:0xf bank_mask:0xf
	v_mov_b32_dpp v35, v16 row_shr:1 row_mask:0xf bank_mask:0xf
	v_pk_fma_f32 v[36:37], v[78:79], v[36:37], v[122:123]
	v_mov_b32_e32 v31, 0
	v_mov_b32_dpp v45, v27 row_ror:2 row_mask:0xf bank_mask:0xf
	v_mov_b32_e32 v28, 0
	v_mov_b32_e32 v38, 0
	v_mov_b32_dpp v44, v23 row_shr:2 row_mask:0xf bank_mask:0xf
	v_pk_fma_f32 v[34:35], v[124:125], v[34:35], v[36:37]
	v_mov_b32_e32 v36, v20
	v_mov_b32_e32 v37, v16
	v_mov_b32_e32 v39, 0
	v_mov_b32_e32 v41, 0
	v_mov_b32_e32 v43, 0
	v_mov_b32_dpp v31, v27 row_ror:1 row_mask:0xf bank_mask:0xf
	v_mov_b32_dpp v45, v19 row_shr:2 row_mask:0xf bank_mask:0xf
	v_mov_b32_dpp v28, v29 row_ror:1 row_mask:0xf bank_mask:0xf
	v_mov_b32_dpp v38, v29 row_ror:2 row_mask:0xf bank_mask:0xf
	v_mov_b32_dpp v30, v23 row_shr:1 row_mask:0xf bank_mask:0xf
	v_pk_fma_f32 v[34:35], v[36:37], v[126:127], v[34:35]
	v_mov_b32_e32 v29, 0
	v_mov_b32_dpp v39, v25 row_ror:2 row_mask:0xf bank_mask:0xf
	v_mov_b32_dpp v41, v26 row_ror:1 row_mask:0xf bank_mask:0xf
	v_mov_b32_dpp v43, v26 row_ror:2 row_mask:0xf bank_mask:0xf
	v_mov_b32_dpp v31, v19 row_shr:1 row_mask:0xf bank_mask:0xf
	v_pk_fma_f32 v[26:27], v[76:77], v[44:45], v[72:73]
	v_mov_b32_dpp v38, v21 row_shr:2 row_mask:0xf bank_mask:0xf
	v_mov_b32_dpp v29, v25 row_ror:1 row_mask:0xf bank_mask:0xf
	v_mov_b32_dpp v39, v17 row_shr:2 row_mask:0xf bank_mask:0xf
	v_pk_fma_f32 v[26:27], v[86:87], v[30:31], v[26:27]
	v_mul_f32_e32 v31, 0x3d372713, v34
	v_mov_b32_dpp v28, v21 row_shr:1 row_mask:0xf bank_mask:0xf
	v_mov_b32_dpp v29, v17 row_shr:1 row_mask:0xf bank_mask:0xf
	v_pk_fma_f32 v[24:25], v[74:75], v[38:39], v[70:71]
	v_mul_f32_e32 v31, v34, v31
	v_mov_b32_dpp v42, v22 row_shr:2 row_mask:0xf bank_mask:0xf
	v_pk_fma_f32 v[24:25], v[84:85], v[28:29], v[24:25]
	v_mov_b32_e32 v28, v21
	v_mov_b32_e32 v29, v17
	v_mov_b32_dpp v43, v18 row_shr:2 row_mask:0xf bank_mask:0xf
	v_fma_f32 v31, v34, v31, v34
	v_mov_b32_dpp v40, v22 row_shr:1 row_mask:0xf bank_mask:0xf
	v_pk_fma_f32 v[24:25], v[28:29], v[66:67], v[24:25]
	v_mov_b32_dpp v41, v18 row_shr:1 row_mask:0xf bank_mask:0xf
	v_pk_fma_f32 v[28:29], v[114:115], v[42:43], v[118:119]
	v_mul_f32_e32 v31, 0x3fcc422a, v31
	v_pk_fma_f32 v[28:29], v[128:129], v[40:41], v[28:29]
	v_mov_b32_e32 v36, v22
	v_mov_b32_e32 v37, v18
	v_mul_f32_e32 v31, 0xbfb8aa3b, v31
	v_pk_fma_f32 v[28:29], v[36:37], v[130:131], v[28:29]
	v_exp_f32_e32 v36, v31
	v_mul_f32_e32 v31, 0x3d372713, v24
	v_mul_f32_e32 v31, v24, v31
	v_fma_f32 v31, v24, v31, v24
	v_add_f32_e32 v36, 1.0, v36
	v_mul_f32_e32 v31, 0x3fcc422a, v31
	v_rcp_f32_e32 v36, v36
	v_mul_f32_e32 v31, 0xbfb8aa3b, v31
	v_mov_b32_e32 v30, v23
	v_exp_f32_e32 v37, v31
	v_mov_b32_e32 v31, v19
	v_pk_fma_f32 v[26:27], v[30:31], v[68:69], v[26:27]
	v_mul_f32_e32 v31, 0x3d372713, v28
	v_mul_f32_e32 v30, v34, v36
	v_mul_f32_e32 v31, v28, v31
	v_mul_f32_e32 v34, 0x3d372713, v26
	v_fma_f32 v31, v28, v31, v28
	v_mul_f32_e32 v34, v26, v34
; __device__ __forceinline__ unsigned cvt_pk_bf16(float lo, float hi) { unsigned r; asm volatile("v_cvt_pk_bf16_f32 %0, %1, %2" : "=v"(r) : "v"(lo), "v"(hi)); return r; }
; __device__ __forceinline__ float gelu_t(float x) { const float u = 1.5957691216f * (x + 0.044715f * x * x * x); return x * sigm(u); }
; __device__ __forceinline__ float dpp_shr1(float old, float src) { return __int_as_float(__builtin_amdgcn_update_dpp(__float_as_int(old), __float_as_int(src), 0x111, 0xf, 0xf, false)); }
; __device__ __forceinline__ float dpp_shr2(float old, float src) { return __int_as_float(__builtin_amdgcn_update_dpp(__float_as_int(old), __float_as_int(src), 0x112, 0xf, 0xf, false)); }
; __device__ __forceinline__ float dpp_ror1(float src) { return __int_as_float(__builtin_amdgcn_update_dpp(0, __float_as_int(src), 0x121, 0xf, 0xf, false)); }
; __device__ __forceinline__ float dpp_ror2(float src) { return __int_as_float(__builtin_amdgcn_update_dpp(0, __float_as_int(src), 0x122, 0xf, 0xf, false)); }
;     __device__ __forceinline__ void operator()(AccT& acc, const Unit& u, int wr, int wc, int fr, int fq) const {
;     ...
;                 for (int m = 0; m < 4; ++m) {
;                     f32x4 c2[2];
; #pragma unroll
;                     for (int bj = 0; bj < 2; ++bj) { const f32x4 cur = acc[ai][bj][m][n]; const f32x4 pv = (m == 0) ? hv[bj] : acc[ai][bj][m == 0 ? 0 : m - 1][n];
; #pragma unroll
;                         for (int j = 0; j < 4; ++j) { const float p1 = dpp_shr1(dpp_ror1(pv[j]), cur[j]), p2 = dpp_shr2(dpp_ror2(pv[j]), cur[j]);
;                             c2[bj][j] = bia[bj][j] + wgt[bj][0][j] * p2 + wgt[bj][1][j] * p1 + wgt[bj][2][j] * cur[j]; } }
;                     u32x2 w; w.x = cvt_pk_bf16(gelu_t(c2[0][0]) * c2[1][0], gelu_t(c2[0][1]) * c2[1][1]); w.y = cvt_pk_bf16(gelu_t(c2[0][2]) * c2[1][2], gelu_t(c2[0][3]) * c2[1][3]);
;                     if (n == 0) pend[ai][m] = w;
;                     else { u32x4 w4; w4.x = pend[ai][m].x; w4.y = pend[ai][m].y; w4.z = w.x; w4.w = w.y;
;                         *(u32x4*)(F + (size_t)(t0 + ai * 128 + wr * 64 + m * 16 + fr) * FF + cg - 4) = w4; }
	v_add_f32_e32 v37, 1.0, v37
	v_mul_f32_e32 v31, 0x3fcc422a, v31
	v_fma_f32 v34, v26, v34, v26
	v_rcp_f32_e32 v37, v37
	v_mul_f32_e32 v31, 0xbfb8aa3b, v31
	v_mul_f32_e32 v34, 0x3fcc422a, v34
	v_exp_f32_e32 v31, v31
	v_mul_f32_e32 v34, 0xbfb8aa3b, v34
	v_exp_f32_e32 v34, v34
	v_mul_f32_e32 v24, v24, v37
	v_mul_f32_e32 v24, v24, v25
	v_add_f32_e32 v25, 1.0, v31
	v_rcp_f32_e32 v25, v25
	v_add_f32_e32 v31, 1.0, v34
	v_rcp_f32_e32 v31, v31
	v_mul_f32_e32 v30, v30, v35
	v_cvt_pk_bf16_f32 v90, v30, v24
	v_mul_f32_e32 v24, v28, v25
	v_mul_f32_e32 v24, v24, v29
	v_mul_f32_e32 v25, v26, v31
	v_mul_f32_e32 v25, v25, v27
	v_cvt_pk_bf16_f32 v91, v24, v25
	v_add_u32_e32 v24, 0x90, v132
	v_mad_i64_i32 v[24:25], s[6:7], v24, s94, v[32:33]
	v_lshl_add_u64 v[24:25], v[24:25], 0, v[94:95]
	v_mov_b32_e32 v26, 0
	v_mov_b32_e32 v27, 0
	global_store_dwordx4 v[24:25], v[88:91], off sc1
	v_mov_b32_e32 v24, 0
	v_mov_b32_dpp v26, v20 row_ror:2 row_mask:0xf bank_mask:0xf
	v_mov_b32_e32 v30, 0
	v_mov_b32_e32 v34, 0
	v_mov_b32_e32 v25, 0
	v_mov_b32_dpp v27, v16 row_ror:2 row_mask:0xf bank_mask:0xf
	v_mov_b32_dpp v24, v20 row_ror:1 row_mask:0xf bank_mask:0xf
	v_mov_b32_dpp v26, v12 row_shr:2 row_mask:0xf bank_mask:0xf
	v_mov_b32_dpp v30, v22 row_ror:1 row_mask:0xf bank_mask:0xf
	v_mov_b32_dpp v34, v22 row_ror:2 row_mask:0xf bank_mask:0xf
	v_mov_b32_e32 v22, 0
	v_mov_b32_e32 v36, 0
	v_mov_b32_dpp v25, v16 row_ror:1 row_mask:0xf bank_mask:0xf
	v_mov_b32_dpp v27, v8 row_shr:2 row_mask:0xf bank_mask:0xf
	v_mov_b32_e32 v37, 0
	v_mov_b32_dpp v24, v12 row_shr:1 row_mask:0xf bank_mask:0xf
	v_mov_b32_dpp v22, v23 row_ror:1 row_mask:0xf bank_mask:0xf
	v_mov_b32_dpp v36, v23 row_ror:2 row_mask:0xf bank_mask:0xf
	v_mov_b32_dpp v25, v8 row_shr:1 row_mask:0xf bank_mask:0xf
	v_pk_fma_f32 v[26:27], v[78:79], v[26:27], v[122:123]
	v_mov_b32_e32 v23, 0
	v_mov_b32_dpp v37, v19 row_ror:2 row_mask:0xf bank_mask:0xf
	v_mov_b32_e32 v20, 0
	v_mov_b32_e32 v28, 0
	v_mov_b32_dpp v36, v15 row_shr:2 row_mask:0xf bank_mask:0xf
	v_pk_fma_f32 v[24:25], v[124:125], v[24:25], v[26:27]
	v_mov_b32_e32 v26, v12
	v_mov_b32_e32 v27, v8
	v_mov_b32_e32 v29, 0
	v_mov_b32_e32 v31, 0
	v_mov_b32_e32 v35, 0
	v_mov_b32_dpp v23, v19 row_ror:1 row_mask:0xf bank_mask:0xf
	v_mov_b32_dpp v37, v11 row_shr:2 row_mask:0xf bank_mask:0xf
	v_mov_b32_dpp v20, v21 row_ror:1 row_mask:0xf bank_mask:0xf
	v_mov_b32_dpp v28, v21 row_ror:2 row_mask:0xf bank_mask:0xf
	v_mov_b32_dpp v22, v15 row_shr:1 row_mask:0xf bank_mask:0xf
	v_pk_fma_f32 v[24:25], v[26:27], v[126:127], v[24:25]
	v_mov_b32_e32 v21, 0
	v_mov_b32_dpp v29, v17 row_ror:2 row_mask:0xf bank_mask:0xf
	v_mov_b32_dpp v31, v18 row_ror:1 row_mask:0xf bank_mask:0xf
	v_mov_b32_dpp v35, v18 row_ror:2 row_mask:0xf bank_mask:0xf
	v_mov_b32_dpp v23, v11 row_shr:1 row_mask:0xf bank_mask:0xf
	v_pk_fma_f32 v[18:19], v[76:77], v[36:37], v[72:73]
	v_mov_b32_dpp v28, v13 row_shr:2 row_mask:0xf bank_mask:0xf
	v_mov_b32_dpp v21, v17 row_ror:1 row_mask:0xf bank_mask:0xf
	v_mov_b32_dpp v29, v9 row_shr:2 row_mask:0xf bank_mask:0xf
	v_pk_fma_f32 v[18:19], v[86:87], v[22:23], v[18:19]
	v_mul_f32_e32 v23, 0x3d372713, v24
	v_mov_b32_dpp v20, v13 row_shr:1 row_mask:0xf bank_mask:0xf
	v_mov_b32_dpp v21, v9 row_shr:1 row_mask:0xf bank_mask:0xf
	v_pk_fma_f32 v[16:17], v[74:75], v[28:29], v[70:71]
	v_mul_f32_e32 v23, v24, v23
	v_mov_b32_dpp v34, v14 row_shr:2 row_mask:0xf bank_mask:0xf
	v_pk_fma_f32 v[16:17], v[84:85], v[20:21], v[16:17]
	v_mov_b32_e32 v20, v13
	v_mov_b32_e32 v21, v9
	v_mov_b32_dpp v35, v10 row_shr:2 row_mask:0xf bank_mask:0xf
	v_fma_f32 v23, v24, v23, v24
	v_mov_b32_dpp v30, v14 row_shr:1 row_mask:0xf bank_mask:0xf
	v_pk_fma_f32 v[16:17], v[20:21], v[66:67], v[16:17]
	v_mov_b32_dpp v31, v10 row_shr:1 row_mask:0xf bank_mask:0xf
	v_pk_fma_f32 v[20:21], v[114:115], v[34:35], v[118:119]
	v_mul_f32_e32 v23, 0x3fcc422a, v23
	v_pk_fma_f32 v[20:21], v[128:129], v[30:31], v[20:21]
	v_mov_b32_e32 v26, v14
	v_mov_b32_e32 v27, v10
	v_mul_f32_e32 v23, 0xbfb8aa3b, v23
	v_pk_fma_f32 v[20:21], v[26:27], v[130:131], v[20:21]
	v_exp_f32_e32 v26, v23
	v_mul_f32_e32 v23, 0x3d372713, v16
	v_mul_f32_e32 v23, v16, v23
	v_fma_f32 v23, v16, v23, v16
	v_add_f32_e32 v26, 1.0, v26
	v_mul_f32_e32 v23, 0x3fcc422a, v23
	v_rcp_f32_e32 v26, v26
	v_mul_f32_e32 v23, 0xbfb8aa3b, v23
	v_mov_b32_e32 v22, v15
	v_exp_f32_e32 v27, v23
	v_mov_b32_e32 v23, v11
	v_pk_fma_f32 v[18:19], v[22:23], v[68:69], v[18:19]
	v_mul_f32_e32 v23, 0x3d372713, v20
	v_mul_f32_e32 v22, v24, v26
	v_mul_f32_e32 v23, v20, v23
	v_mul_f32_e32 v24, 0x3d372713, v18
	v_fma_f32 v23, v20, v23, v20
	v_mul_f32_e32 v24, v18, v24
	v_add_f32_e32 v27, 1.0, v27
	v_mul_f32_e32 v23, 0x3fcc422a, v23
	v_fma_f32 v24, v18, v24, v18
	v_rcp_f32_e32 v27, v27
	v_mul_f32_e32 v23, 0xbfb8aa3b, v23
	v_mul_f32_e32 v24, 0x3fcc422a, v24
	v_exp_f32_e32 v23, v23
	v_mul_f32_e32 v24, 0xbfb8aa3b, v24
	v_exp_f32_e32 v24, v24
	v_mul_f32_e32 v16, v16, v27
	v_mul_f32_e32 v16, v16, v17
	v_add_f32_e32 v17, 1.0, v23
	v_rcp_f32_e32 v17, v17
; __device__ __forceinline__ unsigned cvt_pk_bf16(float lo, float hi) { unsigned r; asm volatile("v_cvt_pk_bf16_f32 %0, %1, %2" : "=v"(r) : "v"(lo), "v"(hi)); return r; }
; __device__ __forceinline__ float gelu_t(float x) { const float u = 1.5957691216f * (x + 0.044715f * x * x * x); return x * sigm(u); }
; #define PG8_BAR __builtin_amdgcn_s_barrier()
; __device__ __forceinline__ float dpp_shr1(float old, float src) { return __int_as_float(__builtin_amdgcn_update_dpp(__float_as_int(old), __float_as_int(src), 0x111, 0xf, 0xf, false)); }
; template <class Epi, class Sched, bool F8 = false>
; __device__ __forceinline__ void gemm_phase(LAS unsigned char* lds, const int lda, const int ldb, const Sched& S, const Epi& E) {
;     ...
;         if (!has_next) break;
;         if (!(Epi::KEEP && cur.kind == 0)) {
; #pragma unroll
;         for (int a = 0; a < 2; ++a)
; #pragma unroll
;             for (int b = 0; b < 2; ++b)
; #pragma unroll
;                 for (int m = 0; m < 4; ++m)
; #pragma unroll
;                     for (int n = 0; n < 2; ++n) acc[a][b][m][n] = (f32x4){0.f, 0.f, 0.f, 0.f};
;         }
;         cur = nxt; cA = nA; cB = nB; ++ui;
;         if (wr == 1) PG8_BAR;
;     __device__ __forceinline__ void operator()(AccT& acc, const Unit& u, int wr, int wc, int fr, int fq) const {
;     ...
;                 for (int m = 0; m < 4; ++m) {
;                     f32x4 c2[2];
; #pragma unroll
;                     for (int bj = 0; bj < 2; ++bj) { const f32x4 cur = acc[ai][bj][m][n]; const f32x4 pv = (m == 0) ? hv[bj] : acc[ai][bj][m == 0 ? 0 : m - 1][n];
; #pragma unroll
;                         for (int j = 0; j < 4; ++j) { const float p1 = dpp_shr1(dpp_ror1(pv[j]), cur[j]), p2 = dpp_shr2(dpp_ror2(pv[j]), cur[j]);
;                             c2[bj][j] = bia[bj][j] + wgt[bj][0][j] * p2 + wgt[bj][1][j] * p1 + wgt[bj][2][j] * cur[j]; } }
;                     u32x2 w; w.x = cvt_pk_bf16(gelu_t(c2[0][0]) * c2[1][0], gelu_t(c2[0][1]) * c2[1][1]); w.y = cvt_pk_bf16(gelu_t(c2[0][2]) * c2[1][2], gelu_t(c2[0][3]) * c2[1][3]);
;                     if (n == 0) pend[ai][m] = w;
;                     else { u32x4 w4; w4.x = pend[ai][m].x; w4.y = pend[ai][m].y; w4.z = w.x; w4.w = w.y;
;                         *(u32x4*)(F + (size_t)(t0 + ai * 128 + wr * 64 + m * 16 + fr) * FF + cg - 4) = w4; }
	v_add_f32_e32 v23, 1.0, v24
	v_rcp_f32_e32 v23, v23
	v_mul_f32_e32 v22, v22, v25
	v_cvt_pk_bf16_f32 v82, v22, v16
	v_mul_f32_e32 v16, v20, v17
	v_mul_f32_e32 v16, v16, v21
	v_mul_f32_e32 v17, v18, v23
	v_mul_f32_e32 v17, v17, v19
	v_cvt_pk_bf16_f32 v83, v16, v17
	v_add_u32_e32 v16, 0xa0, v132
	v_mad_i64_i32 v[16:17], s[6:7], v16, s94, v[32:33]
	v_lshl_add_u64 v[16:17], v[16:17], 0, v[94:95]
	global_store_dwordx4 v[16:17], v[80:83], off sc1
	v_mov_b32_e32 v16, 0
	v_mov_b32_e32 v18, 0
	v_mov_b32_e32 v19, 0
	v_mov_b32_dpp v16, v12 row_ror:1 row_mask:0xf bank_mask:0xf
	v_mov_b32_dpp v18, v12 row_ror:2 row_mask:0xf bank_mask:0xf
	v_mov_b32_e32 v12, 0
	v_mov_b32_e32 v20, 0
	v_mov_b32_e32 v17, 0
	v_mov_b32_dpp v19, v8 row_ror:2 row_mask:0xf bank_mask:0xf
	v_mov_b32_e32 v21, 0
	v_mov_b32_dpp v18, v4 row_shr:2 row_mask:0xf bank_mask:0xf
	v_mov_b32_dpp v12, v13 row_ror:1 row_mask:0xf bank_mask:0xf
	v_mov_b32_dpp v20, v13 row_ror:2 row_mask:0xf bank_mask:0xf
	v_mov_b32_dpp v17, v8 row_ror:1 row_mask:0xf bank_mask:0xf
	v_mov_b32_dpp v19, v0 row_shr:2 row_mask:0xf bank_mask:0xf
	v_mov_b32_e32 v13, 0
	v_mov_b32_dpp v21, v9 row_ror:2 row_mask:0xf bank_mask:0xf
	v_mov_b32_dpp v16, v4 row_shr:1 row_mask:0xf bank_mask:0xf
	v_mov_b32_dpp v20, v5 row_shr:2 row_mask:0xf bank_mask:0xf
	v_mov_b32_dpp v17, v0 row_shr:1 row_mask:0xf bank_mask:0xf
	v_pk_fma_f32 v[18:19], v[78:79], v[18:19], v[122:123]
	v_mov_b32_dpp v13, v9 row_ror:1 row_mask:0xf bank_mask:0xf
	v_mov_b32_dpp v21, v1 row_shr:2 row_mask:0xf bank_mask:0xf
	v_mov_b32_dpp v12, v5 row_shr:1 row_mask:0xf bank_mask:0xf
	v_pk_fma_f32 v[16:17], v[124:125], v[16:17], v[18:19]
	v_mov_b32_e32 v18, v4
	v_mov_b32_e32 v19, v0
	v_mov_b32_dpp v13, v1 row_shr:1 row_mask:0xf bank_mask:0xf
	v_pk_fma_f32 v[8:9], v[74:75], v[20:21], v[70:71]
	v_mov_b32_e32 v23, 0
	v_mov_b32_e32 v25, 0
	v_pk_fma_f32 v[16:17], v[18:19], v[126:127], v[16:17]
	v_pk_fma_f32 v[8:9], v[84:85], v[12:13], v[8:9]
	v_mov_b32_e32 v0, v5
	v_mov_b32_dpp v23, v10 row_ror:1 row_mask:0xf bank_mask:0xf
	v_mov_b32_dpp v25, v10 row_ror:2 row_mask:0xf bank_mask:0xf
	v_pk_fma_f32 v[0:1], v[0:1], v[66:67], v[8:9]
	v_mov_b32_dpp v23, v2 row_shr:1 row_mask:0xf bank_mask:0xf
	v_mov_b32_dpp v25, v2 row_shr:2 row_mask:0xf bank_mask:0xf
	v_mov_b32_e32 v9, v2
	v_mul_f32_e32 v2, 0x3d372713, v16
	v_mul_f32_e32 v2, v16, v2
	v_fma_f32 v2, v16, v2, v16
	v_mov_b32_e32 v22, 0
	v_mov_b32_e32 v24, 0
	v_mul_f32_e32 v2, 0x3fcc422a, v2
	v_mov_b32_dpp v22, v14 row_ror:1 row_mask:0xf bank_mask:0xf
	v_mov_b32_dpp v24, v14 row_ror:2 row_mask:0xf bank_mask:0xf
	v_mul_f32_e32 v2, 0xbfb8aa3b, v2
	v_mov_b32_dpp v22, v6 row_shr:1 row_mask:0xf bank_mask:0xf
	v_mov_b32_dpp v24, v6 row_shr:2 row_mask:0xf bank_mask:0xf
	v_mov_b32_e32 v8, v6
	v_exp_f32_e32 v6, v2
	v_mul_f32_e32 v2, 0x3d372713, v0
	v_mul_f32_e32 v2, v0, v2
	v_fma_f32 v2, v0, v2, v0
	v_mul_f32_e32 v2, 0x3fcc422a, v2
	v_mul_f32_e32 v2, 0xbfb8aa3b, v2
	v_exp_f32_e32 v10, v2
	v_mov_b32_e32 v14, 0
	v_mov_b32_e32 v26, 0
	v_mov_b32_e32 v27, 0
	v_mov_b32_dpp v14, v15 row_ror:1 row_mask:0xf bank_mask:0xf
	v_mov_b32_dpp v26, v15 row_ror:2 row_mask:0xf bank_mask:0xf
	v_mov_b32_e32 v2, v7
	v_mov_b32_dpp v14, v7 row_shr:1 row_mask:0xf bank_mask:0xf
	v_mov_b32_dpp v26, v7 row_shr:2 row_mask:0xf bank_mask:0xf
	v_add_f32_e32 v7, 1.0, v10
	v_pk_fma_f32 v[4:5], v[114:115], v[24:25], v[118:119]
	v_mov_b32_e32 v15, 0
	v_mov_b32_dpp v27, v11 row_ror:2 row_mask:0xf bank_mask:0xf
	v_rcp_f32_e32 v7, v7
	v_pk_fma_f32 v[4:5], v[128:129], v[22:23], v[4:5]
	v_mov_b32_dpp v15, v11 row_ror:1 row_mask:0xf bank_mask:0xf
	v_mov_b32_dpp v27, v3 row_shr:2 row_mask:0xf bank_mask:0xf
	v_pk_fma_f32 v[4:5], v[8:9], v[130:131], v[4:5]
	v_mov_b32_dpp v15, v3 row_shr:1 row_mask:0xf bank_mask:0xf
	v_pk_fma_f32 v[8:9], v[76:77], v[26:27], v[72:73]
	v_mul_f32_e32 v0, v0, v7
	v_pk_fma_f32 v[8:9], v[86:87], v[14:15], v[8:9]
	v_mul_f32_e32 v7, 0x3d372713, v4
	v_pk_fma_f32 v[2:3], v[2:3], v[68:69], v[8:9]
	v_mul_f32_e32 v7, v4, v7
	v_mul_f32_e32 v8, 0x3d372713, v2
	v_fma_f32 v7, v4, v7, v4
	v_mul_f32_e32 v8, v2, v8
	v_mul_f32_e32 v7, 0x3fcc422a, v7
	v_fma_f32 v8, v2, v8, v2
	v_mul_f32_e32 v7, 0xbfb8aa3b, v7
	v_mul_f32_e32 v8, 0x3fcc422a, v8
	v_exp_f32_e32 v7, v7
	v_mul_f32_e32 v8, 0xbfb8aa3b, v8
	v_exp_f32_e32 v8, v8
	v_add_f32_e32 v6, 1.0, v6
	v_rcp_f32_e32 v6, v6
	v_mul_f32_e32 v0, v0, v1
	v_add_f32_e32 v1, 1.0, v7
	v_rcp_f32_e32 v1, v1
	v_add_f32_e32 v7, 1.0, v8
	v_rcp_f32_e32 v7, v7
	v_mul_f32_e32 v6, v16, v6
	v_mul_f32_e32 v6, v6, v17
	v_cvt_pk_bf16_f32 v66, v6, v0
	v_mul_f32_e32 v0, v4, v1
	v_mul_f32_e32 v0, v0, v5
	v_mul_f32_e32 v1, v2, v7
	v_mul_f32_e32 v1, v1, v3
	v_cvt_pk_bf16_f32 v67, v0, v1
	v_add_u32_e32 v0, 0xb0, v132
	v_mad_i64_i32 v[0:1], s[6:7], v0, s94, v[32:33]
	v_lshl_add_u64 v[0:1], v[0:1], 0, v[94:95]
	s_andn2_b64 vcc, exec, s[0:1]
	s_mov_b64 s[0:1], -1
	global_store_dwordx4 v[0:1], v[64:67], off sc1
	s_cbranch_vccnz .LBB0_774
	s_and_b64 vcc, exec, s[4:5]
	s_cbranch_vccnz .LBB0_773
	s_barrier
	s_branch .LBB0_773

; #define LAS __attribute__((address_space(3)))
; __device__ __forceinline__ void transpose_item(const float* W, int N, bf16_t* WT, int nkt, int k0, int n0, int r0, int kbd, LAS float* scr, int lane) {
;     const size_t dst_off = ((size_t)(r0 >> 8) * nkt + kbd) * 16384 + (size_t)(r0 & 255) * 64;
;     const int l15 = lane & 15, lq = lane >> 4;
;     f32x4 v[16];
; #pragma unroll
;     for (int i = 0; i < 16; ++i) v[i] = *(const f32x4*)(W + (size_t)(k0 + 4 * i + lq) * N + n0 + 4 * l15);
; #pragma unroll
;     for (int i = 0; i < 16; ++i) { LAS float* d = scr + (4 * i + lq) * 65 + 4 * l15; d[0] = v[i][0]; d[1] = v[i][1]; d[2] = v[i][2]; d[3] = v[i][3]; }
; __device__ __forceinline__ void phase_convert_wdown(const Params& p, LAS float* scr, int cw, int NCW, int lane) {
;     ...
;     for (int it = cw; it < 172 * 64; it += NCW) { const int nb = it % 64, kb = it / 64; transpose_item(p.in[24], 4096, (bf16_t*)(ws + WS_W_DOWN), 172, kb * 64, nb * 64, nb * 64, kb, scr, lane); }
.LBB0_801:
	s_ashr_i32 s9, s0, 31
	s_lshr_b32 s9, s9, 26
	s_add_i32 s9, s0, s9
	s_and_b32 s12, s7, 0x3000
	s_ashr_i32 s15, s9, 6
	s_andn2_b32 s9, s9, 63
	s_lshl_b32 s14, s12, 1
	s_lshl_b32 s12, s15, 12
	v_or_b32_e32 v20, s9, v22
	s_sub_i32 s12, s5, s12
	v_or_b32_e32 v56, 4, v20
	v_or_b32_e32 v58, 8, v20
	v_or_b32_e32 v60, 12, v20
	v_or_b32_e32 v62, 16, v20
	v_or_b32_e32 v64, 20, v20
	v_or_b32_e32 v66, 24, v20
	v_or_b32_e32 v68, 28, v20
	v_or_b32_e32 v70, 32, v20
	v_or_b32_e32 v72, 36, v20
	v_or_b32_e32 v74, 40, v20
	v_or_b32_e32 v76, 44, v20
	v_or_b32_e32 v78, 48, v20
	v_or_b32_e32 v80, 52, v20
	v_or_b32_e32 v82, 56, v20
	v_ashrrev_i32_e32 v21, 31, v20
	v_or_b32_e32 v84, 60, v20
	s_ashr_i32 s13, s12, 31
	v_ashrrev_i32_e32 v57, 31, v56
	v_ashrrev_i32_e32 v59, 31, v58
	v_ashrrev_i32_e32 v61, 31, v60
	v_ashrrev_i32_e32 v63, 31, v62
	v_ashrrev_i32_e32 v65, 31, v64
	v_ashrrev_i32_e32 v67, 31, v66
	v_ashrrev_i32_e32 v69, 31, v68
	v_ashrrev_i32_e32 v71, 31, v70
	v_ashrrev_i32_e32 v73, 31, v72
	v_ashrrev_i32_e32 v75, 31, v74
	v_ashrrev_i32_e32 v77, 31, v76
	v_ashrrev_i32_e32 v79, 31, v78
	v_ashrrev_i32_e32 v81, 31, v80
	v_ashrrev_i32_e32 v83, 31, v82
	v_lshlrev_b64 v[20:21], 14, v[20:21]
	v_ashrrev_i32_e32 v85, 31, v84
	v_lshl_add_u64 v[86:87], s[12:13], 2, v[2:3]
	v_lshlrev_b64 v[56:57], 14, v[56:57]
	v_lshlrev_b64 v[58:59], 14, v[58:59]
	v_lshlrev_b64 v[60:61], 14, v[60:61]
	v_lshlrev_b64 v[62:63], 14, v[62:63]
	v_lshlrev_b64 v[64:65], 14, v[64:65]
	v_lshlrev_b64 v[66:67], 14, v[66:67]
	v_lshlrev_b64 v[68:69], 14, v[68:69]
	v_lshlrev_b64 v[70:71], 14, v[70:71]
	v_lshlrev_b64 v[72:73], 14, v[72:73]
	v_lshlrev_b64 v[74:75], 14, v[74:75]
	v_lshlrev_b64 v[76:77], 14, v[76:77]
	v_lshlrev_b64 v[78:79], 14, v[78:79]
	v_lshlrev_b64 v[80:81], 14, v[80:81]
	v_lshlrev_b64 v[82:83], 14, v[82:83]
	v_lshlrev_b64 v[84:85], 14, v[84:85]
	v_lshl_add_u64 v[20:21], v[86:87], 0, v[20:21]
	v_lshl_add_u64 v[92:93], v[86:87], 0, v[56:57]
	v_lshl_add_u64 v[94:95], v[86:87], 0, v[58:59]
	v_lshl_add_u64 v[96:97], v[86:87], 0, v[60:61]
	v_lshl_add_u64 v[98:99], v[86:87], 0, v[62:63]
	v_lshl_add_u64 v[100:101], v[86:87], 0, v[64:65]
	v_lshl_add_u64 v[102:103], v[86:87], 0, v[66:67]
	v_lshl_add_u64 v[104:105], v[86:87], 0, v[68:69]
	v_lshl_add_u64 v[106:107], v[86:87], 0, v[70:71]
	v_lshl_add_u64 v[108:109], v[86:87], 0, v[72:73]
	v_lshl_add_u64 v[110:111], v[86:87], 0, v[74:75]
	v_lshl_add_u64 v[112:113], v[86:87], 0, v[76:77]
	v_lshl_add_u64 v[114:115], v[86:87], 0, v[78:79]
	v_lshl_add_u64 v[116:117], v[86:87], 0, v[80:81]
	v_lshl_add_u64 v[118:119], v[86:87], 0, v[82:83]
	v_lshl_add_u64 v[120:121], v[86:87], 0, v[84:85]
	global_load_dwordx4 v[56:59], v[20:21], off
	global_load_dwordx4 v[60:63], v[92:93], off
	global_load_dwordx4 v[64:67], v[94:95], off
	global_load_dwordx4 v[68:71], v[96:97], off
	global_load_dwordx4 v[72:75], v[98:99], off
	global_load_dwordx4 v[76:79], v[100:101], off
	global_load_dwordx4 v[80:83], v[102:103], off
	global_load_dwordx4 v[84:87], v[104:105], off
	global_load_dwordx4 v[88:91], v[106:107], off
	global_load_dwordx4 v[92:95], v[108:109], off
	global_load_dwordx4 v[96:99], v[110:111], off
	s_nop 0
	global_load_dwordx4 v[100:103], v[112:113], off
	global_load_dwordx4 v[104:107], v[114:115], off
	global_load_dwordx4 v[108:111], v[116:117], off
	s_nop 0
	global_load_dwordx4 v[112:115], v[118:119], off
	s_nop 0
	global_load_dwordx4 v[116:119], v[120:121], off
	s_sub_i32 s16, s0, s9
	s_lshr_b32 s9, s16, 2
	s_mulk_i32 s9, 0xac
	s_add_i32 s12, s9, s15
	s_ashr_i32 s13, s12, 31
	s_add_u32 s9, s3, s14
	s_addc_u32 s14, s4, 0
	s_lshl_b64 s[12:13], s[12:13], 15
	s_add_u32 s12, s9, s12
	s_addc_u32 s13, s14, s13
	v_lshl_add_u64 v[20:21], s[12:13], 0, v[0:1]
	v_lshl_add_u64 v[120:121], v[20:21], 0, v[4:5]
	v_lshl_add_u64 v[122:123], v[20:21], 0, v[6:7]
	s_waitcnt vmcnt(15)
	ds_write2_b32 v24, v56, v57 offset1:1
	ds_write2_b32 v24, v58, v59 offset0:2 offset1:3
	s_waitcnt vmcnt(14)
	ds_write2_b32 v25, v60, v61 offset1:1
	ds_write2_b32 v26, v62, v63 offset1:1
	s_waitcnt vmcnt(13)
	ds_write2_b32 v27, v64, v65 offset1:1
	ds_write2_b32 v28, v66, v67 offset1:1
	s_waitcnt vmcnt(12)
	ds_write2_b32 v29, v68, v69 offset1:1
	ds_write2_b32 v30, v70, v71 offset1:1
	s_waitcnt vmcnt(11)
	ds_write2_b32 v31, v72, v73 offset1:1
	ds_write2_b32 v32, v74, v75 offset1:1
	s_waitcnt vmcnt(10)
	ds_write2_b32 v33, v76, v77 offset1:1
	ds_write2_b32 v34, v78, v79 offset1:1
	s_waitcnt vmcnt(9)
	ds_write2_b32 v35, v80, v81 offset1:1
	ds_write2_b32 v36, v82, v83 offset1:1
	s_waitcnt vmcnt(8)
	ds_write2_b32 v37, v84, v85 offset1:1
	ds_write2_b32 v38, v86, v87 offset1:1
	s_waitcnt vmcnt(7)
	ds_write2_b32 v39, v88, v89 offset1:1
	ds_write2_b32 v40, v90, v91 offset1:1
	s_waitcnt vmcnt(6)
	ds_write2_b32 v41, v92, v93 offset1:1
	ds_write2_b32 v42, v94, v95 offset1:1
	s_waitcnt vmcnt(5)
; #define LAS __attribute__((address_space(3)))
; __device__ __forceinline__ unsigned cvt_pk_bf16(float lo, float hi) { unsigned r; asm volatile("v_cvt_pk_bf16_f32 %0, %1, %2" : "=v"(r) : "v"(lo), "v"(hi)); return r; }
; #define LDS_WAIT() asm volatile("s_waitcnt lgkmcnt(0)" ::: "memory")
; __device__ __forceinline__ void transpose_item(const float* W, int N, bf16_t* WT, int nkt, int k0, int n0, int r0, int kbd, LAS float* scr, int lane) {
;     ...
;     for (int i = 0; i < 16; ++i) { LAS float* d = scr + (4 * i + lq) * 65 + 4 * l15; d[0] = v[i][0]; d[1] = v[i][1]; d[2] = v[i][2]; d[3] = v[i][3]; }
;     LDS_WAIT();
;     const int c = lane & 7;
; #pragma unroll
;     for (int j = 0; j < 8; ++j) { const int n = (lane >> 3) + 8 * j; const LAS float* s = scr + (8 * c) * 65 + n;
;         u32x4 o; o.x = cvt_pk_bf16(s[0], s[65]); o.y = cvt_pk_bf16(s[2 * 65], s[3 * 65]); o.z = cvt_pk_bf16(s[4 * 65], s[5 * 65]); o.w = cvt_pk_bf16(s[6 * 65], s[7 * 65]);
;         *(u32x4*)(WT + dst_off + (size_t)n * 64 + 8 * c) = o; }
;     LDS_WAIT();
; __device__ __forceinline__ void phase_convert_wdown(const Params& p, LAS float* scr, int cw, int NCW, int lane) {
;     ...
;     for (int it = cw; it < 172 * 64; it += NCW) { const int nb = it % 64, kb = it / 64; transpose_item(p.in[24], 4096, (bf16_t*)(ws + WS_W_DOWN), 172, kb * 64, nb * 64, nb * 64, kb, scr, lane); }
	ds_write2_b32 v43, v96, v97 offset1:1
	ds_write2_b32 v44, v98, v99 offset1:1
	s_waitcnt vmcnt(4)
	ds_write2_b32 v45, v100, v101 offset1:1
	ds_write2_b32 v46, v102, v103 offset1:1
	s_waitcnt vmcnt(3)
	ds_write2_b32 v47, v104, v105 offset1:1
	ds_write2_b32 v48, v106, v107 offset1:1
	s_waitcnt vmcnt(2)
	ds_write2_b32 v49, v108, v109 offset1:1
	ds_write2_b32 v50, v110, v111 offset1:1
	s_waitcnt vmcnt(1)
	ds_write2_b32 v51, v112, v113 offset1:1
	ds_write2_b32 v52, v114, v115 offset1:1
	s_waitcnt vmcnt(0)
	ds_write2_b32 v53, v116, v117 offset1:1
	ds_write2_b32 v54, v118, v119 offset1:1
	s_waitcnt lgkmcnt(0)
	ds_read2_b32 v[56:57], v23 offset1:65
	s_waitcnt lgkmcnt(0)
	v_cvt_pk_bf16_f32 v56, v56, v57
	ds_read2_b32 v[58:59], v23 offset0:130 offset1:195
	s_waitcnt lgkmcnt(0)
	v_cvt_pk_bf16_f32 v57, v58, v59
	ds_read2_b32 v[58:59], v55 offset0:4 offset1:69
	s_waitcnt lgkmcnt(0)
	v_cvt_pk_bf16_f32 v58, v58, v59
	ds_read2_b32 v[60:61], v55 offset0:134 offset1:199
	s_waitcnt lgkmcnt(0)
	v_cvt_pk_bf16_f32 v59, v60, v61
	ds_read2_b32 v[60:61], v23 offset0:8 offset1:73
	global_store_dwordx4 v[120:121], v[56:59], off sc1
	v_lshl_add_u64 v[124:125], v[20:21], 0, v[8:9]
	v_lshl_add_u64 v[126:127], v[20:21], 0, v[10:11]
	s_waitcnt lgkmcnt(0)
	v_cvt_pk_bf16_f32 v56, v60, v61
	ds_read2_b32 v[58:59], v23 offset0:138 offset1:203
	s_waitcnt lgkmcnt(0)
	v_cvt_pk_bf16_f32 v57, v58, v59
	ds_read2_b32 v[58:59], v55 offset0:12 offset1:77
	s_waitcnt lgkmcnt(0)
	v_cvt_pk_bf16_f32 v58, v58, v59
	ds_read2_b32 v[60:61], v55 offset0:142 offset1:207
	s_waitcnt lgkmcnt(0)
	v_cvt_pk_bf16_f32 v59, v60, v61
	ds_read2_b32 v[60:61], v23 offset0:16 offset1:81
	global_store_dwordx4 v[122:123], v[56:59], off sc1
	v_lshl_add_u64 v[128:129], v[20:21], 0, v[12:13]
	v_lshl_add_u64 v[130:131], v[20:21], 0, v[14:15]
	s_waitcnt lgkmcnt(0)
	v_cvt_pk_bf16_f32 v56, v60, v61
	ds_read2_b32 v[58:59], v23 offset0:146 offset1:211
	s_waitcnt lgkmcnt(0)
	v_cvt_pk_bf16_f32 v57, v58, v59
	ds_read2_b32 v[58:59], v55 offset0:20 offset1:85
	s_waitcnt lgkmcnt(0)
	v_cvt_pk_bf16_f32 v58, v58, v59
	ds_read2_b32 v[60:61], v55 offset0:150 offset1:215
	s_waitcnt lgkmcnt(0)
	v_cvt_pk_bf16_f32 v59, v60, v61
	ds_read2_b32 v[60:61], v23 offset0:24 offset1:89
	global_store_dwordx4 v[124:125], v[56:59], off sc1
	v_lshl_add_u64 v[132:133], v[20:21], 0, v[16:17]
	v_lshl_add_u64 v[20:21], v[20:21], 0, v[18:19]
	s_waitcnt lgkmcnt(0)
	v_cvt_pk_bf16_f32 v56, v60, v61
	ds_read2_b32 v[58:59], v23 offset0:154 offset1:219
	s_waitcnt lgkmcnt(0)
	v_cvt_pk_bf16_f32 v57, v58, v59
	ds_read2_b32 v[58:59], v55 offset0:28 offset1:93
	s_waitcnt lgkmcnt(0)
	v_cvt_pk_bf16_f32 v58, v58, v59
	ds_read2_b32 v[60:61], v55 offset0:158 offset1:223
	s_waitcnt lgkmcnt(0)
	v_cvt_pk_bf16_f32 v59, v60, v61
	ds_read2_b32 v[60:61], v23 offset0:32 offset1:97
	global_store_dwordx4 v[126:127], v[56:59], off sc1
	s_add_i32 s0, s0, s1
	s_add_i32 s5, s5, s6
	s_waitcnt lgkmcnt(0)
	v_cvt_pk_bf16_f32 v56, v60, v61
	ds_read2_b32 v[58:59], v23 offset0:162 offset1:227
	s_waitcnt lgkmcnt(0)
	v_cvt_pk_bf16_f32 v57, v58, v59
	ds_read2_b32 v[58:59], v55 offset0:36 offset1:101
	s_waitcnt lgkmcnt(0)
	v_cvt_pk_bf16_f32 v58, v58, v59
	ds_read2_b32 v[60:61], v55 offset0:166 offset1:231
	s_waitcnt lgkmcnt(0)
	v_cvt_pk_bf16_f32 v59, v60, v61
	ds_read2_b32 v[60:61], v23 offset0:40 offset1:105
	global_store_dwordx4 v[128:129], v[56:59], off sc1
	s_add_i32 s7, s7, s8
	s_cmpk_lt_i32 s0, 0x2b00
	s_waitcnt lgkmcnt(0)
	v_cvt_pk_bf16_f32 v56, v60, v61
	ds_read2_b32 v[58:59], v23 offset0:170 offset1:235
	s_waitcnt lgkmcnt(0)
	v_cvt_pk_bf16_f32 v57, v58, v59
	ds_read2_b32 v[58:59], v55 offset0:44 offset1:109
	s_waitcnt lgkmcnt(0)
	v_cvt_pk_bf16_f32 v58, v58, v59
	ds_read2_b32 v[60:61], v55 offset0:174 offset1:239
	s_waitcnt lgkmcnt(0)
	v_cvt_pk_bf16_f32 v59, v60, v61
	ds_read2_b32 v[60:61], v23 offset0:48 offset1:113
	global_store_dwordx4 v[130:131], v[56:59], off sc1
	s_waitcnt lgkmcnt(0)
	s_nop 0
	v_cvt_pk_bf16_f32 v56, v60, v61
	ds_read2_b32 v[58:59], v23 offset0:178 offset1:243
	s_waitcnt lgkmcnt(0)
	v_cvt_pk_bf16_f32 v57, v58, v59
	ds_read2_b32 v[58:59], v55 offset0:52 offset1:117
	s_waitcnt lgkmcnt(0)
	v_cvt_pk_bf16_f32 v58, v58, v59
	ds_read2_b32 v[60:61], v55 offset0:182 offset1:247
	s_waitcnt lgkmcnt(0)
	v_cvt_pk_bf16_f32 v59, v60, v61
	ds_read2_b32 v[60:61], v23 offset0:56 offset1:121
	global_store_dwordx4 v[132:133], v[56:59], off sc1
	s_waitcnt lgkmcnt(0)
	s_nop 0
	v_cvt_pk_bf16_f32 v56, v60, v61
	ds_read2_b32 v[58:59], v23 offset0:186 offset1:251
	s_waitcnt lgkmcnt(0)
	v_cvt_pk_bf16_f32 v57, v58, v59
	ds_read2_b32 v[58:59], v55 offset0:60 offset1:125
	s_waitcnt lgkmcnt(0)
	v_cvt_pk_bf16_f32 v58, v58, v59
	ds_read2_b32 v[60:61], v55 offset0:190 offset1:255
	s_waitcnt lgkmcnt(0)
	v_cvt_pk_bf16_f32 v59, v60, v61
	global_store_dwordx4 v[20:21], v[56:59], off sc1
	s_waitcnt lgkmcnt(0)
	s_cbranch_scc1 .LBB0_801

; __device__ __forceinline__ u32x4 pack8(const f32x4 v0, const f32x4 v1) { u32x4 w; w.x = cvt_pk_bf16(v0[0], v0[1]); w.y = cvt_pk_bf16(v0[2], v0[3]); w.z = cvt_pk_bf16(v1[0], v1[1]); w.w = cvt_pk_bf16(v1[2], v1[3]); return w; }
;     __device__ __forceinline__ void operator()(AccT& acc, const Unit& u, int wr, int wc, int fr, int fq) const {
;     ...
;         for (int ai = 0; ai < 2; ++ai)
; #pragma unroll
;             for (int m = 0; m < 4; ++m) { const int row = row0 + ai * 128 + m * 16; bf16_t* rowp = O + (size_t)row * DM + col0; float ss = 0.f;
; #pragma unroll
;                 for (int bj = 0; bj < 2; ++bj) { const f32x4 v0 = acc[ai][bj][m][0], v1 = acc[ai][bj][m][1];
;                     ss += (v0[0] * v0[0] + v0[1] * v0[1]) + (v0[2] * v0[2] + v0[3] * v0[3]) + (v1[0] * v1[0] + v1[1] * v1[1]) + (v1[2] * v1[2] + v1[3] * v1[3]);
;                     *(u32x4*)(rowp + bj * 128) = pack8(v0, v1); }
;                 ss += __shfl_xor(ss, 16); ss += __shfl_xor(ss, 32);
;                 if (fq == 0) SSQ[(size_t)(u.pn * 4 + wc) * MT + row] = ss; }
.LBB0_938:
	v_mul_f32_e32 v148, v125, v125
	v_mul_f32_e32 v149, v127, v127
	v_fmac_f32_e32 v148, v124, v124
	v_fmac_f32_e32 v149, v126, v126
	v_add_f32_e32 v148, v148, v149
	v_mul_f32_e32 v149, v121, v121
	v_fmac_f32_e32 v149, v120, v120
	v_add_f32_e32 v148, v149, v148
	v_mul_f32_e32 v149, v123, v123
	v_mov_b32_e32 v136, v254
	v_fmac_f32_e32 v149, v122, v122
	v_add_f32_e32 v150, v149, v148
	v_cvt_pk_bf16_f32 v148, v124, v125
	v_mul_f32_e32 v124, v117, v117
	v_mul_f32_e32 v125, v119, v119
	s_lshl_b32 s4, s88, 8
	v_fmac_f32_e32 v124, v116, v116
	v_fmac_f32_e32 v125, v118, v118
	s_add_i32 s4, s4, s71
	v_add_f32_e32 v124, v124, v125
	v_mul_f32_e32 v125, v113, v113
	v_bfe_u32 v137, v136, 4, 2
	v_and_or_b32 v136, v136, 15, s4
	s_lshl_b32 s4, s87, 8
	v_fmac_f32_e32 v125, v112, v112
	s_or_b32 s4, s4, s72
	v_add_f32_e32 v124, v125, v124
	v_mul_f32_e32 v125, v115, v115
	v_lshl_or_b32 v140, v137, 3, s4
	s_lshl_b32 s4, s87, 2
	v_fmac_f32_e32 v125, v114, v114
	s_or_b32 s4, s4, s70
	v_cvt_pk_bf16_f32 v149, v126, v127
	v_add_f32_e32 v124, v125, v124
	v_and_b32_e32 v126, 64, v147
	s_ashr_i32 s5, s4, 31
	v_add_f32_e32 v125, v124, v150
	v_xor_b32_e32 v124, 16, v147
	v_add_u32_e32 v126, 64, v126
	s_lshl_b64 s[12:13], s[4:5], 15
	v_cmp_lt_i32_e64 s[4:5], v124, v126
	v_cmp_eq_u32_e32 vcc, 0, v137
	v_ashrrev_i32_e32 v137, 31, v136
	v_cndmask_b32_e64 v124, v147, v124, s[4:5]
	v_lshlrev_b64 v[138:139], 13, v[136:137]
	v_lshlrev_b32_e32 v124, 2, v124
	v_ashrrev_i32_e32 v141, 31, v140
	v_lshl_add_u64 v[138:139], s[28:29], 0, v[138:139]
	ds_bpermute_b32 v127, v124, v125
	v_lshl_add_u64 v[138:139], v[140:141], 1, v[138:139]
	v_cvt_pk_bf16_f32 v150, v120, v121
	v_cvt_pk_bf16_f32 v151, v122, v123
	global_store_dwordx4 v[138:139], v[148:151], off sc1
	s_nop 1
	v_cvt_pk_bf16_f32 v148, v116, v117
	v_xor_b32_e32 v116, 32, v147
	v_cmp_lt_i32_e64 s[4:5], v116, v126
	s_waitcnt lgkmcnt(0)
	v_add_f32_e32 v117, v125, v127
	v_cvt_pk_bf16_f32 v149, v118, v119
	v_cvt_pk_bf16_f32 v150, v112, v113
	v_cvt_pk_bf16_f32 v151, v114, v115
	global_store_dwordx4 v[138:139], v[148:151], off offset:256 sc1
	v_cndmask_b32_e64 v116, v147, v116, s[4:5]
	v_lshlrev_b32_e32 v116, 2, v116
	ds_bpermute_b32 v120, v116, v117
	s_and_saveexec_b64 s[4:5], vcc
	s_cbranch_execz .LBB0_940
	s_add_u32 s14, s68, s12
	s_addc_u32 s15, s69, s13
	s_waitcnt lgkmcnt(0)
	v_add_f32_e32 v114, v117, v120
	v_lshl_add_u64 v[112:113], v[136:137], 2, s[14:15]
	global_store_dword v[112:113], v114, off
.LBB0_940:
	s_or_b64 exec, exec, s[4:5]
	v_mul_f32_e32 v114, v109, v109
	v_mul_f32_e32 v115, v111, v111
	v_fmac_f32_e32 v114, v108, v108
	v_fmac_f32_e32 v115, v110, v110
	v_cvt_pk_bf16_f32 v108, v108, v109
	v_cvt_pk_bf16_f32 v109, v110, v111
	v_mul_f32_e32 v110, v101, v101
	v_mul_f32_e32 v111, v103, v103
	v_fmac_f32_e32 v110, v100, v100
	v_fmac_f32_e32 v111, v102, v102
	v_add_f32_e32 v114, v114, v115
	v_mul_f32_e32 v115, v105, v105
	v_add_f32_e32 v110, v110, v111
	v_mul_f32_e32 v111, v97, v97
	v_fmac_f32_e32 v115, v104, v104
	v_fmac_f32_e32 v111, v96, v96
	v_add_f32_e32 v114, v115, v114
	v_mul_f32_e32 v115, v107, v107
	v_add_f32_e32 v110, v111, v110
	v_mul_f32_e32 v111, v99, v99
	v_fmac_f32_e32 v115, v106, v106
	v_fmac_f32_e32 v111, v98, v98
	v_add_f32_e32 v114, v115, v114
	v_add_f32_e32 v110, v111, v110
	v_add_f32_e32 v114, v110, v114
	v_or_b32_e32 v112, 16, v136
	ds_bpermute_b32 v115, v124, v114
	v_ashrrev_i32_e32 v113, 31, v112
	v_lshlrev_b64 v[112:113], 13, v[112:113]
	v_lshl_add_u64 v[112:113], s[28:29], 0, v[112:113]
	v_lshl_add_u64 v[112:113], v[140:141], 1, v[112:113]
	v_cvt_pk_bf16_f32 v110, v104, v105
	v_cvt_pk_bf16_f32 v111, v106, v107
	global_store_dwordx4 v[112:113], v[108:111], off sc1
	v_cvt_pk_bf16_f32 v104, v100, v101
	s_waitcnt lgkmcnt(0)
	v_add_f32_e32 v100, v114, v115
	ds_bpermute_b32 v101, v116, v100
	v_cvt_pk_bf16_f32 v105, v102, v103
	v_cvt_pk_bf16_f32 v106, v96, v97
	v_cvt_pk_bf16_f32 v107, v98, v99
	global_store_dwordx4 v[112:113], v[104:107], off offset:256 sc1
	s_and_saveexec_b64 s[4:5], vcc
	s_cbranch_execz .LBB0_942
	s_add_u32 s14, s68, s12
	s_addc_u32 s15, s69, s13
	s_waitcnt lgkmcnt(0)
	v_add_f32_e32 v98, v100, v101
	v_lshl_add_u64 v[96:97], v[136:137], 2, s[14:15]
	global_store_dword v[96:97], v98, off offset:64
.LBB0_942:
	s_or_b64 exec, exec, s[4:5]
	v_mul_f32_e32 v98, v93, v93
	v_mul_f32_e32 v99, v95, v95
	v_fmac_f32_e32 v98, v92, v92
	v_fmac_f32_e32 v99, v94, v94
	v_cvt_pk_bf16_f32 v92, v92, v93
	v_cvt_pk_bf16_f32 v93, v94, v95
	v_mul_f32_e32 v94, v85, v85
	v_mul_f32_e32 v95, v87, v87
	v_fmac_f32_e32 v94, v84, v84
	v_fmac_f32_e32 v95, v86, v86
	v_add_f32_e32 v98, v98, v99
	v_mul_f32_e32 v99, v89, v89
	v_add_f32_e32 v94, v94, v95
	v_mul_f32_e32 v95, v81, v81
	v_fmac_f32_e32 v99, v88, v88
	v_fmac_f32_e32 v95, v80, v80
	v_add_f32_e32 v98, v99, v98
	v_mul_f32_e32 v99, v91, v91
	v_add_f32_e32 v94, v95, v94
	v_mul_f32_e32 v95, v83, v83
	v_fmac_f32_e32 v99, v90, v90
	v_fmac_f32_e32 v95, v82, v82
	v_add_f32_e32 v98, v99, v98
	v_add_f32_e32 v94, v95, v94
	v_add_f32_e32 v98, v94, v98
	v_or_b32_e32 v96, 32, v136
	ds_bpermute_b32 v99, v124, v98
	v_ashrrev_i32_e32 v97, 31, v96
	v_lshlrev_b64 v[96:97], 13, v[96:97]
	v_lshl_add_u64 v[96:97], s[28:29], 0, v[96:97]
	v_lshl_add_u64 v[96:97], v[140:141], 1, v[96:97]
	v_cvt_pk_bf16_f32 v94, v88, v89
	v_cvt_pk_bf16_f32 v95, v90, v91
	global_store_dwordx4 v[96:97], v[92:95], off sc1
	v_cvt_pk_bf16_f32 v88, v84, v85
	s_waitcnt lgkmcnt(0)
	v_add_f32_e32 v84, v98, v99
	ds_bpermute_b32 v85, v116, v84
	v_cvt_pk_bf16_f32 v89, v86, v87
	v_cvt_pk_bf16_f32 v90, v80, v81
	v_cvt_pk_bf16_f32 v91, v82, v83
	global_store_dwordx4 v[96:97], v[88:91], off offset:256 sc1
	s_and_saveexec_b64 s[4:5], vcc
	s_cbranch_execz .LBB0_944
	s_add_u32 s14, s68, s12
	s_addc_u32 s15, s69, s13
	s_waitcnt lgkmcnt(0)
	v_add_f32_e32 v82, v84, v85
	v_lshl_add_u64 v[80:81], v[136:137], 2, s[14:15]
	global_store_dword v[80:81], v82, off offset:128
; __device__ __forceinline__ u32x4 pack8(const f32x4 v0, const f32x4 v1) { u32x4 w; w.x = cvt_pk_bf16(v0[0], v0[1]); w.y = cvt_pk_bf16(v0[2], v0[3]); w.z = cvt_pk_bf16(v1[0], v1[1]); w.w = cvt_pk_bf16(v1[2], v1[3]); return w; }
;     __device__ __forceinline__ void operator()(AccT& acc, const Unit& u, int wr, int wc, int fr, int fq) const {
;     ...
;         for (int ai = 0; ai < 2; ++ai)
; #pragma unroll
;             for (int m = 0; m < 4; ++m) { const int row = row0 + ai * 128 + m * 16; bf16_t* rowp = O + (size_t)row * DM + col0; float ss = 0.f;
; #pragma unroll
;                 for (int bj = 0; bj < 2; ++bj) { const f32x4 v0 = acc[ai][bj][m][0], v1 = acc[ai][bj][m][1];
;                     ss += (v0[0] * v0[0] + v0[1] * v0[1]) + (v0[2] * v0[2] + v0[3] * v0[3]) + (v1[0] * v1[0] + v1[1] * v1[1]) + (v1[2] * v1[2] + v1[3] * v1[3]);
;                     *(u32x4*)(rowp + bj * 128) = pack8(v0, v1); }
;                 ss += __shfl_xor(ss, 16); ss += __shfl_xor(ss, 32);
;                 if (fq == 0) SSQ[(size_t)(u.pn * 4 + wc) * MT + row] = ss; }
.LBB0_944:
	s_or_b64 exec, exec, s[4:5]
	v_mul_f32_e32 v82, v77, v77
	v_mul_f32_e32 v83, v79, v79
	v_fmac_f32_e32 v82, v76, v76
	v_fmac_f32_e32 v83, v78, v78
	v_cvt_pk_bf16_f32 v76, v76, v77
	v_cvt_pk_bf16_f32 v77, v78, v79
	v_mul_f32_e32 v78, v69, v69
	v_mul_f32_e32 v79, v71, v71
	v_fmac_f32_e32 v78, v68, v68
	v_fmac_f32_e32 v79, v70, v70
	v_add_f32_e32 v82, v82, v83
	v_mul_f32_e32 v83, v73, v73
	v_add_f32_e32 v78, v78, v79
	v_mul_f32_e32 v79, v65, v65
	v_fmac_f32_e32 v83, v72, v72
	v_fmac_f32_e32 v79, v64, v64
	v_add_f32_e32 v82, v83, v82
	v_mul_f32_e32 v83, v75, v75
	v_add_f32_e32 v78, v79, v78
	v_mul_f32_e32 v79, v67, v67
	v_fmac_f32_e32 v83, v74, v74
	v_fmac_f32_e32 v79, v66, v66
	v_add_f32_e32 v82, v83, v82
	v_add_f32_e32 v78, v79, v78
	v_add_f32_e32 v82, v78, v82
	v_or_b32_e32 v80, 48, v136
	ds_bpermute_b32 v83, v124, v82
	v_ashrrev_i32_e32 v81, 31, v80
	v_lshlrev_b64 v[80:81], 13, v[80:81]
	v_lshl_add_u64 v[80:81], s[28:29], 0, v[80:81]
	v_lshl_add_u64 v[80:81], v[140:141], 1, v[80:81]
	v_cvt_pk_bf16_f32 v78, v72, v73
	v_cvt_pk_bf16_f32 v79, v74, v75
	global_store_dwordx4 v[80:81], v[76:79], off sc1
	v_cvt_pk_bf16_f32 v72, v68, v69
	s_waitcnt lgkmcnt(0)
	v_add_f32_e32 v68, v82, v83
	ds_bpermute_b32 v69, v116, v68
	v_cvt_pk_bf16_f32 v73, v70, v71
	v_cvt_pk_bf16_f32 v74, v64, v65
	v_cvt_pk_bf16_f32 v75, v66, v67
	global_store_dwordx4 v[80:81], v[72:75], off offset:256 sc1
	s_and_saveexec_b64 s[4:5], vcc
	s_cbranch_execz .LBB0_946
	s_add_u32 s14, s68, s12
	s_addc_u32 s15, s69, s13
	s_waitcnt lgkmcnt(0)
	v_add_f32_e32 v66, v68, v69
	v_lshl_add_u64 v[64:65], v[136:137], 2, s[14:15]
	global_store_dword v[64:65], v66, off offset:192
.LBB0_946:
	s_or_b64 exec, exec, s[4:5]
	v_mul_f32_e32 v66, v61, v61
	v_mul_f32_e32 v67, v63, v63
	v_fmac_f32_e32 v66, v60, v60
	v_fmac_f32_e32 v67, v62, v62
	v_add_f32_e32 v66, v66, v67
	v_mul_f32_e32 v67, v57, v57
	v_fmac_f32_e32 v67, v56, v56
	v_cvt_pk_bf16_f32 v60, v60, v61
	v_cvt_pk_bf16_f32 v61, v62, v63
	v_cvt_pk_bf16_f32 v62, v56, v57
	v_mul_f32_e32 v56, v53, v53
	v_mul_f32_e32 v57, v55, v55
	v_fmac_f32_e32 v56, v52, v52
	v_fmac_f32_e32 v57, v54, v54
	v_add_f32_e32 v56, v56, v57
	v_mul_f32_e32 v57, v49, v49
	v_fmac_f32_e32 v57, v48, v48
	v_add_f32_e32 v66, v67, v66
	v_mul_f32_e32 v67, v59, v59
	v_add_f32_e32 v56, v57, v56
	v_mul_f32_e32 v57, v51, v51
	v_fmac_f32_e32 v67, v58, v58
	v_fmac_f32_e32 v57, v50, v50
	v_add_f32_e32 v66, v67, v66
	v_add_f32_e32 v56, v57, v56
	v_cvt_pk_bf16_f32 v63, v58, v59
	v_add_f32_e32 v58, v56, v66
	ds_bpermute_b32 v59, v124, v58
	v_add_co_u32_e64 v56, s[4:5], s33, v138
	v_lshl_add_u64 v[64:65], v[138:139], 0, s[36:37]
	s_nop 0
	v_addc_co_u32_e64 v57, s[4:5], 0, v139, s[4:5]
	global_store_dwordx4 v[56:57], v[60:63], off sc1
	v_cvt_pk_bf16_f32 v56, v52, v53
	s_waitcnt lgkmcnt(0)
	v_add_f32_e32 v52, v58, v59
	ds_bpermute_b32 v53, v116, v52
	v_cvt_pk_bf16_f32 v57, v54, v55
	v_cvt_pk_bf16_f32 v58, v48, v49
	v_cvt_pk_bf16_f32 v59, v50, v51
	global_store_dwordx4 v[64:65], v[56:59], off offset:256 sc1
	s_and_saveexec_b64 s[4:5], vcc
	s_cbranch_execz .LBB0_948
	s_add_u32 s14, s68, s12
	s_addc_u32 s15, s69, s13
	s_waitcnt lgkmcnt(0)
	v_add_f32_e32 v50, v52, v53
	v_lshl_add_u64 v[48:49], v[136:137], 2, s[14:15]
	global_store_dword v[48:49], v50, off offset:512
; __device__ __forceinline__ u32x4 pack8(const f32x4 v0, const f32x4 v1) { u32x4 w; w.x = cvt_pk_bf16(v0[0], v0[1]); w.y = cvt_pk_bf16(v0[2], v0[3]); w.z = cvt_pk_bf16(v1[0], v1[1]); w.w = cvt_pk_bf16(v1[2], v1[3]); return w; }
;     __device__ __forceinline__ void operator()(AccT& acc, const Unit& u, int wr, int wc, int fr, int fq) const {
;     ...
;         for (int ai = 0; ai < 2; ++ai)
; #pragma unroll
;             for (int m = 0; m < 4; ++m) { const int row = row0 + ai * 128 + m * 16; bf16_t* rowp = O + (size_t)row * DM + col0; float ss = 0.f;
; #pragma unroll
;                 for (int bj = 0; bj < 2; ++bj) { const f32x4 v0 = acc[ai][bj][m][0], v1 = acc[ai][bj][m][1];
;                     ss += (v0[0] * v0[0] + v0[1] * v0[1]) + (v0[2] * v0[2] + v0[3] * v0[3]) + (v1[0] * v1[0] + v1[1] * v1[1]) + (v1[2] * v1[2] + v1[3] * v1[3]);
;                     *(u32x4*)(rowp + bj * 128) = pack8(v0, v1); }
;                 ss += __shfl_xor(ss, 16); ss += __shfl_xor(ss, 32);
;                 if (fq == 0) SSQ[(size_t)(u.pn * 4 + wc) * MT + row] = ss; }
.LBB0_948:
	s_or_b64 exec, exec, s[4:5]
	v_mul_f32_e32 v50, v45, v45
	v_mul_f32_e32 v51, v47, v47
	v_fmac_f32_e32 v50, v44, v44
	v_fmac_f32_e32 v51, v46, v46
	v_add_f32_e32 v50, v50, v51
	v_mul_f32_e32 v51, v41, v41
	v_fmac_f32_e32 v51, v40, v40
	v_cvt_pk_bf16_f32 v44, v44, v45
	v_cvt_pk_bf16_f32 v45, v46, v47
	v_cvt_pk_bf16_f32 v46, v40, v41
	v_mul_f32_e32 v40, v37, v37
	v_mul_f32_e32 v41, v39, v39
	v_fmac_f32_e32 v40, v36, v36
	v_fmac_f32_e32 v41, v38, v38
	v_add_f32_e32 v40, v40, v41
	v_mul_f32_e32 v41, v33, v33
	v_fmac_f32_e32 v41, v32, v32
	v_add_f32_e32 v50, v51, v50
	v_mul_f32_e32 v51, v43, v43
	v_add_f32_e32 v40, v41, v40
	v_mul_f32_e32 v41, v35, v35
	v_fmac_f32_e32 v51, v42, v42
	v_fmac_f32_e32 v41, v34, v34
	v_add_f32_e32 v50, v51, v50
	v_add_f32_e32 v40, v41, v40
	v_cvt_pk_bf16_f32 v47, v42, v43
	v_add_f32_e32 v42, v40, v50
	ds_bpermute_b32 v43, v124, v42
	v_add_co_u32_e64 v40, s[4:5], s62, v138
	v_lshl_add_u64 v[48:49], v[138:139], 0, s[38:39]
	s_nop 0
	v_addc_co_u32_e64 v41, s[4:5], 0, v139, s[4:5]
	global_store_dwordx4 v[40:41], v[44:47], off sc1
	v_cvt_pk_bf16_f32 v40, v36, v37
	s_waitcnt lgkmcnt(0)
	v_add_f32_e32 v36, v42, v43
	ds_bpermute_b32 v37, v116, v36
	v_cvt_pk_bf16_f32 v41, v38, v39
	v_cvt_pk_bf16_f32 v42, v32, v33
	v_cvt_pk_bf16_f32 v43, v34, v35
	global_store_dwordx4 v[48:49], v[40:43], off offset:256 sc1
	s_and_saveexec_b64 s[4:5], vcc
	s_cbranch_execz .LBB0_950
	s_add_u32 s14, s68, s12
	s_addc_u32 s15, s69, s13
	s_waitcnt lgkmcnt(0)
	v_add_f32_e32 v34, v36, v37
	v_lshl_add_u64 v[32:33], v[136:137], 2, s[14:15]
	global_store_dword v[32:33], v34, off offset:576
.LBB0_950:
	s_or_b64 exec, exec, s[4:5]
	v_mul_f32_e32 v34, v29, v29
	v_mul_f32_e32 v35, v31, v31
	v_fmac_f32_e32 v34, v28, v28
	v_fmac_f32_e32 v35, v30, v30
	v_add_f32_e32 v34, v34, v35
	v_mul_f32_e32 v35, v25, v25
	v_fmac_f32_e32 v35, v24, v24
	v_cvt_pk_bf16_f32 v28, v28, v29
	v_cvt_pk_bf16_f32 v29, v30, v31
	v_cvt_pk_bf16_f32 v30, v24, v25
	v_mul_f32_e32 v24, v21, v21
	v_mul_f32_e32 v25, v23, v23
	v_fmac_f32_e32 v24, v20, v20
	v_fmac_f32_e32 v25, v22, v22
	v_add_f32_e32 v24, v24, v25
	v_mul_f32_e32 v25, v17, v17
	v_fmac_f32_e32 v25, v16, v16
	v_add_f32_e32 v34, v35, v34
	v_mul_f32_e32 v35, v27, v27
	v_add_f32_e32 v24, v25, v24
	v_mul_f32_e32 v25, v19, v19
	v_fmac_f32_e32 v35, v26, v26
	v_fmac_f32_e32 v25, v18, v18
	v_add_f32_e32 v34, v35, v34
	v_add_f32_e32 v24, v25, v24
	v_cvt_pk_bf16_f32 v31, v26, v27
	v_add_f32_e32 v26, v24, v34
	ds_bpermute_b32 v27, v124, v26
	v_add_co_u32_e64 v24, s[4:5], s63, v138
	v_lshl_add_u64 v[32:33], v[138:139], 0, s[40:41]
	s_nop 0
	v_addc_co_u32_e64 v25, s[4:5], 0, v139, s[4:5]
	global_store_dwordx4 v[24:25], v[28:31], off sc1
	v_cvt_pk_bf16_f32 v24, v20, v21
	s_waitcnt lgkmcnt(0)
	v_add_f32_e32 v20, v26, v27
	ds_bpermute_b32 v21, v116, v20
	v_cvt_pk_bf16_f32 v25, v22, v23
	v_cvt_pk_bf16_f32 v26, v16, v17
	v_cvt_pk_bf16_f32 v27, v18, v19
	global_store_dwordx4 v[32:33], v[24:27], off offset:256 sc1
	s_and_saveexec_b64 s[4:5], vcc
	s_cbranch_execz .LBB0_952
	s_add_u32 s14, s68, s12
	s_addc_u32 s15, s69, s13
	s_waitcnt lgkmcnt(0)
	v_add_f32_e32 v18, v20, v21
	v_lshl_add_u64 v[16:17], v[136:137], 2, s[14:15]
	global_store_dword v[16:17], v18, off offset:640
.LBB0_952:
	s_or_b64 exec, exec, s[4:5]
	v_mul_f32_e32 v18, v13, v13
	v_mul_f32_e32 v19, v15, v15
	v_fmac_f32_e32 v18, v12, v12
	v_fmac_f32_e32 v19, v14, v14
	v_add_f32_e32 v18, v18, v19
	v_mul_f32_e32 v19, v9, v9
	v_fmac_f32_e32 v19, v8, v8
	v_cvt_pk_bf16_f32 v12, v12, v13
	v_cvt_pk_bf16_f32 v13, v14, v15
	v_cvt_pk_bf16_f32 v14, v8, v9
	v_mul_f32_e32 v8, v5, v5
	v_mul_f32_e32 v9, v7, v7
	v_fmac_f32_e32 v8, v4, v4
	v_fmac_f32_e32 v9, v6, v6
	v_add_f32_e32 v8, v8, v9
	v_mul_f32_e32 v9, v1, v1
	v_fmac_f32_e32 v9, v0, v0
	v_add_f32_e32 v18, v19, v18
	v_mul_f32_e32 v19, v11, v11
	v_add_f32_e32 v8, v9, v8
	v_mul_f32_e32 v9, v3, v3
	v_fmac_f32_e32 v19, v10, v10
	v_fmac_f32_e32 v9, v2, v2
	v_add_f32_e32 v18, v19, v18
	v_add_f32_e32 v8, v9, v8
	v_cvt_pk_bf16_f32 v15, v10, v11
	v_add_f32_e32 v10, v8, v18
	ds_bpermute_b32 v11, v124, v10
	v_add_co_u32_e64 v8, s[4:5], s84, v138
	v_lshl_add_u64 v[16:17], v[138:139], 0, s[42:43]
	s_nop 0
	v_addc_co_u32_e64 v9, s[4:5], 0, v139, s[4:5]
	global_store_dwordx4 v[8:9], v[12:15], off sc1
	v_cvt_pk_bf16_f32 v8, v4, v5
	s_waitcnt lgkmcnt(0)
	v_add_f32_e32 v4, v10, v11
	ds_bpermute_b32 v5, v116, v4
	v_cvt_pk_bf16_f32 v9, v6, v7
	v_cvt_pk_bf16_f32 v10, v0, v1
	v_cvt_pk_bf16_f32 v11, v2, v3
	global_store_dwordx4 v[16:17], v[8:11], off offset:256 sc1
	s_and_saveexec_b64 s[4:5], vcc
	s_cbranch_execz .LBB0_954
	s_add_u32 s12, s68, s12
	s_addc_u32 s13, s69, s13
	s_waitcnt lgkmcnt(0)
	v_add_f32_e32 v2, v4, v5
	v_lshl_add_u64 v[0:1], v[136:137], 2, s[12:13]
	global_store_dword v[0:1], v2, off offset:704

; __device__ __forceinline__ float bf_lo(unsigned w) { return __uint_as_float(w << 16); }
; __device__ __forceinline__ float bf_hi(unsigned w) { return __uint_as_float(w & 0xffff0000u); }
; __device__ __forceinline__ void phase_final(const Params& p, int gw, int NGW, int lane) {
;     ...
;     for (int row = gw; row < MT; row += NGW) {
;         const float r = rsqrtf(wave_sum(SSQ[(size_t)lane * MT + row]) * (1.f / DM) + EPSN);
;         const u32x2* dr = (const u32x2*)(DN + (size_t)row * DM) + lane; const u32x2* hr = (const u32x2*)(H1 + (size_t)row * DM) + lane; f32x4* o = (f32x4*)(p.out + (size_t)row * DM) + lane;
;         const f32x4* gp = g + lane;
;         asm volatile("" : "+v"(gp), "+v"(dr), "+v"(hr), "+v"(o));
; #pragma unroll 8
;         for (int j = 0; j < 16; ++j) { const u32x2 dw = dr[64 * j]; const f32x4 dn = {bf_lo(dw.x), bf_hi(dw.x), bf_lo(dw.y), bf_hi(dw.y)}; const u32x2 hw = hr[64 * j]; const f32x4 hh = {bf_lo(hw.x), bf_hi(hw.x), bf_lo(hw.y), bf_hi(hw.y)}; o[64 * j] = hh + dn * r * gp[64 * j]; }
;     }
.Lfin_row:
	s_ashr_i32 s35, s34, 31
	s_lshl_b64 s[2:3], s[34:35], 13
	s_lshl_b64 s[6:7], s[34:35], 14
	s_add_i32 s10, s34, s60
	s_min_i32 s10, s10, 0x1fff
	s_ashr_i32 s11, s10, 31
	v_lshl_add_u64 v[10:11], s[10:11], 2, v[0:1]
	v_lshl_add_u64 v[12:13], v[2:3], 0, s[2:3]
	v_lshl_add_u64 v[14:15], v[4:5], 0, s[2:3]
	v_lshl_add_u64 v[16:17], v[8:9], 0, s[6:7]
	global_load_dword v33, v[10:11], off
	v_lshl_add_u64 v[22:23], v[16:17], 0, s[8:9]
	global_load_dwordx2 v[64:65], v[12:13], off offset:-4096
	global_load_dwordx2 v[96:97], v[14:15], off offset:-4096
	global_load_dwordx4 v[128:131], v[36:37], off offset:-4096
	global_load_dwordx2 v[66:67], v[12:13], off offset:-3584
	global_load_dwordx2 v[98:99], v[14:15], off offset:-3584
	global_load_dwordx4 v[132:135], v[36:37], off offset:-3072
	global_load_dwordx2 v[68:69], v[12:13], off offset:-3072
	global_load_dwordx2 v[100:101], v[14:15], off offset:-3072
	global_load_dwordx4 v[136:139], v[36:37], off offset:-2048
	global_load_dwordx2 v[70:71], v[12:13], off offset:-2560
	global_load_dwordx2 v[102:103], v[14:15], off offset:-2560
	global_load_dwordx4 v[140:143], v[36:37], off offset:-1024
	global_load_dwordx2 v[72:73], v[12:13], off offset:-2048
	global_load_dwordx2 v[104:105], v[14:15], off offset:-2048
	global_load_dwordx4 v[144:147], v[36:37], off
	global_load_dwordx2 v[74:75], v[12:13], off offset:-1536
	global_load_dwordx2 v[106:107], v[14:15], off offset:-1536
	global_load_dwordx4 v[148:151], v[36:37], off offset:1024
	global_load_dwordx2 v[76:77], v[12:13], off offset:-1024
	global_load_dwordx2 v[108:109], v[14:15], off offset:-1024
	global_load_dwordx4 v[152:155], v[36:37], off offset:2048
	global_load_dwordx2 v[78:79], v[12:13], off offset:-512
	global_load_dwordx2 v[110:111], v[14:15], off offset:-512
	global_load_dwordx4 v[156:159], v[36:37], off offset:3072
	global_load_dwordx2 v[80:81], v[12:13], off
	global_load_dwordx2 v[112:113], v[14:15], off
	global_load_dwordx4 v[160:163], v[38:39], off offset:-4096
	global_load_dwordx2 v[82:83], v[12:13], off offset:512
	global_load_dwordx2 v[114:115], v[14:15], off offset:512
	global_load_dwordx4 v[164:167], v[38:39], off offset:-3072
	global_load_dwordx2 v[84:85], v[12:13], off offset:1024
	global_load_dwordx2 v[116:117], v[14:15], off offset:1024
	global_load_dwordx4 v[168:171], v[38:39], off offset:-2048
	global_load_dwordx2 v[86:87], v[12:13], off offset:1536
	global_load_dwordx2 v[118:119], v[14:15], off offset:1536
	global_load_dwordx4 v[172:175], v[38:39], off offset:-1024
	global_load_dwordx2 v[88:89], v[12:13], off offset:2048
	global_load_dwordx2 v[120:121], v[14:15], off offset:2048
	global_load_dwordx4 v[176:179], v[38:39], off
	global_load_dwordx2 v[90:91], v[12:13], off offset:2560
	global_load_dwordx2 v[122:123], v[14:15], off offset:2560
	global_load_dwordx4 v[180:183], v[38:39], off offset:1024
	global_load_dwordx2 v[92:93], v[12:13], off offset:3072
	global_load_dwordx2 v[124:125], v[14:15], off offset:3072
	global_load_dwordx4 v[184:187], v[38:39], off offset:2048
	global_load_dwordx2 v[94:95], v[12:13], off offset:3584
	global_load_dwordx2 v[126:127], v[14:15], off offset:3584
	global_load_dwordx4 v[188:191], v[38:39], off offset:3072
	s_waitcnt vmcnt(45)
	v_lshlrev_b32_e32 v40, 16, v64
	v_and_b32_e32 v41, 0xffff0000, v64
	v_lshlrev_b32_e32 v42, 16, v65
	v_and_b32_e32 v43, 0xffff0000, v65
	v_lshlrev_b32_e32 v44, 16, v96
	v_and_b32_e32 v45, 0xffff0000, v96
	v_lshlrev_b32_e32 v46, 16, v97
	v_and_b32_e32 v47, 0xffff0000, v97
	v_pk_mul_f32 v[40:41], v[18:19], v[40:41]
	v_pk_mul_f32 v[42:43], v[18:19], v[42:43]
	v_pk_fma_f32 v[128:129], v[128:129], v[40:41], v[44:45]
	v_pk_fma_f32 v[130:131], v[130:131], v[42:43], v[46:47]
	global_store_dwordx4 v[16:17], v[128:131], off offset:-4096 sc1
	s_waitcnt vmcnt(43)
	v_lshlrev_b32_e32 v48, 16, v66
	v_and_b32_e32 v49, 0xffff0000, v66
	v_lshlrev_b32_e32 v50, 16, v67
	v_and_b32_e32 v51, 0xffff0000, v67
	v_lshlrev_b32_e32 v52, 16, v98
	v_and_b32_e32 v53, 0xffff0000, v98
	v_lshlrev_b32_e32 v54, 16, v99
	v_and_b32_e32 v55, 0xffff0000, v99
	v_pk_mul_f32 v[48:49], v[18:19], v[48:49]
	v_pk_mul_f32 v[50:51], v[18:19], v[50:51]
	v_pk_fma_f32 v[132:133], v[132:133], v[48:49], v[52:53]
	v_pk_fma_f32 v[134:135], v[134:135], v[50:51], v[54:55]
	global_store_dwordx4 v[16:17], v[132:135], off offset:-3072 sc1
	s_waitcnt vmcnt(41)
	v_lshlrev_b32_e32 v40, 16, v68
	v_and_b32_e32 v41, 0xffff0000, v68
	v_lshlrev_b32_e32 v42, 16, v69
	v_and_b32_e32 v43, 0xffff0000, v69
	v_lshlrev_b32_e32 v44, 16, v100
	v_and_b32_e32 v45, 0xffff0000, v100
	v_lshlrev_b32_e32 v46, 16, v101
	v_and_b32_e32 v47, 0xffff0000, v101
	v_pk_mul_f32 v[40:41], v[18:19], v[40:41]
	v_pk_mul_f32 v[42:43], v[18:19], v[42:43]
	v_pk_fma_f32 v[136:137], v[136:137], v[40:41], v[44:45]
	v_pk_fma_f32 v[138:139], v[138:139], v[42:43], v[46:47]
	global_store_dwordx4 v[16:17], v[136:139], off offset:-2048 sc1
	s_waitcnt vmcnt(39)
	v_lshlrev_b32_e32 v48, 16, v70
	v_and_b32_e32 v49, 0xffff0000, v70
	v_lshlrev_b32_e32 v50, 16, v71
	v_and_b32_e32 v51, 0xffff0000, v71
	v_lshlrev_b32_e32 v52, 16, v102
	v_and_b32_e32 v53, 0xffff0000, v102
	v_lshlrev_b32_e32 v54, 16, v103
	v_and_b32_e32 v55, 0xffff0000, v103
	v_pk_mul_f32 v[48:49], v[18:19], v[48:49]
	v_pk_mul_f32 v[50:51], v[18:19], v[50:51]
	v_pk_fma_f32 v[140:141], v[140:141], v[48:49], v[52:53]
	v_pk_fma_f32 v[142:143], v[142:143], v[50:51], v[54:55]
	global_store_dwordx4 v[16:17], v[140:143], off offset:-1024 sc1
	s_waitcnt vmcnt(37)
; __device__ __forceinline__ float bf_lo(unsigned w) { return __uint_as_float(w << 16); }
; __device__ __forceinline__ float bf_hi(unsigned w) { return __uint_as_float(w & 0xffff0000u); }
; __device__ __forceinline__ void phase_final(const Params& p, int gw, int NGW, int lane) {
;     ...
;     for (int row = gw; row < MT; row += NGW) {
;         const float r = rsqrtf(wave_sum(SSQ[(size_t)lane * MT + row]) * (1.f / DM) + EPSN);
;         const u32x2* dr = (const u32x2*)(DN + (size_t)row * DM) + lane; const u32x2* hr = (const u32x2*)(H1 + (size_t)row * DM) + lane; f32x4* o = (f32x4*)(p.out + (size_t)row * DM) + lane;
;         const f32x4* gp = g + lane;
;         asm volatile("" : "+v"(gp), "+v"(dr), "+v"(hr), "+v"(o));
; #pragma unroll 8
;         for (int j = 0; j < 16; ++j) { const u32x2 dw = dr[64 * j]; const f32x4 dn = {bf_lo(dw.x), bf_hi(dw.x), bf_lo(dw.y), bf_hi(dw.y)}; const u32x2 hw = hr[64 * j]; const f32x4 hh = {bf_lo(hw.x), bf_hi(hw.x), bf_lo(hw.y), bf_hi(hw.y)}; o[64 * j] = hh + dn * r * gp[64 * j]; }
;     }
	v_lshlrev_b32_e32 v40, 16, v72
	v_and_b32_e32 v41, 0xffff0000, v72
	v_lshlrev_b32_e32 v42, 16, v73
	v_and_b32_e32 v43, 0xffff0000, v73
	v_lshlrev_b32_e32 v44, 16, v104
	v_and_b32_e32 v45, 0xffff0000, v104
	v_lshlrev_b32_e32 v46, 16, v105
	v_and_b32_e32 v47, 0xffff0000, v105
	v_pk_mul_f32 v[40:41], v[18:19], v[40:41]
	v_pk_mul_f32 v[42:43], v[18:19], v[42:43]
	v_pk_fma_f32 v[144:145], v[144:145], v[40:41], v[44:45]
	v_pk_fma_f32 v[146:147], v[146:147], v[42:43], v[46:47]
	global_store_dwordx4 v[16:17], v[144:147], off sc1
	s_waitcnt vmcnt(35)
	v_lshlrev_b32_e32 v48, 16, v74
	v_and_b32_e32 v49, 0xffff0000, v74
	v_lshlrev_b32_e32 v50, 16, v75
	v_and_b32_e32 v51, 0xffff0000, v75
	v_lshlrev_b32_e32 v52, 16, v106
	v_and_b32_e32 v53, 0xffff0000, v106
	v_lshlrev_b32_e32 v54, 16, v107
	v_and_b32_e32 v55, 0xffff0000, v107
	v_pk_mul_f32 v[48:49], v[18:19], v[48:49]
	v_pk_mul_f32 v[50:51], v[18:19], v[50:51]
	v_pk_fma_f32 v[148:149], v[148:149], v[48:49], v[52:53]
	v_pk_fma_f32 v[150:151], v[150:151], v[50:51], v[54:55]
	global_store_dwordx4 v[16:17], v[148:151], off offset:1024 sc1
	s_waitcnt vmcnt(33)
	v_lshlrev_b32_e32 v40, 16, v76
	v_and_b32_e32 v41, 0xffff0000, v76
	v_lshlrev_b32_e32 v42, 16, v77
	v_and_b32_e32 v43, 0xffff0000, v77
	v_lshlrev_b32_e32 v44, 16, v108
	v_and_b32_e32 v45, 0xffff0000, v108
	v_lshlrev_b32_e32 v46, 16, v109
	v_and_b32_e32 v47, 0xffff0000, v109
	v_pk_mul_f32 v[40:41], v[18:19], v[40:41]
	v_pk_mul_f32 v[42:43], v[18:19], v[42:43]
	v_pk_fma_f32 v[152:153], v[152:153], v[40:41], v[44:45]
	v_pk_fma_f32 v[154:155], v[154:155], v[42:43], v[46:47]
	global_store_dwordx4 v[16:17], v[152:155], off offset:2048 sc1
	s_waitcnt vmcnt(31)
	v_lshlrev_b32_e32 v48, 16, v78
	v_and_b32_e32 v49, 0xffff0000, v78
	v_lshlrev_b32_e32 v50, 16, v79
	v_and_b32_e32 v51, 0xffff0000, v79
	v_lshlrev_b32_e32 v52, 16, v110
	v_and_b32_e32 v53, 0xffff0000, v110
	v_lshlrev_b32_e32 v54, 16, v111
	v_and_b32_e32 v55, 0xffff0000, v111
	v_pk_mul_f32 v[48:49], v[18:19], v[48:49]
	v_pk_mul_f32 v[50:51], v[18:19], v[50:51]
	v_pk_fma_f32 v[156:157], v[156:157], v[48:49], v[52:53]
	v_pk_fma_f32 v[158:159], v[158:159], v[50:51], v[54:55]
	global_store_dwordx4 v[16:17], v[156:159], off offset:3072 sc1
	s_waitcnt vmcnt(29)
	v_lshlrev_b32_e32 v40, 16, v80
	v_and_b32_e32 v41, 0xffff0000, v80
	v_lshlrev_b32_e32 v42, 16, v81
	v_and_b32_e32 v43, 0xffff0000, v81
	v_lshlrev_b32_e32 v44, 16, v112
	v_and_b32_e32 v45, 0xffff0000, v112
	v_lshlrev_b32_e32 v46, 16, v113
	v_and_b32_e32 v47, 0xffff0000, v113
	v_pk_mul_f32 v[40:41], v[18:19], v[40:41]
	v_pk_mul_f32 v[42:43], v[18:19], v[42:43]
	v_pk_fma_f32 v[160:161], v[160:161], v[40:41], v[44:45]
	v_pk_fma_f32 v[162:163], v[162:163], v[42:43], v[46:47]
	global_store_dwordx4 v[22:23], v[160:163], off offset:-4096 sc1
	s_waitcnt vmcnt(27)
	v_lshlrev_b32_e32 v48, 16, v82
	v_and_b32_e32 v49, 0xffff0000, v82
	v_lshlrev_b32_e32 v50, 16, v83
	v_and_b32_e32 v51, 0xffff0000, v83
	v_lshlrev_b32_e32 v52, 16, v114
	v_and_b32_e32 v53, 0xffff0000, v114
	v_lshlrev_b32_e32 v54, 16, v115
	v_and_b32_e32 v55, 0xffff0000, v115
	v_pk_mul_f32 v[48:49], v[18:19], v[48:49]
	v_pk_mul_f32 v[50:51], v[18:19], v[50:51]
	v_pk_fma_f32 v[164:165], v[164:165], v[48:49], v[52:53]
	v_pk_fma_f32 v[166:167], v[166:167], v[50:51], v[54:55]
	global_store_dwordx4 v[22:23], v[164:167], off offset:-3072 sc1
	s_waitcnt vmcnt(25)
	v_lshlrev_b32_e32 v40, 16, v84
	v_and_b32_e32 v41, 0xffff0000, v84
	v_lshlrev_b32_e32 v42, 16, v85
	v_and_b32_e32 v43, 0xffff0000, v85
	v_lshlrev_b32_e32 v44, 16, v116
	v_and_b32_e32 v45, 0xffff0000, v116
	v_lshlrev_b32_e32 v46, 16, v117
	v_and_b32_e32 v47, 0xffff0000, v117
	v_pk_mul_f32 v[40:41], v[18:19], v[40:41]
	v_pk_mul_f32 v[42:43], v[18:19], v[42:43]
	v_pk_fma_f32 v[168:169], v[168:169], v[40:41], v[44:45]
	v_pk_fma_f32 v[170:171], v[170:171], v[42:43], v[46:47]
	global_store_dwordx4 v[22:23], v[168:171], off offset:-2048 sc1
	s_waitcnt vmcnt(23)
; __device__ __forceinline__ float bf_lo(unsigned w) { return __uint_as_float(w << 16); }
; __device__ __forceinline__ float bf_hi(unsigned w) { return __uint_as_float(w & 0xffff0000u); }
; __device__ __forceinline__ void phase_final(const Params& p, int gw, int NGW, int lane) {
;     ...
;     for (int row = gw; row < MT; row += NGW) {
;         const float r = rsqrtf(wave_sum(SSQ[(size_t)lane * MT + row]) * (1.f / DM) + EPSN);
;         const u32x2* dr = (const u32x2*)(DN + (size_t)row * DM) + lane; const u32x2* hr = (const u32x2*)(H1 + (size_t)row * DM) + lane; f32x4* o = (f32x4*)(p.out + (size_t)row * DM) + lane;
;         const f32x4* gp = g + lane;
;         asm volatile("" : "+v"(gp), "+v"(dr), "+v"(hr), "+v"(o));
; #pragma unroll 8
;         for (int j = 0; j < 16; ++j) { const u32x2 dw = dr[64 * j]; const f32x4 dn = {bf_lo(dw.x), bf_hi(dw.x), bf_lo(dw.y), bf_hi(dw.y)}; const u32x2 hw = hr[64 * j]; const f32x4 hh = {bf_lo(hw.x), bf_hi(hw.x), bf_lo(hw.y), bf_hi(hw.y)}; o[64 * j] = hh + dn * r * gp[64 * j]; }
;     }
	v_lshlrev_b32_e32 v48, 16, v86
	v_and_b32_e32 v49, 0xffff0000, v86
	v_lshlrev_b32_e32 v50, 16, v87
	v_and_b32_e32 v51, 0xffff0000, v87
	v_lshlrev_b32_e32 v52, 16, v118
	v_and_b32_e32 v53, 0xffff0000, v118
	v_lshlrev_b32_e32 v54, 16, v119
	v_and_b32_e32 v55, 0xffff0000, v119
	v_pk_mul_f32 v[48:49], v[18:19], v[48:49]
	v_pk_mul_f32 v[50:51], v[18:19], v[50:51]
	v_pk_fma_f32 v[172:173], v[172:173], v[48:49], v[52:53]
	v_pk_fma_f32 v[174:175], v[174:175], v[50:51], v[54:55]
	global_store_dwordx4 v[22:23], v[172:175], off offset:-1024 sc1
	s_waitcnt vmcnt(21)
	v_lshlrev_b32_e32 v40, 16, v88
	v_and_b32_e32 v41, 0xffff0000, v88
	v_lshlrev_b32_e32 v42, 16, v89
	v_and_b32_e32 v43, 0xffff0000, v89
	v_lshlrev_b32_e32 v44, 16, v120
	v_and_b32_e32 v45, 0xffff0000, v120
	v_lshlrev_b32_e32 v46, 16, v121
	v_and_b32_e32 v47, 0xffff0000, v121
	v_pk_mul_f32 v[40:41], v[18:19], v[40:41]
	v_pk_mul_f32 v[42:43], v[18:19], v[42:43]
	v_pk_fma_f32 v[176:177], v[176:177], v[40:41], v[44:45]
	v_pk_fma_f32 v[178:179], v[178:179], v[42:43], v[46:47]
	global_store_dwordx4 v[22:23], v[176:179], off sc1
	s_waitcnt vmcnt(19)
	v_lshlrev_b32_e32 v48, 16, v90
	v_and_b32_e32 v49, 0xffff0000, v90
	v_lshlrev_b32_e32 v50, 16, v91
	v_and_b32_e32 v51, 0xffff0000, v91
	v_lshlrev_b32_e32 v52, 16, v122
	v_and_b32_e32 v53, 0xffff0000, v122
	v_lshlrev_b32_e32 v54, 16, v123
	v_and_b32_e32 v55, 0xffff0000, v123
	v_pk_mul_f32 v[48:49], v[18:19], v[48:49]
	v_pk_mul_f32 v[50:51], v[18:19], v[50:51]
	v_pk_fma_f32 v[180:181], v[180:181], v[48:49], v[52:53]
	v_pk_fma_f32 v[182:183], v[182:183], v[50:51], v[54:55]
	global_store_dwordx4 v[22:23], v[180:183], off offset:1024 sc1
	s_waitcnt vmcnt(17)
	v_lshlrev_b32_e32 v40, 16, v92
	v_and_b32_e32 v41, 0xffff0000, v92
	v_lshlrev_b32_e32 v42, 16, v93
	v_and_b32_e32 v43, 0xffff0000, v93
	v_lshlrev_b32_e32 v44, 16, v124
	v_and_b32_e32 v45, 0xffff0000, v124
	v_lshlrev_b32_e32 v46, 16, v125
	v_and_b32_e32 v47, 0xffff0000, v125
	v_pk_mul_f32 v[40:41], v[18:19], v[40:41]
	v_pk_mul_f32 v[42:43], v[18:19], v[42:43]
	v_pk_fma_f32 v[184:185], v[184:185], v[40:41], v[44:45]
	v_pk_fma_f32 v[186:187], v[186:187], v[42:43], v[46:47]
	global_store_dwordx4 v[22:23], v[184:187], off offset:2048 sc1
	s_waitcnt vmcnt(15)
	v_lshlrev_b32_e32 v48, 16, v94
	v_and_b32_e32 v49, 0xffff0000, v94
	v_lshlrev_b32_e32 v50, 16, v95
	v_and_b32_e32 v51, 0xffff0000, v95
	v_lshlrev_b32_e32 v52, 16, v126
	v_and_b32_e32 v53, 0xffff0000, v126
	v_lshlrev_b32_e32 v54, 16, v127
	v_and_b32_e32 v55, 0xffff0000, v127
	v_pk_mul_f32 v[48:49], v[18:19], v[48:49]
	v_pk_mul_f32 v[50:51], v[18:19], v[50:51]
	v_pk_fma_f32 v[188:189], v[188:189], v[48:49], v[52:53]
	v_pk_fma_f32 v[190:191], v[190:191], v[50:51], v[54:55]
	global_store_dwordx4 v[22:23], v[188:191], off offset:3072 sc1
	ds_bpermute_b32 v11, v26, v33
	s_waitcnt lgkmcnt(0)
	v_add_f32_e32 v10, v33, v11
	ds_bpermute_b32 v11, v27, v10
	s_waitcnt lgkmcnt(0)
	v_add_f32_e32 v10, v10, v11
	ds_bpermute_b32 v11, v28, v10
	s_waitcnt lgkmcnt(0)
	v_add_f32_e32 v10, v10, v11
	ds_bpermute_b32 v11, v29, v10
	s_waitcnt lgkmcnt(0)
	v_add_f32_e32 v10, v10, v11
	ds_bpermute_b32 v11, v30, v10
	s_waitcnt lgkmcnt(0)
	v_add_f32_e32 v10, v10, v11
	ds_bpermute_b32 v11, v31, v10
	s_waitcnt lgkmcnt(0)
	v_add_f32_e32 v10, v10, v11
	v_fmamk_f32 v14, v10, 0x39800000, v32
	v_mul_f32_e32 v15, 0x4b800000, v14
	v_cmp_gt_f32_e32 vcc, s4, v14
	s_nop 1
	v_cndmask_b32_e32 v14, v14, v15, vcc
	v_rsq_f32_e32 v18, v14
	s_nop 0
	v_mul_f32_e32 v19, 0x45800000, v18
	v_cndmask_b32_e32 v18, v18, v19, vcc
	v_mov_b32_e32 v19, v18
	s_add_i32 s34, s34, s60
	s_cmpk_gt_i32 s34, 0x1fff
	s_cbranch_scc0 .Lfin_row
